# stack2 = v085 stack + k-tile boundary rotation extended to the 18 remaining boundaries (hoisted reads renamed into spare VGPR quads)
# baseline (speedup 1.0000x reference)
; template <bool SWAP>
; DI void gemm_tile(const bf16_t* __restrict__ A, int lda, const bf16_t* __restrict__ Bt, int ldb, int K, f32x16 (&acc)[2][2], bf16_t* As, bf16_t* Bs_unused) {
;     ...
;   auto load_stage = [&](u32x4 (&ra)[4], u32x4 (&rb)[4], int t) __attribute__((always_inline)) {
; #pragma unroll
;     for (int i = 0; i < 4; ++i) { ra[i] = *(const u32x4*)(ga + (size_t)(32 * i) * lda + t * 64); rb[i] = *(const u32x4*)(gb + (size_t)(32 * i) * ldb + t * 64); }
;   };
;   auto write_stage = [&](const u32x4 (&ra)[4], const u32x4 (&rb)[4], int buf) __attribute__((always_inline)) {
;     bf16_t* Ad = As + buf * 2 * GT_IMG; bf16_t* Bd = Ad + GT_IMG;
; #pragma unroll
;     for (int i = 0; i < 4; ++i) { *(u32x4*)(Ad + (lr + 32 * i) * 72 + lc) = ra[i]; *(u32x4*)(Bd + (lr + 32 * i) * 72 + lc) = rb[i]; }
;   };
;   const int fr = lane & 31, fk = (lane >> 5) * 8;
;   const int pao = (wm * 64 + fr) * 72 + fk, pbo = GT_IMG + (wn * 64 + fr) * 72 + fk;
;   auto frag_read = [&](bf16x8 (&f)[4], const bf16_t* pa, const bf16_t* pb, int so) __attribute__((always_inline)) {
;     f[0] = *(const bf16x8*)(pa + so); f[1] = *(const bf16x8*)(pb + so); f[2] = *(const bf16x8*)(pb + 32 * 72 + so); f[3] = *(const bf16x8*)(pa + 32 * 72 + so);
;   };
;   auto mfma4 = [&](const bf16x8 (&f)[4]) __attribute__((always_inline)) {
;     if (SWAP) {
;       acc[0][0] = MFMA32(f[1], f[0], acc[0][0]); acc[0][1] = MFMA32(f[2], f[0], acc[0][1]);
;       acc[1][0] = MFMA32(f[1], f[3], acc[1][0]); acc[1][1] = MFMA32(f[2], f[3], acc[1][1]);
;     } else {
;       acc[0][0] = MFMA32(f[0], f[1], acc[0][0]); acc[0][1] = MFMA32(f[0], f[2], acc[0][1]);
;       acc[1][0] = MFMA32(f[3], f[1], acc[1][0]); acc[1][1] = MFMA32(f[3], f[2], acc[1][1]);
;     }
;   };
;   auto step = [&](int buf, u32x4 (&ra)[4], u32x4 (&rb)[4], bool do_write, bool do_load, int tload) __attribute__((always_inline)) {
;     const bf16_t* pa = As + buf * 2 * GT_IMG + pao; const bf16_t* pb = As + buf * 2 * GT_IMG + pbo;
;     bf16_t* Ad = As + (buf ^ 1) * 2 * GT_IMG; bf16_t* Bd = Ad + GT_IMG;
;     bf16x8 F0[4], F1[4];
;     frag_read(F0, pa, pb, 0);
;     __builtin_amdgcn_sched_barrier(0);
;     frag_read(F1, pa, pb, 16);
;     mfma4(F0);
;     __builtin_amdgcn_sched_barrier(0);
;     frag_read(F0, pa, pb, 32);
;     mfma4(F1);
;     if (do_write) {
; #pragma unroll
.LBB0_193:
	s_ashr_i32 s7, s6, 31
	s_lshl_b64 s[8:9], s[6:7], 18
	v_mov_b32_e32 v34, v195
	s_add_u32 s8, s63, s8
	s_addc_u32 s9, s70, s9
	v_ashrrev_i32_e32 v32, 3, v34
	s_ashr_i32 s1, s0, 31
	v_ashrrev_i32_e32 v33, 31, v32
	s_lshl_b64 s[14:15], s[0:1], 18
	v_readlane_b32 s1, v235, 57
	v_lshlrev_b64 v[0:1], 11, v[32:33]
	s_waitcnt lgkmcnt(0)
	v_lshlrev_b32_e32 v4, 4, v34
	s_add_u32 s14, s1, s14
	v_readlane_b32 s1, v235, 58
	v_lshl_add_u64 v[2:3], s[8:9], 0, v[0:1]
	v_and_b32_e32 v192, 0x70, v4
	s_addc_u32 s15, s1, s15
	v_lshl_add_u64 v[80:81], v[2:3], 0, v[192:193]
	s_mov_b32 s1, 0x10000
	v_lshl_add_u64 v[0:1], s[14:15], 0, v[0:1]
	v_add_co_u32_e32 v84, vcc, s1, v80
	v_lshl_add_u64 v[82:83], v[0:1], 0, v[192:193]
	s_nop 0
	v_addc_co_u32_e32 v85, vcc, 0, v81, vcc
	v_add_co_u32_e32 v86, vcc, s1, v82
	s_mov_b32 s1, 0x20000
	s_nop 0
	v_addc_co_u32_e32 v87, vcc, 0, v83, vcc
	global_load_dwordx4 v[0:3], v[80:81], off
	global_load_dwordx4 v[4:7], v[82:83], off
	v_add_co_u32_e32 v88, vcc, s1, v80
	global_load_dwordx4 v[8:11], v[84:85], off
	global_load_dwordx4 v[12:15], v[86:87], off
	v_addc_co_u32_e32 v89, vcc, 0, v81, vcc
	v_add_co_u32_e32 v90, vcc, s1, v82
	s_mov_b32 s1, 0x30000
	s_nop 0
	v_addc_co_u32_e32 v91, vcc, 0, v83, vcc
	global_load_dwordx4 v[16:19], v[88:89], off
	global_load_dwordx4 v[20:23], v[90:91], off
	v_add_co_u32_e32 v92, vcc, s1, v80
	v_mul_lo_u32 v32, v32, s71
	s_nop 0
	v_addc_co_u32_e32 v93, vcc, 0, v81, vcc
	global_load_dwordx4 v[24:27], v[92:93], off
	v_add_co_u32_e32 v94, vcc, s1, v82
	v_add3_u32 v100, 32, v32, v192
	s_nop 0
	v_addc_co_u32_e32 v95, vcc, 0, v83, vcc
	global_load_dwordx4 v[28:31], v[94:95], off
	global_load_dwordx4 v[104:107], v[80:81], off offset:128
	global_load_dwordx4 v[108:111], v[82:83], off offset:128
	global_load_dwordx4 v[112:115], v[84:85], off offset:128
	global_load_dwordx4 v[116:119], v[86:87], off offset:128
	global_load_dwordx4 v[120:123], v[88:89], off offset:128
	global_load_dwordx4 v[124:127], v[90:91], off offset:128
	global_load_dwordx4 v[128:131], v[92:93], off offset:128
	global_load_dwordx4 v[132:135], v[94:95], off offset:128
	s_barrier
	v_add_u32_e32 v103, 0xd800, v100
	s_waitcnt vmcnt(15)
	ds_write_b128 v100, v[0:3]
	s_waitcnt vmcnt(14)
	ds_write_b128 v100, v[4:7] offset:18432
	s_waitcnt vmcnt(13)
	ds_write_b128 v100, v[8:11] offset:4608
	s_waitcnt vmcnt(12)
	ds_write_b128 v100, v[12:15] offset:23040
	s_waitcnt vmcnt(11)
	ds_write_b128 v100, v[16:19] offset:9216
	s_waitcnt vmcnt(10)
	ds_write_b128 v100, v[20:23] offset:27648
	s_waitcnt vmcnt(9)
	ds_write_b128 v100, v[24:27] offset:13824
	s_waitcnt vmcnt(8)
	ds_write_b128 v100, v[28:31] offset:32256
	global_load_dwordx4 v[136:139], v[80:81], off offset:256
	global_load_dwordx4 v[64:67], v[82:83], off offset:256
	global_load_dwordx4 v[140:143], v[84:85], off offset:256
	global_load_dwordx4 v[68:71], v[86:87], off offset:256
	global_load_dwordx4 v[144:147], v[88:89], off offset:256
	global_load_dwordx4 v[72:75], v[90:91], off offset:256
	global_load_dwordx4 v[148:151], v[92:93], off offset:256
	global_load_dwordx4 v[76:79], v[94:95], off offset:256
	v_lshrrev_b32_e32 v0, 2, v34
	v_lshrrev_b32_e32 v2, 1, v34
	v_and_b32_e32 v3, 31, v34
	v_and_b32_e32 v1, 0x5f, v34
	v_and_b32_e32 v0, 8, v0
	v_and_or_b32 v2, v2, s80, v3
	v_mad_u64_u32 v[2:3], s[8:9], v2, s72, v[0:1]
	v_lshl_add_u32 v101, v2, 1, 32
	v_mad_u32_u24 v0, v1, s72, v0
	s_waitcnt lgkmcnt(0)
	s_barrier
	v_lshl_add_u32 v102, v0, 1, 32
	ds_read_b128 v[0:3], v101
	ds_read_b128 v[4:7], v102 offset:18432
	ds_read_b128 v[8:11], v102 offset:23040
	ds_read_b128 v[12:15], v101 offset:4608
	ds_read_b128 v[152:155], v102 offset:18464
	ds_read_b128 v[156:159], v102 offset:23072
	ds_read_b128 v[160:163], v101 offset:32
	ds_read_b128 v[164:167], v101 offset:4640
	s_waitcnt lgkmcnt(6)
	v_mfma_f32_32x32x16_bf16 v[48:63], v[4:7], v[0:3], 0
	s_waitcnt lgkmcnt(5)
	v_mfma_f32_32x32x16_bf16 v[32:47], v[8:11], v[0:3], 0
	s_waitcnt lgkmcnt(4)
	v_mfma_f32_32x32x16_bf16 v[16:31], v[4:7], v[12:15], 0
	v_mfma_f32_32x32x16_bf16 v[0:15], v[8:11], v[12:15], 0
	s_waitcnt lgkmcnt(1)
	v_mfma_f32_32x32x16_bf16 v[48:63], v[152:155], v[160:163], v[48:63]
	v_mfma_f32_32x32x16_bf16 v[32:47], v[156:159], v[160:163], v[32:47]
	s_waitcnt lgkmcnt(0)
	v_mfma_f32_32x32x16_bf16 v[16:31], v[152:155], v[164:167], v[16:31]
	ds_read_b128 v[152:155], v102 offset:18496
	ds_read_b128 v[160:163], v102 offset:23104
	ds_read_b128 v[168:171], v101 offset:64
	ds_read_b128 v[172:175], v101 offset:4672
	s_waitcnt vmcnt(15)
	ds_write_b128 v100, v[104:107] offset:36864
	s_waitcnt vmcnt(13)
	ds_write_b128 v100, v[112:115] offset:41472
	s_waitcnt vmcnt(11)
	ds_write_b128 v100, v[120:123] offset:46080
	s_waitcnt vmcnt(9)
	ds_write_b128 v100, v[128:131] offset:50688
	v_mfma_f32_32x32x16_bf16 v[0:15], v[156:159], v[164:167], v[0:15]
	ds_read_b128 v[104:107], v102 offset:18528
	ds_read_b128 v[112:115], v102 offset:23136
	ds_read_b128 v[120:123], v101 offset:96
	ds_read_b128 v[128:131], v101 offset:4704
	s_waitcnt lgkmcnt(9)
	v_mfma_f32_32x32x16_bf16 v[48:63], v[152:155], v[168:171], v[48:63]
	ds_write_b128 v100, v[108:111] offset:55296
	ds_write_b128 v100, v[116:119] offset:59904
	ds_write_b128 v100, v[124:127] offset:64512
	s_waitcnt vmcnt(8)
	ds_write_b128 v103, v[132:135] offset:13824
	v_mfma_f32_32x32x16_bf16 v[32:47], v[160:163], v[168:171], v[32:47]
	s_waitcnt lgkmcnt(12)
	v_mfma_f32_32x32x16_bf16 v[16:31], v[152:155], v[172:175], v[16:31]
	v_mfma_f32_32x32x16_bf16 v[0:15], v[160:163], v[172:175], v[0:15]
	s_waitcnt lgkmcnt(0)
	s_barrier
; template <bool SWAP>
; DI void gemm_tile(const bf16_t* __restrict__ A, int lda, const bf16_t* __restrict__ Bt, int ldb, int K, f32x16 (&acc)[2][2], bf16_t* As, bf16_t* Bs_unused) {
;     ...
;   auto step = [&](int buf, u32x4 (&ra)[4], u32x4 (&rb)[4], bool do_write, bool do_load, int tload) __attribute__((always_inline)) {
;     const bf16_t* pa = As + buf * 2 * GT_IMG + pao; const bf16_t* pb = As + buf * 2 * GT_IMG + pbo;
;     bf16_t* Ad = As + (buf ^ 1) * 2 * GT_IMG; bf16_t* Bd = Ad + GT_IMG;
;     bf16x8 F0[4], F1[4];
;     frag_read(F0, pa, pb, 0);
;     __builtin_amdgcn_sched_barrier(0);
;     frag_read(F1, pa, pb, 16);
;     mfma4(F0);
;     __builtin_amdgcn_sched_barrier(0);
;     frag_read(F0, pa, pb, 32);
;     mfma4(F1);
;     if (do_write) {
; #pragma unroll
;       for (int i = 0; i < 4; ++i) *(u32x4*)(Ad + (lr + 32 * i) * 72 + lc) = ra[i];
;     }
;     __builtin_amdgcn_sched_barrier(0);
;     frag_read(F1, pa, pb, 48);
;     mfma4(F0);
;     if (do_write) {
; #pragma unroll
;       for (int i = 0; i < 4; ++i) *(u32x4*)(Bd + (lr + 32 * i) * 72 + lc) = rb[i];
;     }
;     __builtin_amdgcn_sched_barrier(0);
;     mfma4(F1);
;     if (do_load) load_stage(ra, rb, tload);
;     __builtin_amdgcn_sched_barrier(0);
;   };
;   const int nk = K >> 6;
;   load_stage(ra0, rb0, 0); load_stage(ra1, rb1, 1);
;   __syncthreads();
;   write_stage(ra0, rb0, 0);
;   load_stage(ra0, rb0, 2);
;   __syncthreads();
;   for (int kt = 0; kt < nk; kt += 2) {
;     step(0, ra1, rb1, true, kt + 3 < nk, kt + 3);
;     __syncthreads();
;     step(1, ra0, rb0, kt + 2 < nk, kt + 4 < nk, kt + 4);
;     __syncthreads();
	ds_read_b128 v[152:155], v102 offset:55296
	ds_read_b128 v[156:159], v102 offset:59904
	ds_read_b128 v[160:163], v101 offset:36864
	ds_read_b128 v[164:167], v101 offset:41472
	v_mfma_f32_32x32x16_bf16 v[48:63], v[104:107], v[120:123], v[48:63]
	v_mfma_f32_32x32x16_bf16 v[32:47], v[112:115], v[120:123], v[32:47]
	v_mfma_f32_32x32x16_bf16 v[16:31], v[104:107], v[128:131], v[16:31]
	v_mfma_f32_32x32x16_bf16 v[0:15], v[112:115], v[128:131], v[0:15]
	global_load_dwordx4 v[104:107], v[80:81], off offset:384
	global_load_dwordx4 v[108:111], v[82:83], off offset:384
	global_load_dwordx4 v[112:115], v[84:85], off offset:384
	global_load_dwordx4 v[116:119], v[86:87], off offset:384
	global_load_dwordx4 v[120:123], v[88:89], off offset:384
	global_load_dwordx4 v[124:127], v[90:91], off offset:384
	global_load_dwordx4 v[128:131], v[92:93], off offset:384
	global_load_dwordx4 v[132:135], v[94:95], off offset:384
	s_waitcnt lgkmcnt(1)
	v_mfma_f32_32x32x16_bf16 v[48:63], v[152:155], v[160:163], v[48:63]
	v_mfma_f32_32x32x16_bf16 v[32:47], v[156:159], v[160:163], v[32:47]
	s_waitcnt lgkmcnt(0)
	v_mfma_f32_32x32x16_bf16 v[16:31], v[152:155], v[164:167], v[16:31]
	ds_read_b128 v[152:155], v102 offset:55328
	ds_read_b128 v[160:163], v102 offset:59936
	ds_read_b128 v[168:171], v101 offset:36896
	ds_read_b128 v[172:175], v101 offset:41504
	v_mfma_f32_32x32x16_bf16 v[0:15], v[156:159], v[164:167], v[0:15]
	s_waitcnt lgkmcnt(1)
	v_mfma_f32_32x32x16_bf16 v[48:63], v[152:155], v[168:171], v[48:63]
	v_mfma_f32_32x32x16_bf16 v[32:47], v[160:163], v[168:171], v[32:47]
	s_waitcnt lgkmcnt(0)
	v_mfma_f32_32x32x16_bf16 v[16:31], v[152:155], v[172:175], v[16:31]
	ds_read_b128 v[152:155], v102 offset:55360
	ds_read_b128 v[156:159], v102 offset:59968
	ds_read_b128 v[164:167], v101 offset:36928
	ds_read_b128 v[168:171], v101 offset:41536
	s_waitcnt vmcnt(15)
	ds_write_b128 v100, v[136:139]
	s_waitcnt vmcnt(13)
	ds_write_b128 v100, v[140:143] offset:4608
	s_waitcnt vmcnt(11)
	ds_write_b128 v100, v[144:147] offset:9216
	s_waitcnt vmcnt(9)
	ds_write_b128 v100, v[148:151] offset:13824
	v_mfma_f32_32x32x16_bf16 v[0:15], v[160:163], v[172:175], v[0:15]
	ds_read_b128 v[136:139], v102 offset:55392
	ds_read_b128 v[140:143], v102 offset:60000
	ds_read_b128 v[144:147], v101 offset:36960
	ds_read_b128 v[148:151], v101 offset:41568
	s_waitcnt lgkmcnt(9)
	v_mfma_f32_32x32x16_bf16 v[48:63], v[152:155], v[164:167], v[48:63]
	ds_write_b128 v100, v[64:67] offset:18432
	ds_write_b128 v100, v[68:71] offset:23040
	ds_write_b128 v100, v[72:75] offset:27648
	s_waitcnt vmcnt(8)
	ds_write_b128 v100, v[76:79] offset:32256
	v_mfma_f32_32x32x16_bf16 v[32:47], v[156:159], v[164:167], v[32:47]
	s_waitcnt lgkmcnt(12)
	v_mfma_f32_32x32x16_bf16 v[16:31], v[152:155], v[168:171], v[16:31]
	v_mfma_f32_32x32x16_bf16 v[0:15], v[156:159], v[168:171], v[0:15]
	s_waitcnt lgkmcnt(0)
	s_barrier
	ds_read_b128 v[152:155], v102 offset:18432
	ds_read_b128 v[156:159], v102 offset:23040
	ds_read_b128 v[160:163], v101
	ds_read_b128 v[164:167], v101 offset:4608
	v_mfma_f32_32x32x16_bf16 v[48:63], v[136:139], v[144:147], v[48:63]
	v_mfma_f32_32x32x16_bf16 v[32:47], v[140:143], v[144:147], v[32:47]
	v_mfma_f32_32x32x16_bf16 v[16:31], v[136:139], v[148:151], v[16:31]
	v_mfma_f32_32x32x16_bf16 v[0:15], v[140:143], v[148:151], v[0:15]
	global_load_dwordx4 v[64:67], v[80:81], off offset:512
	global_load_dwordx4 v[68:71], v[82:83], off offset:512
	global_load_dwordx4 v[72:75], v[84:85], off offset:512
	global_load_dwordx4 v[76:79], v[86:87], off offset:512
	global_load_dwordx4 v[136:139], v[88:89], off offset:512
	global_load_dwordx4 v[140:143], v[90:91], off offset:512
	global_load_dwordx4 v[144:147], v[92:93], off offset:512
	global_load_dwordx4 v[148:151], v[94:95], off offset:512
	s_waitcnt lgkmcnt(1)
	v_mfma_f32_32x32x16_bf16 v[48:63], v[152:155], v[160:163], v[48:63]
	v_mfma_f32_32x32x16_bf16 v[32:47], v[156:159], v[160:163], v[32:47]
	s_waitcnt lgkmcnt(0)
	v_mfma_f32_32x32x16_bf16 v[16:31], v[152:155], v[164:167], v[16:31]
	ds_read_b128 v[152:155], v102 offset:18464
	ds_read_b128 v[160:163], v102 offset:23072
	ds_read_b128 v[168:171], v101 offset:32
	ds_read_b128 v[172:175], v101 offset:4640
	v_mfma_f32_32x32x16_bf16 v[0:15], v[156:159], v[164:167], v[0:15]
	s_waitcnt lgkmcnt(1)
	v_mfma_f32_32x32x16_bf16 v[48:63], v[152:155], v[168:171], v[48:63]
	v_mfma_f32_32x32x16_bf16 v[32:47], v[160:163], v[168:171], v[32:47]
	s_waitcnt lgkmcnt(0)
	v_mfma_f32_32x32x16_bf16 v[16:31], v[152:155], v[172:175], v[16:31]
	ds_read_b128 v[152:155], v102 offset:18496
	ds_read_b128 v[156:159], v102 offset:23104
	ds_read_b128 v[164:167], v101 offset:64
	ds_read_b128 v[168:171], v101 offset:4672
	s_waitcnt vmcnt(15)
	ds_write_b128 v100, v[104:107] offset:36864
	s_waitcnt vmcnt(13)
	ds_write_b128 v100, v[112:115] offset:41472
	s_waitcnt vmcnt(11)
	ds_write_b128 v100, v[120:123] offset:46080
	s_waitcnt vmcnt(9)
	ds_write_b128 v100, v[128:131] offset:50688
	v_mfma_f32_32x32x16_bf16 v[0:15], v[160:163], v[172:175], v[0:15]
	ds_read_b128 v[104:107], v102 offset:18528
	ds_read_b128 v[112:115], v102 offset:23136
	ds_read_b128 v[120:123], v101 offset:96
	ds_read_b128 v[128:131], v101 offset:4704
	s_waitcnt lgkmcnt(9)
	v_mfma_f32_32x32x16_bf16 v[48:63], v[152:155], v[164:167], v[48:63]
	ds_write_b128 v100, v[108:111] offset:55296
	ds_write_b128 v100, v[116:119] offset:59904
	ds_write_b128 v100, v[124:127] offset:64512
	s_waitcnt vmcnt(8)
	ds_write_b128 v103, v[132:135] offset:13824
	v_mfma_f32_32x32x16_bf16 v[32:47], v[156:159], v[164:167], v[32:47]
	s_waitcnt lgkmcnt(12)
	v_mfma_f32_32x32x16_bf16 v[16:31], v[152:155], v[168:171], v[16:31]
	v_mfma_f32_32x32x16_bf16 v[0:15], v[156:159], v[168:171], v[0:15]
	s_waitcnt lgkmcnt(0)
	s_barrier
; template <bool SWAP>
; DI void gemm_tile(const bf16_t* __restrict__ A, int lda, const bf16_t* __restrict__ Bt, int ldb, int K, f32x16 (&acc)[2][2], bf16_t* As, bf16_t* Bs_unused) {
;     ...
;   auto step = [&](int buf, u32x4 (&ra)[4], u32x4 (&rb)[4], bool do_write, bool do_load, int tload) __attribute__((always_inline)) {
;     const bf16_t* pa = As + buf * 2 * GT_IMG + pao; const bf16_t* pb = As + buf * 2 * GT_IMG + pbo;
;     bf16_t* Ad = As + (buf ^ 1) * 2 * GT_IMG; bf16_t* Bd = Ad + GT_IMG;
;     bf16x8 F0[4], F1[4];
;     frag_read(F0, pa, pb, 0);
;     __builtin_amdgcn_sched_barrier(0);
;     frag_read(F1, pa, pb, 16);
;     mfma4(F0);
;     __builtin_amdgcn_sched_barrier(0);
;     frag_read(F0, pa, pb, 32);
;     mfma4(F1);
;     if (do_write) {
; #pragma unroll
;       for (int i = 0; i < 4; ++i) *(u32x4*)(Ad + (lr + 32 * i) * 72 + lc) = ra[i];
;     }
;     __builtin_amdgcn_sched_barrier(0);
;     frag_read(F1, pa, pb, 48);
;     mfma4(F0);
;     if (do_write) {
; #pragma unroll
;       for (int i = 0; i < 4; ++i) *(u32x4*)(Bd + (lr + 32 * i) * 72 + lc) = rb[i];
;     }
;     __builtin_amdgcn_sched_barrier(0);
;     mfma4(F1);
;     if (do_load) load_stage(ra, rb, tload);
;     __builtin_amdgcn_sched_barrier(0);
;   };
;   const int nk = K >> 6;
;   load_stage(ra0, rb0, 0); load_stage(ra1, rb1, 1);
;   __syncthreads();
;   write_stage(ra0, rb0, 0);
;   load_stage(ra0, rb0, 2);
;   __syncthreads();
;   for (int kt = 0; kt < nk; kt += 2) {
;     step(0, ra1, rb1, true, kt + 3 < nk, kt + 3);
;     __syncthreads();
;     step(1, ra0, rb0, kt + 2 < nk, kt + 4 < nk, kt + 4);
;     __syncthreads();
	ds_read_b128 v[152:155], v102 offset:55296
	ds_read_b128 v[156:159], v102 offset:59904
	ds_read_b128 v[160:163], v101 offset:36864
	ds_read_b128 v[164:167], v101 offset:41472
	v_mfma_f32_32x32x16_bf16 v[48:63], v[104:107], v[120:123], v[48:63]
	v_mfma_f32_32x32x16_bf16 v[32:47], v[112:115], v[120:123], v[32:47]
	v_mfma_f32_32x32x16_bf16 v[16:31], v[104:107], v[128:131], v[16:31]
	v_mfma_f32_32x32x16_bf16 v[0:15], v[112:115], v[128:131], v[0:15]
	global_load_dwordx4 v[104:107], v[80:81], off offset:640
	global_load_dwordx4 v[108:111], v[82:83], off offset:640
	global_load_dwordx4 v[112:115], v[84:85], off offset:640
	global_load_dwordx4 v[116:119], v[86:87], off offset:640
	global_load_dwordx4 v[120:123], v[88:89], off offset:640
	global_load_dwordx4 v[124:127], v[90:91], off offset:640
	global_load_dwordx4 v[128:131], v[92:93], off offset:640
	global_load_dwordx4 v[132:135], v[94:95], off offset:640
	s_waitcnt lgkmcnt(1)
	v_mfma_f32_32x32x16_bf16 v[48:63], v[152:155], v[160:163], v[48:63]
	v_mfma_f32_32x32x16_bf16 v[32:47], v[156:159], v[160:163], v[32:47]
	s_waitcnt lgkmcnt(0)
	v_mfma_f32_32x32x16_bf16 v[16:31], v[152:155], v[164:167], v[16:31]
	ds_read_b128 v[152:155], v102 offset:55328
	ds_read_b128 v[160:163], v102 offset:59936
	ds_read_b128 v[168:171], v101 offset:36896
	ds_read_b128 v[172:175], v101 offset:41504
	v_mfma_f32_32x32x16_bf16 v[0:15], v[156:159], v[164:167], v[0:15]
	s_waitcnt lgkmcnt(1)
	v_mfma_f32_32x32x16_bf16 v[48:63], v[152:155], v[168:171], v[48:63]
	v_mfma_f32_32x32x16_bf16 v[32:47], v[160:163], v[168:171], v[32:47]
	s_waitcnt lgkmcnt(0)
	v_mfma_f32_32x32x16_bf16 v[16:31], v[152:155], v[172:175], v[16:31]
	ds_read_b128 v[152:155], v102 offset:55360
	ds_read_b128 v[156:159], v102 offset:59968
	ds_read_b128 v[164:167], v101 offset:36928
	ds_read_b128 v[168:171], v101 offset:41536
	s_waitcnt vmcnt(15)
	ds_write_b128 v100, v[64:67]
	s_waitcnt vmcnt(13)
	ds_write_b128 v100, v[72:75] offset:4608
	s_waitcnt vmcnt(11)
	ds_write_b128 v100, v[136:139] offset:9216
	s_waitcnt vmcnt(9)
	ds_write_b128 v100, v[144:147] offset:13824
	v_mfma_f32_32x32x16_bf16 v[0:15], v[160:163], v[172:175], v[0:15]
	ds_read_b128 v[64:67], v102 offset:55392
	ds_read_b128 v[72:75], v102 offset:60000
	ds_read_b128 v[136:139], v101 offset:36960
	ds_read_b128 v[144:147], v101 offset:41568
	s_waitcnt lgkmcnt(9)
	v_mfma_f32_32x32x16_bf16 v[48:63], v[152:155], v[164:167], v[48:63]
	ds_write_b128 v100, v[68:71] offset:18432
	ds_write_b128 v100, v[76:79] offset:23040
	ds_write_b128 v100, v[140:143] offset:27648
	s_waitcnt vmcnt(8)
	ds_write_b128 v100, v[148:151] offset:32256
	v_mfma_f32_32x32x16_bf16 v[32:47], v[156:159], v[164:167], v[32:47]
	s_waitcnt lgkmcnt(12)
	v_mfma_f32_32x32x16_bf16 v[16:31], v[152:155], v[168:171], v[16:31]
	v_mfma_f32_32x32x16_bf16 v[0:15], v[156:159], v[168:171], v[0:15]
	s_waitcnt lgkmcnt(0)
	s_barrier
	ds_read_b128 v[152:155], v102 offset:18432
	ds_read_b128 v[156:159], v102 offset:23040
	ds_read_b128 v[160:163], v101
	ds_read_b128 v[164:167], v101 offset:4608
	v_mfma_f32_32x32x16_bf16 v[48:63], v[64:67], v[136:139], v[48:63]
	v_mfma_f32_32x32x16_bf16 v[32:47], v[72:75], v[136:139], v[32:47]
	v_mfma_f32_32x32x16_bf16 v[16:31], v[64:67], v[144:147], v[16:31]
	v_mfma_f32_32x32x16_bf16 v[0:15], v[72:75], v[144:147], v[0:15]
	global_load_dwordx4 v[64:67], v[80:81], off offset:768
	global_load_dwordx4 v[68:71], v[82:83], off offset:768
	global_load_dwordx4 v[72:75], v[84:85], off offset:768
	global_load_dwordx4 v[76:79], v[86:87], off offset:768
	global_load_dwordx4 v[136:139], v[88:89], off offset:768
	global_load_dwordx4 v[140:143], v[90:91], off offset:768
	global_load_dwordx4 v[144:147], v[92:93], off offset:768
	global_load_dwordx4 v[148:151], v[94:95], off offset:768
	s_waitcnt lgkmcnt(1)
	v_mfma_f32_32x32x16_bf16 v[48:63], v[152:155], v[160:163], v[48:63]
	v_mfma_f32_32x32x16_bf16 v[32:47], v[156:159], v[160:163], v[32:47]
	s_waitcnt lgkmcnt(0)
	v_mfma_f32_32x32x16_bf16 v[16:31], v[152:155], v[164:167], v[16:31]
	ds_read_b128 v[152:155], v102 offset:18464
	ds_read_b128 v[160:163], v102 offset:23072
	ds_read_b128 v[168:171], v101 offset:32
	ds_read_b128 v[172:175], v101 offset:4640
	v_mfma_f32_32x32x16_bf16 v[0:15], v[156:159], v[164:167], v[0:15]
	s_waitcnt lgkmcnt(1)
	v_mfma_f32_32x32x16_bf16 v[48:63], v[152:155], v[168:171], v[48:63]
	v_mfma_f32_32x32x16_bf16 v[32:47], v[160:163], v[168:171], v[32:47]
	s_waitcnt lgkmcnt(0)
	v_mfma_f32_32x32x16_bf16 v[16:31], v[152:155], v[172:175], v[16:31]
	ds_read_b128 v[152:155], v102 offset:18496
	ds_read_b128 v[156:159], v102 offset:23104
	ds_read_b128 v[164:167], v101 offset:64
	ds_read_b128 v[168:171], v101 offset:4672
	s_waitcnt vmcnt(15)
	ds_write_b128 v100, v[104:107] offset:36864
	s_waitcnt vmcnt(13)
	ds_write_b128 v100, v[112:115] offset:41472
	s_waitcnt vmcnt(11)
	ds_write_b128 v100, v[120:123] offset:46080
	s_waitcnt vmcnt(9)
	ds_write_b128 v100, v[128:131] offset:50688
	v_mfma_f32_32x32x16_bf16 v[0:15], v[160:163], v[172:175], v[0:15]
	ds_read_b128 v[104:107], v102 offset:18528
	ds_read_b128 v[112:115], v102 offset:23136
	ds_read_b128 v[120:123], v101 offset:96
	ds_read_b128 v[128:131], v101 offset:4704
	s_waitcnt lgkmcnt(9)
	v_mfma_f32_32x32x16_bf16 v[48:63], v[152:155], v[164:167], v[48:63]
	ds_write_b128 v100, v[108:111] offset:55296
	ds_write_b128 v100, v[116:119] offset:59904
	ds_write_b128 v100, v[124:127] offset:64512
	s_waitcnt vmcnt(8)
	ds_write_b128 v103, v[132:135] offset:13824
	v_mfma_f32_32x32x16_bf16 v[32:47], v[156:159], v[164:167], v[32:47]
	s_waitcnt lgkmcnt(12)
	v_mfma_f32_32x32x16_bf16 v[16:31], v[152:155], v[168:171], v[16:31]
	v_mfma_f32_32x32x16_bf16 v[0:15], v[156:159], v[168:171], v[0:15]
	s_waitcnt lgkmcnt(0)
	s_barrier
; template <bool SWAP>
; DI void gemm_tile(const bf16_t* __restrict__ A, int lda, const bf16_t* __restrict__ Bt, int ldb, int K, f32x16 (&acc)[2][2], bf16_t* As, bf16_t* Bs_unused) {
;     ...
;   auto step = [&](int buf, u32x4 (&ra)[4], u32x4 (&rb)[4], bool do_write, bool do_load, int tload) __attribute__((always_inline)) {
;     const bf16_t* pa = As + buf * 2 * GT_IMG + pao; const bf16_t* pb = As + buf * 2 * GT_IMG + pbo;
;     bf16_t* Ad = As + (buf ^ 1) * 2 * GT_IMG; bf16_t* Bd = Ad + GT_IMG;
;     bf16x8 F0[4], F1[4];
;     frag_read(F0, pa, pb, 0);
;     __builtin_amdgcn_sched_barrier(0);
;     frag_read(F1, pa, pb, 16);
;     mfma4(F0);
;     __builtin_amdgcn_sched_barrier(0);
;     frag_read(F0, pa, pb, 32);
;     mfma4(F1);
;     if (do_write) {
; #pragma unroll
;       for (int i = 0; i < 4; ++i) *(u32x4*)(Ad + (lr + 32 * i) * 72 + lc) = ra[i];
;     }
;     __builtin_amdgcn_sched_barrier(0);
;     frag_read(F1, pa, pb, 48);
;     mfma4(F0);
;     if (do_write) {
; #pragma unroll
;       for (int i = 0; i < 4; ++i) *(u32x4*)(Bd + (lr + 32 * i) * 72 + lc) = rb[i];
;     }
;     __builtin_amdgcn_sched_barrier(0);
;     mfma4(F1);
;     if (do_load) load_stage(ra, rb, tload);
;     __builtin_amdgcn_sched_barrier(0);
;   };
;   const int nk = K >> 6;
;   load_stage(ra0, rb0, 0); load_stage(ra1, rb1, 1);
;   __syncthreads();
;   write_stage(ra0, rb0, 0);
;   load_stage(ra0, rb0, 2);
;   __syncthreads();
;   for (int kt = 0; kt < nk; kt += 2) {
;     step(0, ra1, rb1, true, kt + 3 < nk, kt + 3);
;     __syncthreads();
;     step(1, ra0, rb0, kt + 2 < nk, kt + 4 < nk, kt + 4);
;     __syncthreads();
	ds_read_b128 v[152:155], v102 offset:55296
	ds_read_b128 v[156:159], v102 offset:59904
	ds_read_b128 v[160:163], v101 offset:36864
	ds_read_b128 v[164:167], v101 offset:41472
	v_mfma_f32_32x32x16_bf16 v[48:63], v[104:107], v[120:123], v[48:63]
	v_mfma_f32_32x32x16_bf16 v[32:47], v[112:115], v[120:123], v[32:47]
	v_mfma_f32_32x32x16_bf16 v[16:31], v[104:107], v[128:131], v[16:31]
	v_mfma_f32_32x32x16_bf16 v[0:15], v[112:115], v[128:131], v[0:15]
	global_load_dwordx4 v[104:107], v[80:81], off offset:896
	global_load_dwordx4 v[108:111], v[82:83], off offset:896
	global_load_dwordx4 v[112:115], v[84:85], off offset:896
	global_load_dwordx4 v[116:119], v[86:87], off offset:896
	global_load_dwordx4 v[120:123], v[88:89], off offset:896
	global_load_dwordx4 v[124:127], v[90:91], off offset:896
	global_load_dwordx4 v[128:131], v[92:93], off offset:896
	global_load_dwordx4 v[132:135], v[94:95], off offset:896
	s_waitcnt lgkmcnt(1)
	v_mfma_f32_32x32x16_bf16 v[48:63], v[152:155], v[160:163], v[48:63]
	v_mfma_f32_32x32x16_bf16 v[32:47], v[156:159], v[160:163], v[32:47]
	s_waitcnt lgkmcnt(0)
	v_mfma_f32_32x32x16_bf16 v[16:31], v[152:155], v[164:167], v[16:31]
	ds_read_b128 v[152:155], v102 offset:55328
	ds_read_b128 v[160:163], v102 offset:59936
	ds_read_b128 v[168:171], v101 offset:36896
	ds_read_b128 v[172:175], v101 offset:41504
	v_mfma_f32_32x32x16_bf16 v[0:15], v[156:159], v[164:167], v[0:15]
	s_waitcnt lgkmcnt(1)
	v_mfma_f32_32x32x16_bf16 v[48:63], v[152:155], v[168:171], v[48:63]
	v_mfma_f32_32x32x16_bf16 v[32:47], v[160:163], v[168:171], v[32:47]
	s_waitcnt lgkmcnt(0)
	v_mfma_f32_32x32x16_bf16 v[16:31], v[152:155], v[172:175], v[16:31]
	ds_read_b128 v[152:155], v102 offset:55360
	ds_read_b128 v[156:159], v102 offset:59968
	ds_read_b128 v[164:167], v101 offset:36928
	ds_read_b128 v[168:171], v101 offset:41536
	s_waitcnt vmcnt(15)
	ds_write_b128 v100, v[64:67]
	s_waitcnt vmcnt(13)
	ds_write_b128 v100, v[72:75] offset:4608
	s_waitcnt vmcnt(11)
	ds_write_b128 v100, v[136:139] offset:9216
	s_waitcnt vmcnt(9)
	ds_write_b128 v100, v[144:147] offset:13824
	v_mfma_f32_32x32x16_bf16 v[0:15], v[160:163], v[172:175], v[0:15]
	ds_read_b128 v[64:67], v102 offset:55392
	ds_read_b128 v[72:75], v102 offset:60000
	ds_read_b128 v[136:139], v101 offset:36960
	ds_read_b128 v[144:147], v101 offset:41568
	s_waitcnt lgkmcnt(9)
	v_mfma_f32_32x32x16_bf16 v[48:63], v[152:155], v[164:167], v[48:63]
	ds_write_b128 v100, v[68:71] offset:18432
	ds_write_b128 v100, v[76:79] offset:23040
	ds_write_b128 v100, v[140:143] offset:27648
	s_waitcnt vmcnt(8)
	ds_write_b128 v100, v[148:151] offset:32256
	v_mfma_f32_32x32x16_bf16 v[32:47], v[156:159], v[164:167], v[32:47]
	s_waitcnt lgkmcnt(12)
	v_mfma_f32_32x32x16_bf16 v[16:31], v[152:155], v[168:171], v[16:31]
	v_mfma_f32_32x32x16_bf16 v[0:15], v[156:159], v[168:171], v[0:15]
	s_waitcnt lgkmcnt(0)
	s_barrier
	ds_read_b128 v[152:155], v102 offset:18432
	ds_read_b128 v[156:159], v102 offset:23040
	ds_read_b128 v[160:163], v101
	ds_read_b128 v[164:167], v101 offset:4608
	v_mfma_f32_32x32x16_bf16 v[48:63], v[64:67], v[136:139], v[48:63]
	v_mfma_f32_32x32x16_bf16 v[32:47], v[72:75], v[136:139], v[32:47]
	v_mfma_f32_32x32x16_bf16 v[16:31], v[64:67], v[144:147], v[16:31]
	v_mfma_f32_32x32x16_bf16 v[0:15], v[72:75], v[144:147], v[0:15]
	global_load_dwordx4 v[64:67], v[80:81], off offset:1024
	global_load_dwordx4 v[68:71], v[82:83], off offset:1024
	global_load_dwordx4 v[72:75], v[84:85], off offset:1024
	global_load_dwordx4 v[76:79], v[86:87], off offset:1024
	global_load_dwordx4 v[136:139], v[88:89], off offset:1024
	global_load_dwordx4 v[140:143], v[90:91], off offset:1024
	global_load_dwordx4 v[144:147], v[92:93], off offset:1024
	global_load_dwordx4 v[148:151], v[94:95], off offset:1024
	s_waitcnt lgkmcnt(1)
	v_mfma_f32_32x32x16_bf16 v[48:63], v[152:155], v[160:163], v[48:63]
	v_mfma_f32_32x32x16_bf16 v[32:47], v[156:159], v[160:163], v[32:47]
	s_waitcnt lgkmcnt(0)
	v_mfma_f32_32x32x16_bf16 v[16:31], v[152:155], v[164:167], v[16:31]
	ds_read_b128 v[152:155], v102 offset:18464
	ds_read_b128 v[160:163], v102 offset:23072
	ds_read_b128 v[168:171], v101 offset:32
	ds_read_b128 v[172:175], v101 offset:4640
	v_mfma_f32_32x32x16_bf16 v[0:15], v[156:159], v[164:167], v[0:15]
	s_waitcnt lgkmcnt(1)
	v_mfma_f32_32x32x16_bf16 v[48:63], v[152:155], v[168:171], v[48:63]
	v_mfma_f32_32x32x16_bf16 v[32:47], v[160:163], v[168:171], v[32:47]
	s_waitcnt lgkmcnt(0)
	v_mfma_f32_32x32x16_bf16 v[16:31], v[152:155], v[172:175], v[16:31]
	ds_read_b128 v[152:155], v102 offset:18496
	ds_read_b128 v[156:159], v102 offset:23104
	ds_read_b128 v[164:167], v101 offset:64
	ds_read_b128 v[168:171], v101 offset:4672
	s_waitcnt vmcnt(15)
	ds_write_b128 v100, v[104:107] offset:36864
	s_waitcnt vmcnt(13)
	ds_write_b128 v100, v[112:115] offset:41472
	s_waitcnt vmcnt(11)
	ds_write_b128 v100, v[120:123] offset:46080
	s_waitcnt vmcnt(9)
	ds_write_b128 v100, v[128:131] offset:50688
	v_mfma_f32_32x32x16_bf16 v[0:15], v[160:163], v[172:175], v[0:15]
	ds_read_b128 v[104:107], v102 offset:18528
	ds_read_b128 v[112:115], v102 offset:23136
	ds_read_b128 v[120:123], v101 offset:96
	ds_read_b128 v[128:131], v101 offset:4704
	s_waitcnt lgkmcnt(9)
	v_mfma_f32_32x32x16_bf16 v[48:63], v[152:155], v[164:167], v[48:63]
	ds_write_b128 v100, v[108:111] offset:55296
	ds_write_b128 v100, v[116:119] offset:59904
	ds_write_b128 v100, v[124:127] offset:64512
	s_waitcnt vmcnt(8)
	ds_write_b128 v103, v[132:135] offset:13824
	v_mfma_f32_32x32x16_bf16 v[32:47], v[156:159], v[164:167], v[32:47]
	s_waitcnt lgkmcnt(12)
	v_mfma_f32_32x32x16_bf16 v[16:31], v[152:155], v[168:171], v[16:31]
	v_mfma_f32_32x32x16_bf16 v[0:15], v[156:159], v[168:171], v[0:15]
	s_waitcnt lgkmcnt(0)
	s_barrier
; template <bool SWAP>
; DI void gemm_tile(const bf16_t* __restrict__ A, int lda, const bf16_t* __restrict__ Bt, int ldb, int K, f32x16 (&acc)[2][2], bf16_t* As, bf16_t* Bs_unused) {
;     ...
;   auto step = [&](int buf, u32x4 (&ra)[4], u32x4 (&rb)[4], bool do_write, bool do_load, int tload) __attribute__((always_inline)) {
;     const bf16_t* pa = As + buf * 2 * GT_IMG + pao; const bf16_t* pb = As + buf * 2 * GT_IMG + pbo;
;     bf16_t* Ad = As + (buf ^ 1) * 2 * GT_IMG; bf16_t* Bd = Ad + GT_IMG;
;     bf16x8 F0[4], F1[4];
;     frag_read(F0, pa, pb, 0);
;     __builtin_amdgcn_sched_barrier(0);
;     frag_read(F1, pa, pb, 16);
;     mfma4(F0);
;     __builtin_amdgcn_sched_barrier(0);
;     frag_read(F0, pa, pb, 32);
;     mfma4(F1);
;     if (do_write) {
; #pragma unroll
;       for (int i = 0; i < 4; ++i) *(u32x4*)(Ad + (lr + 32 * i) * 72 + lc) = ra[i];
;     }
;     __builtin_amdgcn_sched_barrier(0);
;     frag_read(F1, pa, pb, 48);
;     mfma4(F0);
;     if (do_write) {
; #pragma unroll
;       for (int i = 0; i < 4; ++i) *(u32x4*)(Bd + (lr + 32 * i) * 72 + lc) = rb[i];
;     }
;     __builtin_amdgcn_sched_barrier(0);
;     mfma4(F1);
;     if (do_load) load_stage(ra, rb, tload);
;     __builtin_amdgcn_sched_barrier(0);
;   };
;   const int nk = K >> 6;
;   load_stage(ra0, rb0, 0); load_stage(ra1, rb1, 1);
;   __syncthreads();
;   write_stage(ra0, rb0, 0);
;   load_stage(ra0, rb0, 2);
;   __syncthreads();
;   for (int kt = 0; kt < nk; kt += 2) {
;     step(0, ra1, rb1, true, kt + 3 < nk, kt + 3);
;     __syncthreads();
;     step(1, ra0, rb0, kt + 2 < nk, kt + 4 < nk, kt + 4);
;     __syncthreads();
	ds_read_b128 v[152:155], v102 offset:55296
	ds_read_b128 v[156:159], v102 offset:59904
	ds_read_b128 v[160:163], v101 offset:36864
	ds_read_b128 v[164:167], v101 offset:41472
	v_mfma_f32_32x32x16_bf16 v[48:63], v[104:107], v[120:123], v[48:63]
	v_mfma_f32_32x32x16_bf16 v[32:47], v[112:115], v[120:123], v[32:47]
	v_mfma_f32_32x32x16_bf16 v[16:31], v[104:107], v[128:131], v[16:31]
	v_mfma_f32_32x32x16_bf16 v[0:15], v[112:115], v[128:131], v[0:15]
	global_load_dwordx4 v[104:107], v[80:81], off offset:1152
	global_load_dwordx4 v[108:111], v[82:83], off offset:1152
	global_load_dwordx4 v[112:115], v[84:85], off offset:1152
	global_load_dwordx4 v[116:119], v[86:87], off offset:1152
	global_load_dwordx4 v[120:123], v[88:89], off offset:1152
	global_load_dwordx4 v[124:127], v[90:91], off offset:1152
	global_load_dwordx4 v[128:131], v[92:93], off offset:1152
	global_load_dwordx4 v[132:135], v[94:95], off offset:1152
	s_waitcnt lgkmcnt(1)
	v_mfma_f32_32x32x16_bf16 v[48:63], v[152:155], v[160:163], v[48:63]
	v_mfma_f32_32x32x16_bf16 v[32:47], v[156:159], v[160:163], v[32:47]
	s_waitcnt lgkmcnt(0)
	v_mfma_f32_32x32x16_bf16 v[16:31], v[152:155], v[164:167], v[16:31]
	ds_read_b128 v[152:155], v102 offset:55328
	ds_read_b128 v[160:163], v102 offset:59936
	ds_read_b128 v[168:171], v101 offset:36896
	ds_read_b128 v[172:175], v101 offset:41504
	v_mfma_f32_32x32x16_bf16 v[0:15], v[156:159], v[164:167], v[0:15]
	s_waitcnt lgkmcnt(1)
	v_mfma_f32_32x32x16_bf16 v[48:63], v[152:155], v[168:171], v[48:63]
	v_mfma_f32_32x32x16_bf16 v[32:47], v[160:163], v[168:171], v[32:47]
	s_waitcnt lgkmcnt(0)
	v_mfma_f32_32x32x16_bf16 v[16:31], v[152:155], v[172:175], v[16:31]
	ds_read_b128 v[152:155], v102 offset:55360
	ds_read_b128 v[156:159], v102 offset:59968
	ds_read_b128 v[164:167], v101 offset:36928
	ds_read_b128 v[168:171], v101 offset:41536
	s_waitcnt vmcnt(15)
	ds_write_b128 v100, v[64:67]
	s_waitcnt vmcnt(13)
	ds_write_b128 v100, v[72:75] offset:4608
	s_waitcnt vmcnt(11)
	ds_write_b128 v100, v[136:139] offset:9216
	s_waitcnt vmcnt(9)
	ds_write_b128 v100, v[144:147] offset:13824
	v_mfma_f32_32x32x16_bf16 v[0:15], v[160:163], v[172:175], v[0:15]
	ds_read_b128 v[64:67], v102 offset:55392
	ds_read_b128 v[72:75], v102 offset:60000
	ds_read_b128 v[136:139], v101 offset:36960
	ds_read_b128 v[144:147], v101 offset:41568
	s_waitcnt lgkmcnt(9)
	v_mfma_f32_32x32x16_bf16 v[48:63], v[152:155], v[164:167], v[48:63]
	ds_write_b128 v100, v[68:71] offset:18432
	ds_write_b128 v100, v[76:79] offset:23040
	ds_write_b128 v100, v[140:143] offset:27648
	s_waitcnt vmcnt(8)
	ds_write_b128 v100, v[148:151] offset:32256
	v_mfma_f32_32x32x16_bf16 v[32:47], v[156:159], v[164:167], v[32:47]
	s_waitcnt lgkmcnt(12)
	v_mfma_f32_32x32x16_bf16 v[16:31], v[152:155], v[168:171], v[16:31]
	v_mfma_f32_32x32x16_bf16 v[0:15], v[156:159], v[168:171], v[0:15]
	s_waitcnt lgkmcnt(0)
	s_barrier
	ds_read_b128 v[152:155], v102 offset:18432
	ds_read_b128 v[156:159], v102 offset:23040
	ds_read_b128 v[160:163], v101
	ds_read_b128 v[164:167], v101 offset:4608
	v_mfma_f32_32x32x16_bf16 v[48:63], v[64:67], v[136:139], v[48:63]
	v_mfma_f32_32x32x16_bf16 v[32:47], v[72:75], v[136:139], v[32:47]
	v_mfma_f32_32x32x16_bf16 v[16:31], v[64:67], v[144:147], v[16:31]
	v_mfma_f32_32x32x16_bf16 v[0:15], v[72:75], v[144:147], v[0:15]
	global_load_dwordx4 v[64:67], v[80:81], off offset:1280
	global_load_dwordx4 v[68:71], v[82:83], off offset:1280
	global_load_dwordx4 v[72:75], v[84:85], off offset:1280
	global_load_dwordx4 v[76:79], v[86:87], off offset:1280
	global_load_dwordx4 v[136:139], v[88:89], off offset:1280
	global_load_dwordx4 v[140:143], v[90:91], off offset:1280
	global_load_dwordx4 v[144:147], v[92:93], off offset:1280
	global_load_dwordx4 v[148:151], v[94:95], off offset:1280
	s_waitcnt lgkmcnt(1)
	v_mfma_f32_32x32x16_bf16 v[48:63], v[152:155], v[160:163], v[48:63]
	v_mfma_f32_32x32x16_bf16 v[32:47], v[156:159], v[160:163], v[32:47]
	s_waitcnt lgkmcnt(0)
	v_mfma_f32_32x32x16_bf16 v[16:31], v[152:155], v[164:167], v[16:31]
	ds_read_b128 v[152:155], v102 offset:18464
	ds_read_b128 v[160:163], v102 offset:23072
	ds_read_b128 v[168:171], v101 offset:32
	ds_read_b128 v[172:175], v101 offset:4640
	v_mfma_f32_32x32x16_bf16 v[0:15], v[156:159], v[164:167], v[0:15]
	s_waitcnt lgkmcnt(1)
	v_mfma_f32_32x32x16_bf16 v[48:63], v[152:155], v[168:171], v[48:63]
	v_mfma_f32_32x32x16_bf16 v[32:47], v[160:163], v[168:171], v[32:47]
	s_waitcnt lgkmcnt(0)
	v_mfma_f32_32x32x16_bf16 v[16:31], v[152:155], v[172:175], v[16:31]
	ds_read_b128 v[152:155], v102 offset:18496
	ds_read_b128 v[156:159], v102 offset:23104
	ds_read_b128 v[164:167], v101 offset:64
	ds_read_b128 v[168:171], v101 offset:4672
	s_waitcnt vmcnt(15)
	ds_write_b128 v100, v[104:107] offset:36864
	s_waitcnt vmcnt(13)
	ds_write_b128 v100, v[112:115] offset:41472
	s_waitcnt vmcnt(11)
	ds_write_b128 v100, v[120:123] offset:46080
	s_waitcnt vmcnt(9)
	ds_write_b128 v100, v[128:131] offset:50688
	v_mfma_f32_32x32x16_bf16 v[0:15], v[160:163], v[172:175], v[0:15]
	ds_read_b128 v[104:107], v102 offset:18528
	ds_read_b128 v[112:115], v102 offset:23136
	ds_read_b128 v[120:123], v101 offset:96
	ds_read_b128 v[128:131], v101 offset:4704
	s_waitcnt lgkmcnt(9)
	v_mfma_f32_32x32x16_bf16 v[48:63], v[152:155], v[164:167], v[48:63]
	ds_write_b128 v100, v[108:111] offset:55296
	ds_write_b128 v100, v[116:119] offset:59904
	ds_write_b128 v100, v[124:127] offset:64512
	s_waitcnt vmcnt(8)
	ds_write_b128 v103, v[132:135] offset:13824
	v_mfma_f32_32x32x16_bf16 v[32:47], v[156:159], v[164:167], v[32:47]
	s_waitcnt lgkmcnt(12)
	v_mfma_f32_32x32x16_bf16 v[16:31], v[152:155], v[168:171], v[16:31]
	v_mfma_f32_32x32x16_bf16 v[0:15], v[156:159], v[168:171], v[0:15]
	s_waitcnt lgkmcnt(0)
	s_barrier
; template <bool SWAP>
; DI void gemm_tile(const bf16_t* __restrict__ A, int lda, const bf16_t* __restrict__ Bt, int ldb, int K, f32x16 (&acc)[2][2], bf16_t* As, bf16_t* Bs_unused) {
;     ...
;   auto step = [&](int buf, u32x4 (&ra)[4], u32x4 (&rb)[4], bool do_write, bool do_load, int tload) __attribute__((always_inline)) {
;     const bf16_t* pa = As + buf * 2 * GT_IMG + pao; const bf16_t* pb = As + buf * 2 * GT_IMG + pbo;
;     bf16_t* Ad = As + (buf ^ 1) * 2 * GT_IMG; bf16_t* Bd = Ad + GT_IMG;
;     bf16x8 F0[4], F1[4];
;     frag_read(F0, pa, pb, 0);
;     __builtin_amdgcn_sched_barrier(0);
;     frag_read(F1, pa, pb, 16);
;     mfma4(F0);
;     __builtin_amdgcn_sched_barrier(0);
;     frag_read(F0, pa, pb, 32);
;     mfma4(F1);
;     if (do_write) {
; #pragma unroll
;       for (int i = 0; i < 4; ++i) *(u32x4*)(Ad + (lr + 32 * i) * 72 + lc) = ra[i];
;     }
;     __builtin_amdgcn_sched_barrier(0);
;     frag_read(F1, pa, pb, 48);
;     mfma4(F0);
;     if (do_write) {
; #pragma unroll
;       for (int i = 0; i < 4; ++i) *(u32x4*)(Bd + (lr + 32 * i) * 72 + lc) = rb[i];
;     }
;     __builtin_amdgcn_sched_barrier(0);
;     mfma4(F1);
;     if (do_load) load_stage(ra, rb, tload);
;     __builtin_amdgcn_sched_barrier(0);
;   };
;   const int nk = K >> 6;
;   load_stage(ra0, rb0, 0); load_stage(ra1, rb1, 1);
;   __syncthreads();
;   write_stage(ra0, rb0, 0);
;   load_stage(ra0, rb0, 2);
;   __syncthreads();
;   for (int kt = 0; kt < nk; kt += 2) {
;     step(0, ra1, rb1, true, kt + 3 < nk, kt + 3);
;     __syncthreads();
;     step(1, ra0, rb0, kt + 2 < nk, kt + 4 < nk, kt + 4);
;     __syncthreads();
	ds_read_b128 v[152:155], v102 offset:55296
	ds_read_b128 v[156:159], v102 offset:59904
	ds_read_b128 v[160:163], v101 offset:36864
	ds_read_b128 v[164:167], v101 offset:41472
	v_mfma_f32_32x32x16_bf16 v[48:63], v[104:107], v[120:123], v[48:63]
	v_mfma_f32_32x32x16_bf16 v[32:47], v[112:115], v[120:123], v[32:47]
	v_mfma_f32_32x32x16_bf16 v[16:31], v[104:107], v[128:131], v[16:31]
	v_mfma_f32_32x32x16_bf16 v[0:15], v[112:115], v[128:131], v[0:15]
	global_load_dwordx4 v[104:107], v[80:81], off offset:1408
	global_load_dwordx4 v[108:111], v[82:83], off offset:1408
	global_load_dwordx4 v[112:115], v[84:85], off offset:1408
	global_load_dwordx4 v[116:119], v[86:87], off offset:1408
	global_load_dwordx4 v[120:123], v[88:89], off offset:1408
	global_load_dwordx4 v[124:127], v[90:91], off offset:1408
	global_load_dwordx4 v[128:131], v[92:93], off offset:1408
	global_load_dwordx4 v[132:135], v[94:95], off offset:1408
	s_waitcnt lgkmcnt(1)
	v_mfma_f32_32x32x16_bf16 v[48:63], v[152:155], v[160:163], v[48:63]
	v_mfma_f32_32x32x16_bf16 v[32:47], v[156:159], v[160:163], v[32:47]
	s_waitcnt lgkmcnt(0)
	v_mfma_f32_32x32x16_bf16 v[16:31], v[152:155], v[164:167], v[16:31]
	ds_read_b128 v[152:155], v102 offset:55328
	ds_read_b128 v[160:163], v102 offset:59936
	ds_read_b128 v[168:171], v101 offset:36896
	ds_read_b128 v[172:175], v101 offset:41504
	v_mfma_f32_32x32x16_bf16 v[0:15], v[156:159], v[164:167], v[0:15]
	s_waitcnt lgkmcnt(1)
	v_mfma_f32_32x32x16_bf16 v[48:63], v[152:155], v[168:171], v[48:63]
	v_mfma_f32_32x32x16_bf16 v[32:47], v[160:163], v[168:171], v[32:47]
	s_waitcnt lgkmcnt(0)
	v_mfma_f32_32x32x16_bf16 v[16:31], v[152:155], v[172:175], v[16:31]
	ds_read_b128 v[152:155], v102 offset:55360
	ds_read_b128 v[156:159], v102 offset:59968
	ds_read_b128 v[164:167], v101 offset:36928
	ds_read_b128 v[168:171], v101 offset:41536
	s_waitcnt vmcnt(15)
	ds_write_b128 v100, v[64:67]
	s_waitcnt vmcnt(13)
	ds_write_b128 v100, v[72:75] offset:4608
	s_waitcnt vmcnt(11)
	ds_write_b128 v100, v[136:139] offset:9216
	s_waitcnt vmcnt(9)
	ds_write_b128 v100, v[144:147] offset:13824
	v_mfma_f32_32x32x16_bf16 v[0:15], v[160:163], v[172:175], v[0:15]
	ds_read_b128 v[64:67], v102 offset:55392
	ds_read_b128 v[72:75], v102 offset:60000
	ds_read_b128 v[136:139], v101 offset:36960
	ds_read_b128 v[144:147], v101 offset:41568
	s_waitcnt lgkmcnt(9)
	v_mfma_f32_32x32x16_bf16 v[48:63], v[152:155], v[164:167], v[48:63]
	ds_write_b128 v100, v[68:71] offset:18432
	ds_write_b128 v100, v[76:79] offset:23040
	ds_write_b128 v100, v[140:143] offset:27648
	s_waitcnt vmcnt(8)
	ds_write_b128 v100, v[148:151] offset:32256
	v_mfma_f32_32x32x16_bf16 v[32:47], v[156:159], v[164:167], v[32:47]
	s_waitcnt lgkmcnt(12)
	v_mfma_f32_32x32x16_bf16 v[16:31], v[152:155], v[168:171], v[16:31]
	v_mfma_f32_32x32x16_bf16 v[0:15], v[156:159], v[168:171], v[0:15]
	s_waitcnt lgkmcnt(0)
	s_barrier
	ds_read_b128 v[152:155], v102 offset:18432
	ds_read_b128 v[156:159], v102 offset:23040
	ds_read_b128 v[160:163], v101
	ds_read_b128 v[164:167], v101 offset:4608
	v_mfma_f32_32x32x16_bf16 v[48:63], v[64:67], v[136:139], v[48:63]
	v_mfma_f32_32x32x16_bf16 v[32:47], v[72:75], v[136:139], v[32:47]
	v_mfma_f32_32x32x16_bf16 v[16:31], v[64:67], v[144:147], v[16:31]
	v_mfma_f32_32x32x16_bf16 v[0:15], v[72:75], v[144:147], v[0:15]
	global_load_dwordx4 v[64:67], v[80:81], off offset:1536
	global_load_dwordx4 v[68:71], v[82:83], off offset:1536
	global_load_dwordx4 v[72:75], v[84:85], off offset:1536
	global_load_dwordx4 v[76:79], v[86:87], off offset:1536
	global_load_dwordx4 v[136:139], v[88:89], off offset:1536
	global_load_dwordx4 v[140:143], v[90:91], off offset:1536
	global_load_dwordx4 v[144:147], v[92:93], off offset:1536
	global_load_dwordx4 v[148:151], v[94:95], off offset:1536
	s_waitcnt lgkmcnt(1)
	v_mfma_f32_32x32x16_bf16 v[48:63], v[152:155], v[160:163], v[48:63]
	v_mfma_f32_32x32x16_bf16 v[32:47], v[156:159], v[160:163], v[32:47]
	s_waitcnt lgkmcnt(0)
	v_mfma_f32_32x32x16_bf16 v[16:31], v[152:155], v[164:167], v[16:31]
	ds_read_b128 v[152:155], v102 offset:18464
	ds_read_b128 v[160:163], v102 offset:23072
	ds_read_b128 v[168:171], v101 offset:32
	ds_read_b128 v[172:175], v101 offset:4640
	v_mfma_f32_32x32x16_bf16 v[0:15], v[156:159], v[164:167], v[0:15]
	s_waitcnt lgkmcnt(1)
	v_mfma_f32_32x32x16_bf16 v[48:63], v[152:155], v[168:171], v[48:63]
	v_mfma_f32_32x32x16_bf16 v[32:47], v[160:163], v[168:171], v[32:47]
	s_waitcnt lgkmcnt(0)
	v_mfma_f32_32x32x16_bf16 v[16:31], v[152:155], v[172:175], v[16:31]
	ds_read_b128 v[152:155], v102 offset:18496
	ds_read_b128 v[156:159], v102 offset:23104
	ds_read_b128 v[164:167], v101 offset:64
	ds_read_b128 v[168:171], v101 offset:4672
	s_waitcnt vmcnt(15)
	ds_write_b128 v100, v[104:107] offset:36864
	s_waitcnt vmcnt(13)
	ds_write_b128 v100, v[112:115] offset:41472
	s_waitcnt vmcnt(11)
	ds_write_b128 v100, v[120:123] offset:46080
	s_waitcnt vmcnt(9)
	ds_write_b128 v100, v[128:131] offset:50688
	v_mfma_f32_32x32x16_bf16 v[0:15], v[160:163], v[172:175], v[0:15]
	ds_read_b128 v[104:107], v102 offset:18528
	ds_read_b128 v[112:115], v102 offset:23136
	ds_read_b128 v[120:123], v101 offset:96
	ds_read_b128 v[128:131], v101 offset:4704
	s_waitcnt lgkmcnt(9)
	v_mfma_f32_32x32x16_bf16 v[48:63], v[152:155], v[164:167], v[48:63]
	ds_write_b128 v100, v[108:111] offset:55296
	ds_write_b128 v100, v[116:119] offset:59904
	ds_write_b128 v100, v[124:127] offset:64512
	s_waitcnt vmcnt(8)
	ds_write_b128 v103, v[132:135] offset:13824
	v_mfma_f32_32x32x16_bf16 v[32:47], v[156:159], v[164:167], v[32:47]
	s_waitcnt lgkmcnt(12)
	v_mfma_f32_32x32x16_bf16 v[16:31], v[152:155], v[168:171], v[16:31]
	v_mfma_f32_32x32x16_bf16 v[0:15], v[156:159], v[168:171], v[0:15]
	s_waitcnt lgkmcnt(0)
	s_barrier
; template <bool SWAP>
; DI void gemm_tile(const bf16_t* __restrict__ A, int lda, const bf16_t* __restrict__ Bt, int ldb, int K, f32x16 (&acc)[2][2], bf16_t* As, bf16_t* Bs_unused) {
;     ...
;   auto step = [&](int buf, u32x4 (&ra)[4], u32x4 (&rb)[4], bool do_write, bool do_load, int tload) __attribute__((always_inline)) {
;     const bf16_t* pa = As + buf * 2 * GT_IMG + pao; const bf16_t* pb = As + buf * 2 * GT_IMG + pbo;
;     bf16_t* Ad = As + (buf ^ 1) * 2 * GT_IMG; bf16_t* Bd = Ad + GT_IMG;
;     bf16x8 F0[4], F1[4];
;     frag_read(F0, pa, pb, 0);
;     __builtin_amdgcn_sched_barrier(0);
;     frag_read(F1, pa, pb, 16);
;     mfma4(F0);
;     __builtin_amdgcn_sched_barrier(0);
;     frag_read(F0, pa, pb, 32);
;     mfma4(F1);
;     if (do_write) {
; #pragma unroll
;       for (int i = 0; i < 4; ++i) *(u32x4*)(Ad + (lr + 32 * i) * 72 + lc) = ra[i];
;     }
;     __builtin_amdgcn_sched_barrier(0);
;     frag_read(F1, pa, pb, 48);
;     mfma4(F0);
;     if (do_write) {
; #pragma unroll
;       for (int i = 0; i < 4; ++i) *(u32x4*)(Bd + (lr + 32 * i) * 72 + lc) = rb[i];
;     }
;     __builtin_amdgcn_sched_barrier(0);
;     mfma4(F1);
;     if (do_load) load_stage(ra, rb, tload);
;     __builtin_amdgcn_sched_barrier(0);
;   };
;   const int nk = K >> 6;
;   load_stage(ra0, rb0, 0); load_stage(ra1, rb1, 1);
;   __syncthreads();
;   write_stage(ra0, rb0, 0);
;   load_stage(ra0, rb0, 2);
;   __syncthreads();
;   for (int kt = 0; kt < nk; kt += 2) {
;     step(0, ra1, rb1, true, kt + 3 < nk, kt + 3);
;     __syncthreads();
;     step(1, ra0, rb0, kt + 2 < nk, kt + 4 < nk, kt + 4);
;     __syncthreads();
	ds_read_b128 v[152:155], v102 offset:55296
	ds_read_b128 v[156:159], v102 offset:59904
	ds_read_b128 v[160:163], v101 offset:36864
	ds_read_b128 v[164:167], v101 offset:41472
	v_mfma_f32_32x32x16_bf16 v[48:63], v[104:107], v[120:123], v[48:63]
	v_mfma_f32_32x32x16_bf16 v[32:47], v[112:115], v[120:123], v[32:47]
	v_mfma_f32_32x32x16_bf16 v[16:31], v[104:107], v[128:131], v[16:31]
	v_mfma_f32_32x32x16_bf16 v[0:15], v[112:115], v[128:131], v[0:15]
	global_load_dwordx4 v[104:107], v[80:81], off offset:1664
	global_load_dwordx4 v[108:111], v[82:83], off offset:1664
	global_load_dwordx4 v[112:115], v[84:85], off offset:1664
	global_load_dwordx4 v[116:119], v[86:87], off offset:1664
	global_load_dwordx4 v[120:123], v[88:89], off offset:1664
	global_load_dwordx4 v[124:127], v[90:91], off offset:1664
	global_load_dwordx4 v[128:131], v[92:93], off offset:1664
	global_load_dwordx4 v[132:135], v[94:95], off offset:1664
	s_waitcnt lgkmcnt(1)
	v_mfma_f32_32x32x16_bf16 v[48:63], v[152:155], v[160:163], v[48:63]
	v_mfma_f32_32x32x16_bf16 v[32:47], v[156:159], v[160:163], v[32:47]
	s_waitcnt lgkmcnt(0)
	v_mfma_f32_32x32x16_bf16 v[16:31], v[152:155], v[164:167], v[16:31]
	ds_read_b128 v[152:155], v102 offset:55328
	ds_read_b128 v[160:163], v102 offset:59936
	ds_read_b128 v[168:171], v101 offset:36896
	ds_read_b128 v[172:175], v101 offset:41504
	v_mfma_f32_32x32x16_bf16 v[0:15], v[156:159], v[164:167], v[0:15]
	s_waitcnt lgkmcnt(1)
	v_mfma_f32_32x32x16_bf16 v[48:63], v[152:155], v[168:171], v[48:63]
	v_mfma_f32_32x32x16_bf16 v[32:47], v[160:163], v[168:171], v[32:47]
	s_waitcnt lgkmcnt(0)
	v_mfma_f32_32x32x16_bf16 v[16:31], v[152:155], v[172:175], v[16:31]
	ds_read_b128 v[152:155], v102 offset:55360
	ds_read_b128 v[156:159], v102 offset:59968
	ds_read_b128 v[164:167], v101 offset:36928
	ds_read_b128 v[168:171], v101 offset:41536
	s_waitcnt vmcnt(15)
	ds_write_b128 v100, v[64:67]
	s_waitcnt vmcnt(13)
	ds_write_b128 v100, v[72:75] offset:4608
	s_waitcnt vmcnt(11)
	ds_write_b128 v100, v[136:139] offset:9216
	s_waitcnt vmcnt(9)
	ds_write_b128 v100, v[144:147] offset:13824
	v_mfma_f32_32x32x16_bf16 v[0:15], v[160:163], v[172:175], v[0:15]
	ds_read_b128 v[64:67], v102 offset:55392
	ds_read_b128 v[72:75], v102 offset:60000
	ds_read_b128 v[136:139], v101 offset:36960
	ds_read_b128 v[144:147], v101 offset:41568
	s_waitcnt lgkmcnt(9)
	v_mfma_f32_32x32x16_bf16 v[48:63], v[152:155], v[164:167], v[48:63]
	ds_write_b128 v100, v[68:71] offset:18432
	ds_write_b128 v100, v[76:79] offset:23040
	ds_write_b128 v100, v[140:143] offset:27648
	s_waitcnt vmcnt(8)
	ds_write_b128 v100, v[148:151] offset:32256
	v_mfma_f32_32x32x16_bf16 v[32:47], v[156:159], v[164:167], v[32:47]
	s_waitcnt lgkmcnt(12)
	v_mfma_f32_32x32x16_bf16 v[16:31], v[152:155], v[168:171], v[16:31]
	v_mfma_f32_32x32x16_bf16 v[0:15], v[156:159], v[168:171], v[0:15]
	s_waitcnt lgkmcnt(0)
	s_barrier
	ds_read_b128 v[152:155], v102 offset:18432
	ds_read_b128 v[156:159], v102 offset:23040
	ds_read_b128 v[160:163], v101
	ds_read_b128 v[164:167], v101 offset:4608
	v_mfma_f32_32x32x16_bf16 v[48:63], v[64:67], v[136:139], v[48:63]
	v_mfma_f32_32x32x16_bf16 v[32:47], v[72:75], v[136:139], v[32:47]
	v_mfma_f32_32x32x16_bf16 v[16:31], v[64:67], v[144:147], v[16:31]
	v_mfma_f32_32x32x16_bf16 v[0:15], v[72:75], v[144:147], v[0:15]
	global_load_dwordx4 v[64:67], v[80:81], off offset:1792
	global_load_dwordx4 v[68:71], v[82:83], off offset:1792
	global_load_dwordx4 v[72:75], v[84:85], off offset:1792
	global_load_dwordx4 v[76:79], v[86:87], off offset:1792
	global_load_dwordx4 v[136:139], v[88:89], off offset:1792
	global_load_dwordx4 v[140:143], v[90:91], off offset:1792
	global_load_dwordx4 v[144:147], v[92:93], off offset:1792
	global_load_dwordx4 v[148:151], v[94:95], off offset:1792
	s_waitcnt lgkmcnt(1)
	v_mfma_f32_32x32x16_bf16 v[48:63], v[152:155], v[160:163], v[48:63]
	v_mfma_f32_32x32x16_bf16 v[32:47], v[156:159], v[160:163], v[32:47]
	s_waitcnt lgkmcnt(0)
	v_mfma_f32_32x32x16_bf16 v[16:31], v[152:155], v[164:167], v[16:31]
	ds_read_b128 v[152:155], v102 offset:18464
	ds_read_b128 v[160:163], v102 offset:23072
	ds_read_b128 v[168:171], v101 offset:32
	ds_read_b128 v[172:175], v101 offset:4640
	v_mfma_f32_32x32x16_bf16 v[0:15], v[156:159], v[164:167], v[0:15]
	s_waitcnt lgkmcnt(1)
	v_mfma_f32_32x32x16_bf16 v[48:63], v[152:155], v[168:171], v[48:63]
	v_mfma_f32_32x32x16_bf16 v[32:47], v[160:163], v[168:171], v[32:47]
	s_waitcnt lgkmcnt(0)
	v_mfma_f32_32x32x16_bf16 v[16:31], v[152:155], v[172:175], v[16:31]
	ds_read_b128 v[152:155], v102 offset:18496
	ds_read_b128 v[156:159], v102 offset:23104
	ds_read_b128 v[164:167], v101 offset:64
	ds_read_b128 v[168:171], v101 offset:4672
	s_waitcnt vmcnt(15)
	ds_write_b128 v100, v[104:107] offset:36864
	s_waitcnt vmcnt(13)
	ds_write_b128 v100, v[112:115] offset:41472
	s_waitcnt vmcnt(11)
	ds_write_b128 v100, v[120:123] offset:46080
	s_waitcnt vmcnt(9)
	ds_write_b128 v100, v[128:131] offset:50688
	v_mfma_f32_32x32x16_bf16 v[0:15], v[160:163], v[172:175], v[0:15]
	ds_read_b128 v[104:107], v102 offset:18528
	ds_read_b128 v[112:115], v102 offset:23136
	ds_read_b128 v[120:123], v101 offset:96
	ds_read_b128 v[128:131], v101 offset:4704
	s_waitcnt lgkmcnt(9)
	v_mfma_f32_32x32x16_bf16 v[48:63], v[152:155], v[164:167], v[48:63]
	ds_write_b128 v100, v[108:111] offset:55296
	ds_write_b128 v100, v[116:119] offset:59904
	ds_write_b128 v100, v[124:127] offset:64512
	s_waitcnt vmcnt(8)
	ds_write_b128 v103, v[132:135] offset:13824
	v_mfma_f32_32x32x16_bf16 v[32:47], v[156:159], v[164:167], v[32:47]
	s_waitcnt lgkmcnt(12)
	v_mfma_f32_32x32x16_bf16 v[16:31], v[152:155], v[168:171], v[16:31]
	v_mfma_f32_32x32x16_bf16 v[0:15], v[156:159], v[168:171], v[0:15]
	s_waitcnt lgkmcnt(0)
	s_barrier
; template <bool SWAP>
; DI void gemm_tile(const bf16_t* __restrict__ A, int lda, const bf16_t* __restrict__ Bt, int ldb, int K, f32x16 (&acc)[2][2], bf16_t* As, bf16_t* Bs_unused) {
;     ...
;   auto step = [&](int buf, u32x4 (&ra)[4], u32x4 (&rb)[4], bool do_write, bool do_load, int tload) __attribute__((always_inline)) {
;     const bf16_t* pa = As + buf * 2 * GT_IMG + pao; const bf16_t* pb = As + buf * 2 * GT_IMG + pbo;
;     bf16_t* Ad = As + (buf ^ 1) * 2 * GT_IMG; bf16_t* Bd = Ad + GT_IMG;
;     bf16x8 F0[4], F1[4];
;     frag_read(F0, pa, pb, 0);
;     __builtin_amdgcn_sched_barrier(0);
;     frag_read(F1, pa, pb, 16);
;     mfma4(F0);
;     __builtin_amdgcn_sched_barrier(0);
;     frag_read(F0, pa, pb, 32);
;     mfma4(F1);
;     if (do_write) {
; #pragma unroll
;       for (int i = 0; i < 4; ++i) *(u32x4*)(Ad + (lr + 32 * i) * 72 + lc) = ra[i];
;     }
;     __builtin_amdgcn_sched_barrier(0);
;     frag_read(F1, pa, pb, 48);
;     mfma4(F0);
;     if (do_write) {
; #pragma unroll
;       for (int i = 0; i < 4; ++i) *(u32x4*)(Bd + (lr + 32 * i) * 72 + lc) = rb[i];
;     }
;     __builtin_amdgcn_sched_barrier(0);
;     mfma4(F1);
;     if (do_load) load_stage(ra, rb, tload);
;     __builtin_amdgcn_sched_barrier(0);
;   };
;   const int nk = K >> 6;
;   load_stage(ra0, rb0, 0); load_stage(ra1, rb1, 1);
;   __syncthreads();
;   write_stage(ra0, rb0, 0);
;   load_stage(ra0, rb0, 2);
;   __syncthreads();
;   for (int kt = 0; kt < nk; kt += 2) {
;     step(0, ra1, rb1, true, kt + 3 < nk, kt + 3);
;     __syncthreads();
;     step(1, ra0, rb0, kt + 2 < nk, kt + 4 < nk, kt + 4);
;     __syncthreads();
	ds_read_b128 v[180:183], v102 offset:55296
	ds_read_b128 v[184:187], v102 offset:59904
	ds_read_b128 v[188:191], v101 offset:36864
	ds_read_b128 v[220:223], v101 offset:41472
	v_mfma_f32_32x32x16_bf16 v[48:63], v[104:107], v[120:123], v[48:63]
	v_mfma_f32_32x32x16_bf16 v[32:47], v[112:115], v[120:123], v[32:47]
	v_mfma_f32_32x32x16_bf16 v[16:31], v[104:107], v[128:131], v[16:31]
	v_mfma_f32_32x32x16_bf16 v[0:15], v[112:115], v[128:131], v[0:15]
	global_load_dwordx4 v[104:107], v[80:81], off offset:1920
	s_nop 0
	global_load_dwordx4 v[80:83], v[82:83], off offset:1920
	s_nop 0
	global_load_dwordx4 v[108:111], v[84:85], off offset:1920
	s_nop 0
	global_load_dwordx4 v[84:87], v[86:87], off offset:1920
	s_nop 0
	global_load_dwordx4 v[112:115], v[88:89], off offset:1920
	s_nop 0
	global_load_dwordx4 v[88:91], v[90:91], off offset:1920
	s_nop 0
	global_load_dwordx4 v[116:119], v[92:93], off offset:1920
	s_nop 0
	global_load_dwordx4 v[92:95], v[94:95], off offset:1920
	s_waitcnt lgkmcnt(1)
	v_mfma_f32_32x32x16_bf16 v[48:63], v[180:183], v[188:191], v[48:63]
	v_mfma_f32_32x32x16_bf16 v[32:47], v[184:187], v[188:191], v[32:47]
	s_waitcnt lgkmcnt(0)
	v_mfma_f32_32x32x16_bf16 v[16:31], v[180:183], v[220:223], v[16:31]
	ds_read_b128 v[120:123], v102 offset:55328
	ds_read_b128 v[128:131], v102 offset:59936
	ds_read_b128 v[152:155], v101 offset:36896
	ds_read_b128 v[156:159], v101 offset:41504
	v_mfma_f32_32x32x16_bf16 v[0:15], v[184:187], v[220:223], v[0:15]
	s_waitcnt lgkmcnt(1)
	v_mfma_f32_32x32x16_bf16 v[48:63], v[120:123], v[152:155], v[48:63]
	v_mfma_f32_32x32x16_bf16 v[32:47], v[128:131], v[152:155], v[32:47]
	s_waitcnt lgkmcnt(0)
	v_mfma_f32_32x32x16_bf16 v[16:31], v[120:123], v[156:159], v[16:31]
	ds_read_b128 v[120:123], v102 offset:55360
	ds_read_b128 v[124:127], v102 offset:59968
	ds_read_b128 v[132:135], v101 offset:36928
	ds_read_b128 v[152:155], v101 offset:41536
	s_waitcnt vmcnt(15)
	ds_write_b128 v100, v[64:67]
	s_waitcnt vmcnt(13)
	ds_write_b128 v100, v[72:75] offset:4608
	s_waitcnt vmcnt(11)
	ds_write_b128 v100, v[136:139] offset:9216
	s_waitcnt vmcnt(9)
	ds_write_b128 v100, v[144:147] offset:13824
	v_mfma_f32_32x32x16_bf16 v[0:15], v[128:131], v[156:159], v[0:15]
	s_waitcnt lgkmcnt(5)
	v_mfma_f32_32x32x16_bf16 v[48:63], v[120:123], v[132:135], v[48:63]
	s_waitcnt lgkmcnt(4)
	v_mfma_f32_32x32x16_bf16 v[16:31], v[120:123], v[152:155], v[16:31]
	ds_read_b128 v[64:67], v102 offset:55392
	ds_read_b128 v[72:75], v102 offset:60000
	ds_read_b128 v[120:123], v101 offset:36960
	ds_read_b128 v[128:131], v101 offset:41568
	ds_write_b128 v100, v[68:71] offset:18432
	ds_write_b128 v100, v[76:79] offset:23040
	ds_write_b128 v100, v[140:143] offset:27648
	s_waitcnt vmcnt(8)
	ds_write_b128 v100, v[148:151] offset:32256
	v_mfma_f32_32x32x16_bf16 v[32:47], v[124:127], v[132:135], v[32:47]
	v_mfma_f32_32x32x16_bf16 v[0:15], v[124:127], v[152:155], v[0:15]
	s_waitcnt lgkmcnt(0)
	s_barrier
	ds_read_b128 v[180:183], v102 offset:18432
	ds_read_b128 v[184:187], v102 offset:23040
	ds_read_b128 v[188:191], v101
	ds_read_b128 v[220:223], v101 offset:4608
	v_mfma_f32_32x32x16_bf16 v[48:63], v[64:67], v[120:123], v[48:63]
	v_mfma_f32_32x32x16_bf16 v[32:47], v[72:75], v[120:123], v[32:47]
	v_mfma_f32_32x32x16_bf16 v[16:31], v[64:67], v[128:131], v[16:31]
	v_mfma_f32_32x32x16_bf16 v[0:15], v[72:75], v[128:131], v[0:15]
	s_waitcnt lgkmcnt(1)
	v_mfma_f32_32x32x16_bf16 v[48:63], v[180:183], v[188:191], v[48:63]
	v_mfma_f32_32x32x16_bf16 v[32:47], v[184:187], v[188:191], v[32:47]
	s_waitcnt lgkmcnt(0)
	v_mfma_f32_32x32x16_bf16 v[16:31], v[180:183], v[220:223], v[16:31]
	ds_read_b128 v[64:67], v102 offset:18464
	ds_read_b128 v[72:75], v102 offset:23072
	ds_read_b128 v[120:123], v101 offset:32
	ds_read_b128 v[124:127], v101 offset:4640
	v_mfma_f32_32x32x16_bf16 v[0:15], v[184:187], v[220:223], v[0:15]
	s_waitcnt lgkmcnt(1)
	v_mfma_f32_32x32x16_bf16 v[48:63], v[64:67], v[120:123], v[48:63]
	v_mfma_f32_32x32x16_bf16 v[32:47], v[72:75], v[120:123], v[32:47]
	s_waitcnt lgkmcnt(0)
	v_mfma_f32_32x32x16_bf16 v[16:31], v[64:67], v[124:127], v[16:31]
	ds_read_b128 v[64:67], v102 offset:18496
	ds_read_b128 v[68:71], v102 offset:23104
	ds_read_b128 v[76:79], v101 offset:64
	ds_read_b128 v[120:123], v101 offset:4672
	s_waitcnt vmcnt(7)
	ds_write_b128 v100, v[104:107] offset:36864
	s_waitcnt vmcnt(5)
	ds_write_b128 v100, v[108:111] offset:41472
	s_waitcnt vmcnt(3)
	ds_write_b128 v100, v[112:115] offset:46080
	s_waitcnt vmcnt(1)
	ds_write_b128 v100, v[116:119] offset:50688
	v_mfma_f32_32x32x16_bf16 v[0:15], v[72:75], v[124:127], v[0:15]
	s_waitcnt lgkmcnt(5)
	v_mfma_f32_32x32x16_bf16 v[48:63], v[64:67], v[76:79], v[48:63]
	v_mfma_f32_32x32x16_bf16 v[32:47], v[68:71], v[76:79], v[32:47]
	s_waitcnt lgkmcnt(4)
	v_mfma_f32_32x32x16_bf16 v[16:31], v[64:67], v[120:123], v[16:31]
	ds_read_b128 v[64:67], v102 offset:18528
	ds_read_b128 v[72:75], v102 offset:23136
	ds_read_b128 v[76:79], v101 offset:96
	ds_read_b128 v[104:107], v101 offset:4704
	ds_write_b128 v100, v[80:83] offset:55296
	ds_write_b128 v100, v[84:87] offset:59904
	ds_write_b128 v100, v[88:91] offset:64512
	s_waitcnt vmcnt(0)
	ds_write_b128 v103, v[92:95] offset:13824
	v_mfma_f32_32x32x16_bf16 v[0:15], v[68:71], v[120:123], v[0:15]
	s_waitcnt lgkmcnt(0)
	s_barrier
; DI bf16_t f2bf(float x) { return (bf16_t)(pk_bf16(x, 0.f) & 0xffffu); }
; DI int crow(int r, int h) { return (r & 3) + 8 * (r >> 2) + 4 * h; }
; template <bool SWAP>
; DI void gemm_tile(const bf16_t* __restrict__ A, int lda, const bf16_t* __restrict__ Bt, int ldb, int K, f32x16 (&acc)[2][2], bf16_t* As, bf16_t* Bs_unused) {
;     ...
;   auto step = [&](int buf, u32x4 (&ra)[4], u32x4 (&rb)[4], bool do_write, bool do_load, int tload) __attribute__((always_inline)) {
;     const bf16_t* pa = As + buf * 2 * GT_IMG + pao; const bf16_t* pb = As + buf * 2 * GT_IMG + pbo;
;     bf16_t* Ad = As + (buf ^ 1) * 2 * GT_IMG; bf16_t* Bd = Ad + GT_IMG;
;     bf16x8 F0[4], F1[4];
;     frag_read(F0, pa, pb, 0);
;     __builtin_amdgcn_sched_barrier(0);
;     frag_read(F1, pa, pb, 16);
;     mfma4(F0);
;     __builtin_amdgcn_sched_barrier(0);
;     frag_read(F0, pa, pb, 32);
;     mfma4(F1);
;     if (do_write) {
; #pragma unroll
;       for (int i = 0; i < 4; ++i) *(u32x4*)(Ad + (lr + 32 * i) * 72 + lc) = ra[i];
;     }
;     __builtin_amdgcn_sched_barrier(0);
;     frag_read(F1, pa, pb, 48);
;     mfma4(F0);
;     if (do_write) {
; #pragma unroll
;       for (int i = 0; i < 4; ++i) *(u32x4*)(Bd + (lr + 32 * i) * 72 + lc) = rb[i];
;     }
;     __builtin_amdgcn_sched_barrier(0);
;     mfma4(F1);
;     if (do_load) load_stage(ra, rb, tload);
;     __builtin_amdgcn_sched_barrier(0);
;   };
;   const int nk = K >> 6;
;   load_stage(ra0, rb0, 0); load_stage(ra1, rb1, 1);
;   __syncthreads();
;   write_stage(ra0, rb0, 0);
;   load_stage(ra0, rb0, 2);
;   __syncthreads();
;   for (int kt = 0; kt < nk; kt += 2) {
;     step(0, ra1, rb1, true, kt + 3 < nk, kt + 3);
;     __syncthreads();
;     step(1, ra0, rb0, kt + 2 < nk, kt + 4 < nk, kt + 4);
;     __syncthreads();
;   }
; DI void phase_up(const Params& p, int g, char* smem, int bid, int nb) {
;     ...
; #pragma unroll
;         for (int r = 0; r < 16; ++r) {
;           const float v = fmaxf(acc[mi][ni][r], 0.f);
;           (U + (size_t)mt * 128 * 4096)[(wm * 64 + mi * 32 + crow(r, h)) * 4096 + nt * 128 + wn * 64 + ni * 32 + l31] = f2bf(v * v);
	ds_read_b128 v[180:183], v102 offset:55296
	ds_read_b128 v[184:187], v102 offset:59904
	ds_read_b128 v[188:191], v101 offset:36864
	ds_read_b128 v[220:223], v101 offset:41472
	v_mfma_f32_32x32x16_bf16 v[48:63], v[64:67], v[76:79], v[48:63]
	v_mfma_f32_32x32x16_bf16 v[32:47], v[72:75], v[76:79], v[32:47]
	v_mfma_f32_32x32x16_bf16 v[16:31], v[64:67], v[104:107], v[16:31]
	v_mfma_f32_32x32x16_bf16 v[0:15], v[72:75], v[104:107], v[0:15]
	s_waitcnt lgkmcnt(1)
	v_mfma_f32_32x32x16_bf16 v[48:63], v[180:183], v[188:191], v[48:63]
	v_mfma_f32_32x32x16_bf16 v[32:47], v[184:187], v[188:191], v[32:47]
	s_waitcnt lgkmcnt(0)
	v_mfma_f32_32x32x16_bf16 v[16:31], v[180:183], v[220:223], v[16:31]
	ds_read_b128 v[64:67], v102 offset:55328
	ds_read_b128 v[72:75], v102 offset:59936
	ds_read_b128 v[80:83], v101 offset:36896
	ds_read_b128 v[84:87], v101 offset:41504
	v_mfma_f32_32x32x16_bf16 v[0:15], v[184:187], v[220:223], v[0:15]
	s_waitcnt lgkmcnt(1)
	v_mfma_f32_32x32x16_bf16 v[48:63], v[64:67], v[80:83], v[48:63]
	v_mfma_f32_32x32x16_bf16 v[32:47], v[72:75], v[80:83], v[32:47]
	s_waitcnt lgkmcnt(0)
	v_mfma_f32_32x32x16_bf16 v[16:31], v[64:67], v[84:87], v[16:31]
	v_mfma_f32_32x32x16_bf16 v[0:15], v[72:75], v[84:87], v[0:15]
	ds_read_b128 v[64:67], v101 offset:41536
	ds_read_b128 v[68:71], v102 offset:59968
	ds_read_b128 v[72:75], v102 offset:55360
	ds_read_b128 v[76:79], v101 offset:36928
	s_waitcnt lgkmcnt(0)
	v_mfma_f32_32x32x16_bf16 v[48:63], v[72:75], v[76:79], v[48:63]
	v_mfma_f32_32x32x16_bf16 v[32:47], v[68:71], v[76:79], v[32:47]
	v_mfma_f32_32x32x16_bf16 v[16:31], v[72:75], v[64:67], v[16:31]
	v_mfma_f32_32x32x16_bf16 v[0:15], v[68:71], v[64:67], v[0:15]
	ds_read_b128 v[64:67], v101 offset:41568
	ds_read_b128 v[68:71], v102 offset:60000
	ds_read_b128 v[72:75], v102 offset:55392
	ds_read_b128 v[76:79], v101 offset:36960
	s_waitcnt lgkmcnt(0)
	v_mfma_f32_32x32x16_bf16 v[48:63], v[72:75], v[76:79], v[48:63]
	v_mfma_f32_32x32x16_bf16 v[32:47], v[68:71], v[76:79], v[32:47]
	v_mfma_f32_32x32x16_bf16 v[16:31], v[72:75], v[64:67], v[16:31]
	v_mfma_f32_32x32x16_bf16 v[0:15], v[68:71], v[64:67], v[0:15]
	s_lshl_b64 s[6:7], s[6:7], 20
	s_barrier
	s_add_u32 s6, s94, s6
	s_addc_u32 s7, s95, s7
	s_lshl_b32 s0, s0, 8
	s_movk_i32 s1, 0x90
	v_and_b32_e32 v64, 63, v195
	v_lshrrev_b32_e32 v65, 6, v195
	v_and_b32_e32 v66, 31, v64
	v_lshrrev_b32_e32 v67, 5, v64
	v_mul_u32_u24_e32 v68, 0x2400, v65
	v_lshrrev_b32_e32 v70, 3, v64
	v_and_b32_e32 v71, 7, v64
	v_mad_u32_u24 v69, v66, s1, v68
	v_mad_u32_u24 v72, v70, s1, v68
	v_lshl_add_u32 v69, v67, 3, v69
	v_lshl_add_u32 v72, v71, 4, v72
	v_add_u32_e32 v69, 32, v69
	v_add_u32_e32 v72, 32, v72
	v_lshl_add_u32 v73, v96, 6, v70
	v_lshlrev_b32_e32 v73, 13, v73
	v_lshl_add_u32 v73, v97, 7, v73
	v_lshl_add_u32 v73, v71, 4, v73
	v_add_u32_e32 v76, s0, v73
	v_mov_b32_e32 v77, 0
	s_mov_b64 s[8:9], 0x10000
	v_lshl_add_u64 v[136:137], s[6:7], 0, v[76:77]
	v_lshl_add_u64 v[138:139], v[136:137], 0, s[8:9]
	v_lshl_add_u64 v[140:141], v[138:139], 0, s[8:9]
	v_lshl_add_u64 v[142:143], v[140:141], 0, s[8:9]
	v_lshl_add_u64 v[144:145], v[142:143], 0, s[8:9]
	v_lshl_add_u64 v[146:147], v[144:145], 0, s[8:9]
	v_lshl_add_u64 v[148:149], v[146:147], 0, s[8:9]
	v_lshl_add_u64 v[150:151], v[148:149], 0, s[8:9]
	v_max_f32_e32 v48, 0, v48
	v_max_f32_e32 v49, 0, v49
	v_max_f32_e32 v50, 0, v50
	v_max_f32_e32 v51, 0, v51
	v_mul_f32_e32 v48, v48, v48
	v_mul_f32_e32 v49, v49, v49
	v_mul_f32_e32 v50, v50, v50
	v_mul_f32_e32 v51, v51, v51
	v_cvt_pk_bf16_f32 v48, v48, v49
	v_cvt_pk_bf16_f32 v49, v50, v51
	ds_write_b64 v69, v[48:49]
	v_max_f32_e32 v52, 0, v52
	v_max_f32_e32 v53, 0, v53
	v_max_f32_e32 v54, 0, v54
	v_max_f32_e32 v55, 0, v55
	v_mul_f32_e32 v52, v52, v52
	v_mul_f32_e32 v53, v53, v53
	v_mul_f32_e32 v54, v54, v54
	v_mul_f32_e32 v55, v55, v55
	v_cvt_pk_bf16_f32 v52, v52, v53
	v_cvt_pk_bf16_f32 v53, v54, v55
	ds_write_b64 v69, v[52:53] offset:16
	v_max_f32_e32 v56, 0, v56
	v_max_f32_e32 v57, 0, v57
	v_max_f32_e32 v58, 0, v58
	v_max_f32_e32 v59, 0, v59
	v_mul_f32_e32 v56, v56, v56
	v_mul_f32_e32 v57, v57, v57
	v_mul_f32_e32 v58, v58, v58
	v_mul_f32_e32 v59, v59, v59
	v_cvt_pk_bf16_f32 v56, v56, v57
	v_cvt_pk_bf16_f32 v57, v58, v59
	ds_write_b64 v69, v[56:57] offset:32
	v_max_f32_e32 v60, 0, v60
	v_max_f32_e32 v61, 0, v61
	v_max_f32_e32 v62, 0, v62
	v_max_f32_e32 v63, 0, v63
	v_mul_f32_e32 v60, v60, v60
	v_mul_f32_e32 v61, v61, v61
	v_mul_f32_e32 v62, v62, v62
	v_mul_f32_e32 v63, v63, v63
	v_cvt_pk_bf16_f32 v60, v60, v61
	v_cvt_pk_bf16_f32 v61, v62, v63
	ds_write_b64 v69, v[60:61] offset:48
	v_max_f32_e32 v32, 0, v32
	v_max_f32_e32 v33, 0, v33
	v_max_f32_e32 v34, 0, v34
	v_max_f32_e32 v35, 0, v35
	v_mul_f32_e32 v32, v32, v32
	v_mul_f32_e32 v33, v33, v33
	v_mul_f32_e32 v34, v34, v34
	v_mul_f32_e32 v35, v35, v35
	v_cvt_pk_bf16_f32 v32, v32, v33
	v_cvt_pk_bf16_f32 v33, v34, v35
	ds_write_b64 v69, v[32:33] offset:64
	v_max_f32_e32 v36, 0, v36
	v_max_f32_e32 v37, 0, v37
	v_max_f32_e32 v38, 0, v38
	v_max_f32_e32 v39, 0, v39
	v_mul_f32_e32 v36, v36, v36
	v_mul_f32_e32 v37, v37, v37
	v_mul_f32_e32 v38, v38, v38
	v_mul_f32_e32 v39, v39, v39
	v_cvt_pk_bf16_f32 v36, v36, v37
	v_cvt_pk_bf16_f32 v37, v38, v39
	ds_write_b64 v69, v[36:37] offset:80
	v_max_f32_e32 v40, 0, v40
	v_max_f32_e32 v41, 0, v41
	v_max_f32_e32 v42, 0, v42
	v_max_f32_e32 v43, 0, v43
	v_mul_f32_e32 v40, v40, v40
	v_mul_f32_e32 v41, v41, v41
	v_mul_f32_e32 v42, v42, v42
	v_mul_f32_e32 v43, v43, v43
	v_cvt_pk_bf16_f32 v40, v40, v41
	v_cvt_pk_bf16_f32 v41, v42, v43
	ds_write_b64 v69, v[40:41] offset:96
	v_max_f32_e32 v44, 0, v44
	v_max_f32_e32 v45, 0, v45
	v_max_f32_e32 v46, 0, v46
	v_max_f32_e32 v47, 0, v47
	v_mul_f32_e32 v44, v44, v44
	v_mul_f32_e32 v45, v45, v45
	v_mul_f32_e32 v46, v46, v46
	v_mul_f32_e32 v47, v47, v47
	v_cvt_pk_bf16_f32 v44, v44, v45
	v_cvt_pk_bf16_f32 v45, v46, v47
	ds_write_b64 v69, v[44:45] offset:112
	v_max_f32_e32 v16, 0, v16
	v_max_f32_e32 v17, 0, v17
	v_max_f32_e32 v18, 0, v18
	v_max_f32_e32 v19, 0, v19
	v_mul_f32_e32 v16, v16, v16
	v_mul_f32_e32 v17, v17, v17
	v_mul_f32_e32 v18, v18, v18
	v_mul_f32_e32 v19, v19, v19
	v_cvt_pk_bf16_f32 v16, v16, v17
	v_cvt_pk_bf16_f32 v17, v18, v19
	s_waitcnt lgkmcnt(4)
; DI bf16_t f2bf(float x) { return (bf16_t)(pk_bf16(x, 0.f) & 0xffffu); }
; DI int crow(int r, int h) { return (r & 3) + 8 * (r >> 2) + 4 * h; }
;   DI bool next(int& mt, int& nt) {
;     if (j >= total) return false;
;     if (simple) { mt = j & 127; nt = j >> 7; }
;     else { const int half = j / (8 * NT), jj = j - half * 8 * NT; mt = xcd * 16 + half * 8 + (jj & 7); nt = jj >> 3; }
;     j += step; return true;
; DI void phase_up(const Params& p, int g, char* smem, int bid, int nb) {
;     ...
; #pragma unroll
;         for (int r = 0; r < 16; ++r) {
;           const float v = fmaxf(acc[mi][ni][r], 0.f);
;           (U + (size_t)mt * 128 * 4096)[(wm * 64 + mi * 32 + crow(r, h)) * 4096 + nt * 128 + wn * 64 + ni * 32 + l31] = f2bf(v * v);
	ds_write_b64 v69, v[16:17] offset:4608
	v_max_f32_e32 v20, 0, v20
	v_max_f32_e32 v21, 0, v21
	v_max_f32_e32 v22, 0, v22
	v_max_f32_e32 v23, 0, v23
	v_mul_f32_e32 v20, v20, v20
	v_mul_f32_e32 v21, v21, v21
	v_mul_f32_e32 v22, v22, v22
	v_mul_f32_e32 v23, v23, v23
	v_cvt_pk_bf16_f32 v20, v20, v21
	v_cvt_pk_bf16_f32 v21, v22, v23
	ds_write_b64 v69, v[20:21] offset:4624
	v_max_f32_e32 v24, 0, v24
	v_max_f32_e32 v25, 0, v25
	v_max_f32_e32 v26, 0, v26
	v_max_f32_e32 v27, 0, v27
	v_mul_f32_e32 v24, v24, v24
	v_mul_f32_e32 v25, v25, v25
	v_mul_f32_e32 v26, v26, v26
	v_mul_f32_e32 v27, v27, v27
	v_cvt_pk_bf16_f32 v24, v24, v25
	v_cvt_pk_bf16_f32 v25, v26, v27
	ds_write_b64 v69, v[24:25] offset:4640
	v_max_f32_e32 v28, 0, v28
	v_max_f32_e32 v29, 0, v29
	v_max_f32_e32 v30, 0, v30
	v_max_f32_e32 v31, 0, v31
	v_mul_f32_e32 v28, v28, v28
	v_mul_f32_e32 v29, v29, v29
	v_mul_f32_e32 v30, v30, v30
	v_mul_f32_e32 v31, v31, v31
	v_cvt_pk_bf16_f32 v28, v28, v29
	v_cvt_pk_bf16_f32 v29, v30, v31
	ds_write_b64 v69, v[28:29] offset:4656
	v_max_f32_e32 v0, 0, v0
	v_max_f32_e32 v1, 0, v1
	v_max_f32_e32 v2, 0, v2
	v_max_f32_e32 v3, 0, v3
	v_mul_f32_e32 v0, v0, v0
	v_mul_f32_e32 v1, v1, v1
	v_mul_f32_e32 v2, v2, v2
	v_mul_f32_e32 v3, v3, v3
	v_cvt_pk_bf16_f32 v0, v0, v1
	v_cvt_pk_bf16_f32 v1, v2, v3
	s_waitcnt lgkmcnt(4)
	ds_write_b64 v69, v[0:1] offset:4672
	v_max_f32_e32 v4, 0, v4
	v_max_f32_e32 v5, 0, v5
	v_max_f32_e32 v6, 0, v6
	v_max_f32_e32 v7, 0, v7
	v_mul_f32_e32 v4, v4, v4
	v_mul_f32_e32 v5, v5, v5
	v_mul_f32_e32 v6, v6, v6
	v_mul_f32_e32 v7, v7, v7
	v_cvt_pk_bf16_f32 v4, v4, v5
	v_cvt_pk_bf16_f32 v5, v6, v7
	ds_write_b64 v69, v[4:5] offset:4688
	v_max_f32_e32 v8, 0, v8
	v_max_f32_e32 v9, 0, v9
	v_max_f32_e32 v10, 0, v10
	v_max_f32_e32 v11, 0, v11
	v_mul_f32_e32 v8, v8, v8
	v_mul_f32_e32 v9, v9, v9
	v_mul_f32_e32 v10, v10, v10
	v_mul_f32_e32 v11, v11, v11
	v_cvt_pk_bf16_f32 v8, v8, v9
	v_cvt_pk_bf16_f32 v9, v10, v11
	ds_write_b64 v69, v[8:9] offset:4704
	v_max_f32_e32 v12, 0, v12
	v_max_f32_e32 v13, 0, v13
	v_max_f32_e32 v14, 0, v14
	v_max_f32_e32 v15, 0, v15
	v_mul_f32_e32 v12, v12, v12
	v_mul_f32_e32 v13, v13, v13
	v_mul_f32_e32 v14, v14, v14
	v_mul_f32_e32 v15, v15, v15
	v_cvt_pk_bf16_f32 v12, v12, v13
	v_cvt_pk_bf16_f32 v13, v14, v15
	ds_write_b64 v69, v[12:13] offset:4720
	s_waitcnt lgkmcnt(0)
	ds_read_b128 v[104:107], v72
	ds_read_b128 v[108:111], v72 offset:1152
	ds_read_b128 v[112:115], v72 offset:2304
	ds_read_b128 v[116:119], v72 offset:3456
	ds_read_b128 v[120:123], v72 offset:4608
	ds_read_b128 v[124:127], v72 offset:5760
	ds_read_b128 v[128:131], v72 offset:6912
	ds_read_b128 v[132:135], v72 offset:8064
	s_waitcnt lgkmcnt(7)
	global_store_dwordx4 v[136:137], v[104:107], off
	s_waitcnt lgkmcnt(6)
	global_store_dwordx4 v[138:139], v[108:111], off
	s_waitcnt lgkmcnt(5)
	global_store_dwordx4 v[140:141], v[112:115], off
	s_waitcnt lgkmcnt(4)
	global_store_dwordx4 v[142:143], v[116:119], off
	s_waitcnt lgkmcnt(3)
	global_store_dwordx4 v[144:145], v[120:123], off
	s_waitcnt lgkmcnt(2)
	global_store_dwordx4 v[146:147], v[124:127], off
	s_waitcnt lgkmcnt(1)
	global_store_dwordx4 v[148:149], v[128:131], off
	s_waitcnt lgkmcnt(0)
	global_store_dwordx4 v[150:151], v[132:135], off
	s_add_i32 s11, s11, s12
	s_cmp_ge_i32 s11, s13
	s_cbranch_scc1 .LBB0_198

; template <bool SWAP>
; DI void gemm_tile(const bf16_t* __restrict__ A, int lda, const bf16_t* __restrict__ Bt, int ldb, int K, f32x16 (&acc)[2][2], bf16_t* As, bf16_t* Bs_unused) {
;     ...
;   auto load_stage = [&](u32x4 (&ra)[4], u32x4 (&rb)[4], int t) __attribute__((always_inline)) {
; #pragma unroll
;     for (int i = 0; i < 4; ++i) { ra[i] = *(const u32x4*)(ga + (size_t)(32 * i) * lda + t * 64); rb[i] = *(const u32x4*)(gb + (size_t)(32 * i) * ldb + t * 64); }
;   };
;   auto write_stage = [&](const u32x4 (&ra)[4], const u32x4 (&rb)[4], int buf) __attribute__((always_inline)) {
;     bf16_t* Ad = As + buf * 2 * GT_IMG; bf16_t* Bd = Ad + GT_IMG;
; #pragma unroll
;     for (int i = 0; i < 4; ++i) { *(u32x4*)(Ad + (lr + 32 * i) * 72 + lc) = ra[i]; *(u32x4*)(Bd + (lr + 32 * i) * 72 + lc) = rb[i]; }
;   };
;   const int fr = lane & 31, fk = (lane >> 5) * 8;
;   const int pao = (wm * 64 + fr) * 72 + fk, pbo = GT_IMG + (wn * 64 + fr) * 72 + fk;
;   auto frag_read = [&](bf16x8 (&f)[4], const bf16_t* pa, const bf16_t* pb, int so) __attribute__((always_inline)) {
;     f[0] = *(const bf16x8*)(pa + so); f[1] = *(const bf16x8*)(pb + so); f[2] = *(const bf16x8*)(pb + 32 * 72 + so); f[3] = *(const bf16x8*)(pa + 32 * 72 + so);
;   };
;   auto mfma4 = [&](const bf16x8 (&f)[4]) __attribute__((always_inline)) {
;     if (SWAP) {
;       acc[0][0] = MFMA32(f[1], f[0], acc[0][0]); acc[0][1] = MFMA32(f[2], f[0], acc[0][1]);
;       acc[1][0] = MFMA32(f[1], f[3], acc[1][0]); acc[1][1] = MFMA32(f[2], f[3], acc[1][1]);
;     } else {
;       acc[0][0] = MFMA32(f[0], f[1], acc[0][0]); acc[0][1] = MFMA32(f[0], f[2], acc[0][1]);
;       acc[1][0] = MFMA32(f[3], f[1], acc[1][0]); acc[1][1] = MFMA32(f[3], f[2], acc[1][1]);
;     }
;   };
;   auto step = [&](int buf, u32x4 (&ra)[4], u32x4 (&rb)[4], bool do_write, bool do_load, int tload) __attribute__((always_inline)) {
;     const bf16_t* pa = As + buf * 2 * GT_IMG + pao; const bf16_t* pb = As + buf * 2 * GT_IMG + pbo;
;     bf16_t* Ad = As + (buf ^ 1) * 2 * GT_IMG; bf16_t* Bd = Ad + GT_IMG;
;     bf16x8 F0[4], F1[4];
;     frag_read(F0, pa, pb, 0);
;     __builtin_amdgcn_sched_barrier(0);
;     frag_read(F1, pa, pb, 16);
;     mfma4(F0);
;     __builtin_amdgcn_sched_barrier(0);
;     frag_read(F0, pa, pb, 32);
;     mfma4(F1);
;     if (do_write) {
; #pragma unroll
.LBB0_211:
	s_ashr_i32 s7, s6, 31
	s_add_i32 s11, s11, s12
	s_lshl_b64 s[8:9], s[6:7], 18
	v_mov_b32_e32 v34, v195
	s_add_u32 s8, s4, s8
	s_addc_u32 s9, s5, s9
	v_ashrrev_i32_e32 v32, 3, v34
	s_ashr_i32 s1, s0, 31
	v_ashrrev_i32_e32 v33, 31, v32
	s_lshl_b64 s[14:15], s[0:1], 18
	v_readlane_b32 s1, v235, 59
	v_lshlrev_b64 v[0:1], 11, v[32:33]
	s_waitcnt lgkmcnt(0)
	v_lshlrev_b32_e32 v4, 4, v34
	s_add_u32 s14, s1, s14
	v_readlane_b32 s1, v235, 60
	v_lshl_add_u64 v[2:3], s[8:9], 0, v[0:1]
	v_and_b32_e32 v192, 0x70, v4
	s_addc_u32 s15, s1, s15
	v_lshl_add_u64 v[80:81], v[2:3], 0, v[192:193]
	s_mov_b32 s1, 0x10000
	v_lshl_add_u64 v[0:1], s[14:15], 0, v[0:1]
	v_add_co_u32_e32 v84, vcc, s1, v80
	v_lshl_add_u64 v[82:83], v[0:1], 0, v[192:193]
	s_nop 0
	v_addc_co_u32_e32 v85, vcc, 0, v81, vcc
	v_add_co_u32_e32 v86, vcc, s1, v82
	s_mov_b32 s1, 0x20000
	s_nop 0
	v_addc_co_u32_e32 v87, vcc, 0, v83, vcc
	global_load_dwordx4 v[0:3], v[80:81], off
	global_load_dwordx4 v[4:7], v[82:83], off
	v_add_co_u32_e32 v88, vcc, s1, v80
	global_load_dwordx4 v[8:11], v[84:85], off
	global_load_dwordx4 v[12:15], v[86:87], off
	v_addc_co_u32_e32 v89, vcc, 0, v81, vcc
	v_add_co_u32_e32 v90, vcc, s1, v82
	s_mov_b32 s1, 0x30000
	s_nop 0
	v_addc_co_u32_e32 v91, vcc, 0, v83, vcc
	global_load_dwordx4 v[16:19], v[88:89], off
	global_load_dwordx4 v[20:23], v[90:91], off
	v_add_co_u32_e32 v92, vcc, s1, v80
	v_mul_lo_u32 v32, v32, s71
	s_nop 0
	v_addc_co_u32_e32 v93, vcc, 0, v81, vcc
	global_load_dwordx4 v[24:27], v[92:93], off
	v_add_co_u32_e32 v94, vcc, s1, v82
	v_add3_u32 v100, 32, v32, v192
	s_nop 0
	v_addc_co_u32_e32 v95, vcc, 0, v83, vcc
	global_load_dwordx4 v[28:31], v[94:95], off
	global_load_dwordx4 v[104:107], v[80:81], off offset:128
	global_load_dwordx4 v[108:111], v[82:83], off offset:128
	global_load_dwordx4 v[112:115], v[84:85], off offset:128
	global_load_dwordx4 v[116:119], v[86:87], off offset:128
	global_load_dwordx4 v[120:123], v[88:89], off offset:128
	global_load_dwordx4 v[124:127], v[90:91], off offset:128
	global_load_dwordx4 v[128:131], v[92:93], off offset:128
	global_load_dwordx4 v[132:135], v[94:95], off offset:128
	s_waitcnt vmcnt(63) expcnt(7) lgkmcnt(15)
	s_barrier
	v_add_u32_e32 v103, 0xd800, v100
	s_waitcnt vmcnt(15)
	ds_write_b128 v100, v[0:3]
	s_waitcnt vmcnt(14)
	ds_write_b128 v100, v[4:7] offset:18432
	s_waitcnt vmcnt(13)
	ds_write_b128 v100, v[8:11] offset:4608
	s_waitcnt vmcnt(12)
	ds_write_b128 v100, v[12:15] offset:23040
	s_waitcnt vmcnt(11)
	ds_write_b128 v100, v[16:19] offset:9216
	s_waitcnt vmcnt(10)
	ds_write_b128 v100, v[20:23] offset:27648
	s_waitcnt vmcnt(9)
	ds_write_b128 v100, v[24:27] offset:13824
	s_waitcnt vmcnt(8)
	ds_write_b128 v100, v[28:31] offset:32256
	global_load_dwordx4 v[136:139], v[80:81], off offset:256
	global_load_dwordx4 v[64:67], v[82:83], off offset:256
	global_load_dwordx4 v[140:143], v[84:85], off offset:256
	global_load_dwordx4 v[68:71], v[86:87], off offset:256
	global_load_dwordx4 v[144:147], v[88:89], off offset:256
	global_load_dwordx4 v[72:75], v[90:91], off offset:256
	global_load_dwordx4 v[148:151], v[92:93], off offset:256
	global_load_dwordx4 v[76:79], v[94:95], off offset:256
	v_lshrrev_b32_e32 v0, 2, v34
	v_lshrrev_b32_e32 v2, 1, v34
	v_and_b32_e32 v3, 31, v34
	v_and_b32_e32 v1, 0x5f, v34
	v_and_b32_e32 v0, 8, v0
	v_and_or_b32 v2, v2, s80, v3
	v_mad_u64_u32 v[2:3], s[8:9], v2, s72, v[0:1]
	v_lshl_add_u32 v101, v2, 1, 32
	v_mad_u32_u24 v0, v1, s72, v0
	s_waitcnt lgkmcnt(0)
	s_barrier
	v_lshl_add_u32 v102, v0, 1, 32
	ds_read_b128 v[0:3], v101
	ds_read_b128 v[4:7], v102 offset:18432
	ds_read_b128 v[8:11], v102 offset:23040
	ds_read_b128 v[12:15], v101 offset:4608
	ds_read_b128 v[152:155], v102 offset:18464
	ds_read_b128 v[156:159], v102 offset:23072
	ds_read_b128 v[160:163], v101 offset:32
	ds_read_b128 v[164:167], v101 offset:4640
	s_waitcnt lgkmcnt(6)
	v_mfma_f32_32x32x16_bf16 v[48:63], v[0:3], v[4:7], 0
	s_waitcnt lgkmcnt(5)
	v_mfma_f32_32x32x16_bf16 v[16:31], v[0:3], v[8:11], 0
	s_waitcnt lgkmcnt(4)
	v_mfma_f32_32x32x16_bf16 v[32:47], v[12:15], v[4:7], 0
	v_mfma_f32_32x32x16_bf16 v[0:15], v[12:15], v[8:11], 0
	s_waitcnt lgkmcnt(1)
	v_mfma_f32_32x32x16_bf16 v[48:63], v[160:163], v[152:155], v[48:63]
	v_mfma_f32_32x32x16_bf16 v[16:31], v[160:163], v[156:159], v[16:31]
	s_waitcnt lgkmcnt(0)
	v_mfma_f32_32x32x16_bf16 v[32:47], v[164:167], v[152:155], v[32:47]
	ds_read_b128 v[152:155], v102 offset:18496
	ds_read_b128 v[160:163], v102 offset:23104
	ds_read_b128 v[168:171], v101 offset:64
	ds_read_b128 v[172:175], v101 offset:4672
	s_waitcnt vmcnt(15)
	ds_write_b128 v100, v[104:107] offset:36864
	s_waitcnt vmcnt(13)
	ds_write_b128 v100, v[112:115] offset:41472
	s_waitcnt vmcnt(11)
	ds_write_b128 v100, v[120:123] offset:46080
	s_waitcnt vmcnt(9)
	ds_write_b128 v100, v[128:131] offset:50688
	v_mfma_f32_32x32x16_bf16 v[0:15], v[164:167], v[156:159], v[0:15]
	ds_read_b128 v[104:107], v102 offset:18528
	ds_read_b128 v[112:115], v102 offset:23136
	ds_read_b128 v[120:123], v101 offset:96
	ds_read_b128 v[128:131], v101 offset:4704
	s_waitcnt lgkmcnt(9)
	v_mfma_f32_32x32x16_bf16 v[48:63], v[168:171], v[152:155], v[48:63]
	ds_write_b128 v100, v[108:111] offset:55296
	ds_write_b128 v100, v[116:119] offset:59904
	ds_write_b128 v100, v[124:127] offset:64512
	s_waitcnt vmcnt(8)
	ds_write_b128 v103, v[132:135] offset:13824
	v_mfma_f32_32x32x16_bf16 v[16:31], v[168:171], v[160:163], v[16:31]
	s_waitcnt lgkmcnt(12)
	v_mfma_f32_32x32x16_bf16 v[32:47], v[172:175], v[152:155], v[32:47]
	v_mfma_f32_32x32x16_bf16 v[0:15], v[172:175], v[160:163], v[0:15]
	s_waitcnt lgkmcnt(0)
	s_barrier
; template <bool SWAP>
; DI void gemm_tile(const bf16_t* __restrict__ A, int lda, const bf16_t* __restrict__ Bt, int ldb, int K, f32x16 (&acc)[2][2], bf16_t* As, bf16_t* Bs_unused) {
;     ...
;   auto step = [&](int buf, u32x4 (&ra)[4], u32x4 (&rb)[4], bool do_write, bool do_load, int tload) __attribute__((always_inline)) {
;     const bf16_t* pa = As + buf * 2 * GT_IMG + pao; const bf16_t* pb = As + buf * 2 * GT_IMG + pbo;
;     bf16_t* Ad = As + (buf ^ 1) * 2 * GT_IMG; bf16_t* Bd = Ad + GT_IMG;
;     bf16x8 F0[4], F1[4];
;     frag_read(F0, pa, pb, 0);
;     __builtin_amdgcn_sched_barrier(0);
;     frag_read(F1, pa, pb, 16);
;     mfma4(F0);
;     __builtin_amdgcn_sched_barrier(0);
;     frag_read(F0, pa, pb, 32);
;     mfma4(F1);
;     if (do_write) {
; #pragma unroll
;       for (int i = 0; i < 4; ++i) *(u32x4*)(Ad + (lr + 32 * i) * 72 + lc) = ra[i];
;     }
;     __builtin_amdgcn_sched_barrier(0);
;     frag_read(F1, pa, pb, 48);
;     mfma4(F0);
;     if (do_write) {
; #pragma unroll
;       for (int i = 0; i < 4; ++i) *(u32x4*)(Bd + (lr + 32 * i) * 72 + lc) = rb[i];
;     }
;     __builtin_amdgcn_sched_barrier(0);
;     mfma4(F1);
;     if (do_load) load_stage(ra, rb, tload);
;     __builtin_amdgcn_sched_barrier(0);
;   };
;   const int nk = K >> 6;
;   load_stage(ra0, rb0, 0); load_stage(ra1, rb1, 1);
;   __syncthreads();
;   write_stage(ra0, rb0, 0);
;   load_stage(ra0, rb0, 2);
;   __syncthreads();
;   for (int kt = 0; kt < nk; kt += 2) {
;     step(0, ra1, rb1, true, kt + 3 < nk, kt + 3);
;     __syncthreads();
;     step(1, ra0, rb0, kt + 2 < nk, kt + 4 < nk, kt + 4);
;     __syncthreads();
	ds_read_b128 v[152:155], v102 offset:55296
	ds_read_b128 v[156:159], v102 offset:59904
	ds_read_b128 v[160:163], v101 offset:36864
	ds_read_b128 v[164:167], v101 offset:41472
	v_mfma_f32_32x32x16_bf16 v[48:63], v[120:123], v[104:107], v[48:63]
	v_mfma_f32_32x32x16_bf16 v[16:31], v[120:123], v[112:115], v[16:31]
	v_mfma_f32_32x32x16_bf16 v[32:47], v[128:131], v[104:107], v[32:47]
	v_mfma_f32_32x32x16_bf16 v[0:15], v[128:131], v[112:115], v[0:15]
	global_load_dwordx4 v[104:107], v[80:81], off offset:384
	global_load_dwordx4 v[108:111], v[82:83], off offset:384
	global_load_dwordx4 v[112:115], v[84:85], off offset:384
	global_load_dwordx4 v[116:119], v[86:87], off offset:384
	global_load_dwordx4 v[120:123], v[88:89], off offset:384
	global_load_dwordx4 v[124:127], v[90:91], off offset:384
	global_load_dwordx4 v[128:131], v[92:93], off offset:384
	global_load_dwordx4 v[132:135], v[94:95], off offset:384
	s_waitcnt lgkmcnt(1)
	v_mfma_f32_32x32x16_bf16 v[48:63], v[160:163], v[152:155], v[48:63]
	v_mfma_f32_32x32x16_bf16 v[16:31], v[160:163], v[156:159], v[16:31]
	s_waitcnt lgkmcnt(0)
	v_mfma_f32_32x32x16_bf16 v[32:47], v[164:167], v[152:155], v[32:47]
	ds_read_b128 v[152:155], v102 offset:55328
	ds_read_b128 v[160:163], v102 offset:59936
	ds_read_b128 v[168:171], v101 offset:36896
	ds_read_b128 v[172:175], v101 offset:41504
	v_mfma_f32_32x32x16_bf16 v[0:15], v[164:167], v[156:159], v[0:15]
	s_waitcnt lgkmcnt(1)
	v_mfma_f32_32x32x16_bf16 v[48:63], v[168:171], v[152:155], v[48:63]
	v_mfma_f32_32x32x16_bf16 v[16:31], v[168:171], v[160:163], v[16:31]
	s_waitcnt lgkmcnt(0)
	v_mfma_f32_32x32x16_bf16 v[32:47], v[172:175], v[152:155], v[32:47]
	ds_read_b128 v[152:155], v102 offset:55360
	ds_read_b128 v[156:159], v102 offset:59968
	ds_read_b128 v[164:167], v101 offset:36928
	ds_read_b128 v[168:171], v101 offset:41536
	s_waitcnt vmcnt(15)
	ds_write_b128 v100, v[136:139]
	s_waitcnt vmcnt(13)
	ds_write_b128 v100, v[140:143] offset:4608
	s_waitcnt vmcnt(11)
	ds_write_b128 v100, v[144:147] offset:9216
	s_waitcnt vmcnt(9)
	ds_write_b128 v100, v[148:151] offset:13824
	v_mfma_f32_32x32x16_bf16 v[0:15], v[172:175], v[160:163], v[0:15]
	ds_read_b128 v[136:139], v102 offset:55392
	ds_read_b128 v[140:143], v102 offset:60000
	ds_read_b128 v[144:147], v101 offset:36960
	ds_read_b128 v[148:151], v101 offset:41568
	s_waitcnt lgkmcnt(9)
	v_mfma_f32_32x32x16_bf16 v[48:63], v[164:167], v[152:155], v[48:63]
	ds_write_b128 v100, v[64:67] offset:18432
	ds_write_b128 v100, v[68:71] offset:23040
	ds_write_b128 v100, v[72:75] offset:27648
	s_waitcnt vmcnt(8)
	ds_write_b128 v100, v[76:79] offset:32256
	v_mfma_f32_32x32x16_bf16 v[16:31], v[164:167], v[156:159], v[16:31]
	s_waitcnt lgkmcnt(12)
	v_mfma_f32_32x32x16_bf16 v[32:47], v[168:171], v[152:155], v[32:47]
	v_mfma_f32_32x32x16_bf16 v[0:15], v[168:171], v[156:159], v[0:15]
	s_waitcnt lgkmcnt(0)
	s_barrier
	ds_read_b128 v[152:155], v102 offset:18432
	ds_read_b128 v[156:159], v102 offset:23040
	ds_read_b128 v[160:163], v101
	ds_read_b128 v[164:167], v101 offset:4608
	v_mfma_f32_32x32x16_bf16 v[48:63], v[144:147], v[136:139], v[48:63]
	v_mfma_f32_32x32x16_bf16 v[16:31], v[144:147], v[140:143], v[16:31]
	v_mfma_f32_32x32x16_bf16 v[32:47], v[148:151], v[136:139], v[32:47]
	v_mfma_f32_32x32x16_bf16 v[0:15], v[148:151], v[140:143], v[0:15]
	global_load_dwordx4 v[64:67], v[80:81], off offset:512
	global_load_dwordx4 v[68:71], v[82:83], off offset:512
	global_load_dwordx4 v[72:75], v[84:85], off offset:512
	global_load_dwordx4 v[76:79], v[86:87], off offset:512
	global_load_dwordx4 v[136:139], v[88:89], off offset:512
	global_load_dwordx4 v[140:143], v[90:91], off offset:512
	global_load_dwordx4 v[144:147], v[92:93], off offset:512
	global_load_dwordx4 v[148:151], v[94:95], off offset:512
	s_waitcnt lgkmcnt(1)
	v_mfma_f32_32x32x16_bf16 v[48:63], v[160:163], v[152:155], v[48:63]
	v_mfma_f32_32x32x16_bf16 v[16:31], v[160:163], v[156:159], v[16:31]
	s_waitcnt lgkmcnt(0)
	v_mfma_f32_32x32x16_bf16 v[32:47], v[164:167], v[152:155], v[32:47]
	ds_read_b128 v[152:155], v102 offset:18464
	ds_read_b128 v[160:163], v102 offset:23072
	ds_read_b128 v[168:171], v101 offset:32
	ds_read_b128 v[172:175], v101 offset:4640
	v_mfma_f32_32x32x16_bf16 v[0:15], v[164:167], v[156:159], v[0:15]
	s_waitcnt lgkmcnt(1)
	v_mfma_f32_32x32x16_bf16 v[48:63], v[168:171], v[152:155], v[48:63]
	v_mfma_f32_32x32x16_bf16 v[16:31], v[168:171], v[160:163], v[16:31]
	s_waitcnt lgkmcnt(0)
	v_mfma_f32_32x32x16_bf16 v[32:47], v[172:175], v[152:155], v[32:47]
	ds_read_b128 v[152:155], v102 offset:18496
	ds_read_b128 v[156:159], v102 offset:23104
	ds_read_b128 v[164:167], v101 offset:64
	ds_read_b128 v[168:171], v101 offset:4672
	s_waitcnt vmcnt(15)
	ds_write_b128 v100, v[104:107] offset:36864
	s_waitcnt vmcnt(13)
	ds_write_b128 v100, v[112:115] offset:41472
	s_waitcnt vmcnt(11)
	ds_write_b128 v100, v[120:123] offset:46080
	s_waitcnt vmcnt(9)
	ds_write_b128 v100, v[128:131] offset:50688
	v_mfma_f32_32x32x16_bf16 v[0:15], v[172:175], v[160:163], v[0:15]
	ds_read_b128 v[104:107], v102 offset:18528
	ds_read_b128 v[112:115], v102 offset:23136
	ds_read_b128 v[120:123], v101 offset:96
	ds_read_b128 v[128:131], v101 offset:4704
	s_waitcnt lgkmcnt(9)
	v_mfma_f32_32x32x16_bf16 v[48:63], v[164:167], v[152:155], v[48:63]
	ds_write_b128 v100, v[108:111] offset:55296
	ds_write_b128 v100, v[116:119] offset:59904
	ds_write_b128 v100, v[124:127] offset:64512
	s_waitcnt vmcnt(8)
	ds_write_b128 v103, v[132:135] offset:13824
	v_mfma_f32_32x32x16_bf16 v[16:31], v[164:167], v[156:159], v[16:31]
	s_waitcnt lgkmcnt(12)
	v_mfma_f32_32x32x16_bf16 v[32:47], v[168:171], v[152:155], v[32:47]
	v_mfma_f32_32x32x16_bf16 v[0:15], v[168:171], v[156:159], v[0:15]
	s_waitcnt lgkmcnt(0)
	s_barrier
; template <bool SWAP>
; DI void gemm_tile(const bf16_t* __restrict__ A, int lda, const bf16_t* __restrict__ Bt, int ldb, int K, f32x16 (&acc)[2][2], bf16_t* As, bf16_t* Bs_unused) {
;     ...
;   auto step = [&](int buf, u32x4 (&ra)[4], u32x4 (&rb)[4], bool do_write, bool do_load, int tload) __attribute__((always_inline)) {
;     const bf16_t* pa = As + buf * 2 * GT_IMG + pao; const bf16_t* pb = As + buf * 2 * GT_IMG + pbo;
;     bf16_t* Ad = As + (buf ^ 1) * 2 * GT_IMG; bf16_t* Bd = Ad + GT_IMG;
;     bf16x8 F0[4], F1[4];
;     frag_read(F0, pa, pb, 0);
;     __builtin_amdgcn_sched_barrier(0);
;     frag_read(F1, pa, pb, 16);
;     mfma4(F0);
;     __builtin_amdgcn_sched_barrier(0);
;     frag_read(F0, pa, pb, 32);
;     mfma4(F1);
;     if (do_write) {
; #pragma unroll
;       for (int i = 0; i < 4; ++i) *(u32x4*)(Ad + (lr + 32 * i) * 72 + lc) = ra[i];
;     }
;     __builtin_amdgcn_sched_barrier(0);
;     frag_read(F1, pa, pb, 48);
;     mfma4(F0);
;     if (do_write) {
; #pragma unroll
;       for (int i = 0; i < 4; ++i) *(u32x4*)(Bd + (lr + 32 * i) * 72 + lc) = rb[i];
;     }
;     __builtin_amdgcn_sched_barrier(0);
;     mfma4(F1);
;     if (do_load) load_stage(ra, rb, tload);
;     __builtin_amdgcn_sched_barrier(0);
;   };
;   const int nk = K >> 6;
;   load_stage(ra0, rb0, 0); load_stage(ra1, rb1, 1);
;   __syncthreads();
;   write_stage(ra0, rb0, 0);
;   load_stage(ra0, rb0, 2);
;   __syncthreads();
;   for (int kt = 0; kt < nk; kt += 2) {
;     step(0, ra1, rb1, true, kt + 3 < nk, kt + 3);
;     __syncthreads();
;     step(1, ra0, rb0, kt + 2 < nk, kt + 4 < nk, kt + 4);
;     __syncthreads();
	ds_read_b128 v[152:155], v102 offset:55296
	ds_read_b128 v[156:159], v102 offset:59904
	ds_read_b128 v[160:163], v101 offset:36864
	ds_read_b128 v[164:167], v101 offset:41472
	v_mfma_f32_32x32x16_bf16 v[48:63], v[120:123], v[104:107], v[48:63]
	v_mfma_f32_32x32x16_bf16 v[16:31], v[120:123], v[112:115], v[16:31]
	v_mfma_f32_32x32x16_bf16 v[32:47], v[128:131], v[104:107], v[32:47]
	v_mfma_f32_32x32x16_bf16 v[0:15], v[128:131], v[112:115], v[0:15]
	global_load_dwordx4 v[104:107], v[80:81], off offset:640
	global_load_dwordx4 v[108:111], v[82:83], off offset:640
	global_load_dwordx4 v[112:115], v[84:85], off offset:640
	global_load_dwordx4 v[116:119], v[86:87], off offset:640
	global_load_dwordx4 v[120:123], v[88:89], off offset:640
	global_load_dwordx4 v[124:127], v[90:91], off offset:640
	global_load_dwordx4 v[128:131], v[92:93], off offset:640
	global_load_dwordx4 v[132:135], v[94:95], off offset:640
	s_waitcnt lgkmcnt(1)
	v_mfma_f32_32x32x16_bf16 v[48:63], v[160:163], v[152:155], v[48:63]
	v_mfma_f32_32x32x16_bf16 v[16:31], v[160:163], v[156:159], v[16:31]
	s_waitcnt lgkmcnt(0)
	v_mfma_f32_32x32x16_bf16 v[32:47], v[164:167], v[152:155], v[32:47]
	ds_read_b128 v[152:155], v102 offset:55328
	ds_read_b128 v[160:163], v102 offset:59936
	ds_read_b128 v[168:171], v101 offset:36896
	ds_read_b128 v[172:175], v101 offset:41504
	v_mfma_f32_32x32x16_bf16 v[0:15], v[164:167], v[156:159], v[0:15]
	s_waitcnt lgkmcnt(1)
	v_mfma_f32_32x32x16_bf16 v[48:63], v[168:171], v[152:155], v[48:63]
	v_mfma_f32_32x32x16_bf16 v[16:31], v[168:171], v[160:163], v[16:31]
	s_waitcnt lgkmcnt(0)
	v_mfma_f32_32x32x16_bf16 v[32:47], v[172:175], v[152:155], v[32:47]
	ds_read_b128 v[152:155], v102 offset:55360
	ds_read_b128 v[156:159], v102 offset:59968
	ds_read_b128 v[164:167], v101 offset:36928
	ds_read_b128 v[168:171], v101 offset:41536
	s_waitcnt vmcnt(15)
	ds_write_b128 v100, v[64:67]
	s_waitcnt vmcnt(13)
	ds_write_b128 v100, v[72:75] offset:4608
	s_waitcnt vmcnt(11)
	ds_write_b128 v100, v[136:139] offset:9216
	s_waitcnt vmcnt(9)
	ds_write_b128 v100, v[144:147] offset:13824
	v_mfma_f32_32x32x16_bf16 v[0:15], v[172:175], v[160:163], v[0:15]
	ds_read_b128 v[64:67], v102 offset:55392
	ds_read_b128 v[72:75], v102 offset:60000
	ds_read_b128 v[136:139], v101 offset:36960
	ds_read_b128 v[144:147], v101 offset:41568
	s_waitcnt lgkmcnt(9)
	v_mfma_f32_32x32x16_bf16 v[48:63], v[164:167], v[152:155], v[48:63]
	ds_write_b128 v100, v[68:71] offset:18432
	ds_write_b128 v100, v[76:79] offset:23040
	ds_write_b128 v100, v[140:143] offset:27648
	s_waitcnt vmcnt(8)
	ds_write_b128 v100, v[148:151] offset:32256
	v_mfma_f32_32x32x16_bf16 v[16:31], v[164:167], v[156:159], v[16:31]
	s_waitcnt lgkmcnt(12)
	v_mfma_f32_32x32x16_bf16 v[32:47], v[168:171], v[152:155], v[32:47]
	v_mfma_f32_32x32x16_bf16 v[0:15], v[168:171], v[156:159], v[0:15]
	s_waitcnt lgkmcnt(0)
	s_barrier
	ds_read_b128 v[152:155], v102 offset:18432
	ds_read_b128 v[156:159], v102 offset:23040
	ds_read_b128 v[160:163], v101
	ds_read_b128 v[164:167], v101 offset:4608
	v_mfma_f32_32x32x16_bf16 v[48:63], v[136:139], v[64:67], v[48:63]
	v_mfma_f32_32x32x16_bf16 v[16:31], v[136:139], v[72:75], v[16:31]
	v_mfma_f32_32x32x16_bf16 v[32:47], v[144:147], v[64:67], v[32:47]
	v_mfma_f32_32x32x16_bf16 v[0:15], v[144:147], v[72:75], v[0:15]
	global_load_dwordx4 v[64:67], v[80:81], off offset:768
	global_load_dwordx4 v[68:71], v[82:83], off offset:768
	global_load_dwordx4 v[72:75], v[84:85], off offset:768
	global_load_dwordx4 v[76:79], v[86:87], off offset:768
	global_load_dwordx4 v[136:139], v[88:89], off offset:768
	global_load_dwordx4 v[140:143], v[90:91], off offset:768
	global_load_dwordx4 v[144:147], v[92:93], off offset:768
	global_load_dwordx4 v[148:151], v[94:95], off offset:768
	s_waitcnt lgkmcnt(1)
	v_mfma_f32_32x32x16_bf16 v[48:63], v[160:163], v[152:155], v[48:63]
	v_mfma_f32_32x32x16_bf16 v[16:31], v[160:163], v[156:159], v[16:31]
	s_waitcnt lgkmcnt(0)
	v_mfma_f32_32x32x16_bf16 v[32:47], v[164:167], v[152:155], v[32:47]
	ds_read_b128 v[152:155], v102 offset:18464
	ds_read_b128 v[160:163], v102 offset:23072
	ds_read_b128 v[168:171], v101 offset:32
	ds_read_b128 v[172:175], v101 offset:4640
	v_mfma_f32_32x32x16_bf16 v[0:15], v[164:167], v[156:159], v[0:15]
	s_waitcnt lgkmcnt(1)
	v_mfma_f32_32x32x16_bf16 v[48:63], v[168:171], v[152:155], v[48:63]
	v_mfma_f32_32x32x16_bf16 v[16:31], v[168:171], v[160:163], v[16:31]
	s_waitcnt lgkmcnt(0)
	v_mfma_f32_32x32x16_bf16 v[32:47], v[172:175], v[152:155], v[32:47]
	ds_read_b128 v[152:155], v102 offset:18496
	ds_read_b128 v[156:159], v102 offset:23104
	ds_read_b128 v[164:167], v101 offset:64
	ds_read_b128 v[168:171], v101 offset:4672
	s_waitcnt vmcnt(15)
	ds_write_b128 v100, v[104:107] offset:36864
	s_waitcnt vmcnt(13)
	ds_write_b128 v100, v[112:115] offset:41472
	s_waitcnt vmcnt(11)
	ds_write_b128 v100, v[120:123] offset:46080
	s_waitcnt vmcnt(9)
	ds_write_b128 v100, v[128:131] offset:50688
	v_mfma_f32_32x32x16_bf16 v[0:15], v[172:175], v[160:163], v[0:15]
	ds_read_b128 v[104:107], v102 offset:18528
	ds_read_b128 v[112:115], v102 offset:23136
	ds_read_b128 v[120:123], v101 offset:96
	ds_read_b128 v[128:131], v101 offset:4704
	s_waitcnt lgkmcnt(9)
	v_mfma_f32_32x32x16_bf16 v[48:63], v[164:167], v[152:155], v[48:63]
	ds_write_b128 v100, v[108:111] offset:55296
	ds_write_b128 v100, v[116:119] offset:59904
	ds_write_b128 v100, v[124:127] offset:64512
	s_waitcnt vmcnt(8)
	ds_write_b128 v103, v[132:135] offset:13824
	v_mfma_f32_32x32x16_bf16 v[16:31], v[164:167], v[156:159], v[16:31]
	s_waitcnt lgkmcnt(12)
	v_mfma_f32_32x32x16_bf16 v[32:47], v[168:171], v[152:155], v[32:47]
	v_mfma_f32_32x32x16_bf16 v[0:15], v[168:171], v[156:159], v[0:15]
	s_waitcnt lgkmcnt(0)
	s_barrier
; template <bool SWAP>
; DI void gemm_tile(const bf16_t* __restrict__ A, int lda, const bf16_t* __restrict__ Bt, int ldb, int K, f32x16 (&acc)[2][2], bf16_t* As, bf16_t* Bs_unused) {
;     ...
;   auto step = [&](int buf, u32x4 (&ra)[4], u32x4 (&rb)[4], bool do_write, bool do_load, int tload) __attribute__((always_inline)) {
;     const bf16_t* pa = As + buf * 2 * GT_IMG + pao; const bf16_t* pb = As + buf * 2 * GT_IMG + pbo;
;     bf16_t* Ad = As + (buf ^ 1) * 2 * GT_IMG; bf16_t* Bd = Ad + GT_IMG;
;     bf16x8 F0[4], F1[4];
;     frag_read(F0, pa, pb, 0);
;     __builtin_amdgcn_sched_barrier(0);
;     frag_read(F1, pa, pb, 16);
;     mfma4(F0);
;     __builtin_amdgcn_sched_barrier(0);
;     frag_read(F0, pa, pb, 32);
;     mfma4(F1);
;     if (do_write) {
; #pragma unroll
;       for (int i = 0; i < 4; ++i) *(u32x4*)(Ad + (lr + 32 * i) * 72 + lc) = ra[i];
;     }
;     __builtin_amdgcn_sched_barrier(0);
;     frag_read(F1, pa, pb, 48);
;     mfma4(F0);
;     if (do_write) {
; #pragma unroll
;       for (int i = 0; i < 4; ++i) *(u32x4*)(Bd + (lr + 32 * i) * 72 + lc) = rb[i];
;     }
;     __builtin_amdgcn_sched_barrier(0);
;     mfma4(F1);
;     if (do_load) load_stage(ra, rb, tload);
;     __builtin_amdgcn_sched_barrier(0);
;   };
;   const int nk = K >> 6;
;   load_stage(ra0, rb0, 0); load_stage(ra1, rb1, 1);
;   __syncthreads();
;   write_stage(ra0, rb0, 0);
;   load_stage(ra0, rb0, 2);
;   __syncthreads();
;   for (int kt = 0; kt < nk; kt += 2) {
;     step(0, ra1, rb1, true, kt + 3 < nk, kt + 3);
;     __syncthreads();
;     step(1, ra0, rb0, kt + 2 < nk, kt + 4 < nk, kt + 4);
;     __syncthreads();
	ds_read_b128 v[152:155], v102 offset:55296
	ds_read_b128 v[156:159], v102 offset:59904
	ds_read_b128 v[160:163], v101 offset:36864
	ds_read_b128 v[164:167], v101 offset:41472
	v_mfma_f32_32x32x16_bf16 v[48:63], v[120:123], v[104:107], v[48:63]
	v_mfma_f32_32x32x16_bf16 v[16:31], v[120:123], v[112:115], v[16:31]
	v_mfma_f32_32x32x16_bf16 v[32:47], v[128:131], v[104:107], v[32:47]
	v_mfma_f32_32x32x16_bf16 v[0:15], v[128:131], v[112:115], v[0:15]
	global_load_dwordx4 v[104:107], v[80:81], off offset:896
	global_load_dwordx4 v[108:111], v[82:83], off offset:896
	global_load_dwordx4 v[112:115], v[84:85], off offset:896
	global_load_dwordx4 v[116:119], v[86:87], off offset:896
	global_load_dwordx4 v[120:123], v[88:89], off offset:896
	global_load_dwordx4 v[124:127], v[90:91], off offset:896
	global_load_dwordx4 v[128:131], v[92:93], off offset:896
	global_load_dwordx4 v[132:135], v[94:95], off offset:896
	s_waitcnt lgkmcnt(1)
	v_mfma_f32_32x32x16_bf16 v[48:63], v[160:163], v[152:155], v[48:63]
	v_mfma_f32_32x32x16_bf16 v[16:31], v[160:163], v[156:159], v[16:31]
	s_waitcnt lgkmcnt(0)
	v_mfma_f32_32x32x16_bf16 v[32:47], v[164:167], v[152:155], v[32:47]
	ds_read_b128 v[152:155], v102 offset:55328
	ds_read_b128 v[160:163], v102 offset:59936
	ds_read_b128 v[168:171], v101 offset:36896
	ds_read_b128 v[172:175], v101 offset:41504
	v_mfma_f32_32x32x16_bf16 v[0:15], v[164:167], v[156:159], v[0:15]
	s_waitcnt lgkmcnt(1)
	v_mfma_f32_32x32x16_bf16 v[48:63], v[168:171], v[152:155], v[48:63]
	v_mfma_f32_32x32x16_bf16 v[16:31], v[168:171], v[160:163], v[16:31]
	s_waitcnt lgkmcnt(0)
	v_mfma_f32_32x32x16_bf16 v[32:47], v[172:175], v[152:155], v[32:47]
	ds_read_b128 v[152:155], v102 offset:55360
	ds_read_b128 v[156:159], v102 offset:59968
	ds_read_b128 v[164:167], v101 offset:36928
	ds_read_b128 v[168:171], v101 offset:41536
	s_waitcnt vmcnt(15)
	ds_write_b128 v100, v[64:67]
	s_waitcnt vmcnt(13)
	ds_write_b128 v100, v[72:75] offset:4608
	s_waitcnt vmcnt(11)
	ds_write_b128 v100, v[136:139] offset:9216
	s_waitcnt vmcnt(9)
	ds_write_b128 v100, v[144:147] offset:13824
	v_mfma_f32_32x32x16_bf16 v[0:15], v[172:175], v[160:163], v[0:15]
	ds_read_b128 v[64:67], v102 offset:55392
	ds_read_b128 v[72:75], v102 offset:60000
	ds_read_b128 v[136:139], v101 offset:36960
	ds_read_b128 v[144:147], v101 offset:41568
	s_waitcnt lgkmcnt(9)
	v_mfma_f32_32x32x16_bf16 v[48:63], v[164:167], v[152:155], v[48:63]
	ds_write_b128 v100, v[68:71] offset:18432
	ds_write_b128 v100, v[76:79] offset:23040
	ds_write_b128 v100, v[140:143] offset:27648
	s_waitcnt vmcnt(8)
	ds_write_b128 v100, v[148:151] offset:32256
	v_mfma_f32_32x32x16_bf16 v[16:31], v[164:167], v[156:159], v[16:31]
	s_waitcnt lgkmcnt(12)
	v_mfma_f32_32x32x16_bf16 v[32:47], v[168:171], v[152:155], v[32:47]
	v_mfma_f32_32x32x16_bf16 v[0:15], v[168:171], v[156:159], v[0:15]
	s_waitcnt lgkmcnt(0)
	s_barrier
	ds_read_b128 v[152:155], v102 offset:18432
	ds_read_b128 v[156:159], v102 offset:23040
	ds_read_b128 v[160:163], v101
	ds_read_b128 v[164:167], v101 offset:4608
	v_mfma_f32_32x32x16_bf16 v[48:63], v[136:139], v[64:67], v[48:63]
	v_mfma_f32_32x32x16_bf16 v[16:31], v[136:139], v[72:75], v[16:31]
	v_mfma_f32_32x32x16_bf16 v[32:47], v[144:147], v[64:67], v[32:47]
	v_mfma_f32_32x32x16_bf16 v[0:15], v[144:147], v[72:75], v[0:15]
	global_load_dwordx4 v[64:67], v[80:81], off offset:1024
	global_load_dwordx4 v[68:71], v[82:83], off offset:1024
	global_load_dwordx4 v[72:75], v[84:85], off offset:1024
	global_load_dwordx4 v[76:79], v[86:87], off offset:1024
	global_load_dwordx4 v[136:139], v[88:89], off offset:1024
	global_load_dwordx4 v[140:143], v[90:91], off offset:1024
	global_load_dwordx4 v[144:147], v[92:93], off offset:1024
	global_load_dwordx4 v[148:151], v[94:95], off offset:1024
	s_waitcnt lgkmcnt(1)
	v_mfma_f32_32x32x16_bf16 v[48:63], v[160:163], v[152:155], v[48:63]
	v_mfma_f32_32x32x16_bf16 v[16:31], v[160:163], v[156:159], v[16:31]
	s_waitcnt lgkmcnt(0)
	v_mfma_f32_32x32x16_bf16 v[32:47], v[164:167], v[152:155], v[32:47]
	ds_read_b128 v[152:155], v102 offset:18464
	ds_read_b128 v[160:163], v102 offset:23072
	ds_read_b128 v[168:171], v101 offset:32
	ds_read_b128 v[172:175], v101 offset:4640
	v_mfma_f32_32x32x16_bf16 v[0:15], v[164:167], v[156:159], v[0:15]
	s_waitcnt lgkmcnt(1)
	v_mfma_f32_32x32x16_bf16 v[48:63], v[168:171], v[152:155], v[48:63]
	v_mfma_f32_32x32x16_bf16 v[16:31], v[168:171], v[160:163], v[16:31]
	s_waitcnt lgkmcnt(0)
	v_mfma_f32_32x32x16_bf16 v[32:47], v[172:175], v[152:155], v[32:47]
	ds_read_b128 v[152:155], v102 offset:18496
	ds_read_b128 v[156:159], v102 offset:23104
	ds_read_b128 v[164:167], v101 offset:64
	ds_read_b128 v[168:171], v101 offset:4672
	s_waitcnt vmcnt(15)
	ds_write_b128 v100, v[104:107] offset:36864
	s_waitcnt vmcnt(13)
	ds_write_b128 v100, v[112:115] offset:41472
	s_waitcnt vmcnt(11)
	ds_write_b128 v100, v[120:123] offset:46080
	s_waitcnt vmcnt(9)
	ds_write_b128 v100, v[128:131] offset:50688
	v_mfma_f32_32x32x16_bf16 v[0:15], v[172:175], v[160:163], v[0:15]
	ds_read_b128 v[104:107], v102 offset:18528
	ds_read_b128 v[112:115], v102 offset:23136
	ds_read_b128 v[120:123], v101 offset:96
	ds_read_b128 v[128:131], v101 offset:4704
	s_waitcnt lgkmcnt(9)
	v_mfma_f32_32x32x16_bf16 v[48:63], v[164:167], v[152:155], v[48:63]
	ds_write_b128 v100, v[108:111] offset:55296
	ds_write_b128 v100, v[116:119] offset:59904
	ds_write_b128 v100, v[124:127] offset:64512
	s_waitcnt vmcnt(8)
	ds_write_b128 v103, v[132:135] offset:13824
	v_mfma_f32_32x32x16_bf16 v[16:31], v[164:167], v[156:159], v[16:31]
	s_waitcnt lgkmcnt(12)
	v_mfma_f32_32x32x16_bf16 v[32:47], v[168:171], v[152:155], v[32:47]
	v_mfma_f32_32x32x16_bf16 v[0:15], v[168:171], v[156:159], v[0:15]
	s_waitcnt lgkmcnt(0)
	s_barrier
; template <bool SWAP>
; DI void gemm_tile(const bf16_t* __restrict__ A, int lda, const bf16_t* __restrict__ Bt, int ldb, int K, f32x16 (&acc)[2][2], bf16_t* As, bf16_t* Bs_unused) {
;     ...
;   auto step = [&](int buf, u32x4 (&ra)[4], u32x4 (&rb)[4], bool do_write, bool do_load, int tload) __attribute__((always_inline)) {
;     const bf16_t* pa = As + buf * 2 * GT_IMG + pao; const bf16_t* pb = As + buf * 2 * GT_IMG + pbo;
;     bf16_t* Ad = As + (buf ^ 1) * 2 * GT_IMG; bf16_t* Bd = Ad + GT_IMG;
;     bf16x8 F0[4], F1[4];
;     frag_read(F0, pa, pb, 0);
;     __builtin_amdgcn_sched_barrier(0);
;     frag_read(F1, pa, pb, 16);
;     mfma4(F0);
;     __builtin_amdgcn_sched_barrier(0);
;     frag_read(F0, pa, pb, 32);
;     mfma4(F1);
;     if (do_write) {
; #pragma unroll
;       for (int i = 0; i < 4; ++i) *(u32x4*)(Ad + (lr + 32 * i) * 72 + lc) = ra[i];
;     }
;     __builtin_amdgcn_sched_barrier(0);
;     frag_read(F1, pa, pb, 48);
;     mfma4(F0);
;     if (do_write) {
; #pragma unroll
;       for (int i = 0; i < 4; ++i) *(u32x4*)(Bd + (lr + 32 * i) * 72 + lc) = rb[i];
;     }
;     __builtin_amdgcn_sched_barrier(0);
;     mfma4(F1);
;     if (do_load) load_stage(ra, rb, tload);
;     __builtin_amdgcn_sched_barrier(0);
;   };
;   const int nk = K >> 6;
;   load_stage(ra0, rb0, 0); load_stage(ra1, rb1, 1);
;   __syncthreads();
;   write_stage(ra0, rb0, 0);
;   load_stage(ra0, rb0, 2);
;   __syncthreads();
;   for (int kt = 0; kt < nk; kt += 2) {
;     step(0, ra1, rb1, true, kt + 3 < nk, kt + 3);
;     __syncthreads();
;     step(1, ra0, rb0, kt + 2 < nk, kt + 4 < nk, kt + 4);
;     __syncthreads();
	ds_read_b128 v[152:155], v102 offset:55296
	ds_read_b128 v[156:159], v102 offset:59904
	ds_read_b128 v[160:163], v101 offset:36864
	ds_read_b128 v[164:167], v101 offset:41472
	v_mfma_f32_32x32x16_bf16 v[48:63], v[120:123], v[104:107], v[48:63]
	v_mfma_f32_32x32x16_bf16 v[16:31], v[120:123], v[112:115], v[16:31]
	v_mfma_f32_32x32x16_bf16 v[32:47], v[128:131], v[104:107], v[32:47]
	v_mfma_f32_32x32x16_bf16 v[0:15], v[128:131], v[112:115], v[0:15]
	global_load_dwordx4 v[104:107], v[80:81], off offset:1152
	global_load_dwordx4 v[108:111], v[82:83], off offset:1152
	global_load_dwordx4 v[112:115], v[84:85], off offset:1152
	global_load_dwordx4 v[116:119], v[86:87], off offset:1152
	global_load_dwordx4 v[120:123], v[88:89], off offset:1152
	global_load_dwordx4 v[124:127], v[90:91], off offset:1152
	global_load_dwordx4 v[128:131], v[92:93], off offset:1152
	global_load_dwordx4 v[132:135], v[94:95], off offset:1152
	s_waitcnt lgkmcnt(1)
	v_mfma_f32_32x32x16_bf16 v[48:63], v[160:163], v[152:155], v[48:63]
	v_mfma_f32_32x32x16_bf16 v[16:31], v[160:163], v[156:159], v[16:31]
	s_waitcnt lgkmcnt(0)
	v_mfma_f32_32x32x16_bf16 v[32:47], v[164:167], v[152:155], v[32:47]
	ds_read_b128 v[152:155], v102 offset:55328
	ds_read_b128 v[160:163], v102 offset:59936
	ds_read_b128 v[168:171], v101 offset:36896
	ds_read_b128 v[172:175], v101 offset:41504
	v_mfma_f32_32x32x16_bf16 v[0:15], v[164:167], v[156:159], v[0:15]
	s_waitcnt lgkmcnt(1)
	v_mfma_f32_32x32x16_bf16 v[48:63], v[168:171], v[152:155], v[48:63]
	v_mfma_f32_32x32x16_bf16 v[16:31], v[168:171], v[160:163], v[16:31]
	s_waitcnt lgkmcnt(0)
	v_mfma_f32_32x32x16_bf16 v[32:47], v[172:175], v[152:155], v[32:47]
	ds_read_b128 v[152:155], v102 offset:55360
	ds_read_b128 v[156:159], v102 offset:59968
	ds_read_b128 v[164:167], v101 offset:36928
	ds_read_b128 v[168:171], v101 offset:41536
	s_waitcnt vmcnt(15)
	ds_write_b128 v100, v[64:67]
	s_waitcnt vmcnt(13)
	ds_write_b128 v100, v[72:75] offset:4608
	s_waitcnt vmcnt(11)
	ds_write_b128 v100, v[136:139] offset:9216
	s_waitcnt vmcnt(9)
	ds_write_b128 v100, v[144:147] offset:13824
	v_mfma_f32_32x32x16_bf16 v[0:15], v[172:175], v[160:163], v[0:15]
	ds_read_b128 v[64:67], v102 offset:55392
	ds_read_b128 v[72:75], v102 offset:60000
	ds_read_b128 v[136:139], v101 offset:36960
	ds_read_b128 v[144:147], v101 offset:41568
	s_waitcnt lgkmcnt(9)
	v_mfma_f32_32x32x16_bf16 v[48:63], v[164:167], v[152:155], v[48:63]
	ds_write_b128 v100, v[68:71] offset:18432
	ds_write_b128 v100, v[76:79] offset:23040
	ds_write_b128 v100, v[140:143] offset:27648
	s_waitcnt vmcnt(8)
	ds_write_b128 v100, v[148:151] offset:32256
	v_mfma_f32_32x32x16_bf16 v[16:31], v[164:167], v[156:159], v[16:31]
	s_waitcnt lgkmcnt(12)
	v_mfma_f32_32x32x16_bf16 v[32:47], v[168:171], v[152:155], v[32:47]
	v_mfma_f32_32x32x16_bf16 v[0:15], v[168:171], v[156:159], v[0:15]
	s_waitcnt lgkmcnt(0)
	s_barrier
	ds_read_b128 v[152:155], v102 offset:18432
	ds_read_b128 v[156:159], v102 offset:23040
	ds_read_b128 v[160:163], v101
	ds_read_b128 v[164:167], v101 offset:4608
	v_mfma_f32_32x32x16_bf16 v[48:63], v[136:139], v[64:67], v[48:63]
	v_mfma_f32_32x32x16_bf16 v[16:31], v[136:139], v[72:75], v[16:31]
	v_mfma_f32_32x32x16_bf16 v[32:47], v[144:147], v[64:67], v[32:47]
	v_mfma_f32_32x32x16_bf16 v[0:15], v[144:147], v[72:75], v[0:15]
	global_load_dwordx4 v[64:67], v[80:81], off offset:1280
	global_load_dwordx4 v[68:71], v[82:83], off offset:1280
	global_load_dwordx4 v[72:75], v[84:85], off offset:1280
	global_load_dwordx4 v[76:79], v[86:87], off offset:1280
	global_load_dwordx4 v[136:139], v[88:89], off offset:1280
	global_load_dwordx4 v[140:143], v[90:91], off offset:1280
	global_load_dwordx4 v[144:147], v[92:93], off offset:1280
	global_load_dwordx4 v[148:151], v[94:95], off offset:1280
	s_waitcnt lgkmcnt(1)
	v_mfma_f32_32x32x16_bf16 v[48:63], v[160:163], v[152:155], v[48:63]
	v_mfma_f32_32x32x16_bf16 v[16:31], v[160:163], v[156:159], v[16:31]
	s_waitcnt lgkmcnt(0)
	v_mfma_f32_32x32x16_bf16 v[32:47], v[164:167], v[152:155], v[32:47]
	ds_read_b128 v[152:155], v102 offset:18464
	ds_read_b128 v[160:163], v102 offset:23072
	ds_read_b128 v[168:171], v101 offset:32
	ds_read_b128 v[172:175], v101 offset:4640
	v_mfma_f32_32x32x16_bf16 v[0:15], v[164:167], v[156:159], v[0:15]
	s_waitcnt lgkmcnt(1)
	v_mfma_f32_32x32x16_bf16 v[48:63], v[168:171], v[152:155], v[48:63]
	v_mfma_f32_32x32x16_bf16 v[16:31], v[168:171], v[160:163], v[16:31]
	s_waitcnt lgkmcnt(0)
	v_mfma_f32_32x32x16_bf16 v[32:47], v[172:175], v[152:155], v[32:47]
	ds_read_b128 v[152:155], v102 offset:18496
	ds_read_b128 v[156:159], v102 offset:23104
	ds_read_b128 v[164:167], v101 offset:64
	ds_read_b128 v[168:171], v101 offset:4672
	s_waitcnt vmcnt(15)
	ds_write_b128 v100, v[104:107] offset:36864
	s_waitcnt vmcnt(13)
	ds_write_b128 v100, v[112:115] offset:41472
	s_waitcnt vmcnt(11)
	ds_write_b128 v100, v[120:123] offset:46080
	s_waitcnt vmcnt(9)
	ds_write_b128 v100, v[128:131] offset:50688
	v_mfma_f32_32x32x16_bf16 v[0:15], v[172:175], v[160:163], v[0:15]
	ds_read_b128 v[104:107], v102 offset:18528
	ds_read_b128 v[112:115], v102 offset:23136
	ds_read_b128 v[120:123], v101 offset:96
	ds_read_b128 v[128:131], v101 offset:4704
	s_waitcnt lgkmcnt(9)
	v_mfma_f32_32x32x16_bf16 v[48:63], v[164:167], v[152:155], v[48:63]
	ds_write_b128 v100, v[108:111] offset:55296
	ds_write_b128 v100, v[116:119] offset:59904
	ds_write_b128 v100, v[124:127] offset:64512
	s_waitcnt vmcnt(8)
	ds_write_b128 v103, v[132:135] offset:13824
	v_mfma_f32_32x32x16_bf16 v[16:31], v[164:167], v[156:159], v[16:31]
	s_waitcnt lgkmcnt(12)
	v_mfma_f32_32x32x16_bf16 v[32:47], v[168:171], v[152:155], v[32:47]
	v_mfma_f32_32x32x16_bf16 v[0:15], v[168:171], v[156:159], v[0:15]
	s_waitcnt lgkmcnt(0)
	s_barrier
; template <bool SWAP>
; DI void gemm_tile(const bf16_t* __restrict__ A, int lda, const bf16_t* __restrict__ Bt, int ldb, int K, f32x16 (&acc)[2][2], bf16_t* As, bf16_t* Bs_unused) {
;     ...
;   auto step = [&](int buf, u32x4 (&ra)[4], u32x4 (&rb)[4], bool do_write, bool do_load, int tload) __attribute__((always_inline)) {
;     const bf16_t* pa = As + buf * 2 * GT_IMG + pao; const bf16_t* pb = As + buf * 2 * GT_IMG + pbo;
;     bf16_t* Ad = As + (buf ^ 1) * 2 * GT_IMG; bf16_t* Bd = Ad + GT_IMG;
;     bf16x8 F0[4], F1[4];
;     frag_read(F0, pa, pb, 0);
;     __builtin_amdgcn_sched_barrier(0);
;     frag_read(F1, pa, pb, 16);
;     mfma4(F0);
;     __builtin_amdgcn_sched_barrier(0);
;     frag_read(F0, pa, pb, 32);
;     mfma4(F1);
;     if (do_write) {
; #pragma unroll
;       for (int i = 0; i < 4; ++i) *(u32x4*)(Ad + (lr + 32 * i) * 72 + lc) = ra[i];
;     }
;     __builtin_amdgcn_sched_barrier(0);
;     frag_read(F1, pa, pb, 48);
;     mfma4(F0);
;     if (do_write) {
; #pragma unroll
;       for (int i = 0; i < 4; ++i) *(u32x4*)(Bd + (lr + 32 * i) * 72 + lc) = rb[i];
;     }
;     __builtin_amdgcn_sched_barrier(0);
;     mfma4(F1);
;     if (do_load) load_stage(ra, rb, tload);
;     __builtin_amdgcn_sched_barrier(0);
;   };
;   const int nk = K >> 6;
;   load_stage(ra0, rb0, 0); load_stage(ra1, rb1, 1);
;   __syncthreads();
;   write_stage(ra0, rb0, 0);
;   load_stage(ra0, rb0, 2);
;   __syncthreads();
;   for (int kt = 0; kt < nk; kt += 2) {
;     step(0, ra1, rb1, true, kt + 3 < nk, kt + 3);
;     __syncthreads();
;     step(1, ra0, rb0, kt + 2 < nk, kt + 4 < nk, kt + 4);
;     __syncthreads();
	ds_read_b128 v[152:155], v102 offset:55296
	ds_read_b128 v[156:159], v102 offset:59904
	ds_read_b128 v[160:163], v101 offset:36864
	ds_read_b128 v[164:167], v101 offset:41472
	v_mfma_f32_32x32x16_bf16 v[48:63], v[120:123], v[104:107], v[48:63]
	v_mfma_f32_32x32x16_bf16 v[16:31], v[120:123], v[112:115], v[16:31]
	v_mfma_f32_32x32x16_bf16 v[32:47], v[128:131], v[104:107], v[32:47]
	v_mfma_f32_32x32x16_bf16 v[0:15], v[128:131], v[112:115], v[0:15]
	global_load_dwordx4 v[104:107], v[80:81], off offset:1408
	global_load_dwordx4 v[108:111], v[82:83], off offset:1408
	global_load_dwordx4 v[112:115], v[84:85], off offset:1408
	global_load_dwordx4 v[116:119], v[86:87], off offset:1408
	global_load_dwordx4 v[120:123], v[88:89], off offset:1408
	global_load_dwordx4 v[124:127], v[90:91], off offset:1408
	global_load_dwordx4 v[128:131], v[92:93], off offset:1408
	global_load_dwordx4 v[132:135], v[94:95], off offset:1408
	s_waitcnt lgkmcnt(1)
	v_mfma_f32_32x32x16_bf16 v[48:63], v[160:163], v[152:155], v[48:63]
	v_mfma_f32_32x32x16_bf16 v[16:31], v[160:163], v[156:159], v[16:31]
	s_waitcnt lgkmcnt(0)
	v_mfma_f32_32x32x16_bf16 v[32:47], v[164:167], v[152:155], v[32:47]
	ds_read_b128 v[152:155], v102 offset:55328
	ds_read_b128 v[160:163], v102 offset:59936
	ds_read_b128 v[168:171], v101 offset:36896
	ds_read_b128 v[172:175], v101 offset:41504
	v_mfma_f32_32x32x16_bf16 v[0:15], v[164:167], v[156:159], v[0:15]
	s_waitcnt lgkmcnt(1)
	v_mfma_f32_32x32x16_bf16 v[48:63], v[168:171], v[152:155], v[48:63]
	v_mfma_f32_32x32x16_bf16 v[16:31], v[168:171], v[160:163], v[16:31]
	s_waitcnt lgkmcnt(0)
	v_mfma_f32_32x32x16_bf16 v[32:47], v[172:175], v[152:155], v[32:47]
	ds_read_b128 v[152:155], v102 offset:55360
	ds_read_b128 v[156:159], v102 offset:59968
	ds_read_b128 v[164:167], v101 offset:36928
	ds_read_b128 v[168:171], v101 offset:41536
	s_waitcnt vmcnt(15)
	ds_write_b128 v100, v[64:67]
	s_waitcnt vmcnt(13)
	ds_write_b128 v100, v[72:75] offset:4608
	s_waitcnt vmcnt(11)
	ds_write_b128 v100, v[136:139] offset:9216
	s_waitcnt vmcnt(9)
	ds_write_b128 v100, v[144:147] offset:13824
	v_mfma_f32_32x32x16_bf16 v[0:15], v[172:175], v[160:163], v[0:15]
	ds_read_b128 v[64:67], v102 offset:55392
	ds_read_b128 v[72:75], v102 offset:60000
	ds_read_b128 v[136:139], v101 offset:36960
	ds_read_b128 v[144:147], v101 offset:41568
	s_waitcnt lgkmcnt(9)
	v_mfma_f32_32x32x16_bf16 v[48:63], v[164:167], v[152:155], v[48:63]
	ds_write_b128 v100, v[68:71] offset:18432
	ds_write_b128 v100, v[76:79] offset:23040
	ds_write_b128 v100, v[140:143] offset:27648
	s_waitcnt vmcnt(8)
	ds_write_b128 v100, v[148:151] offset:32256
	v_mfma_f32_32x32x16_bf16 v[16:31], v[164:167], v[156:159], v[16:31]
	s_waitcnt lgkmcnt(12)
	v_mfma_f32_32x32x16_bf16 v[32:47], v[168:171], v[152:155], v[32:47]
	v_mfma_f32_32x32x16_bf16 v[0:15], v[168:171], v[156:159], v[0:15]
	s_waitcnt lgkmcnt(0)
	s_barrier
	ds_read_b128 v[152:155], v102 offset:18432
	ds_read_b128 v[156:159], v102 offset:23040
	ds_read_b128 v[160:163], v101
	ds_read_b128 v[164:167], v101 offset:4608
	v_mfma_f32_32x32x16_bf16 v[48:63], v[136:139], v[64:67], v[48:63]
	v_mfma_f32_32x32x16_bf16 v[16:31], v[136:139], v[72:75], v[16:31]
	v_mfma_f32_32x32x16_bf16 v[32:47], v[144:147], v[64:67], v[32:47]
	v_mfma_f32_32x32x16_bf16 v[0:15], v[144:147], v[72:75], v[0:15]
	global_load_dwordx4 v[64:67], v[80:81], off offset:1536
	global_load_dwordx4 v[68:71], v[82:83], off offset:1536
	global_load_dwordx4 v[72:75], v[84:85], off offset:1536
	global_load_dwordx4 v[76:79], v[86:87], off offset:1536
	global_load_dwordx4 v[136:139], v[88:89], off offset:1536
	global_load_dwordx4 v[140:143], v[90:91], off offset:1536
	global_load_dwordx4 v[144:147], v[92:93], off offset:1536
	global_load_dwordx4 v[148:151], v[94:95], off offset:1536
	s_waitcnt lgkmcnt(1)
	v_mfma_f32_32x32x16_bf16 v[48:63], v[160:163], v[152:155], v[48:63]
	v_mfma_f32_32x32x16_bf16 v[16:31], v[160:163], v[156:159], v[16:31]
	s_waitcnt lgkmcnt(0)
	v_mfma_f32_32x32x16_bf16 v[32:47], v[164:167], v[152:155], v[32:47]
	ds_read_b128 v[152:155], v102 offset:18464
	ds_read_b128 v[160:163], v102 offset:23072
	ds_read_b128 v[168:171], v101 offset:32
	ds_read_b128 v[172:175], v101 offset:4640
	v_mfma_f32_32x32x16_bf16 v[0:15], v[164:167], v[156:159], v[0:15]
	s_waitcnt lgkmcnt(1)
	v_mfma_f32_32x32x16_bf16 v[48:63], v[168:171], v[152:155], v[48:63]
	v_mfma_f32_32x32x16_bf16 v[16:31], v[168:171], v[160:163], v[16:31]
	s_waitcnt lgkmcnt(0)
	v_mfma_f32_32x32x16_bf16 v[32:47], v[172:175], v[152:155], v[32:47]
	ds_read_b128 v[152:155], v102 offset:18496
	ds_read_b128 v[156:159], v102 offset:23104
	ds_read_b128 v[164:167], v101 offset:64
	ds_read_b128 v[168:171], v101 offset:4672
	s_waitcnt vmcnt(15)
	ds_write_b128 v100, v[104:107] offset:36864
	s_waitcnt vmcnt(13)
	ds_write_b128 v100, v[112:115] offset:41472
	s_waitcnt vmcnt(11)
	ds_write_b128 v100, v[120:123] offset:46080
	s_waitcnt vmcnt(9)
	ds_write_b128 v100, v[128:131] offset:50688
	v_mfma_f32_32x32x16_bf16 v[0:15], v[172:175], v[160:163], v[0:15]
	ds_read_b128 v[104:107], v102 offset:18528
	ds_read_b128 v[112:115], v102 offset:23136
	ds_read_b128 v[120:123], v101 offset:96
	ds_read_b128 v[128:131], v101 offset:4704
	s_waitcnt lgkmcnt(9)
	v_mfma_f32_32x32x16_bf16 v[48:63], v[164:167], v[152:155], v[48:63]
	ds_write_b128 v100, v[108:111] offset:55296
	ds_write_b128 v100, v[116:119] offset:59904
	ds_write_b128 v100, v[124:127] offset:64512
	s_waitcnt vmcnt(8)
	ds_write_b128 v103, v[132:135] offset:13824
	v_mfma_f32_32x32x16_bf16 v[16:31], v[164:167], v[156:159], v[16:31]
	s_waitcnt lgkmcnt(12)
	v_mfma_f32_32x32x16_bf16 v[32:47], v[168:171], v[152:155], v[32:47]
	v_mfma_f32_32x32x16_bf16 v[0:15], v[168:171], v[156:159], v[0:15]
	s_waitcnt lgkmcnt(0)
	s_barrier
; template <bool SWAP>
; DI void gemm_tile(const bf16_t* __restrict__ A, int lda, const bf16_t* __restrict__ Bt, int ldb, int K, f32x16 (&acc)[2][2], bf16_t* As, bf16_t* Bs_unused) {
;     ...
;   auto step = [&](int buf, u32x4 (&ra)[4], u32x4 (&rb)[4], bool do_write, bool do_load, int tload) __attribute__((always_inline)) {
;     const bf16_t* pa = As + buf * 2 * GT_IMG + pao; const bf16_t* pb = As + buf * 2 * GT_IMG + pbo;
;     bf16_t* Ad = As + (buf ^ 1) * 2 * GT_IMG; bf16_t* Bd = Ad + GT_IMG;
;     bf16x8 F0[4], F1[4];
;     frag_read(F0, pa, pb, 0);
;     __builtin_amdgcn_sched_barrier(0);
;     frag_read(F1, pa, pb, 16);
;     mfma4(F0);
;     __builtin_amdgcn_sched_barrier(0);
;     frag_read(F0, pa, pb, 32);
;     mfma4(F1);
;     if (do_write) {
; #pragma unroll
;       for (int i = 0; i < 4; ++i) *(u32x4*)(Ad + (lr + 32 * i) * 72 + lc) = ra[i];
;     }
;     __builtin_amdgcn_sched_barrier(0);
;     frag_read(F1, pa, pb, 48);
;     mfma4(F0);
;     if (do_write) {
; #pragma unroll
;       for (int i = 0; i < 4; ++i) *(u32x4*)(Bd + (lr + 32 * i) * 72 + lc) = rb[i];
;     }
;     __builtin_amdgcn_sched_barrier(0);
;     mfma4(F1);
;     if (do_load) load_stage(ra, rb, tload);
;     __builtin_amdgcn_sched_barrier(0);
;   };
;   const int nk = K >> 6;
;   load_stage(ra0, rb0, 0); load_stage(ra1, rb1, 1);
;   __syncthreads();
;   write_stage(ra0, rb0, 0);
;   load_stage(ra0, rb0, 2);
;   __syncthreads();
;   for (int kt = 0; kt < nk; kt += 2) {
;     step(0, ra1, rb1, true, kt + 3 < nk, kt + 3);
;     __syncthreads();
;     step(1, ra0, rb0, kt + 2 < nk, kt + 4 < nk, kt + 4);
;     __syncthreads();
	ds_read_b128 v[152:155], v102 offset:55296
	ds_read_b128 v[156:159], v102 offset:59904
	ds_read_b128 v[160:163], v101 offset:36864
	ds_read_b128 v[164:167], v101 offset:41472
	v_mfma_f32_32x32x16_bf16 v[48:63], v[120:123], v[104:107], v[48:63]
	v_mfma_f32_32x32x16_bf16 v[16:31], v[120:123], v[112:115], v[16:31]
	v_mfma_f32_32x32x16_bf16 v[32:47], v[128:131], v[104:107], v[32:47]
	v_mfma_f32_32x32x16_bf16 v[0:15], v[128:131], v[112:115], v[0:15]
	global_load_dwordx4 v[104:107], v[80:81], off offset:1664
	global_load_dwordx4 v[108:111], v[82:83], off offset:1664
	global_load_dwordx4 v[112:115], v[84:85], off offset:1664
	global_load_dwordx4 v[116:119], v[86:87], off offset:1664
	global_load_dwordx4 v[120:123], v[88:89], off offset:1664
	global_load_dwordx4 v[124:127], v[90:91], off offset:1664
	global_load_dwordx4 v[128:131], v[92:93], off offset:1664
	global_load_dwordx4 v[132:135], v[94:95], off offset:1664
	s_waitcnt lgkmcnt(1)
	v_mfma_f32_32x32x16_bf16 v[48:63], v[160:163], v[152:155], v[48:63]
	v_mfma_f32_32x32x16_bf16 v[16:31], v[160:163], v[156:159], v[16:31]
	s_waitcnt lgkmcnt(0)
	v_mfma_f32_32x32x16_bf16 v[32:47], v[164:167], v[152:155], v[32:47]
	ds_read_b128 v[152:155], v102 offset:55328
	ds_read_b128 v[160:163], v102 offset:59936
	ds_read_b128 v[168:171], v101 offset:36896
	ds_read_b128 v[172:175], v101 offset:41504
	v_mfma_f32_32x32x16_bf16 v[0:15], v[164:167], v[156:159], v[0:15]
	s_waitcnt lgkmcnt(1)
	v_mfma_f32_32x32x16_bf16 v[48:63], v[168:171], v[152:155], v[48:63]
	v_mfma_f32_32x32x16_bf16 v[16:31], v[168:171], v[160:163], v[16:31]
	s_waitcnt lgkmcnt(0)
	v_mfma_f32_32x32x16_bf16 v[32:47], v[172:175], v[152:155], v[32:47]
	ds_read_b128 v[152:155], v102 offset:55360
	ds_read_b128 v[156:159], v102 offset:59968
	ds_read_b128 v[164:167], v101 offset:36928
	ds_read_b128 v[168:171], v101 offset:41536
	s_waitcnt vmcnt(15)
	ds_write_b128 v100, v[64:67]
	s_waitcnt vmcnt(13)
	ds_write_b128 v100, v[72:75] offset:4608
	s_waitcnt vmcnt(11)
	ds_write_b128 v100, v[136:139] offset:9216
	s_waitcnt vmcnt(9)
	ds_write_b128 v100, v[144:147] offset:13824
	v_mfma_f32_32x32x16_bf16 v[0:15], v[172:175], v[160:163], v[0:15]
	ds_read_b128 v[64:67], v102 offset:55392
	ds_read_b128 v[72:75], v102 offset:60000
	ds_read_b128 v[136:139], v101 offset:36960
	ds_read_b128 v[144:147], v101 offset:41568
	s_waitcnt lgkmcnt(9)
	v_mfma_f32_32x32x16_bf16 v[48:63], v[164:167], v[152:155], v[48:63]
	ds_write_b128 v100, v[68:71] offset:18432
	ds_write_b128 v100, v[76:79] offset:23040
	ds_write_b128 v100, v[140:143] offset:27648
	s_waitcnt vmcnt(8)
	ds_write_b128 v100, v[148:151] offset:32256
	v_mfma_f32_32x32x16_bf16 v[16:31], v[164:167], v[156:159], v[16:31]
	s_waitcnt lgkmcnt(12)
	v_mfma_f32_32x32x16_bf16 v[32:47], v[168:171], v[152:155], v[32:47]
	v_mfma_f32_32x32x16_bf16 v[0:15], v[168:171], v[156:159], v[0:15]
	s_waitcnt lgkmcnt(0)
	s_barrier
	ds_read_b128 v[152:155], v102 offset:18432
	ds_read_b128 v[156:159], v102 offset:23040
	ds_read_b128 v[160:163], v101
	ds_read_b128 v[164:167], v101 offset:4608
	v_mfma_f32_32x32x16_bf16 v[48:63], v[136:139], v[64:67], v[48:63]
	v_mfma_f32_32x32x16_bf16 v[16:31], v[136:139], v[72:75], v[16:31]
	v_mfma_f32_32x32x16_bf16 v[32:47], v[144:147], v[64:67], v[32:47]
	v_mfma_f32_32x32x16_bf16 v[0:15], v[144:147], v[72:75], v[0:15]
	global_load_dwordx4 v[64:67], v[80:81], off offset:1792
	global_load_dwordx4 v[68:71], v[82:83], off offset:1792
	global_load_dwordx4 v[72:75], v[84:85], off offset:1792
	global_load_dwordx4 v[76:79], v[86:87], off offset:1792
	global_load_dwordx4 v[136:139], v[88:89], off offset:1792
	global_load_dwordx4 v[140:143], v[90:91], off offset:1792
	global_load_dwordx4 v[144:147], v[92:93], off offset:1792
	global_load_dwordx4 v[148:151], v[94:95], off offset:1792
	s_waitcnt lgkmcnt(1)
	v_mfma_f32_32x32x16_bf16 v[48:63], v[160:163], v[152:155], v[48:63]
	v_mfma_f32_32x32x16_bf16 v[16:31], v[160:163], v[156:159], v[16:31]
	s_waitcnt lgkmcnt(0)
	v_mfma_f32_32x32x16_bf16 v[32:47], v[164:167], v[152:155], v[32:47]
	ds_read_b128 v[152:155], v102 offset:18464
	ds_read_b128 v[160:163], v102 offset:23072
	ds_read_b128 v[168:171], v101 offset:32
	ds_read_b128 v[172:175], v101 offset:4640
	v_mfma_f32_32x32x16_bf16 v[0:15], v[164:167], v[156:159], v[0:15]
	s_waitcnt lgkmcnt(1)
	v_mfma_f32_32x32x16_bf16 v[48:63], v[168:171], v[152:155], v[48:63]
	v_mfma_f32_32x32x16_bf16 v[16:31], v[168:171], v[160:163], v[16:31]
	s_waitcnt lgkmcnt(0)
	v_mfma_f32_32x32x16_bf16 v[32:47], v[172:175], v[152:155], v[32:47]
	ds_read_b128 v[152:155], v102 offset:18496
	ds_read_b128 v[156:159], v102 offset:23104
	ds_read_b128 v[164:167], v101 offset:64
	ds_read_b128 v[168:171], v101 offset:4672
	s_waitcnt vmcnt(15)
	ds_write_b128 v100, v[104:107] offset:36864
	s_waitcnt vmcnt(13)
	ds_write_b128 v100, v[112:115] offset:41472
	s_waitcnt vmcnt(11)
	ds_write_b128 v100, v[120:123] offset:46080
	s_waitcnt vmcnt(9)
	ds_write_b128 v100, v[128:131] offset:50688
	v_mfma_f32_32x32x16_bf16 v[0:15], v[172:175], v[160:163], v[0:15]
	ds_read_b128 v[104:107], v102 offset:18528
	ds_read_b128 v[112:115], v102 offset:23136
	ds_read_b128 v[120:123], v101 offset:96
	ds_read_b128 v[128:131], v101 offset:4704
	s_waitcnt lgkmcnt(9)
	v_mfma_f32_32x32x16_bf16 v[48:63], v[164:167], v[152:155], v[48:63]
	ds_write_b128 v100, v[108:111] offset:55296
	ds_write_b128 v100, v[116:119] offset:59904
	ds_write_b128 v100, v[124:127] offset:64512
	s_waitcnt vmcnt(8)
	ds_write_b128 v103, v[132:135] offset:13824
	v_mfma_f32_32x32x16_bf16 v[16:31], v[164:167], v[156:159], v[16:31]
	s_waitcnt lgkmcnt(12)
	v_mfma_f32_32x32x16_bf16 v[32:47], v[168:171], v[152:155], v[32:47]
	v_mfma_f32_32x32x16_bf16 v[0:15], v[168:171], v[156:159], v[0:15]
	s_waitcnt lgkmcnt(0)
	s_barrier
; template <bool SWAP>
; DI void gemm_tile(const bf16_t* __restrict__ A, int lda, const bf16_t* __restrict__ Bt, int ldb, int K, f32x16 (&acc)[2][2], bf16_t* As, bf16_t* Bs_unused) {
;     ...
;   auto step = [&](int buf, u32x4 (&ra)[4], u32x4 (&rb)[4], bool do_write, bool do_load, int tload) __attribute__((always_inline)) {
;     const bf16_t* pa = As + buf * 2 * GT_IMG + pao; const bf16_t* pb = As + buf * 2 * GT_IMG + pbo;
;     bf16_t* Ad = As + (buf ^ 1) * 2 * GT_IMG; bf16_t* Bd = Ad + GT_IMG;
;     bf16x8 F0[4], F1[4];
;     frag_read(F0, pa, pb, 0);
;     __builtin_amdgcn_sched_barrier(0);
;     frag_read(F1, pa, pb, 16);
;     mfma4(F0);
;     __builtin_amdgcn_sched_barrier(0);
;     frag_read(F0, pa, pb, 32);
;     mfma4(F1);
;     if (do_write) {
; #pragma unroll
;       for (int i = 0; i < 4; ++i) *(u32x4*)(Ad + (lr + 32 * i) * 72 + lc) = ra[i];
;     }
;     __builtin_amdgcn_sched_barrier(0);
;     frag_read(F1, pa, pb, 48);
;     mfma4(F0);
;     if (do_write) {
; #pragma unroll
;       for (int i = 0; i < 4; ++i) *(u32x4*)(Bd + (lr + 32 * i) * 72 + lc) = rb[i];
;     }
;     __builtin_amdgcn_sched_barrier(0);
;     mfma4(F1);
;     if (do_load) load_stage(ra, rb, tload);
;     __builtin_amdgcn_sched_barrier(0);
;   };
;   const int nk = K >> 6;
;   load_stage(ra0, rb0, 0); load_stage(ra1, rb1, 1);
;   __syncthreads();
;   write_stage(ra0, rb0, 0);
;   load_stage(ra0, rb0, 2);
;   __syncthreads();
;   for (int kt = 0; kt < nk; kt += 2) {
;     step(0, ra1, rb1, true, kt + 3 < nk, kt + 3);
;     __syncthreads();
;     step(1, ra0, rb0, kt + 2 < nk, kt + 4 < nk, kt + 4);
;     __syncthreads();
	ds_read_b128 v[180:183], v102 offset:55296
	ds_read_b128 v[184:187], v102 offset:59904
	ds_read_b128 v[188:191], v101 offset:36864
	ds_read_b128 v[220:223], v101 offset:41472
	v_mfma_f32_32x32x16_bf16 v[48:63], v[120:123], v[104:107], v[48:63]
	v_mfma_f32_32x32x16_bf16 v[16:31], v[120:123], v[112:115], v[16:31]
	v_mfma_f32_32x32x16_bf16 v[32:47], v[128:131], v[104:107], v[32:47]
	v_mfma_f32_32x32x16_bf16 v[0:15], v[128:131], v[112:115], v[0:15]
	global_load_dwordx4 v[104:107], v[80:81], off offset:1920
	s_nop 0
	global_load_dwordx4 v[80:83], v[82:83], off offset:1920
	s_nop 0
	global_load_dwordx4 v[108:111], v[84:85], off offset:1920
	s_nop 0
	global_load_dwordx4 v[84:87], v[86:87], off offset:1920
	s_nop 0
	global_load_dwordx4 v[112:115], v[88:89], off offset:1920
	s_nop 0
	global_load_dwordx4 v[88:91], v[90:91], off offset:1920
	s_nop 0
	global_load_dwordx4 v[116:119], v[92:93], off offset:1920
	s_nop 0
	global_load_dwordx4 v[92:95], v[94:95], off offset:1920
	s_waitcnt lgkmcnt(1)
	v_mfma_f32_32x32x16_bf16 v[48:63], v[188:191], v[180:183], v[48:63]
	v_mfma_f32_32x32x16_bf16 v[16:31], v[188:191], v[184:187], v[16:31]
	s_waitcnt lgkmcnt(0)
	v_mfma_f32_32x32x16_bf16 v[32:47], v[220:223], v[180:183], v[32:47]
	ds_read_b128 v[120:123], v102 offset:55328
	ds_read_b128 v[128:131], v102 offset:59936
	ds_read_b128 v[152:155], v101 offset:36896
	ds_read_b128 v[156:159], v101 offset:41504
	v_mfma_f32_32x32x16_bf16 v[0:15], v[220:223], v[184:187], v[0:15]
	s_waitcnt lgkmcnt(1)
	v_mfma_f32_32x32x16_bf16 v[48:63], v[152:155], v[120:123], v[48:63]
	v_mfma_f32_32x32x16_bf16 v[16:31], v[152:155], v[128:131], v[16:31]
	s_waitcnt lgkmcnt(0)
	v_mfma_f32_32x32x16_bf16 v[32:47], v[156:159], v[120:123], v[32:47]
	ds_read_b128 v[120:123], v102 offset:55360
	ds_read_b128 v[124:127], v102 offset:59968
	ds_read_b128 v[132:135], v101 offset:36928
	ds_read_b128 v[152:155], v101 offset:41536
	s_waitcnt vmcnt(15)
	ds_write_b128 v100, v[64:67]
	s_waitcnt vmcnt(13)
	ds_write_b128 v100, v[72:75] offset:4608
	s_waitcnt vmcnt(11)
	ds_write_b128 v100, v[136:139] offset:9216
	s_waitcnt vmcnt(9)
	ds_write_b128 v100, v[144:147] offset:13824
	v_mfma_f32_32x32x16_bf16 v[0:15], v[156:159], v[128:131], v[0:15]
	s_waitcnt lgkmcnt(5)
	v_mfma_f32_32x32x16_bf16 v[48:63], v[132:135], v[120:123], v[48:63]
	s_waitcnt lgkmcnt(4)
	v_mfma_f32_32x32x16_bf16 v[32:47], v[152:155], v[120:123], v[32:47]
	ds_read_b128 v[64:67], v102 offset:55392
	ds_read_b128 v[72:75], v102 offset:60000
	ds_read_b128 v[120:123], v101 offset:36960
	ds_read_b128 v[128:131], v101 offset:41568
	ds_write_b128 v100, v[68:71] offset:18432
	ds_write_b128 v100, v[76:79] offset:23040
	ds_write_b128 v100, v[140:143] offset:27648
	s_waitcnt vmcnt(8)
	ds_write_b128 v100, v[148:151] offset:32256
	v_mfma_f32_32x32x16_bf16 v[16:31], v[132:135], v[124:127], v[16:31]
	v_mfma_f32_32x32x16_bf16 v[0:15], v[152:155], v[124:127], v[0:15]
	s_waitcnt lgkmcnt(0)
	s_barrier
	ds_read_b128 v[180:183], v102 offset:18432
	ds_read_b128 v[184:187], v102 offset:23040
	ds_read_b128 v[188:191], v101
	ds_read_b128 v[220:223], v101 offset:4608
	v_mfma_f32_32x32x16_bf16 v[48:63], v[120:123], v[64:67], v[48:63]
	v_mfma_f32_32x32x16_bf16 v[16:31], v[120:123], v[72:75], v[16:31]
	v_mfma_f32_32x32x16_bf16 v[32:47], v[128:131], v[64:67], v[32:47]
	v_mfma_f32_32x32x16_bf16 v[0:15], v[128:131], v[72:75], v[0:15]
	s_waitcnt lgkmcnt(1)
	v_mfma_f32_32x32x16_bf16 v[48:63], v[188:191], v[180:183], v[48:63]
	v_mfma_f32_32x32x16_bf16 v[16:31], v[188:191], v[184:187], v[16:31]
	s_waitcnt lgkmcnt(0)
	v_mfma_f32_32x32x16_bf16 v[32:47], v[220:223], v[180:183], v[32:47]
	ds_read_b128 v[64:67], v102 offset:18464
	ds_read_b128 v[72:75], v102 offset:23072
	ds_read_b128 v[120:123], v101 offset:32
	ds_read_b128 v[124:127], v101 offset:4640
	v_mfma_f32_32x32x16_bf16 v[0:15], v[220:223], v[184:187], v[0:15]
	s_waitcnt lgkmcnt(1)
	v_mfma_f32_32x32x16_bf16 v[48:63], v[120:123], v[64:67], v[48:63]
	v_mfma_f32_32x32x16_bf16 v[16:31], v[120:123], v[72:75], v[16:31]
	s_waitcnt lgkmcnt(0)
	v_mfma_f32_32x32x16_bf16 v[32:47], v[124:127], v[64:67], v[32:47]
	ds_read_b128 v[64:67], v102 offset:18496
	ds_read_b128 v[68:71], v102 offset:23104
	ds_read_b128 v[76:79], v101 offset:64
	ds_read_b128 v[120:123], v101 offset:4672
	s_waitcnt vmcnt(7)
	ds_write_b128 v100, v[104:107] offset:36864
	s_waitcnt vmcnt(5)
	ds_write_b128 v100, v[108:111] offset:41472
	s_waitcnt vmcnt(3)
	ds_write_b128 v100, v[112:115] offset:46080
	s_waitcnt vmcnt(1)
	ds_write_b128 v100, v[116:119] offset:50688
	v_mfma_f32_32x32x16_bf16 v[0:15], v[124:127], v[72:75], v[0:15]
	s_waitcnt lgkmcnt(5)
	v_mfma_f32_32x32x16_bf16 v[48:63], v[76:79], v[64:67], v[48:63]
	v_mfma_f32_32x32x16_bf16 v[16:31], v[76:79], v[68:71], v[16:31]
	s_waitcnt lgkmcnt(4)
	v_mfma_f32_32x32x16_bf16 v[32:47], v[120:123], v[64:67], v[32:47]
	ds_read_b128 v[64:67], v102 offset:18528
	ds_read_b128 v[72:75], v102 offset:23136
	ds_read_b128 v[76:79], v101 offset:96
	ds_read_b128 v[104:107], v101 offset:4704
	ds_write_b128 v100, v[80:83] offset:55296
	ds_write_b128 v100, v[84:87] offset:59904
	ds_write_b128 v100, v[88:91] offset:64512
	s_waitcnt vmcnt(0)
	ds_write_b128 v103, v[92:95] offset:13824
	v_mfma_f32_32x32x16_bf16 v[0:15], v[120:123], v[68:71], v[0:15]
	s_waitcnt lgkmcnt(0)
	s_barrier
; #define OPAQUE(x) asm volatile("" : "+v"(x))
; DI int crow(int r, int h) { return (r & 3) + 8 * (r >> 2) + 4 * h; }
; template <bool SWAP>
; DI void gemm_tile(const bf16_t* __restrict__ A, int lda, const bf16_t* __restrict__ Bt, int ldb, int K, f32x16 (&acc)[2][2], bf16_t* As, bf16_t* Bs_unused) {
;     ...
;   auto step = [&](int buf, u32x4 (&ra)[4], u32x4 (&rb)[4], bool do_write, bool do_load, int tload) __attribute__((always_inline)) {
;     const bf16_t* pa = As + buf * 2 * GT_IMG + pao; const bf16_t* pb = As + buf * 2 * GT_IMG + pbo;
;     bf16_t* Ad = As + (buf ^ 1) * 2 * GT_IMG; bf16_t* Bd = Ad + GT_IMG;
;     bf16x8 F0[4], F1[4];
;     frag_read(F0, pa, pb, 0);
;     __builtin_amdgcn_sched_barrier(0);
;     frag_read(F1, pa, pb, 16);
;     mfma4(F0);
;     __builtin_amdgcn_sched_barrier(0);
;     frag_read(F0, pa, pb, 32);
;     mfma4(F1);
;     if (do_write) {
; #pragma unroll
;       for (int i = 0; i < 4; ++i) *(u32x4*)(Ad + (lr + 32 * i) * 72 + lc) = ra[i];
;     }
;     __builtin_amdgcn_sched_barrier(0);
;     frag_read(F1, pa, pb, 48);
;     mfma4(F0);
;     if (do_write) {
; #pragma unroll
;       for (int i = 0; i < 4; ++i) *(u32x4*)(Bd + (lr + 32 * i) * 72 + lc) = rb[i];
;     }
;     __builtin_amdgcn_sched_barrier(0);
;     mfma4(F1);
;     if (do_load) load_stage(ra, rb, tload);
;     __builtin_amdgcn_sched_barrier(0);
;   };
; DI void phase_outproj(const Params& p, int g, char* smem, int bid, int nb) {
;     ...
;     int wm = wm_, wn = wn_, h = h_, l31 = l31_; OPAQUE(wm); OPAQUE(wn); OPAQUE(h); OPAQUE(l31);
;     const int b = row_batch(gi, mt * 128);
;     const float* xt = gi.x + (size_t)mt * 128 * 1024; float* ot = gi.out + (size_t)mt * 128 * 1024;
; #pragma unroll
;     for (int ni = 0; ni < 2; ++ni) {
;       const int col = nt * 128 + wn * 64 + ni * 32 + l31;
;       const float gt = mod[b * 6144 + 2048 + col];
; #pragma unroll
;       for (int mi = 0; mi < 2; ++mi) {
;         float xv[16];
; #pragma unroll
;         for (int r = 0; r < 16; ++r) xv[r] = __builtin_nontemporal_load(&xt[(wm * 64 + mi * 32 + crow(r, h)) * 1024 + col]);
; #pragma unroll
;         for (int r = 0; r < 16; ++r) ot[(wm * 64 + mi * 32 + crow(r, h)) * 1024 + col] = xv[r] + gt * acc[mi][ni][r];
	ds_read_b128 v[180:183], v102 offset:55296
	ds_read_b128 v[184:187], v102 offset:59904
	ds_read_b128 v[188:191], v101 offset:36864
	ds_read_b128 v[220:223], v101 offset:41472
	v_mfma_f32_32x32x16_bf16 v[48:63], v[76:79], v[64:67], v[48:63]
	v_mfma_f32_32x32x16_bf16 v[16:31], v[76:79], v[72:75], v[16:31]
	v_mfma_f32_32x32x16_bf16 v[32:47], v[104:107], v[64:67], v[32:47]
	v_mfma_f32_32x32x16_bf16 v[0:15], v[104:107], v[72:75], v[0:15]
	s_waitcnt lgkmcnt(1)
	v_mfma_f32_32x32x16_bf16 v[48:63], v[188:191], v[180:183], v[48:63]
	v_mfma_f32_32x32x16_bf16 v[16:31], v[188:191], v[184:187], v[16:31]
	s_waitcnt lgkmcnt(0)
	v_mfma_f32_32x32x16_bf16 v[32:47], v[220:223], v[180:183], v[32:47]
	ds_read_b128 v[64:67], v102 offset:55328
	ds_read_b128 v[72:75], v102 offset:59936
	ds_read_b128 v[80:83], v101 offset:36896
	ds_read_b128 v[84:87], v101 offset:41504
	v_mfma_f32_32x32x16_bf16 v[0:15], v[220:223], v[184:187], v[0:15]
	s_waitcnt lgkmcnt(1)
	v_mfma_f32_32x32x16_bf16 v[48:63], v[80:83], v[64:67], v[48:63]
	v_mfma_f32_32x32x16_bf16 v[16:31], v[80:83], v[72:75], v[16:31]
	s_waitcnt lgkmcnt(0)
	v_mfma_f32_32x32x16_bf16 v[32:47], v[84:87], v[64:67], v[32:47]
	v_mfma_f32_32x32x16_bf16 v[0:15], v[84:87], v[72:75], v[0:15]
	ds_read_b128 v[64:67], v101 offset:41536
	ds_read_b128 v[68:71], v102 offset:59968
	ds_read_b128 v[72:75], v102 offset:55360
	ds_read_b128 v[76:79], v101 offset:36928
	s_waitcnt lgkmcnt(0)
	v_mfma_f32_32x32x16_bf16 v[48:63], v[76:79], v[72:75], v[48:63]
	v_mfma_f32_32x32x16_bf16 v[16:31], v[76:79], v[68:71], v[16:31]
	v_mfma_f32_32x32x16_bf16 v[32:47], v[64:67], v[72:75], v[32:47]
	v_mfma_f32_32x32x16_bf16 v[0:15], v[64:67], v[68:71], v[0:15]
	ds_read_b128 v[64:67], v101 offset:41568
	ds_read_b128 v[68:71], v102 offset:60000
	ds_read_b128 v[72:75], v102 offset:55392
	ds_read_b128 v[76:79], v101 offset:36960
	s_waitcnt lgkmcnt(0)
	v_mfma_f32_32x32x16_bf16 v[48:63], v[76:79], v[72:75], v[48:63]
	v_mfma_f32_32x32x16_bf16 v[16:31], v[76:79], v[68:71], v[16:31]
	v_mfma_f32_32x32x16_bf16 v[32:47], v[64:67], v[72:75], v[32:47]
	v_mfma_f32_32x32x16_bf16 v[0:15], v[64:67], v[68:71], v[0:15]
	s_lshr_b32 s1, s6, 4
	v_readlane_b32 s8, v231, 25
	s_add_i32 s1, s8, s1
	s_lshl_b64 s[6:7], s[6:7], 19
	v_readlane_b32 s8, v231, 47
	s_add_u32 s8, s8, s6
	v_readlane_b32 s9, v231, 48
	v_mov_b32_e32 v65, v96
	v_mov_b32_e32 v64, v97
	s_addc_u32 s9, s9, s7
	v_readlane_b32 s14, v231, 23
	s_barrier
	s_add_u32 s6, s14, s6
	v_readlane_b32 s14, v231, 24
	v_mov_b32_e32 v68, v98
	v_mov_b32_e32 v66, v99
	s_addc_u32 s7, s14, s7
	s_lshl_b32 s0, s0, 7
	v_lshlrev_b32_e32 v64, 6, v64
	v_lshlrev_b32_e32 v65, 16, v65
	v_add3_u32 v64, v64, s0, v66
	s_mul_i32 s0, s1, 0x1800
	s_add_i32 s14, s0, 0x800
	s_and_b64 s[0:1], s[22:23], exec
	s_cselect_b32 s0, 0x800, s14
	v_add_u32_e32 v66, s0, v64
	v_ashrrev_i32_e32 v67, 31, v66
	v_lshl_add_u64 v[66:67], v[66:67], 2, s[92:93]
	v_lshl_add_u32 v65, v68, 12, v65
	global_load_dword v74, v[66:67], off
	v_add_u32_e32 v66, v65, v64
	v_ashrrev_i32_e32 v67, 31, v66
	v_lshlrev_b64 v[82:83], 2, v[66:67]
	v_lshl_add_u64 v[66:67], s[8:9], 0, v[82:83]
	global_load_dword v120, v[66:67], off nt
	v_or_b32_e32 v66, 0x400, v65
	v_add_u32_e32 v68, v66, v64
	v_ashrrev_i32_e32 v69, 31, v68
	v_lshlrev_b64 v[84:85], 2, v[68:69]
	v_lshl_add_u64 v[68:69], s[8:9], 0, v[84:85]
	v_or_b32_e32 v67, 0x800, v65
	global_load_dword v121, v[68:69], off nt
	v_add_u32_e32 v68, v67, v64
	v_ashrrev_i32_e32 v69, 31, v68
	v_lshlrev_b64 v[86:87], 2, v[68:69]
	v_lshl_add_u64 v[68:69], s[8:9], 0, v[86:87]
	global_load_dword v122, v[68:69], off nt
	v_or_b32_e32 v68, 0xc00, v65
	v_add_u32_e32 v70, v68, v64
	v_ashrrev_i32_e32 v71, 31, v70
	v_lshlrev_b64 v[88:89], 2, v[70:71]
	v_lshl_add_u64 v[70:71], s[8:9], 0, v[88:89]
	v_add_u32_e32 v69, 0x2000, v65
	global_load_dword v123, v[70:71], off nt
	v_add_u32_e32 v70, v69, v64
	v_ashrrev_i32_e32 v71, 31, v70
	v_lshlrev_b64 v[90:91], 2, v[70:71]
	v_lshl_add_u64 v[70:71], s[8:9], 0, v[90:91]
	global_load_dword v124, v[70:71], off nt
	v_add_u32_e32 v70, 0x2400, v65
	v_add_u32_e32 v72, v70, v64
	v_ashrrev_i32_e32 v73, 31, v72
	v_lshlrev_b64 v[92:93], 2, v[72:73]
	v_lshl_add_u64 v[72:73], s[8:9], 0, v[92:93]
	v_add_u32_e32 v71, 0x2800, v65
	global_load_dword v125, v[72:73], off nt
	v_add_u32_e32 v72, v71, v64
	v_ashrrev_i32_e32 v73, 31, v72
	v_lshlrev_b64 v[94:95], 2, v[72:73]
	v_lshl_add_u64 v[72:73], s[8:9], 0, v[94:95]
	global_load_dword v126, v[72:73], off nt
	v_add_u32_e32 v72, 0x2c00, v65
	v_add_u32_e32 v76, v72, v64
	v_ashrrev_i32_e32 v77, 31, v76
	v_lshlrev_b64 v[100:101], 2, v[76:77]
	v_lshl_add_u64 v[76:77], s[8:9], 0, v[100:101]
	v_add_u32_e32 v73, 0x4000, v65
	global_load_dword v127, v[76:77], off nt
	v_add_u32_e32 v76, v73, v64
	v_ashrrev_i32_e32 v77, 31, v76
	v_lshlrev_b64 v[102:103], 2, v[76:77]
	v_lshl_add_u64 v[76:77], s[8:9], 0, v[102:103]
	v_add_u32_e32 v75, 0x4400, v65
	global_load_dword v128, v[76:77], off nt
	v_add_u32_e32 v76, v75, v64
	v_ashrrev_i32_e32 v77, 31, v76
	v_lshlrev_b64 v[104:105], 2, v[76:77]
	v_lshl_add_u64 v[76:77], s[8:9], 0, v[104:105]
	global_load_dword v129, v[76:77], off nt
	v_add_u32_e32 v76, 0x4800, v65
	v_add_u32_e32 v78, v76, v64
	v_ashrrev_i32_e32 v79, 31, v78
	v_lshlrev_b64 v[106:107], 2, v[78:79]
	v_lshl_add_u64 v[78:79], s[8:9], 0, v[106:107]
	v_add_u32_e32 v77, 0x4c00, v65
	global_load_dword v130, v[78:79], off nt
	v_add_u32_e32 v78, v77, v64
	v_ashrrev_i32_e32 v79, 31, v78
	v_lshlrev_b64 v[108:109], 2, v[78:79]
	v_lshl_add_u64 v[78:79], s[8:9], 0, v[108:109]
	global_load_dword v131, v[78:79], off nt
	v_add_u32_e32 v78, 0x6000, v65
	v_add_u32_e32 v80, v78, v64
	v_ashrrev_i32_e32 v81, 31, v80
	v_lshlrev_b64 v[110:111], 2, v[80:81]
	v_lshl_add_u64 v[80:81], s[8:9], 0, v[110:111]
	v_add_u32_e32 v79, 0x6400, v65
	global_load_dword v132, v[80:81], off nt
	v_add_u32_e32 v80, v79, v64
	v_ashrrev_i32_e32 v81, 31, v80
	v_lshlrev_b64 v[112:113], 2, v[80:81]
	v_lshl_add_u64 v[80:81], s[8:9], 0, v[112:113]
	global_load_dword v133, v[80:81], off nt
	v_add_u32_e32 v80, 0x6800, v65
	v_add_u32_e32 v114, v80, v64
	v_ashrrev_i32_e32 v115, 31, v114
	v_lshlrev_b64 v[114:115], 2, v[114:115]
	v_lshl_add_u64 v[116:117], s[8:9], 0, v[114:115]
	v_add_u32_e32 v81, 0x6c00, v65
	global_load_dword v134, v[116:117], off nt
	v_add_u32_e32 v116, v81, v64
	v_ashrrev_i32_e32 v117, 31, v116
	v_lshlrev_b64 v[116:117], 2, v[116:117]
	v_lshl_add_u64 v[118:119], s[8:9], 0, v[116:117]
	global_load_dword v118, v[118:119], off nt
	s_waitcnt vmcnt(15)
; DI int crow(int r, int h) { return (r & 3) + 8 * (r >> 2) + 4 * h; }
; DI void phase_outproj(const Params& p, int g, char* smem, int bid, int nb) {
;     ...
; #pragma unroll
;     for (int ni = 0; ni < 2; ++ni) {
;       const int col = nt * 128 + wn * 64 + ni * 32 + l31;
;       const float gt = mod[b * 6144 + 2048 + col];
; #pragma unroll
;       for (int mi = 0; mi < 2; ++mi) {
;         float xv[16];
; #pragma unroll
;         for (int r = 0; r < 16; ++r) xv[r] = __builtin_nontemporal_load(&xt[(wm * 64 + mi * 32 + crow(r, h)) * 1024 + col]);
; #pragma unroll
;         for (int r = 0; r < 16; ++r) ot[(wm * 64 + mi * 32 + crow(r, h)) * 1024 + col] = xv[r] + gt * acc[mi][ni][r];
;       }
	v_fmac_f32_e32 v120, v48, v74
	s_waitcnt vmcnt(14)
	v_fmac_f32_e32 v121, v49, v74
	v_lshl_add_u64 v[48:49], s[6:7], 0, v[84:85]
	global_store_dword v[48:49], v121, off
	s_waitcnt vmcnt(14)
	v_fmac_f32_e32 v122, v50, v74
	v_lshl_add_u64 v[48:49], s[6:7], 0, v[86:87]
	global_store_dword v[48:49], v122, off
	v_lshl_add_u64 v[48:49], s[6:7], 0, v[88:89]
	s_waitcnt vmcnt(14)
	v_fmac_f32_e32 v123, v51, v74
	global_store_dword v[48:49], v123, off
	v_lshl_add_u64 v[48:49], s[6:7], 0, v[90:91]
	v_lshl_add_u64 v[82:83], s[6:7], 0, v[82:83]
	global_store_dword v[82:83], v120, off
	s_waitcnt vmcnt(15)
	v_fmac_f32_e32 v124, v52, v74
	global_store_dword v[48:49], v124, off
	v_lshl_add_u64 v[48:49], s[6:7], 0, v[92:93]
	v_add_u32_e32 v120, 0xc000, v65
	v_add_u32_e32 v122, 0xc400, v65
	v_add_u32_e32 v124, 0xc800, v65
	s_cmp_ge_i32 s11, s13
	s_waitcnt vmcnt(15)
	v_fmac_f32_e32 v125, v53, v74
	global_store_dword v[48:49], v125, off
	v_lshl_add_u64 v[48:49], s[6:7], 0, v[94:95]
	s_waitcnt vmcnt(15)
	v_fmac_f32_e32 v126, v54, v74
	global_store_dword v[48:49], v126, off
	v_lshl_add_u64 v[48:49], s[6:7], 0, v[100:101]
	v_add_u32_e32 v126, 0xcc00, v65
	s_waitcnt vmcnt(15)
	v_fmac_f32_e32 v127, v55, v74
	global_store_dword v[48:49], v127, off
	v_lshl_add_u64 v[48:49], s[6:7], 0, v[102:103]
	s_waitcnt vmcnt(15)
	v_fmac_f32_e32 v128, v56, v74
	global_store_dword v[48:49], v128, off
	v_lshl_add_u64 v[48:49], s[6:7], 0, v[104:105]
	v_add_u32_e32 v128, 0xe000, v65
	s_waitcnt vmcnt(15)
	v_fmac_f32_e32 v129, v57, v74
	global_store_dword v[48:49], v129, off
	v_lshl_add_u64 v[48:49], s[6:7], 0, v[106:107]
	s_waitcnt vmcnt(15)
	v_fmac_f32_e32 v130, v58, v74
	global_store_dword v[48:49], v130, off
	v_lshl_add_u64 v[48:49], s[6:7], 0, v[108:109]
	v_add_u32_e32 v130, 0xe400, v65
	s_waitcnt vmcnt(15)
	v_fmac_f32_e32 v131, v59, v74
	global_store_dword v[48:49], v131, off
	v_lshl_add_u64 v[48:49], s[6:7], 0, v[110:111]
	s_waitcnt vmcnt(15)
	v_fmac_f32_e32 v132, v60, v74
	global_store_dword v[48:49], v132, off
	v_lshl_add_u64 v[48:49], s[6:7], 0, v[112:113]
	v_add_u32_e32 v132, 0xe800, v65
	s_waitcnt vmcnt(15)
	v_fmac_f32_e32 v133, v61, v74
	global_store_dword v[48:49], v133, off
	v_lshl_add_u64 v[48:49], s[6:7], 0, v[114:115]
	s_waitcnt vmcnt(15)
	v_fmac_f32_e32 v134, v62, v74
	global_store_dword v[48:49], v134, off
	v_lshl_add_u64 v[48:49], s[6:7], 0, v[116:117]
	v_add_u32_e32 v134, 0xec00, v65
	s_waitcnt vmcnt(15)
	v_fmac_f32_e32 v118, v63, v74
	global_store_dword v[48:49], v118, off
	v_add_u32_e32 v48, 0x8000, v65
	v_add_u32_e32 v50, v48, v64
	v_ashrrev_i32_e32 v51, 31, v50
	v_lshlrev_b64 v[56:57], 2, v[50:51]
	v_lshl_add_u64 v[50:51], s[8:9], 0, v[56:57]
	v_add_u32_e32 v49, 0x8400, v65
	global_load_dword v112, v[50:51], off nt
	v_add_u32_e32 v50, v49, v64
	v_ashrrev_i32_e32 v51, 31, v50
	v_lshlrev_b64 v[58:59], 2, v[50:51]
	v_lshl_add_u64 v[50:51], s[8:9], 0, v[58:59]
	global_load_dword v113, v[50:51], off nt
	v_add_u32_e32 v50, 0x8800, v65
	v_add_u32_e32 v52, v50, v64
	v_ashrrev_i32_e32 v53, 31, v52
	v_lshlrev_b64 v[60:61], 2, v[52:53]
	v_lshl_add_u64 v[52:53], s[8:9], 0, v[60:61]
	v_add_u32_e32 v51, 0x8c00, v65
	global_load_dword v114, v[52:53], off nt
	v_add_u32_e32 v52, v51, v64
	v_ashrrev_i32_e32 v53, 31, v52
	v_lshlrev_b64 v[62:63], 2, v[52:53]
	v_lshl_add_u64 v[52:53], s[8:9], 0, v[62:63]
	global_load_dword v115, v[52:53], off nt
	v_add_u32_e32 v52, 0xa000, v65
	v_add_u32_e32 v54, v52, v64
	v_ashrrev_i32_e32 v55, 31, v54
	v_lshlrev_b64 v[82:83], 2, v[54:55]
	v_lshl_add_u64 v[54:55], s[8:9], 0, v[82:83]
	v_add_u32_e32 v53, 0xa400, v65
	global_load_dword v116, v[54:55], off nt
	v_add_u32_e32 v54, v53, v64
	v_ashrrev_i32_e32 v55, 31, v54
	v_lshlrev_b64 v[84:85], 2, v[54:55]
	v_lshl_add_u64 v[54:55], s[8:9], 0, v[84:85]
	global_load_dword v55, v[54:55], off nt
	v_add_u32_e32 v54, 0xa800, v65
	v_add_u32_e32 v86, v54, v64
	v_ashrrev_i32_e32 v87, 31, v86
	v_lshlrev_b64 v[86:87], 2, v[86:87]
	v_lshl_add_u64 v[88:89], s[8:9], 0, v[86:87]
	v_add_u32_e32 v118, 0xac00, v65
	global_load_dword v117, v[88:89], off nt
	v_add_u32_e32 v88, v118, v64
	v_ashrrev_i32_e32 v89, 31, v88
	v_lshlrev_b64 v[88:89], 2, v[88:89]
	v_lshl_add_u64 v[90:91], s[8:9], 0, v[88:89]
	global_load_dword v119, v[90:91], off nt
	v_add_u32_e32 v90, v120, v64
	v_ashrrev_i32_e32 v91, 31, v90
	v_lshlrev_b64 v[90:91], 2, v[90:91]
	v_lshl_add_u64 v[92:93], s[8:9], 0, v[90:91]
	global_load_dword v121, v[92:93], off nt
	v_add_u32_e32 v92, v122, v64
	v_ashrrev_i32_e32 v93, 31, v92
	v_lshlrev_b64 v[92:93], 2, v[92:93]
	v_lshl_add_u64 v[94:95], s[8:9], 0, v[92:93]
	global_load_dword v123, v[94:95], off nt
	v_add_u32_e32 v94, v124, v64
	v_ashrrev_i32_e32 v95, 31, v94
	v_lshlrev_b64 v[94:95], 2, v[94:95]
	v_lshl_add_u64 v[100:101], s[8:9], 0, v[94:95]
	global_load_dword v125, v[100:101], off nt
	v_add_u32_e32 v100, v126, v64
	v_ashrrev_i32_e32 v101, 31, v100
	v_lshlrev_b64 v[100:101], 2, v[100:101]
	v_lshl_add_u64 v[102:103], s[8:9], 0, v[100:101]
	global_load_dword v127, v[102:103], off nt
	v_add_u32_e32 v102, v128, v64
	v_ashrrev_i32_e32 v103, 31, v102
	v_lshlrev_b64 v[102:103], 2, v[102:103]
	v_lshl_add_u64 v[104:105], s[8:9], 0, v[102:103]
	global_load_dword v129, v[104:105], off nt
	v_add_u32_e32 v104, v130, v64
	v_ashrrev_i32_e32 v105, 31, v104
	v_lshlrev_b64 v[104:105], 2, v[104:105]
	v_lshl_add_u64 v[106:107], s[8:9], 0, v[104:105]
	global_load_dword v131, v[106:107], off nt
	v_add_u32_e32 v106, v132, v64
	v_ashrrev_i32_e32 v107, 31, v106
	v_lshlrev_b64 v[106:107], 2, v[106:107]
	v_lshl_add_u64 v[108:109], s[8:9], 0, v[106:107]
	global_load_dword v133, v[108:109], off nt
	v_add_u32_e32 v108, v134, v64
	v_ashrrev_i32_e32 v109, 31, v108
	v_lshlrev_b64 v[108:109], 2, v[108:109]
	v_lshl_add_u64 v[110:111], s[8:9], 0, v[108:109]
	global_load_dword v110, v[110:111], off nt
	s_waitcnt vmcnt(15)
; DI int crow(int r, int h) { return (r & 3) + 8 * (r >> 2) + 4 * h; }
; DI void phase_outproj(const Params& p, int g, char* smem, int bid, int nb) {
;     ...
; #pragma unroll
;     for (int ni = 0; ni < 2; ++ni) {
;       const int col = nt * 128 + wn * 64 + ni * 32 + l31;
;       const float gt = mod[b * 6144 + 2048 + col];
; #pragma unroll
;       for (int mi = 0; mi < 2; ++mi) {
;         float xv[16];
; #pragma unroll
;         for (int r = 0; r < 16; ++r) xv[r] = __builtin_nontemporal_load(&xt[(wm * 64 + mi * 32 + crow(r, h)) * 1024 + col]);
; #pragma unroll
;         for (int r = 0; r < 16; ++r) ot[(wm * 64 + mi * 32 + crow(r, h)) * 1024 + col] = xv[r] + gt * acc[mi][ni][r];
;       }
	v_fmac_f32_e32 v112, v32, v74
	v_lshl_add_u64 v[56:57], s[6:7], 0, v[56:57]
	global_store_dword v[56:57], v112, off
	s_waitcnt vmcnt(15)
	v_fmac_f32_e32 v113, v33, v74
	v_lshl_add_u64 v[32:33], s[6:7], 0, v[58:59]
	global_store_dword v[32:33], v113, off
	v_lshl_add_u64 v[32:33], s[6:7], 0, v[60:61]
	s_waitcnt vmcnt(15)
	v_fmac_f32_e32 v114, v34, v74
	global_store_dword v[32:33], v114, off
	v_lshl_add_u64 v[32:33], s[6:7], 0, v[62:63]
	s_waitcnt vmcnt(15)
	v_fmac_f32_e32 v115, v35, v74
	global_store_dword v[32:33], v115, off
	v_lshl_add_u64 v[32:33], s[6:7], 0, v[82:83]
	s_waitcnt vmcnt(15)
	v_fmac_f32_e32 v116, v36, v74
	global_store_dword v[32:33], v116, off
	v_lshl_add_u64 v[32:33], s[6:7], 0, v[84:85]
	s_waitcnt vmcnt(15)
	v_fmac_f32_e32 v55, v37, v74
	global_store_dword v[32:33], v55, off
	v_lshl_add_u64 v[32:33], s[6:7], 0, v[86:87]
	v_add_u32_e32 v55, 32, v64
	s_waitcnt vmcnt(15)
	v_fmac_f32_e32 v117, v38, v74
	global_store_dword v[32:33], v117, off
	v_lshl_add_u64 v[32:33], s[6:7], 0, v[88:89]
	s_waitcnt vmcnt(15)
	v_fmac_f32_e32 v119, v39, v74
	global_store_dword v[32:33], v119, off
	v_lshl_add_u64 v[32:33], s[6:7], 0, v[90:91]
	s_waitcnt vmcnt(15)
	v_fmac_f32_e32 v121, v40, v74
	global_store_dword v[32:33], v121, off
	v_lshl_add_u64 v[32:33], s[6:7], 0, v[92:93]
	s_waitcnt vmcnt(15)
	v_fmac_f32_e32 v123, v41, v74
	global_store_dword v[32:33], v123, off
	v_lshl_add_u64 v[32:33], s[6:7], 0, v[94:95]
	s_waitcnt vmcnt(15)
	v_fmac_f32_e32 v125, v42, v74
	global_store_dword v[32:33], v125, off
	v_lshl_add_u64 v[32:33], s[6:7], 0, v[100:101]
	s_waitcnt vmcnt(15)
	v_fmac_f32_e32 v127, v43, v74
	global_store_dword v[32:33], v127, off
	v_lshl_add_u64 v[32:33], s[6:7], 0, v[102:103]
	s_waitcnt vmcnt(15)
	v_fmac_f32_e32 v129, v44, v74
	global_store_dword v[32:33], v129, off
	v_lshl_add_u64 v[32:33], s[6:7], 0, v[104:105]
	s_waitcnt vmcnt(15)
	v_fmac_f32_e32 v131, v45, v74
	global_store_dword v[32:33], v131, off
	v_lshl_add_u64 v[32:33], s[6:7], 0, v[106:107]
	s_waitcnt vmcnt(15)
	v_fmac_f32_e32 v133, v46, v74
	global_store_dword v[32:33], v133, off
	v_lshl_add_u64 v[32:33], s[6:7], 0, v[108:109]
	s_waitcnt vmcnt(15)
	v_fmac_f32_e32 v110, v47, v74
	global_store_dword v[32:33], v110, off
	v_add_u32_e32 v32, s0, v55
	v_ashrrev_i32_e32 v33, 31, v32
	v_lshl_add_u64 v[32:33], v[32:33], 2, s[92:93]
	global_load_dword v74, v[32:33], off
	v_add_u32_e32 v32, v55, v65
	v_ashrrev_i32_e32 v33, 31, v32
	v_lshlrev_b64 v[32:33], 2, v[32:33]
	v_lshl_add_u64 v[34:35], s[8:9], 0, v[32:33]
	global_load_dword v82, v[34:35], off nt
	v_add_u32_e32 v34, v66, v55
	v_ashrrev_i32_e32 v35, 31, v34
	v_lshlrev_b64 v[34:35], 2, v[34:35]
	v_lshl_add_u64 v[36:37], s[8:9], 0, v[34:35]
	global_load_dword v83, v[36:37], off nt
	v_add_u32_e32 v36, v67, v55
	v_ashrrev_i32_e32 v37, 31, v36
	v_lshlrev_b64 v[36:37], 2, v[36:37]
	v_lshl_add_u64 v[38:39], s[8:9], 0, v[36:37]
	global_load_dword v84, v[38:39], off nt
	v_add_u32_e32 v38, v68, v55
	v_ashrrev_i32_e32 v39, 31, v38
	v_lshlrev_b64 v[38:39], 2, v[38:39]
	v_lshl_add_u64 v[40:41], s[8:9], 0, v[38:39]
	global_load_dword v85, v[40:41], off nt
	v_add_u32_e32 v40, v69, v55
	v_ashrrev_i32_e32 v41, 31, v40
	v_lshlrev_b64 v[40:41], 2, v[40:41]
	v_lshl_add_u64 v[42:43], s[8:9], 0, v[40:41]
	global_load_dword v86, v[42:43], off nt
	v_add_u32_e32 v42, v70, v55
	v_ashrrev_i32_e32 v43, 31, v42
	v_lshlrev_b64 v[42:43], 2, v[42:43]
	v_lshl_add_u64 v[44:45], s[8:9], 0, v[42:43]
	global_load_dword v87, v[44:45], off nt
	v_add_u32_e32 v44, v71, v55
	v_ashrrev_i32_e32 v45, 31, v44
	v_lshlrev_b64 v[44:45], 2, v[44:45]
	v_lshl_add_u64 v[46:47], s[8:9], 0, v[44:45]
	global_load_dword v88, v[46:47], off nt
	v_add_u32_e32 v46, v72, v55
	v_ashrrev_i32_e32 v47, 31, v46
	v_lshlrev_b64 v[46:47], 2, v[46:47]
	v_lshl_add_u64 v[56:57], s[8:9], 0, v[46:47]
	global_load_dword v89, v[56:57], off nt
	v_add_u32_e32 v56, v73, v55
	v_ashrrev_i32_e32 v57, 31, v56
	v_lshlrev_b64 v[56:57], 2, v[56:57]
	v_lshl_add_u64 v[58:59], s[8:9], 0, v[56:57]
	global_load_dword v90, v[58:59], off nt
	v_add_u32_e32 v58, v75, v55
	v_ashrrev_i32_e32 v59, 31, v58
	v_lshlrev_b64 v[58:59], 2, v[58:59]
	v_lshl_add_u64 v[60:61], s[8:9], 0, v[58:59]
	global_load_dword v75, v[60:61], off nt
	v_add_u32_e32 v60, v76, v55
	v_ashrrev_i32_e32 v61, 31, v60
	v_lshlrev_b64 v[60:61], 2, v[60:61]
	v_lshl_add_u64 v[62:63], s[8:9], 0, v[60:61]
	global_load_dword v76, v[62:63], off nt
	v_add_u32_e32 v62, v77, v55
	v_ashrrev_i32_e32 v63, 31, v62
	v_lshlrev_b64 v[62:63], 2, v[62:63]
	v_lshl_add_u64 v[64:65], s[8:9], 0, v[62:63]
	global_load_dword v77, v[64:65], off nt
	v_add_u32_e32 v64, v78, v55
	v_ashrrev_i32_e32 v65, 31, v64
	v_lshlrev_b64 v[64:65], 2, v[64:65]
	v_lshl_add_u64 v[66:67], s[8:9], 0, v[64:65]
	global_load_dword v78, v[66:67], off nt
	v_add_u32_e32 v66, v79, v55
	v_ashrrev_i32_e32 v67, 31, v66
	v_lshlrev_b64 v[66:67], 2, v[66:67]
	v_lshl_add_u64 v[68:69], s[8:9], 0, v[66:67]
	global_load_dword v79, v[68:69], off nt
	v_add_u32_e32 v68, v80, v55
	v_ashrrev_i32_e32 v69, 31, v68
	v_lshlrev_b64 v[68:69], 2, v[68:69]
	v_lshl_add_u64 v[70:71], s[8:9], 0, v[68:69]
	global_load_dword v80, v[70:71], off nt
	v_add_u32_e32 v70, v81, v55
	v_ashrrev_i32_e32 v71, 31, v70
	v_lshlrev_b64 v[70:71], 2, v[70:71]
	v_lshl_add_u64 v[72:73], s[8:9], 0, v[70:71]
	global_load_dword v72, v[72:73], off nt
	v_lshl_add_u64 v[32:33], s[6:7], 0, v[32:33]
	s_waitcnt vmcnt(15)
	v_fmac_f32_e32 v82, v16, v74
	global_store_dword v[32:33], v82, off
	s_waitcnt vmcnt(15)
	v_fmac_f32_e32 v83, v17, v74
	v_lshl_add_u64 v[16:17], s[6:7], 0, v[34:35]
	global_store_dword v[16:17], v83, off
	v_lshl_add_u64 v[16:17], s[6:7], 0, v[36:37]
	s_waitcnt vmcnt(15)
; DI int crow(int r, int h) { return (r & 3) + 8 * (r >> 2) + 4 * h; }
; DI void phase_outproj(const Params& p, int g, char* smem, int bid, int nb) {
;     ...
; #pragma unroll
;     for (int ni = 0; ni < 2; ++ni) {
;       const int col = nt * 128 + wn * 64 + ni * 32 + l31;
;       const float gt = mod[b * 6144 + 2048 + col];
; #pragma unroll
;       for (int mi = 0; mi < 2; ++mi) {
;         float xv[16];
; #pragma unroll
;         for (int r = 0; r < 16; ++r) xv[r] = __builtin_nontemporal_load(&xt[(wm * 64 + mi * 32 + crow(r, h)) * 1024 + col]);
; #pragma unroll
;         for (int r = 0; r < 16; ++r) ot[(wm * 64 + mi * 32 + crow(r, h)) * 1024 + col] = xv[r] + gt * acc[mi][ni][r];
;       }
	v_fmac_f32_e32 v84, v18, v74
	global_store_dword v[16:17], v84, off
	v_lshl_add_u64 v[16:17], s[6:7], 0, v[38:39]
	s_waitcnt vmcnt(15)
	v_fmac_f32_e32 v85, v19, v74
	global_store_dword v[16:17], v85, off
	v_lshl_add_u64 v[16:17], s[6:7], 0, v[40:41]
	s_waitcnt vmcnt(15)
	v_fmac_f32_e32 v86, v20, v74
	global_store_dword v[16:17], v86, off
	v_lshl_add_u64 v[16:17], s[6:7], 0, v[42:43]
	s_waitcnt vmcnt(15)
	v_fmac_f32_e32 v87, v21, v74
	global_store_dword v[16:17], v87, off
	v_lshl_add_u64 v[16:17], s[6:7], 0, v[44:45]
	s_waitcnt vmcnt(15)
	v_fmac_f32_e32 v88, v22, v74
	global_store_dword v[16:17], v88, off
	v_lshl_add_u64 v[16:17], s[6:7], 0, v[46:47]
	s_waitcnt vmcnt(15)
	v_fmac_f32_e32 v89, v23, v74
	global_store_dword v[16:17], v89, off
	v_lshl_add_u64 v[16:17], s[6:7], 0, v[56:57]
	s_waitcnt vmcnt(15)
	v_fmac_f32_e32 v90, v24, v74
	global_store_dword v[16:17], v90, off
	v_lshl_add_u64 v[16:17], s[6:7], 0, v[58:59]
	s_waitcnt vmcnt(15)
	v_fmac_f32_e32 v75, v25, v74
	global_store_dword v[16:17], v75, off
	v_lshl_add_u64 v[16:17], s[6:7], 0, v[60:61]
	s_waitcnt vmcnt(15)
	v_fmac_f32_e32 v76, v26, v74
	global_store_dword v[16:17], v76, off
	v_lshl_add_u64 v[16:17], s[6:7], 0, v[62:63]
	s_waitcnt vmcnt(15)
	v_fmac_f32_e32 v77, v27, v74
	global_store_dword v[16:17], v77, off
	v_lshl_add_u64 v[16:17], s[6:7], 0, v[64:65]
	s_waitcnt vmcnt(15)
	v_fmac_f32_e32 v78, v28, v74
	global_store_dword v[16:17], v78, off
	v_lshl_add_u64 v[16:17], s[6:7], 0, v[66:67]
	s_waitcnt vmcnt(15)
	v_fmac_f32_e32 v79, v29, v74
	global_store_dword v[16:17], v79, off
	v_lshl_add_u64 v[16:17], s[6:7], 0, v[68:69]
	s_waitcnt vmcnt(15)
	v_fmac_f32_e32 v80, v30, v74
	global_store_dword v[16:17], v80, off
	v_lshl_add_u64 v[16:17], s[6:7], 0, v[70:71]
	s_waitcnt vmcnt(15)
	v_fmac_f32_e32 v72, v31, v74
	global_store_dword v[16:17], v72, off
	v_add_u32_e32 v16, v48, v55
	v_ashrrev_i32_e32 v17, 31, v16
	v_lshlrev_b64 v[16:17], 2, v[16:17]
	v_lshl_add_u64 v[18:19], s[8:9], 0, v[16:17]
	global_load_dword v56, v[18:19], off nt
	v_add_u32_e32 v18, v49, v55
	v_ashrrev_i32_e32 v19, 31, v18
	v_lshlrev_b64 v[18:19], 2, v[18:19]
	v_lshl_add_u64 v[20:21], s[8:9], 0, v[18:19]
	global_load_dword v57, v[20:21], off nt
	v_add_u32_e32 v20, v50, v55
	v_ashrrev_i32_e32 v21, 31, v20
	v_lshlrev_b64 v[20:21], 2, v[20:21]
	v_lshl_add_u64 v[22:23], s[8:9], 0, v[20:21]
	global_load_dword v50, v[22:23], off nt
	v_add_u32_e32 v22, v51, v55
	v_ashrrev_i32_e32 v23, 31, v22
	v_lshlrev_b64 v[22:23], 2, v[22:23]
	v_lshl_add_u64 v[24:25], s[8:9], 0, v[22:23]
	global_load_dword v51, v[24:25], off nt
	v_add_u32_e32 v24, v52, v55
	v_ashrrev_i32_e32 v25, 31, v24
	v_lshlrev_b64 v[24:25], 2, v[24:25]
	v_lshl_add_u64 v[26:27], s[8:9], 0, v[24:25]
	global_load_dword v52, v[26:27], off nt
	v_add_u32_e32 v26, v53, v55
	v_ashrrev_i32_e32 v27, 31, v26
	v_lshlrev_b64 v[26:27], 2, v[26:27]
	v_lshl_add_u64 v[28:29], s[8:9], 0, v[26:27]
	global_load_dword v53, v[28:29], off nt
	v_add_u32_e32 v28, v54, v55
	v_ashrrev_i32_e32 v29, 31, v28
	v_lshlrev_b64 v[28:29], 2, v[28:29]
	v_lshl_add_u64 v[30:31], s[8:9], 0, v[28:29]
	global_load_dword v54, v[30:31], off nt
	v_add_u32_e32 v30, v118, v55
	v_ashrrev_i32_e32 v31, 31, v30
	v_lshlrev_b64 v[30:31], 2, v[30:31]
	v_lshl_add_u64 v[32:33], s[8:9], 0, v[30:31]
	global_load_dword v58, v[32:33], off nt
	v_add_u32_e32 v32, v120, v55
	v_ashrrev_i32_e32 v33, 31, v32
	v_lshlrev_b64 v[32:33], 2, v[32:33]
	v_lshl_add_u64 v[34:35], s[8:9], 0, v[32:33]
	global_load_dword v59, v[34:35], off nt
	v_add_u32_e32 v34, v122, v55
	v_ashrrev_i32_e32 v35, 31, v34
	v_lshlrev_b64 v[34:35], 2, v[34:35]
	v_lshl_add_u64 v[36:37], s[8:9], 0, v[34:35]
	global_load_dword v60, v[36:37], off nt
	v_add_u32_e32 v36, v124, v55
	v_ashrrev_i32_e32 v37, 31, v36
	v_lshlrev_b64 v[36:37], 2, v[36:37]
	v_lshl_add_u64 v[38:39], s[8:9], 0, v[36:37]
	global_load_dword v61, v[38:39], off nt
	v_add_u32_e32 v38, v126, v55
	v_ashrrev_i32_e32 v39, 31, v38
	v_lshlrev_b64 v[38:39], 2, v[38:39]
	v_lshl_add_u64 v[40:41], s[8:9], 0, v[38:39]
	global_load_dword v62, v[40:41], off nt
	v_add_u32_e32 v40, v128, v55
	v_ashrrev_i32_e32 v41, 31, v40
	v_lshlrev_b64 v[40:41], 2, v[40:41]
	v_lshl_add_u64 v[42:43], s[8:9], 0, v[40:41]
	global_load_dword v63, v[42:43], off nt
	v_add_u32_e32 v42, v130, v55
	v_ashrrev_i32_e32 v43, 31, v42
	v_lshlrev_b64 v[42:43], 2, v[42:43]
	v_lshl_add_u64 v[44:45], s[8:9], 0, v[42:43]
	global_load_dword v64, v[44:45], off nt
	v_add_u32_e32 v44, v132, v55
	v_ashrrev_i32_e32 v45, 31, v44
	v_lshlrev_b64 v[44:45], 2, v[44:45]
	v_lshl_add_u64 v[46:47], s[8:9], 0, v[44:45]
	global_load_dword v65, v[46:47], off nt
	v_add_u32_e32 v46, v134, v55
	v_ashrrev_i32_e32 v47, 31, v46
	v_lshlrev_b64 v[46:47], 2, v[46:47]
	v_lshl_add_u64 v[48:49], s[8:9], 0, v[46:47]
	global_load_dword v48, v[48:49], off nt
	v_lshl_add_u64 v[16:17], s[6:7], 0, v[16:17]
	s_waitcnt vmcnt(15)
	v_fmac_f32_e32 v56, v0, v74
	global_store_dword v[16:17], v56, off
	s_waitcnt vmcnt(15)
	v_fmac_f32_e32 v57, v1, v74
	v_lshl_add_u64 v[0:1], s[6:7], 0, v[18:19]
	global_store_dword v[0:1], v57, off
	v_lshl_add_u64 v[0:1], s[6:7], 0, v[20:21]
	s_waitcnt vmcnt(15)
	v_fmac_f32_e32 v50, v2, v74
	global_store_dword v[0:1], v50, off
	v_lshl_add_u64 v[0:1], s[6:7], 0, v[22:23]
	s_waitcnt vmcnt(15)
	v_fmac_f32_e32 v51, v3, v74
	global_store_dword v[0:1], v51, off
	v_lshl_add_u64 v[0:1], s[6:7], 0, v[24:25]
	s_waitcnt vmcnt(15)
	v_fmac_f32_e32 v52, v4, v74
	global_store_dword v[0:1], v52, off
	v_lshl_add_u64 v[0:1], s[6:7], 0, v[26:27]
	s_waitcnt vmcnt(15)
	v_fmac_f32_e32 v53, v5, v74
	global_store_dword v[0:1], v53, off
	v_lshl_add_u64 v[0:1], s[6:7], 0, v[28:29]
	s_waitcnt vmcnt(15)
	v_fmac_f32_e32 v54, v6, v74
	global_store_dword v[0:1], v54, off
	v_lshl_add_u64 v[0:1], s[6:7], 0, v[30:31]
	s_waitcnt vmcnt(15)
	v_fmac_f32_e32 v58, v7, v74
	global_store_dword v[0:1], v58, off
	v_lshl_add_u64 v[0:1], s[6:7], 0, v[32:33]
	s_waitcnt vmcnt(15)
	v_fmac_f32_e32 v59, v8, v74
	global_store_dword v[0:1], v59, off
	v_lshl_add_u64 v[0:1], s[6:7], 0, v[34:35]
	s_waitcnt vmcnt(15)
	v_fmac_f32_e32 v60, v9, v74
	global_store_dword v[0:1], v60, off
	v_lshl_add_u64 v[0:1], s[6:7], 0, v[36:37]
	s_waitcnt vmcnt(15)
	v_fmac_f32_e32 v61, v10, v74
	global_store_dword v[0:1], v61, off
	v_lshl_add_u64 v[0:1], s[6:7], 0, v[38:39]
	s_waitcnt vmcnt(15)
	v_fmac_f32_e32 v62, v11, v74
	global_store_dword v[0:1], v62, off
	v_lshl_add_u64 v[0:1], s[6:7], 0, v[40:41]
	s_waitcnt vmcnt(15)
	v_fmac_f32_e32 v63, v12, v74
	global_store_dword v[0:1], v63, off
	v_lshl_add_u64 v[0:1], s[6:7], 0, v[42:43]
	s_waitcnt vmcnt(15)
	v_fmac_f32_e32 v64, v13, v74
	global_store_dword v[0:1], v64, off
	v_lshl_add_u64 v[0:1], s[6:7], 0, v[44:45]
	s_waitcnt vmcnt(15)
	v_fmac_f32_e32 v65, v14, v74
	global_store_dword v[0:1], v65, off
	v_lshl_add_u64 v[0:1], s[6:7], 0, v[46:47]
	s_waitcnt vmcnt(15)
	v_fmac_f32_e32 v48, v15, v74
	global_store_dword v[0:1], v48, off
	s_cbranch_scc1 .LBB0_216

; template <bool SWAP>
; DI void gemm_tile(const bf16_t* __restrict__ A, int lda, const bf16_t* __restrict__ Bt, int ldb, int K, f32x16 (&acc)[2][2], bf16_t* As, bf16_t* Bs_unused) {
;     ...
;   const bf16_t* ga = A + (size_t)lr * lda + lc;
;   const bf16_t* gb = Bt + (size_t)lr * ldb + lc;
;   u32x4 ra0[4], rb0[4], ra1[4], rb1[4];
;   auto load_stage = [&](u32x4 (&ra)[4], u32x4 (&rb)[4], int t) __attribute__((always_inline)) {
; #pragma unroll
;     for (int i = 0; i < 4; ++i) { ra[i] = *(const u32x4*)(ga + (size_t)(32 * i) * lda + t * 64); rb[i] = *(const u32x4*)(gb + (size_t)(32 * i) * ldb + t * 64); }
;   };
;   auto write_stage = [&](const u32x4 (&ra)[4], const u32x4 (&rb)[4], int buf) __attribute__((always_inline)) {
;     bf16_t* Ad = As + buf * 2 * GT_IMG; bf16_t* Bd = Ad + GT_IMG;
; #pragma unroll
;     for (int i = 0; i < 4; ++i) { *(u32x4*)(Ad + (lr + 32 * i) * 72 + lc) = ra[i]; *(u32x4*)(Bd + (lr + 32 * i) * 72 + lc) = rb[i]; }
;   };
;   const int fr = lane & 31, fk = (lane >> 5) * 8;
;   const int pao = (wm * 64 + fr) * 72 + fk, pbo = GT_IMG + (wn * 64 + fr) * 72 + fk;
;   auto frag_read = [&](bf16x8 (&f)[4], const bf16_t* pa, const bf16_t* pb, int so) __attribute__((always_inline)) {
;     f[0] = *(const bf16x8*)(pa + so); f[1] = *(const bf16x8*)(pb + so); f[2] = *(const bf16x8*)(pb + 32 * 72 + so); f[3] = *(const bf16x8*)(pa + 32 * 72 + so);
;   };
;   auto mfma4 = [&](const bf16x8 (&f)[4]) __attribute__((always_inline)) {
;     if (SWAP) {
;       acc[0][0] = MFMA32(f[1], f[0], acc[0][0]); acc[0][1] = MFMA32(f[2], f[0], acc[0][1]);
;       acc[1][0] = MFMA32(f[1], f[3], acc[1][0]); acc[1][1] = MFMA32(f[2], f[3], acc[1][1]);
;     } else {
;       acc[0][0] = MFMA32(f[0], f[1], acc[0][0]); acc[0][1] = MFMA32(f[0], f[2], acc[0][1]);
;       acc[1][0] = MFMA32(f[3], f[1], acc[1][0]); acc[1][1] = MFMA32(f[3], f[2], acc[1][1]);
;     }
;   };
;   auto step = [&](int buf, u32x4 (&ra)[4], u32x4 (&rb)[4], bool do_write, bool do_load, int tload) __attribute__((always_inline)) {
;     const bf16_t* pa = As + buf * 2 * GT_IMG + pao; const bf16_t* pb = As + buf * 2 * GT_IMG + pbo;
; DI void phase_merge(const Params& p, int g, char* smem, int bid, int nb) {
;     ...
;   while (ts.next(mt, nt)) {
;     f32x16 acc[2][2]; zero_acc(acc);
;     gemm_tile<false>(OA + (size_t)mt * 128 * 1024, 1024, WA + (size_t)nt * 128 * 1024, 1024, 1024, acc, As, Bs);
.LBB0_222:
	s_ashr_i32 s7, s6, 31
	s_add_i32 s13, s13, s14
	s_lshl_b64 s[0:1], s[6:7], 18
	v_readlane_b32 s7, v235, 61
	s_add_u32 s16, s7, s0
	v_readlane_b32 s7, v235, 62
	v_mov_b32_e32 v34, v195
	s_addc_u32 s17, s7, s1
	s_ashr_i32 s11, s10, 31
	s_lshl_b64 s[8:9], s[10:11], 18
	v_ashrrev_i32_e32 v32, 3, v34
	v_readlane_b32 s7, v235, 63
	v_ashrrev_i32_e32 v33, 31, v32
	s_add_u32 s18, s7, s8
	v_readlane_b32 s7, v233, 0
	v_lshlrev_b64 v[0:1], 11, v[32:33]
	s_waitcnt lgkmcnt(0)
	v_lshlrev_b32_e32 v4, 4, v34
	s_addc_u32 s19, s7, s9
	v_lshl_add_u64 v[2:3], s[16:17], 0, v[0:1]
	v_and_b32_e32 v192, 0x70, v4
	v_lshl_add_u64 v[80:81], v[2:3], 0, v[192:193]
	v_lshl_add_u64 v[0:1], s[18:19], 0, v[0:1]
	s_mov_b32 s18, 0x10000
	v_add_co_u32_e32 v84, vcc, s18, v80
	v_lshl_add_u64 v[82:83], v[0:1], 0, v[192:193]
	s_nop 0
	v_addc_co_u32_e32 v85, vcc, 0, v81, vcc
	v_add_co_u32_e32 v86, vcc, s18, v82
	s_mov_b32 s19, 0x20000
	s_nop 0
	v_addc_co_u32_e32 v87, vcc, 0, v83, vcc
	global_load_dwordx4 v[0:3], v[80:81], off
	global_load_dwordx4 v[4:7], v[82:83], off
	v_add_co_u32_e32 v88, vcc, s19, v80
	global_load_dwordx4 v[8:11], v[84:85], off
	global_load_dwordx4 v[12:15], v[86:87], off
	v_addc_co_u32_e32 v89, vcc, 0, v81, vcc
	v_add_co_u32_e32 v90, vcc, s19, v82
	s_mov_b32 s20, 0x30000
	s_nop 0
	v_addc_co_u32_e32 v91, vcc, 0, v83, vcc
	global_load_dwordx4 v[16:19], v[88:89], off
	global_load_dwordx4 v[20:23], v[90:91], off
	v_add_co_u32_e32 v92, vcc, s20, v80
	v_mul_lo_u32 v32, v32, s71
	s_nop 0
	v_addc_co_u32_e32 v93, vcc, 0, v81, vcc
	global_load_dwordx4 v[24:27], v[92:93], off
	v_add_co_u32_e32 v94, vcc, s20, v82
	v_add3_u32 v96, 32, v32, v192
	s_nop 0
	v_addc_co_u32_e32 v95, vcc, 0, v83, vcc
	global_load_dwordx4 v[28:31], v[94:95], off
	global_load_dwordx4 v[100:103], v[80:81], off offset:128
	global_load_dwordx4 v[104:107], v[82:83], off offset:128
	global_load_dwordx4 v[108:111], v[84:85], off offset:128
	global_load_dwordx4 v[112:115], v[86:87], off offset:128
	global_load_dwordx4 v[116:119], v[88:89], off offset:128
	global_load_dwordx4 v[120:123], v[90:91], off offset:128
	global_load_dwordx4 v[124:127], v[92:93], off offset:128
	global_load_dwordx4 v[128:131], v[94:95], off offset:128
	s_waitcnt vmcnt(63) expcnt(7) lgkmcnt(15)
	s_barrier
	v_add_u32_e32 v99, 0xd800, v96
	s_waitcnt vmcnt(15)
	ds_write_b128 v96, v[0:3]
	s_waitcnt vmcnt(14)
	ds_write_b128 v96, v[4:7] offset:18432
	s_waitcnt vmcnt(13)
	ds_write_b128 v96, v[8:11] offset:4608
	s_waitcnt vmcnt(12)
	ds_write_b128 v96, v[12:15] offset:23040
	s_waitcnt vmcnt(11)
	ds_write_b128 v96, v[16:19] offset:9216
	s_waitcnt vmcnt(10)
	ds_write_b128 v96, v[20:23] offset:27648
	s_waitcnt vmcnt(9)
	ds_write_b128 v96, v[24:27] offset:13824
	s_waitcnt vmcnt(8)
	ds_write_b128 v96, v[28:31] offset:32256
	global_load_dwordx4 v[132:135], v[80:81], off offset:256
	global_load_dwordx4 v[64:67], v[82:83], off offset:256
	global_load_dwordx4 v[136:139], v[84:85], off offset:256
	global_load_dwordx4 v[68:71], v[86:87], off offset:256
	global_load_dwordx4 v[140:143], v[88:89], off offset:256
	global_load_dwordx4 v[72:75], v[90:91], off offset:256
	global_load_dwordx4 v[148:151], v[92:93], off offset:256
	global_load_dwordx4 v[76:79], v[94:95], off offset:256
	v_lshrrev_b32_e32 v0, 2, v34
	v_lshrrev_b32_e32 v2, 1, v34
	v_and_b32_e32 v3, 31, v34
	v_and_b32_e32 v1, 0x5f, v34
	v_and_b32_e32 v0, 8, v0
	v_and_or_b32 v2, v2, s80, v3
	v_mad_u64_u32 v[2:3], s[16:17], v2, s72, v[0:1]
	v_lshl_add_u32 v97, v2, 1, 32
	v_mad_u32_u24 v0, v1, s72, v0
	s_waitcnt lgkmcnt(0)
	s_barrier
	v_lshl_add_u32 v98, v0, 1, 32
	ds_read_b128 v[16:19], v97
	ds_read_b128 v[20:23], v98 offset:18432
	ds_read_b128 v[24:27], v98 offset:23040
	ds_read_b128 v[28:31], v97 offset:4608
	ds_read_b128 v[152:155], v98 offset:18464
	ds_read_b128 v[156:159], v98 offset:23072
	ds_read_b128 v[160:163], v97 offset:32
	ds_read_b128 v[164:167], v97 offset:4640
	s_waitcnt lgkmcnt(6)
	v_mfma_f32_32x32x16_bf16 v[0:15], v[16:19], v[20:23], 0
	s_waitcnt lgkmcnt(5)
	v_mfma_f32_32x32x16_bf16 v[32:47], v[16:19], v[24:27], 0
	s_waitcnt lgkmcnt(4)
	v_mfma_f32_32x32x16_bf16 v[48:63], v[28:31], v[20:23], 0
	v_mfma_f32_32x32x16_bf16 v[16:31], v[28:31], v[24:27], 0
	s_waitcnt lgkmcnt(1)
	v_mfma_f32_32x32x16_bf16 v[0:15], v[160:163], v[152:155], v[0:15]
	v_mfma_f32_32x32x16_bf16 v[32:47], v[160:163], v[156:159], v[32:47]
	s_waitcnt lgkmcnt(0)
	v_mfma_f32_32x32x16_bf16 v[48:63], v[164:167], v[152:155], v[48:63]
	ds_read_b128 v[152:155], v98 offset:18496
	ds_read_b128 v[160:163], v98 offset:23104
	ds_read_b128 v[168:171], v97 offset:64
	ds_read_b128 v[172:175], v97 offset:4672
	s_waitcnt vmcnt(15)
	ds_write_b128 v96, v[100:103] offset:36864
	s_waitcnt vmcnt(13)
	ds_write_b128 v96, v[108:111] offset:41472
	s_waitcnt vmcnt(11)
	ds_write_b128 v96, v[116:119] offset:46080
	s_waitcnt vmcnt(9)
	ds_write_b128 v96, v[124:127] offset:50688
	v_mfma_f32_32x32x16_bf16 v[16:31], v[164:167], v[156:159], v[16:31]
	ds_read_b128 v[100:103], v98 offset:18528
	ds_read_b128 v[108:111], v98 offset:23136
	ds_read_b128 v[116:119], v97 offset:96
	ds_read_b128 v[124:127], v97 offset:4704
	s_waitcnt lgkmcnt(9)
	v_mfma_f32_32x32x16_bf16 v[0:15], v[168:171], v[152:155], v[0:15]
	ds_write_b128 v96, v[104:107] offset:55296
	ds_write_b128 v96, v[112:115] offset:59904
	ds_write_b128 v96, v[120:123] offset:64512
	s_waitcnt vmcnt(8)
	ds_write_b128 v99, v[128:131] offset:13824
	v_mfma_f32_32x32x16_bf16 v[32:47], v[168:171], v[160:163], v[32:47]
	s_waitcnt lgkmcnt(12)
	v_mfma_f32_32x32x16_bf16 v[48:63], v[172:175], v[152:155], v[48:63]
	v_mfma_f32_32x32x16_bf16 v[16:31], v[172:175], v[160:163], v[16:31]
	s_waitcnt lgkmcnt(0)
	s_barrier
; template <bool SWAP>
; DI void gemm_tile(const bf16_t* __restrict__ A, int lda, const bf16_t* __restrict__ Bt, int ldb, int K, f32x16 (&acc)[2][2], bf16_t* As, bf16_t* Bs_unused) {
;     ...
;   auto step = [&](int buf, u32x4 (&ra)[4], u32x4 (&rb)[4], bool do_write, bool do_load, int tload) __attribute__((always_inline)) {
;     const bf16_t* pa = As + buf * 2 * GT_IMG + pao; const bf16_t* pb = As + buf * 2 * GT_IMG + pbo;
;     bf16_t* Ad = As + (buf ^ 1) * 2 * GT_IMG; bf16_t* Bd = Ad + GT_IMG;
;     bf16x8 F0[4], F1[4];
;     frag_read(F0, pa, pb, 0);
;     __builtin_amdgcn_sched_barrier(0);
;     frag_read(F1, pa, pb, 16);
;     mfma4(F0);
;     __builtin_amdgcn_sched_barrier(0);
;     frag_read(F0, pa, pb, 32);
;     mfma4(F1);
;     if (do_write) {
; #pragma unroll
;       for (int i = 0; i < 4; ++i) *(u32x4*)(Ad + (lr + 32 * i) * 72 + lc) = ra[i];
;     }
;     __builtin_amdgcn_sched_barrier(0);
;     frag_read(F1, pa, pb, 48);
;     mfma4(F0);
;     if (do_write) {
; #pragma unroll
;       for (int i = 0; i < 4; ++i) *(u32x4*)(Bd + (lr + 32 * i) * 72 + lc) = rb[i];
;     }
;     __builtin_amdgcn_sched_barrier(0);
;     mfma4(F1);
;     if (do_load) load_stage(ra, rb, tload);
;     __builtin_amdgcn_sched_barrier(0);
;   };
;   const int nk = K >> 6;
;   load_stage(ra0, rb0, 0); load_stage(ra1, rb1, 1);
;   __syncthreads();
;   write_stage(ra0, rb0, 0);
;   load_stage(ra0, rb0, 2);
;   __syncthreads();
;   for (int kt = 0; kt < nk; kt += 2) {
;     step(0, ra1, rb1, true, kt + 3 < nk, kt + 3);
;     __syncthreads();
;     step(1, ra0, rb0, kt + 2 < nk, kt + 4 < nk, kt + 4);
;     __syncthreads();
	ds_read_b128 v[152:155], v98 offset:55296
	ds_read_b128 v[156:159], v98 offset:59904
	ds_read_b128 v[160:163], v97 offset:36864
	ds_read_b128 v[164:167], v97 offset:41472
	v_mfma_f32_32x32x16_bf16 v[0:15], v[116:119], v[100:103], v[0:15]
	v_mfma_f32_32x32x16_bf16 v[32:47], v[116:119], v[108:111], v[32:47]
	v_mfma_f32_32x32x16_bf16 v[48:63], v[124:127], v[100:103], v[48:63]
	v_mfma_f32_32x32x16_bf16 v[16:31], v[124:127], v[108:111], v[16:31]
	global_load_dwordx4 v[100:103], v[80:81], off offset:384
	global_load_dwordx4 v[104:107], v[82:83], off offset:384
	global_load_dwordx4 v[108:111], v[84:85], off offset:384
	global_load_dwordx4 v[112:115], v[86:87], off offset:384
	global_load_dwordx4 v[116:119], v[88:89], off offset:384
	global_load_dwordx4 v[120:123], v[90:91], off offset:384
	global_load_dwordx4 v[124:127], v[92:93], off offset:384
	global_load_dwordx4 v[128:131], v[94:95], off offset:384
	s_waitcnt lgkmcnt(1)
	v_mfma_f32_32x32x16_bf16 v[0:15], v[160:163], v[152:155], v[0:15]
	v_mfma_f32_32x32x16_bf16 v[32:47], v[160:163], v[156:159], v[32:47]
	s_waitcnt lgkmcnt(0)
	v_mfma_f32_32x32x16_bf16 v[48:63], v[164:167], v[152:155], v[48:63]
	ds_read_b128 v[152:155], v98 offset:55328
	ds_read_b128 v[160:163], v98 offset:59936
	ds_read_b128 v[168:171], v97 offset:36896
	ds_read_b128 v[172:175], v97 offset:41504
	v_mfma_f32_32x32x16_bf16 v[16:31], v[164:167], v[156:159], v[16:31]
	s_waitcnt lgkmcnt(1)
	v_mfma_f32_32x32x16_bf16 v[0:15], v[168:171], v[152:155], v[0:15]
	v_mfma_f32_32x32x16_bf16 v[32:47], v[168:171], v[160:163], v[32:47]
	s_waitcnt lgkmcnt(0)
	v_mfma_f32_32x32x16_bf16 v[48:63], v[172:175], v[152:155], v[48:63]
	ds_read_b128 v[152:155], v98 offset:55360
	ds_read_b128 v[156:159], v98 offset:59968
	ds_read_b128 v[164:167], v97 offset:36928
	ds_read_b128 v[168:171], v97 offset:41536
	s_waitcnt vmcnt(15)
	ds_write_b128 v96, v[132:135]
	s_waitcnt vmcnt(13)
	ds_write_b128 v96, v[136:139] offset:4608
	s_waitcnt vmcnt(11)
	ds_write_b128 v96, v[140:143] offset:9216
	s_waitcnt vmcnt(9)
	ds_write_b128 v96, v[148:151] offset:13824
	v_mfma_f32_32x32x16_bf16 v[16:31], v[172:175], v[160:163], v[16:31]
	ds_read_b128 v[132:135], v98 offset:55392
	ds_read_b128 v[136:139], v98 offset:60000
	ds_read_b128 v[140:143], v97 offset:36960
	ds_read_b128 v[148:151], v97 offset:41568
	s_waitcnt lgkmcnt(9)
	v_mfma_f32_32x32x16_bf16 v[0:15], v[164:167], v[152:155], v[0:15]
	ds_write_b128 v96, v[64:67] offset:18432
	ds_write_b128 v96, v[68:71] offset:23040
	ds_write_b128 v96, v[72:75] offset:27648
	s_waitcnt vmcnt(8)
	ds_write_b128 v96, v[76:79] offset:32256
	v_mfma_f32_32x32x16_bf16 v[32:47], v[164:167], v[156:159], v[32:47]
	s_waitcnt lgkmcnt(12)
	v_mfma_f32_32x32x16_bf16 v[48:63], v[168:171], v[152:155], v[48:63]
	v_mfma_f32_32x32x16_bf16 v[16:31], v[168:171], v[156:159], v[16:31]
	s_waitcnt lgkmcnt(0)
	s_barrier
	ds_read_b128 v[152:155], v98 offset:18432
	ds_read_b128 v[156:159], v98 offset:23040
	ds_read_b128 v[160:163], v97
	ds_read_b128 v[164:167], v97 offset:4608
	v_mfma_f32_32x32x16_bf16 v[0:15], v[140:143], v[132:135], v[0:15]
	v_mfma_f32_32x32x16_bf16 v[32:47], v[140:143], v[136:139], v[32:47]
	v_mfma_f32_32x32x16_bf16 v[48:63], v[148:151], v[132:135], v[48:63]
	v_mfma_f32_32x32x16_bf16 v[16:31], v[148:151], v[136:139], v[16:31]
	global_load_dwordx4 v[64:67], v[80:81], off offset:512
	global_load_dwordx4 v[68:71], v[82:83], off offset:512
	global_load_dwordx4 v[72:75], v[84:85], off offset:512
	global_load_dwordx4 v[76:79], v[86:87], off offset:512
	global_load_dwordx4 v[132:135], v[88:89], off offset:512
	global_load_dwordx4 v[136:139], v[90:91], off offset:512
	global_load_dwordx4 v[140:143], v[92:93], off offset:512
	global_load_dwordx4 v[148:151], v[94:95], off offset:512
	s_waitcnt lgkmcnt(1)
	v_mfma_f32_32x32x16_bf16 v[0:15], v[160:163], v[152:155], v[0:15]
	v_mfma_f32_32x32x16_bf16 v[32:47], v[160:163], v[156:159], v[32:47]
	s_waitcnt lgkmcnt(0)
	v_mfma_f32_32x32x16_bf16 v[48:63], v[164:167], v[152:155], v[48:63]
	ds_read_b128 v[152:155], v98 offset:18464
	ds_read_b128 v[160:163], v98 offset:23072
	ds_read_b128 v[168:171], v97 offset:32
	ds_read_b128 v[172:175], v97 offset:4640
	v_mfma_f32_32x32x16_bf16 v[16:31], v[164:167], v[156:159], v[16:31]
	s_waitcnt lgkmcnt(1)
	v_mfma_f32_32x32x16_bf16 v[0:15], v[168:171], v[152:155], v[0:15]
	v_mfma_f32_32x32x16_bf16 v[32:47], v[168:171], v[160:163], v[32:47]
	s_waitcnt lgkmcnt(0)
	v_mfma_f32_32x32x16_bf16 v[48:63], v[172:175], v[152:155], v[48:63]
	ds_read_b128 v[152:155], v98 offset:18496
	ds_read_b128 v[156:159], v98 offset:23104
	ds_read_b128 v[164:167], v97 offset:64
	ds_read_b128 v[168:171], v97 offset:4672
	s_waitcnt vmcnt(15)
	ds_write_b128 v96, v[100:103] offset:36864
	s_waitcnt vmcnt(13)
	ds_write_b128 v96, v[108:111] offset:41472
	s_waitcnt vmcnt(11)
	ds_write_b128 v96, v[116:119] offset:46080
	s_waitcnt vmcnt(9)
	ds_write_b128 v96, v[124:127] offset:50688
	v_mfma_f32_32x32x16_bf16 v[16:31], v[172:175], v[160:163], v[16:31]
	ds_read_b128 v[100:103], v98 offset:18528
	ds_read_b128 v[108:111], v98 offset:23136
	ds_read_b128 v[116:119], v97 offset:96
	ds_read_b128 v[124:127], v97 offset:4704
	s_waitcnt lgkmcnt(9)
	v_mfma_f32_32x32x16_bf16 v[0:15], v[164:167], v[152:155], v[0:15]
	ds_write_b128 v96, v[104:107] offset:55296
	ds_write_b128 v96, v[112:115] offset:59904
	ds_write_b128 v96, v[120:123] offset:64512
	s_waitcnt vmcnt(8)
	ds_write_b128 v99, v[128:131] offset:13824
	v_mfma_f32_32x32x16_bf16 v[32:47], v[164:167], v[156:159], v[32:47]
	s_waitcnt lgkmcnt(12)
	v_mfma_f32_32x32x16_bf16 v[48:63], v[168:171], v[152:155], v[48:63]
	v_mfma_f32_32x32x16_bf16 v[16:31], v[168:171], v[156:159], v[16:31]
	s_waitcnt lgkmcnt(0)
	s_barrier
; template <bool SWAP>
; DI void gemm_tile(const bf16_t* __restrict__ A, int lda, const bf16_t* __restrict__ Bt, int ldb, int K, f32x16 (&acc)[2][2], bf16_t* As, bf16_t* Bs_unused) {
;     ...
;   auto step = [&](int buf, u32x4 (&ra)[4], u32x4 (&rb)[4], bool do_write, bool do_load, int tload) __attribute__((always_inline)) {
;     const bf16_t* pa = As + buf * 2 * GT_IMG + pao; const bf16_t* pb = As + buf * 2 * GT_IMG + pbo;
;     bf16_t* Ad = As + (buf ^ 1) * 2 * GT_IMG; bf16_t* Bd = Ad + GT_IMG;
;     bf16x8 F0[4], F1[4];
;     frag_read(F0, pa, pb, 0);
;     __builtin_amdgcn_sched_barrier(0);
;     frag_read(F1, pa, pb, 16);
;     mfma4(F0);
;     __builtin_amdgcn_sched_barrier(0);
;     frag_read(F0, pa, pb, 32);
;     mfma4(F1);
;     if (do_write) {
; #pragma unroll
;       for (int i = 0; i < 4; ++i) *(u32x4*)(Ad + (lr + 32 * i) * 72 + lc) = ra[i];
;     }
;     __builtin_amdgcn_sched_barrier(0);
;     frag_read(F1, pa, pb, 48);
;     mfma4(F0);
;     if (do_write) {
; #pragma unroll
;       for (int i = 0; i < 4; ++i) *(u32x4*)(Bd + (lr + 32 * i) * 72 + lc) = rb[i];
;     }
;     __builtin_amdgcn_sched_barrier(0);
;     mfma4(F1);
;     if (do_load) load_stage(ra, rb, tload);
;     __builtin_amdgcn_sched_barrier(0);
;   };
;   const int nk = K >> 6;
;   load_stage(ra0, rb0, 0); load_stage(ra1, rb1, 1);
;   __syncthreads();
;   write_stage(ra0, rb0, 0);
;   load_stage(ra0, rb0, 2);
;   __syncthreads();
;   for (int kt = 0; kt < nk; kt += 2) {
;     step(0, ra1, rb1, true, kt + 3 < nk, kt + 3);
;     __syncthreads();
;     step(1, ra0, rb0, kt + 2 < nk, kt + 4 < nk, kt + 4);
;     __syncthreads();
	ds_read_b128 v[152:155], v98 offset:55296
	ds_read_b128 v[156:159], v98 offset:59904
	ds_read_b128 v[160:163], v97 offset:36864
	ds_read_b128 v[164:167], v97 offset:41472
	v_mfma_f32_32x32x16_bf16 v[0:15], v[116:119], v[100:103], v[0:15]
	v_mfma_f32_32x32x16_bf16 v[32:47], v[116:119], v[108:111], v[32:47]
	v_mfma_f32_32x32x16_bf16 v[48:63], v[124:127], v[100:103], v[48:63]
	v_mfma_f32_32x32x16_bf16 v[16:31], v[124:127], v[108:111], v[16:31]
	global_load_dwordx4 v[100:103], v[80:81], off offset:640
	global_load_dwordx4 v[104:107], v[82:83], off offset:640
	global_load_dwordx4 v[108:111], v[84:85], off offset:640
	global_load_dwordx4 v[112:115], v[86:87], off offset:640
	global_load_dwordx4 v[116:119], v[88:89], off offset:640
	global_load_dwordx4 v[120:123], v[90:91], off offset:640
	global_load_dwordx4 v[124:127], v[92:93], off offset:640
	global_load_dwordx4 v[128:131], v[94:95], off offset:640
	s_waitcnt lgkmcnt(1)
	v_mfma_f32_32x32x16_bf16 v[0:15], v[160:163], v[152:155], v[0:15]
	v_mfma_f32_32x32x16_bf16 v[32:47], v[160:163], v[156:159], v[32:47]
	s_waitcnt lgkmcnt(0)
	v_mfma_f32_32x32x16_bf16 v[48:63], v[164:167], v[152:155], v[48:63]
	ds_read_b128 v[152:155], v98 offset:55328
	ds_read_b128 v[160:163], v98 offset:59936
	ds_read_b128 v[168:171], v97 offset:36896
	ds_read_b128 v[172:175], v97 offset:41504
	v_mfma_f32_32x32x16_bf16 v[16:31], v[164:167], v[156:159], v[16:31]
	s_waitcnt lgkmcnt(1)
	v_mfma_f32_32x32x16_bf16 v[0:15], v[168:171], v[152:155], v[0:15]
	v_mfma_f32_32x32x16_bf16 v[32:47], v[168:171], v[160:163], v[32:47]
	s_waitcnt lgkmcnt(0)
	v_mfma_f32_32x32x16_bf16 v[48:63], v[172:175], v[152:155], v[48:63]
	ds_read_b128 v[152:155], v98 offset:55360
	ds_read_b128 v[156:159], v98 offset:59968
	ds_read_b128 v[164:167], v97 offset:36928
	ds_read_b128 v[168:171], v97 offset:41536
	s_waitcnt vmcnt(15)
	ds_write_b128 v96, v[64:67]
	s_waitcnt vmcnt(13)
	ds_write_b128 v96, v[72:75] offset:4608
	s_waitcnt vmcnt(11)
	ds_write_b128 v96, v[132:135] offset:9216
	s_waitcnt vmcnt(9)
	ds_write_b128 v96, v[140:143] offset:13824
	v_mfma_f32_32x32x16_bf16 v[16:31], v[172:175], v[160:163], v[16:31]
	ds_read_b128 v[64:67], v98 offset:55392
	ds_read_b128 v[72:75], v98 offset:60000
	ds_read_b128 v[132:135], v97 offset:36960
	ds_read_b128 v[140:143], v97 offset:41568
	s_waitcnt lgkmcnt(9)
	v_mfma_f32_32x32x16_bf16 v[0:15], v[164:167], v[152:155], v[0:15]
	ds_write_b128 v96, v[68:71] offset:18432
	ds_write_b128 v96, v[76:79] offset:23040
	ds_write_b128 v96, v[136:139] offset:27648
	s_waitcnt vmcnt(8)
	ds_write_b128 v96, v[148:151] offset:32256
	v_mfma_f32_32x32x16_bf16 v[32:47], v[164:167], v[156:159], v[32:47]
	s_waitcnt lgkmcnt(12)
	v_mfma_f32_32x32x16_bf16 v[48:63], v[168:171], v[152:155], v[48:63]
	v_mfma_f32_32x32x16_bf16 v[16:31], v[168:171], v[156:159], v[16:31]
	s_waitcnt lgkmcnt(0)
	s_barrier
	ds_read_b128 v[152:155], v98 offset:18432
	ds_read_b128 v[156:159], v98 offset:23040
	ds_read_b128 v[160:163], v97
	ds_read_b128 v[164:167], v97 offset:4608
	v_mfma_f32_32x32x16_bf16 v[0:15], v[132:135], v[64:67], v[0:15]
	v_mfma_f32_32x32x16_bf16 v[32:47], v[132:135], v[72:75], v[32:47]
	v_mfma_f32_32x32x16_bf16 v[48:63], v[140:143], v[64:67], v[48:63]
	v_mfma_f32_32x32x16_bf16 v[16:31], v[140:143], v[72:75], v[16:31]
	global_load_dwordx4 v[64:67], v[80:81], off offset:768
	global_load_dwordx4 v[68:71], v[82:83], off offset:768
	global_load_dwordx4 v[72:75], v[84:85], off offset:768
	global_load_dwordx4 v[76:79], v[86:87], off offset:768
	global_load_dwordx4 v[132:135], v[88:89], off offset:768
	global_load_dwordx4 v[136:139], v[90:91], off offset:768
	global_load_dwordx4 v[140:143], v[92:93], off offset:768
	global_load_dwordx4 v[148:151], v[94:95], off offset:768
	s_waitcnt lgkmcnt(1)
	v_mfma_f32_32x32x16_bf16 v[0:15], v[160:163], v[152:155], v[0:15]
	v_mfma_f32_32x32x16_bf16 v[32:47], v[160:163], v[156:159], v[32:47]
	s_waitcnt lgkmcnt(0)
	v_mfma_f32_32x32x16_bf16 v[48:63], v[164:167], v[152:155], v[48:63]
	ds_read_b128 v[152:155], v98 offset:18464
	ds_read_b128 v[160:163], v98 offset:23072
	ds_read_b128 v[168:171], v97 offset:32
	ds_read_b128 v[172:175], v97 offset:4640
	v_mfma_f32_32x32x16_bf16 v[16:31], v[164:167], v[156:159], v[16:31]
	s_waitcnt lgkmcnt(1)
	v_mfma_f32_32x32x16_bf16 v[0:15], v[168:171], v[152:155], v[0:15]
	v_mfma_f32_32x32x16_bf16 v[32:47], v[168:171], v[160:163], v[32:47]
	s_waitcnt lgkmcnt(0)
	v_mfma_f32_32x32x16_bf16 v[48:63], v[172:175], v[152:155], v[48:63]
	ds_read_b128 v[152:155], v98 offset:18496
	ds_read_b128 v[156:159], v98 offset:23104
	ds_read_b128 v[164:167], v97 offset:64
	ds_read_b128 v[168:171], v97 offset:4672
	s_waitcnt vmcnt(15)
	ds_write_b128 v96, v[100:103] offset:36864
	s_waitcnt vmcnt(13)
	ds_write_b128 v96, v[108:111] offset:41472
	s_waitcnt vmcnt(11)
	ds_write_b128 v96, v[116:119] offset:46080
	s_waitcnt vmcnt(9)
	ds_write_b128 v96, v[124:127] offset:50688
	v_mfma_f32_32x32x16_bf16 v[16:31], v[172:175], v[160:163], v[16:31]
	ds_read_b128 v[100:103], v98 offset:18528
	ds_read_b128 v[108:111], v98 offset:23136
	ds_read_b128 v[116:119], v97 offset:96
	ds_read_b128 v[124:127], v97 offset:4704
	s_waitcnt lgkmcnt(9)
	v_mfma_f32_32x32x16_bf16 v[0:15], v[164:167], v[152:155], v[0:15]
	ds_write_b128 v96, v[104:107] offset:55296
	ds_write_b128 v96, v[112:115] offset:59904
	ds_write_b128 v96, v[120:123] offset:64512
	s_waitcnt vmcnt(8)
	ds_write_b128 v99, v[128:131] offset:13824
	v_mfma_f32_32x32x16_bf16 v[32:47], v[164:167], v[156:159], v[32:47]
	s_waitcnt lgkmcnt(12)
	v_mfma_f32_32x32x16_bf16 v[48:63], v[168:171], v[152:155], v[48:63]
	v_mfma_f32_32x32x16_bf16 v[16:31], v[168:171], v[156:159], v[16:31]
	s_waitcnt lgkmcnt(0)
	s_barrier
; template <bool SWAP>
; DI void gemm_tile(const bf16_t* __restrict__ A, int lda, const bf16_t* __restrict__ Bt, int ldb, int K, f32x16 (&acc)[2][2], bf16_t* As, bf16_t* Bs_unused) {
;     ...
;   auto step = [&](int buf, u32x4 (&ra)[4], u32x4 (&rb)[4], bool do_write, bool do_load, int tload) __attribute__((always_inline)) {
;     const bf16_t* pa = As + buf * 2 * GT_IMG + pao; const bf16_t* pb = As + buf * 2 * GT_IMG + pbo;
;     bf16_t* Ad = As + (buf ^ 1) * 2 * GT_IMG; bf16_t* Bd = Ad + GT_IMG;
;     bf16x8 F0[4], F1[4];
;     frag_read(F0, pa, pb, 0);
;     __builtin_amdgcn_sched_barrier(0);
;     frag_read(F1, pa, pb, 16);
;     mfma4(F0);
;     __builtin_amdgcn_sched_barrier(0);
;     frag_read(F0, pa, pb, 32);
;     mfma4(F1);
;     if (do_write) {
; #pragma unroll
;       for (int i = 0; i < 4; ++i) *(u32x4*)(Ad + (lr + 32 * i) * 72 + lc) = ra[i];
;     }
;     __builtin_amdgcn_sched_barrier(0);
;     frag_read(F1, pa, pb, 48);
;     mfma4(F0);
;     if (do_write) {
; #pragma unroll
;       for (int i = 0; i < 4; ++i) *(u32x4*)(Bd + (lr + 32 * i) * 72 + lc) = rb[i];
;     }
;     __builtin_amdgcn_sched_barrier(0);
;     mfma4(F1);
;     if (do_load) load_stage(ra, rb, tload);
;     __builtin_amdgcn_sched_barrier(0);
;   };
;   const int nk = K >> 6;
;   load_stage(ra0, rb0, 0); load_stage(ra1, rb1, 1);
;   __syncthreads();
;   write_stage(ra0, rb0, 0);
;   load_stage(ra0, rb0, 2);
;   __syncthreads();
;   for (int kt = 0; kt < nk; kt += 2) {
;     step(0, ra1, rb1, true, kt + 3 < nk, kt + 3);
;     __syncthreads();
;     step(1, ra0, rb0, kt + 2 < nk, kt + 4 < nk, kt + 4);
;     __syncthreads();
	ds_read_b128 v[152:155], v98 offset:55296
	ds_read_b128 v[156:159], v98 offset:59904
	ds_read_b128 v[160:163], v97 offset:36864
	ds_read_b128 v[164:167], v97 offset:41472
	v_mfma_f32_32x32x16_bf16 v[0:15], v[116:119], v[100:103], v[0:15]
	v_mfma_f32_32x32x16_bf16 v[32:47], v[116:119], v[108:111], v[32:47]
	v_mfma_f32_32x32x16_bf16 v[48:63], v[124:127], v[100:103], v[48:63]
	v_mfma_f32_32x32x16_bf16 v[16:31], v[124:127], v[108:111], v[16:31]
	global_load_dwordx4 v[100:103], v[80:81], off offset:896
	global_load_dwordx4 v[104:107], v[82:83], off offset:896
	global_load_dwordx4 v[108:111], v[84:85], off offset:896
	global_load_dwordx4 v[112:115], v[86:87], off offset:896
	global_load_dwordx4 v[116:119], v[88:89], off offset:896
	global_load_dwordx4 v[120:123], v[90:91], off offset:896
	global_load_dwordx4 v[124:127], v[92:93], off offset:896
	global_load_dwordx4 v[128:131], v[94:95], off offset:896
	s_waitcnt lgkmcnt(1)
	v_mfma_f32_32x32x16_bf16 v[0:15], v[160:163], v[152:155], v[0:15]
	v_mfma_f32_32x32x16_bf16 v[32:47], v[160:163], v[156:159], v[32:47]
	s_waitcnt lgkmcnt(0)
	v_mfma_f32_32x32x16_bf16 v[48:63], v[164:167], v[152:155], v[48:63]
	ds_read_b128 v[152:155], v98 offset:55328
	ds_read_b128 v[160:163], v98 offset:59936
	ds_read_b128 v[168:171], v97 offset:36896
	ds_read_b128 v[172:175], v97 offset:41504
	v_mfma_f32_32x32x16_bf16 v[16:31], v[164:167], v[156:159], v[16:31]
	s_waitcnt lgkmcnt(1)
	v_mfma_f32_32x32x16_bf16 v[0:15], v[168:171], v[152:155], v[0:15]
	v_mfma_f32_32x32x16_bf16 v[32:47], v[168:171], v[160:163], v[32:47]
	s_waitcnt lgkmcnt(0)
	v_mfma_f32_32x32x16_bf16 v[48:63], v[172:175], v[152:155], v[48:63]
	ds_read_b128 v[152:155], v98 offset:55360
	ds_read_b128 v[156:159], v98 offset:59968
	ds_read_b128 v[164:167], v97 offset:36928
	ds_read_b128 v[168:171], v97 offset:41536
	s_waitcnt vmcnt(15)
	ds_write_b128 v96, v[64:67]
	s_waitcnt vmcnt(13)
	ds_write_b128 v96, v[72:75] offset:4608
	s_waitcnt vmcnt(11)
	ds_write_b128 v96, v[132:135] offset:9216
	s_waitcnt vmcnt(9)
	ds_write_b128 v96, v[140:143] offset:13824
	v_mfma_f32_32x32x16_bf16 v[16:31], v[172:175], v[160:163], v[16:31]
	ds_read_b128 v[64:67], v98 offset:55392
	ds_read_b128 v[72:75], v98 offset:60000
	ds_read_b128 v[132:135], v97 offset:36960
	ds_read_b128 v[140:143], v97 offset:41568
	s_waitcnt lgkmcnt(9)
	v_mfma_f32_32x32x16_bf16 v[0:15], v[164:167], v[152:155], v[0:15]
	ds_write_b128 v96, v[68:71] offset:18432
	ds_write_b128 v96, v[76:79] offset:23040
	ds_write_b128 v96, v[136:139] offset:27648
	s_waitcnt vmcnt(8)
	ds_write_b128 v96, v[148:151] offset:32256
	v_mfma_f32_32x32x16_bf16 v[32:47], v[164:167], v[156:159], v[32:47]
	s_waitcnt lgkmcnt(12)
	v_mfma_f32_32x32x16_bf16 v[48:63], v[168:171], v[152:155], v[48:63]
	v_mfma_f32_32x32x16_bf16 v[16:31], v[168:171], v[156:159], v[16:31]
	s_waitcnt lgkmcnt(0)
	s_barrier
	ds_read_b128 v[152:155], v98 offset:18432
	ds_read_b128 v[156:159], v98 offset:23040
	ds_read_b128 v[160:163], v97
	ds_read_b128 v[164:167], v97 offset:4608
	v_mfma_f32_32x32x16_bf16 v[0:15], v[132:135], v[64:67], v[0:15]
	v_mfma_f32_32x32x16_bf16 v[32:47], v[132:135], v[72:75], v[32:47]
	v_mfma_f32_32x32x16_bf16 v[48:63], v[140:143], v[64:67], v[48:63]
	v_mfma_f32_32x32x16_bf16 v[16:31], v[140:143], v[72:75], v[16:31]
	global_load_dwordx4 v[64:67], v[80:81], off offset:1024
	global_load_dwordx4 v[68:71], v[82:83], off offset:1024
	global_load_dwordx4 v[72:75], v[84:85], off offset:1024
	global_load_dwordx4 v[76:79], v[86:87], off offset:1024
	global_load_dwordx4 v[132:135], v[88:89], off offset:1024
	global_load_dwordx4 v[136:139], v[90:91], off offset:1024
	global_load_dwordx4 v[140:143], v[92:93], off offset:1024
	global_load_dwordx4 v[148:151], v[94:95], off offset:1024
	s_waitcnt lgkmcnt(1)
	v_mfma_f32_32x32x16_bf16 v[0:15], v[160:163], v[152:155], v[0:15]
	v_mfma_f32_32x32x16_bf16 v[32:47], v[160:163], v[156:159], v[32:47]
	s_waitcnt lgkmcnt(0)
	v_mfma_f32_32x32x16_bf16 v[48:63], v[164:167], v[152:155], v[48:63]
	ds_read_b128 v[152:155], v98 offset:18464
	ds_read_b128 v[160:163], v98 offset:23072
	ds_read_b128 v[168:171], v97 offset:32
	ds_read_b128 v[172:175], v97 offset:4640
	v_mfma_f32_32x32x16_bf16 v[16:31], v[164:167], v[156:159], v[16:31]
	s_waitcnt lgkmcnt(1)
	v_mfma_f32_32x32x16_bf16 v[0:15], v[168:171], v[152:155], v[0:15]
	v_mfma_f32_32x32x16_bf16 v[32:47], v[168:171], v[160:163], v[32:47]
	s_waitcnt lgkmcnt(0)
	v_mfma_f32_32x32x16_bf16 v[48:63], v[172:175], v[152:155], v[48:63]
	ds_read_b128 v[152:155], v98 offset:18496
	ds_read_b128 v[156:159], v98 offset:23104
	ds_read_b128 v[164:167], v97 offset:64
	ds_read_b128 v[168:171], v97 offset:4672
	s_waitcnt vmcnt(15)
	ds_write_b128 v96, v[100:103] offset:36864
	s_waitcnt vmcnt(13)
	ds_write_b128 v96, v[108:111] offset:41472
	s_waitcnt vmcnt(11)
	ds_write_b128 v96, v[116:119] offset:46080
	s_waitcnt vmcnt(9)
	ds_write_b128 v96, v[124:127] offset:50688
	v_mfma_f32_32x32x16_bf16 v[16:31], v[172:175], v[160:163], v[16:31]
	ds_read_b128 v[100:103], v98 offset:18528
	ds_read_b128 v[108:111], v98 offset:23136
	ds_read_b128 v[116:119], v97 offset:96
	ds_read_b128 v[124:127], v97 offset:4704
	s_waitcnt lgkmcnt(9)
	v_mfma_f32_32x32x16_bf16 v[0:15], v[164:167], v[152:155], v[0:15]
	ds_write_b128 v96, v[104:107] offset:55296
	ds_write_b128 v96, v[112:115] offset:59904
	ds_write_b128 v96, v[120:123] offset:64512
	s_waitcnt vmcnt(8)
	ds_write_b128 v99, v[128:131] offset:13824
	v_mfma_f32_32x32x16_bf16 v[32:47], v[164:167], v[156:159], v[32:47]
	s_waitcnt lgkmcnt(12)
	v_mfma_f32_32x32x16_bf16 v[48:63], v[168:171], v[152:155], v[48:63]
	v_mfma_f32_32x32x16_bf16 v[16:31], v[168:171], v[156:159], v[16:31]
	s_waitcnt lgkmcnt(0)
	s_barrier
; template <bool SWAP>
; DI void gemm_tile(const bf16_t* __restrict__ A, int lda, const bf16_t* __restrict__ Bt, int ldb, int K, f32x16 (&acc)[2][2], bf16_t* As, bf16_t* Bs_unused) {
;     ...
;   auto step = [&](int buf, u32x4 (&ra)[4], u32x4 (&rb)[4], bool do_write, bool do_load, int tload) __attribute__((always_inline)) {
;     const bf16_t* pa = As + buf * 2 * GT_IMG + pao; const bf16_t* pb = As + buf * 2 * GT_IMG + pbo;
;     bf16_t* Ad = As + (buf ^ 1) * 2 * GT_IMG; bf16_t* Bd = Ad + GT_IMG;
;     bf16x8 F0[4], F1[4];
;     frag_read(F0, pa, pb, 0);
;     __builtin_amdgcn_sched_barrier(0);
;     frag_read(F1, pa, pb, 16);
;     mfma4(F0);
;     __builtin_amdgcn_sched_barrier(0);
;     frag_read(F0, pa, pb, 32);
;     mfma4(F1);
;     if (do_write) {
; #pragma unroll
;       for (int i = 0; i < 4; ++i) *(u32x4*)(Ad + (lr + 32 * i) * 72 + lc) = ra[i];
;     }
;     __builtin_amdgcn_sched_barrier(0);
;     frag_read(F1, pa, pb, 48);
;     mfma4(F0);
;     if (do_write) {
; #pragma unroll
;       for (int i = 0; i < 4; ++i) *(u32x4*)(Bd + (lr + 32 * i) * 72 + lc) = rb[i];
;     }
;     __builtin_amdgcn_sched_barrier(0);
;     mfma4(F1);
;     if (do_load) load_stage(ra, rb, tload);
;     __builtin_amdgcn_sched_barrier(0);
;   };
;   const int nk = K >> 6;
;   load_stage(ra0, rb0, 0); load_stage(ra1, rb1, 1);
;   __syncthreads();
;   write_stage(ra0, rb0, 0);
;   load_stage(ra0, rb0, 2);
;   __syncthreads();
;   for (int kt = 0; kt < nk; kt += 2) {
;     step(0, ra1, rb1, true, kt + 3 < nk, kt + 3);
;     __syncthreads();
;     step(1, ra0, rb0, kt + 2 < nk, kt + 4 < nk, kt + 4);
;     __syncthreads();
	ds_read_b128 v[152:155], v98 offset:55296
	ds_read_b128 v[156:159], v98 offset:59904
	ds_read_b128 v[160:163], v97 offset:36864
	ds_read_b128 v[164:167], v97 offset:41472
	v_mfma_f32_32x32x16_bf16 v[0:15], v[116:119], v[100:103], v[0:15]
	v_mfma_f32_32x32x16_bf16 v[32:47], v[116:119], v[108:111], v[32:47]
	v_mfma_f32_32x32x16_bf16 v[48:63], v[124:127], v[100:103], v[48:63]
	v_mfma_f32_32x32x16_bf16 v[16:31], v[124:127], v[108:111], v[16:31]
	global_load_dwordx4 v[100:103], v[80:81], off offset:1152
	global_load_dwordx4 v[104:107], v[82:83], off offset:1152
	global_load_dwordx4 v[108:111], v[84:85], off offset:1152
	global_load_dwordx4 v[112:115], v[86:87], off offset:1152
	global_load_dwordx4 v[116:119], v[88:89], off offset:1152
	global_load_dwordx4 v[120:123], v[90:91], off offset:1152
	global_load_dwordx4 v[124:127], v[92:93], off offset:1152
	global_load_dwordx4 v[128:131], v[94:95], off offset:1152
	s_waitcnt lgkmcnt(1)
	v_mfma_f32_32x32x16_bf16 v[0:15], v[160:163], v[152:155], v[0:15]
	v_mfma_f32_32x32x16_bf16 v[32:47], v[160:163], v[156:159], v[32:47]
	s_waitcnt lgkmcnt(0)
	v_mfma_f32_32x32x16_bf16 v[48:63], v[164:167], v[152:155], v[48:63]
	ds_read_b128 v[152:155], v98 offset:55328
	ds_read_b128 v[160:163], v98 offset:59936
	ds_read_b128 v[168:171], v97 offset:36896
	ds_read_b128 v[172:175], v97 offset:41504
	v_mfma_f32_32x32x16_bf16 v[16:31], v[164:167], v[156:159], v[16:31]
	s_waitcnt lgkmcnt(1)
	v_mfma_f32_32x32x16_bf16 v[0:15], v[168:171], v[152:155], v[0:15]
	v_mfma_f32_32x32x16_bf16 v[32:47], v[168:171], v[160:163], v[32:47]
	s_waitcnt lgkmcnt(0)
	v_mfma_f32_32x32x16_bf16 v[48:63], v[172:175], v[152:155], v[48:63]
	ds_read_b128 v[152:155], v98 offset:55360
	ds_read_b128 v[156:159], v98 offset:59968
	ds_read_b128 v[164:167], v97 offset:36928
	ds_read_b128 v[168:171], v97 offset:41536
	s_waitcnt vmcnt(15)
	ds_write_b128 v96, v[64:67]
	s_waitcnt vmcnt(13)
	ds_write_b128 v96, v[72:75] offset:4608
	s_waitcnt vmcnt(11)
	ds_write_b128 v96, v[132:135] offset:9216
	s_waitcnt vmcnt(9)
	ds_write_b128 v96, v[140:143] offset:13824
	v_mfma_f32_32x32x16_bf16 v[16:31], v[172:175], v[160:163], v[16:31]
	ds_read_b128 v[64:67], v98 offset:55392
	ds_read_b128 v[72:75], v98 offset:60000
	ds_read_b128 v[132:135], v97 offset:36960
	ds_read_b128 v[140:143], v97 offset:41568
	s_waitcnt lgkmcnt(9)
	v_mfma_f32_32x32x16_bf16 v[0:15], v[164:167], v[152:155], v[0:15]
	ds_write_b128 v96, v[68:71] offset:18432
	ds_write_b128 v96, v[76:79] offset:23040
	ds_write_b128 v96, v[136:139] offset:27648
	s_waitcnt vmcnt(8)
	ds_write_b128 v96, v[148:151] offset:32256
	v_mfma_f32_32x32x16_bf16 v[32:47], v[164:167], v[156:159], v[32:47]
	s_waitcnt lgkmcnt(12)
	v_mfma_f32_32x32x16_bf16 v[48:63], v[168:171], v[152:155], v[48:63]
	v_mfma_f32_32x32x16_bf16 v[16:31], v[168:171], v[156:159], v[16:31]
	s_waitcnt lgkmcnt(0)
	s_barrier
	ds_read_b128 v[152:155], v98 offset:18432
	ds_read_b128 v[156:159], v98 offset:23040
	ds_read_b128 v[160:163], v97
	ds_read_b128 v[164:167], v97 offset:4608
	v_mfma_f32_32x32x16_bf16 v[0:15], v[132:135], v[64:67], v[0:15]
	v_mfma_f32_32x32x16_bf16 v[32:47], v[132:135], v[72:75], v[32:47]
	v_mfma_f32_32x32x16_bf16 v[48:63], v[140:143], v[64:67], v[48:63]
	v_mfma_f32_32x32x16_bf16 v[16:31], v[140:143], v[72:75], v[16:31]
	global_load_dwordx4 v[64:67], v[80:81], off offset:1280
	global_load_dwordx4 v[68:71], v[82:83], off offset:1280
	global_load_dwordx4 v[72:75], v[84:85], off offset:1280
	global_load_dwordx4 v[76:79], v[86:87], off offset:1280
	global_load_dwordx4 v[132:135], v[88:89], off offset:1280
	global_load_dwordx4 v[136:139], v[90:91], off offset:1280
	global_load_dwordx4 v[140:143], v[92:93], off offset:1280
	global_load_dwordx4 v[148:151], v[94:95], off offset:1280
	s_waitcnt lgkmcnt(1)
	v_mfma_f32_32x32x16_bf16 v[0:15], v[160:163], v[152:155], v[0:15]
	v_mfma_f32_32x32x16_bf16 v[32:47], v[160:163], v[156:159], v[32:47]
	s_waitcnt lgkmcnt(0)
	v_mfma_f32_32x32x16_bf16 v[48:63], v[164:167], v[152:155], v[48:63]
	ds_read_b128 v[152:155], v98 offset:18464
	ds_read_b128 v[160:163], v98 offset:23072
	ds_read_b128 v[168:171], v97 offset:32
	ds_read_b128 v[172:175], v97 offset:4640
	v_mfma_f32_32x32x16_bf16 v[16:31], v[164:167], v[156:159], v[16:31]
	s_waitcnt lgkmcnt(1)
	v_mfma_f32_32x32x16_bf16 v[0:15], v[168:171], v[152:155], v[0:15]
	v_mfma_f32_32x32x16_bf16 v[32:47], v[168:171], v[160:163], v[32:47]
	s_waitcnt lgkmcnt(0)
	v_mfma_f32_32x32x16_bf16 v[48:63], v[172:175], v[152:155], v[48:63]
	ds_read_b128 v[152:155], v98 offset:18496
	ds_read_b128 v[156:159], v98 offset:23104
	ds_read_b128 v[164:167], v97 offset:64
	ds_read_b128 v[168:171], v97 offset:4672
	s_waitcnt vmcnt(15)
	ds_write_b128 v96, v[100:103] offset:36864
	s_waitcnt vmcnt(13)
	ds_write_b128 v96, v[108:111] offset:41472
	s_waitcnt vmcnt(11)
	ds_write_b128 v96, v[116:119] offset:46080
	s_waitcnt vmcnt(9)
	ds_write_b128 v96, v[124:127] offset:50688
	v_mfma_f32_32x32x16_bf16 v[16:31], v[172:175], v[160:163], v[16:31]
	ds_read_b128 v[100:103], v98 offset:18528
	ds_read_b128 v[108:111], v98 offset:23136
	ds_read_b128 v[116:119], v97 offset:96
	ds_read_b128 v[124:127], v97 offset:4704
	s_waitcnt lgkmcnt(9)
	v_mfma_f32_32x32x16_bf16 v[0:15], v[164:167], v[152:155], v[0:15]
	ds_write_b128 v96, v[104:107] offset:55296
	ds_write_b128 v96, v[112:115] offset:59904
	ds_write_b128 v96, v[120:123] offset:64512
	s_waitcnt vmcnt(8)
	ds_write_b128 v99, v[128:131] offset:13824
	v_mfma_f32_32x32x16_bf16 v[32:47], v[164:167], v[156:159], v[32:47]
	s_waitcnt lgkmcnt(12)
	v_mfma_f32_32x32x16_bf16 v[48:63], v[168:171], v[152:155], v[48:63]
	v_mfma_f32_32x32x16_bf16 v[16:31], v[168:171], v[156:159], v[16:31]
	s_waitcnt lgkmcnt(0)
	s_barrier
; template <bool SWAP>
; DI void gemm_tile(const bf16_t* __restrict__ A, int lda, const bf16_t* __restrict__ Bt, int ldb, int K, f32x16 (&acc)[2][2], bf16_t* As, bf16_t* Bs_unused) {
;     ...
;   auto step = [&](int buf, u32x4 (&ra)[4], u32x4 (&rb)[4], bool do_write, bool do_load, int tload) __attribute__((always_inline)) {
;     const bf16_t* pa = As + buf * 2 * GT_IMG + pao; const bf16_t* pb = As + buf * 2 * GT_IMG + pbo;
;     bf16_t* Ad = As + (buf ^ 1) * 2 * GT_IMG; bf16_t* Bd = Ad + GT_IMG;
;     bf16x8 F0[4], F1[4];
;     frag_read(F0, pa, pb, 0);
;     __builtin_amdgcn_sched_barrier(0);
;     frag_read(F1, pa, pb, 16);
;     mfma4(F0);
;     __builtin_amdgcn_sched_barrier(0);
;     frag_read(F0, pa, pb, 32);
;     mfma4(F1);
;     if (do_write) {
; #pragma unroll
;       for (int i = 0; i < 4; ++i) *(u32x4*)(Ad + (lr + 32 * i) * 72 + lc) = ra[i];
;     }
;     __builtin_amdgcn_sched_barrier(0);
;     frag_read(F1, pa, pb, 48);
;     mfma4(F0);
;     if (do_write) {
; #pragma unroll
;       for (int i = 0; i < 4; ++i) *(u32x4*)(Bd + (lr + 32 * i) * 72 + lc) = rb[i];
;     }
;     __builtin_amdgcn_sched_barrier(0);
;     mfma4(F1);
;     if (do_load) load_stage(ra, rb, tload);
;     __builtin_amdgcn_sched_barrier(0);
;   };
;   const int nk = K >> 6;
;   load_stage(ra0, rb0, 0); load_stage(ra1, rb1, 1);
;   __syncthreads();
;   write_stage(ra0, rb0, 0);
;   load_stage(ra0, rb0, 2);
;   __syncthreads();
;   for (int kt = 0; kt < nk; kt += 2) {
;     step(0, ra1, rb1, true, kt + 3 < nk, kt + 3);
;     __syncthreads();
;     step(1, ra0, rb0, kt + 2 < nk, kt + 4 < nk, kt + 4);
;     __syncthreads();
	ds_read_b128 v[152:155], v98 offset:55296
	ds_read_b128 v[156:159], v98 offset:59904
	ds_read_b128 v[160:163], v97 offset:36864
	ds_read_b128 v[164:167], v97 offset:41472
	v_mfma_f32_32x32x16_bf16 v[0:15], v[116:119], v[100:103], v[0:15]
	v_mfma_f32_32x32x16_bf16 v[32:47], v[116:119], v[108:111], v[32:47]
	v_mfma_f32_32x32x16_bf16 v[48:63], v[124:127], v[100:103], v[48:63]
	v_mfma_f32_32x32x16_bf16 v[16:31], v[124:127], v[108:111], v[16:31]
	global_load_dwordx4 v[100:103], v[80:81], off offset:1408
	global_load_dwordx4 v[104:107], v[82:83], off offset:1408
	global_load_dwordx4 v[108:111], v[84:85], off offset:1408
	global_load_dwordx4 v[112:115], v[86:87], off offset:1408
	global_load_dwordx4 v[116:119], v[88:89], off offset:1408
	global_load_dwordx4 v[120:123], v[90:91], off offset:1408
	global_load_dwordx4 v[124:127], v[92:93], off offset:1408
	global_load_dwordx4 v[128:131], v[94:95], off offset:1408
	s_waitcnt lgkmcnt(1)
	v_mfma_f32_32x32x16_bf16 v[0:15], v[160:163], v[152:155], v[0:15]
	v_mfma_f32_32x32x16_bf16 v[32:47], v[160:163], v[156:159], v[32:47]
	s_waitcnt lgkmcnt(0)
	v_mfma_f32_32x32x16_bf16 v[48:63], v[164:167], v[152:155], v[48:63]
	ds_read_b128 v[152:155], v98 offset:55328
	ds_read_b128 v[160:163], v98 offset:59936
	ds_read_b128 v[168:171], v97 offset:36896
	ds_read_b128 v[172:175], v97 offset:41504
	v_mfma_f32_32x32x16_bf16 v[16:31], v[164:167], v[156:159], v[16:31]
	s_waitcnt lgkmcnt(1)
	v_mfma_f32_32x32x16_bf16 v[0:15], v[168:171], v[152:155], v[0:15]
	v_mfma_f32_32x32x16_bf16 v[32:47], v[168:171], v[160:163], v[32:47]
	s_waitcnt lgkmcnt(0)
	v_mfma_f32_32x32x16_bf16 v[48:63], v[172:175], v[152:155], v[48:63]
	ds_read_b128 v[152:155], v98 offset:55360
	ds_read_b128 v[156:159], v98 offset:59968
	ds_read_b128 v[164:167], v97 offset:36928
	ds_read_b128 v[168:171], v97 offset:41536
	s_waitcnt vmcnt(15)
	ds_write_b128 v96, v[64:67]
	s_waitcnt vmcnt(13)
	ds_write_b128 v96, v[72:75] offset:4608
	s_waitcnt vmcnt(11)
	ds_write_b128 v96, v[132:135] offset:9216
	s_waitcnt vmcnt(9)
	ds_write_b128 v96, v[140:143] offset:13824
	v_mfma_f32_32x32x16_bf16 v[16:31], v[172:175], v[160:163], v[16:31]
	ds_read_b128 v[64:67], v98 offset:55392
	ds_read_b128 v[72:75], v98 offset:60000
	ds_read_b128 v[132:135], v97 offset:36960
	ds_read_b128 v[140:143], v97 offset:41568
	s_waitcnt lgkmcnt(9)
	v_mfma_f32_32x32x16_bf16 v[0:15], v[164:167], v[152:155], v[0:15]
	ds_write_b128 v96, v[68:71] offset:18432
	ds_write_b128 v96, v[76:79] offset:23040
	ds_write_b128 v96, v[136:139] offset:27648
	s_waitcnt vmcnt(8)
	ds_write_b128 v96, v[148:151] offset:32256
	v_mfma_f32_32x32x16_bf16 v[32:47], v[164:167], v[156:159], v[32:47]
	s_waitcnt lgkmcnt(12)
	v_mfma_f32_32x32x16_bf16 v[48:63], v[168:171], v[152:155], v[48:63]
	v_mfma_f32_32x32x16_bf16 v[16:31], v[168:171], v[156:159], v[16:31]
	s_waitcnt lgkmcnt(0)
	s_barrier
	ds_read_b128 v[152:155], v98 offset:18432
	ds_read_b128 v[156:159], v98 offset:23040
	ds_read_b128 v[160:163], v97
	ds_read_b128 v[164:167], v97 offset:4608
	v_mfma_f32_32x32x16_bf16 v[0:15], v[132:135], v[64:67], v[0:15]
	v_mfma_f32_32x32x16_bf16 v[32:47], v[132:135], v[72:75], v[32:47]
	v_mfma_f32_32x32x16_bf16 v[48:63], v[140:143], v[64:67], v[48:63]
	v_mfma_f32_32x32x16_bf16 v[16:31], v[140:143], v[72:75], v[16:31]
	global_load_dwordx4 v[64:67], v[80:81], off offset:1536
	global_load_dwordx4 v[68:71], v[82:83], off offset:1536
	global_load_dwordx4 v[72:75], v[84:85], off offset:1536
	global_load_dwordx4 v[76:79], v[86:87], off offset:1536
	global_load_dwordx4 v[132:135], v[88:89], off offset:1536
	global_load_dwordx4 v[136:139], v[90:91], off offset:1536
	global_load_dwordx4 v[140:143], v[92:93], off offset:1536
	global_load_dwordx4 v[148:151], v[94:95], off offset:1536
	s_waitcnt lgkmcnt(1)
	v_mfma_f32_32x32x16_bf16 v[0:15], v[160:163], v[152:155], v[0:15]
	v_mfma_f32_32x32x16_bf16 v[32:47], v[160:163], v[156:159], v[32:47]
	s_waitcnt lgkmcnt(0)
	v_mfma_f32_32x32x16_bf16 v[48:63], v[164:167], v[152:155], v[48:63]
	ds_read_b128 v[152:155], v98 offset:18464
	ds_read_b128 v[160:163], v98 offset:23072
	ds_read_b128 v[168:171], v97 offset:32
	ds_read_b128 v[172:175], v97 offset:4640
	v_mfma_f32_32x32x16_bf16 v[16:31], v[164:167], v[156:159], v[16:31]
	s_waitcnt lgkmcnt(1)
	v_mfma_f32_32x32x16_bf16 v[0:15], v[168:171], v[152:155], v[0:15]
	v_mfma_f32_32x32x16_bf16 v[32:47], v[168:171], v[160:163], v[32:47]
	s_waitcnt lgkmcnt(0)
	v_mfma_f32_32x32x16_bf16 v[48:63], v[172:175], v[152:155], v[48:63]
	ds_read_b128 v[152:155], v98 offset:18496
	ds_read_b128 v[156:159], v98 offset:23104
	ds_read_b128 v[164:167], v97 offset:64
	ds_read_b128 v[168:171], v97 offset:4672
	s_waitcnt vmcnt(15)
	ds_write_b128 v96, v[100:103] offset:36864
	s_waitcnt vmcnt(13)
	ds_write_b128 v96, v[108:111] offset:41472
	s_waitcnt vmcnt(11)
	ds_write_b128 v96, v[116:119] offset:46080
	s_waitcnt vmcnt(9)
	ds_write_b128 v96, v[124:127] offset:50688
	v_mfma_f32_32x32x16_bf16 v[16:31], v[172:175], v[160:163], v[16:31]
	ds_read_b128 v[100:103], v98 offset:18528
	ds_read_b128 v[108:111], v98 offset:23136
	ds_read_b128 v[116:119], v97 offset:96
	ds_read_b128 v[124:127], v97 offset:4704
	s_waitcnt lgkmcnt(9)
	v_mfma_f32_32x32x16_bf16 v[0:15], v[164:167], v[152:155], v[0:15]
	ds_write_b128 v96, v[104:107] offset:55296
	ds_write_b128 v96, v[112:115] offset:59904
	ds_write_b128 v96, v[120:123] offset:64512
	s_waitcnt vmcnt(8)
	ds_write_b128 v99, v[128:131] offset:13824
	v_mfma_f32_32x32x16_bf16 v[32:47], v[164:167], v[156:159], v[32:47]
	s_waitcnt lgkmcnt(12)
	v_mfma_f32_32x32x16_bf16 v[48:63], v[168:171], v[152:155], v[48:63]
	v_mfma_f32_32x32x16_bf16 v[16:31], v[168:171], v[156:159], v[16:31]
	s_waitcnt lgkmcnt(0)
	s_barrier
; template <bool SWAP>
; DI void gemm_tile(const bf16_t* __restrict__ A, int lda, const bf16_t* __restrict__ Bt, int ldb, int K, f32x16 (&acc)[2][2], bf16_t* As, bf16_t* Bs_unused) {
;     ...
;   auto step = [&](int buf, u32x4 (&ra)[4], u32x4 (&rb)[4], bool do_write, bool do_load, int tload) __attribute__((always_inline)) {
;     const bf16_t* pa = As + buf * 2 * GT_IMG + pao; const bf16_t* pb = As + buf * 2 * GT_IMG + pbo;
;     bf16_t* Ad = As + (buf ^ 1) * 2 * GT_IMG; bf16_t* Bd = Ad + GT_IMG;
;     bf16x8 F0[4], F1[4];
;     frag_read(F0, pa, pb, 0);
;     __builtin_amdgcn_sched_barrier(0);
;     frag_read(F1, pa, pb, 16);
;     mfma4(F0);
;     __builtin_amdgcn_sched_barrier(0);
;     frag_read(F0, pa, pb, 32);
;     mfma4(F1);
;     if (do_write) {
; #pragma unroll
;       for (int i = 0; i < 4; ++i) *(u32x4*)(Ad + (lr + 32 * i) * 72 + lc) = ra[i];
;     }
;     __builtin_amdgcn_sched_barrier(0);
;     frag_read(F1, pa, pb, 48);
;     mfma4(F0);
;     if (do_write) {
; #pragma unroll
;       for (int i = 0; i < 4; ++i) *(u32x4*)(Bd + (lr + 32 * i) * 72 + lc) = rb[i];
;     }
;     __builtin_amdgcn_sched_barrier(0);
;     mfma4(F1);
;     if (do_load) load_stage(ra, rb, tload);
;     __builtin_amdgcn_sched_barrier(0);
;   };
;   const int nk = K >> 6;
;   load_stage(ra0, rb0, 0); load_stage(ra1, rb1, 1);
;   __syncthreads();
;   write_stage(ra0, rb0, 0);
;   load_stage(ra0, rb0, 2);
;   __syncthreads();
;   for (int kt = 0; kt < nk; kt += 2) {
;     step(0, ra1, rb1, true, kt + 3 < nk, kt + 3);
;     __syncthreads();
;     step(1, ra0, rb0, kt + 2 < nk, kt + 4 < nk, kt + 4);
;     __syncthreads();
	ds_read_b128 v[152:155], v98 offset:55296
	ds_read_b128 v[156:159], v98 offset:59904
	ds_read_b128 v[160:163], v97 offset:36864
	ds_read_b128 v[164:167], v97 offset:41472
	v_mfma_f32_32x32x16_bf16 v[0:15], v[116:119], v[100:103], v[0:15]
	v_mfma_f32_32x32x16_bf16 v[32:47], v[116:119], v[108:111], v[32:47]
	v_mfma_f32_32x32x16_bf16 v[48:63], v[124:127], v[100:103], v[48:63]
	v_mfma_f32_32x32x16_bf16 v[16:31], v[124:127], v[108:111], v[16:31]
	global_load_dwordx4 v[100:103], v[80:81], off offset:1664
	global_load_dwordx4 v[104:107], v[82:83], off offset:1664
	global_load_dwordx4 v[108:111], v[84:85], off offset:1664
	global_load_dwordx4 v[112:115], v[86:87], off offset:1664
	global_load_dwordx4 v[116:119], v[88:89], off offset:1664
	global_load_dwordx4 v[120:123], v[90:91], off offset:1664
	global_load_dwordx4 v[124:127], v[92:93], off offset:1664
	global_load_dwordx4 v[128:131], v[94:95], off offset:1664
	s_waitcnt lgkmcnt(1)
	v_mfma_f32_32x32x16_bf16 v[0:15], v[160:163], v[152:155], v[0:15]
	v_mfma_f32_32x32x16_bf16 v[32:47], v[160:163], v[156:159], v[32:47]
	s_waitcnt lgkmcnt(0)
	v_mfma_f32_32x32x16_bf16 v[48:63], v[164:167], v[152:155], v[48:63]
	ds_read_b128 v[152:155], v98 offset:55328
	ds_read_b128 v[160:163], v98 offset:59936
	ds_read_b128 v[168:171], v97 offset:36896
	ds_read_b128 v[172:175], v97 offset:41504
	v_mfma_f32_32x32x16_bf16 v[16:31], v[164:167], v[156:159], v[16:31]
	s_waitcnt lgkmcnt(1)
	v_mfma_f32_32x32x16_bf16 v[0:15], v[168:171], v[152:155], v[0:15]
	v_mfma_f32_32x32x16_bf16 v[32:47], v[168:171], v[160:163], v[32:47]
	s_waitcnt lgkmcnt(0)
	v_mfma_f32_32x32x16_bf16 v[48:63], v[172:175], v[152:155], v[48:63]
	ds_read_b128 v[152:155], v98 offset:55360
	ds_read_b128 v[156:159], v98 offset:59968
	ds_read_b128 v[164:167], v97 offset:36928
	ds_read_b128 v[168:171], v97 offset:41536
	s_waitcnt vmcnt(15)
	ds_write_b128 v96, v[64:67]
	s_waitcnt vmcnt(13)
	ds_write_b128 v96, v[72:75] offset:4608
	s_waitcnt vmcnt(11)
	ds_write_b128 v96, v[132:135] offset:9216
	s_waitcnt vmcnt(9)
	ds_write_b128 v96, v[140:143] offset:13824
	v_mfma_f32_32x32x16_bf16 v[16:31], v[172:175], v[160:163], v[16:31]
	ds_read_b128 v[64:67], v98 offset:55392
	ds_read_b128 v[72:75], v98 offset:60000
	ds_read_b128 v[132:135], v97 offset:36960
	ds_read_b128 v[140:143], v97 offset:41568
	s_waitcnt lgkmcnt(9)
	v_mfma_f32_32x32x16_bf16 v[0:15], v[164:167], v[152:155], v[0:15]
	ds_write_b128 v96, v[68:71] offset:18432
	ds_write_b128 v96, v[76:79] offset:23040
	ds_write_b128 v96, v[136:139] offset:27648
	s_waitcnt vmcnt(8)
	ds_write_b128 v96, v[148:151] offset:32256
	v_mfma_f32_32x32x16_bf16 v[32:47], v[164:167], v[156:159], v[32:47]
	s_waitcnt lgkmcnt(12)
	v_mfma_f32_32x32x16_bf16 v[48:63], v[168:171], v[152:155], v[48:63]
	v_mfma_f32_32x32x16_bf16 v[16:31], v[168:171], v[156:159], v[16:31]
	s_waitcnt lgkmcnt(0)
	s_barrier
	ds_read_b128 v[152:155], v98 offset:18432
	ds_read_b128 v[156:159], v98 offset:23040
	ds_read_b128 v[160:163], v97
	ds_read_b128 v[164:167], v97 offset:4608
	v_mfma_f32_32x32x16_bf16 v[0:15], v[132:135], v[64:67], v[0:15]
	v_mfma_f32_32x32x16_bf16 v[32:47], v[132:135], v[72:75], v[32:47]
	v_mfma_f32_32x32x16_bf16 v[48:63], v[140:143], v[64:67], v[48:63]
	v_mfma_f32_32x32x16_bf16 v[16:31], v[140:143], v[72:75], v[16:31]
	global_load_dwordx4 v[64:67], v[80:81], off offset:1792
	global_load_dwordx4 v[68:71], v[82:83], off offset:1792
	global_load_dwordx4 v[72:75], v[84:85], off offset:1792
	global_load_dwordx4 v[76:79], v[86:87], off offset:1792
	global_load_dwordx4 v[132:135], v[88:89], off offset:1792
	global_load_dwordx4 v[136:139], v[90:91], off offset:1792
	global_load_dwordx4 v[140:143], v[92:93], off offset:1792
	global_load_dwordx4 v[148:151], v[94:95], off offset:1792
	s_waitcnt lgkmcnt(1)
	v_mfma_f32_32x32x16_bf16 v[0:15], v[160:163], v[152:155], v[0:15]
	v_mfma_f32_32x32x16_bf16 v[32:47], v[160:163], v[156:159], v[32:47]
	s_waitcnt lgkmcnt(0)
	v_mfma_f32_32x32x16_bf16 v[48:63], v[164:167], v[152:155], v[48:63]
	ds_read_b128 v[152:155], v98 offset:18464
	ds_read_b128 v[160:163], v98 offset:23072
	ds_read_b128 v[168:171], v97 offset:32
	ds_read_b128 v[172:175], v97 offset:4640
	v_mfma_f32_32x32x16_bf16 v[16:31], v[164:167], v[156:159], v[16:31]
	s_waitcnt lgkmcnt(1)
	v_mfma_f32_32x32x16_bf16 v[0:15], v[168:171], v[152:155], v[0:15]
	v_mfma_f32_32x32x16_bf16 v[32:47], v[168:171], v[160:163], v[32:47]
	s_waitcnt lgkmcnt(0)
	v_mfma_f32_32x32x16_bf16 v[48:63], v[172:175], v[152:155], v[48:63]
	ds_read_b128 v[152:155], v98 offset:18496
	ds_read_b128 v[156:159], v98 offset:23104
	ds_read_b128 v[164:167], v97 offset:64
	ds_read_b128 v[168:171], v97 offset:4672
	s_waitcnt vmcnt(15)
	ds_write_b128 v96, v[100:103] offset:36864
	s_waitcnt vmcnt(13)
	ds_write_b128 v96, v[108:111] offset:41472
	s_waitcnt vmcnt(11)
	ds_write_b128 v96, v[116:119] offset:46080
	s_waitcnt vmcnt(9)
	ds_write_b128 v96, v[124:127] offset:50688
	v_mfma_f32_32x32x16_bf16 v[16:31], v[172:175], v[160:163], v[16:31]
	ds_read_b128 v[100:103], v98 offset:18528
	ds_read_b128 v[108:111], v98 offset:23136
	ds_read_b128 v[116:119], v97 offset:96
	ds_read_b128 v[124:127], v97 offset:4704
	s_waitcnt lgkmcnt(9)
	v_mfma_f32_32x32x16_bf16 v[0:15], v[164:167], v[152:155], v[0:15]
	ds_write_b128 v96, v[104:107] offset:55296
	ds_write_b128 v96, v[112:115] offset:59904
	ds_write_b128 v96, v[120:123] offset:64512
	s_waitcnt vmcnt(8)
	ds_write_b128 v99, v[128:131] offset:13824
	v_mfma_f32_32x32x16_bf16 v[32:47], v[164:167], v[156:159], v[32:47]
	s_waitcnt lgkmcnt(12)
	v_mfma_f32_32x32x16_bf16 v[48:63], v[168:171], v[152:155], v[48:63]
	v_mfma_f32_32x32x16_bf16 v[16:31], v[168:171], v[156:159], v[16:31]
	s_waitcnt lgkmcnt(0)
	s_barrier
; template <bool SWAP>
; DI void gemm_tile(const bf16_t* __restrict__ A, int lda, const bf16_t* __restrict__ Bt, int ldb, int K, f32x16 (&acc)[2][2], bf16_t* As, bf16_t* Bs_unused) {
;     ...
;   auto step = [&](int buf, u32x4 (&ra)[4], u32x4 (&rb)[4], bool do_write, bool do_load, int tload) __attribute__((always_inline)) {
;     const bf16_t* pa = As + buf * 2 * GT_IMG + pao; const bf16_t* pb = As + buf * 2 * GT_IMG + pbo;
;     bf16_t* Ad = As + (buf ^ 1) * 2 * GT_IMG; bf16_t* Bd = Ad + GT_IMG;
;     bf16x8 F0[4], F1[4];
;     frag_read(F0, pa, pb, 0);
;     __builtin_amdgcn_sched_barrier(0);
;     frag_read(F1, pa, pb, 16);
;     mfma4(F0);
;     __builtin_amdgcn_sched_barrier(0);
;     frag_read(F0, pa, pb, 32);
;     mfma4(F1);
;     if (do_write) {
; #pragma unroll
;       for (int i = 0; i < 4; ++i) *(u32x4*)(Ad + (lr + 32 * i) * 72 + lc) = ra[i];
;     }
;     __builtin_amdgcn_sched_barrier(0);
;     frag_read(F1, pa, pb, 48);
;     mfma4(F0);
;     if (do_write) {
; #pragma unroll
;       for (int i = 0; i < 4; ++i) *(u32x4*)(Bd + (lr + 32 * i) * 72 + lc) = rb[i];
;     }
;     __builtin_amdgcn_sched_barrier(0);
;     mfma4(F1);
;     if (do_load) load_stage(ra, rb, tload);
;     __builtin_amdgcn_sched_barrier(0);
;   };
;   const int nk = K >> 6;
;   load_stage(ra0, rb0, 0); load_stage(ra1, rb1, 1);
;   __syncthreads();
;   write_stage(ra0, rb0, 0);
;   load_stage(ra0, rb0, 2);
;   __syncthreads();
;   for (int kt = 0; kt < nk; kt += 2) {
;     step(0, ra1, rb1, true, kt + 3 < nk, kt + 3);
;     __syncthreads();
;     step(1, ra0, rb0, kt + 2 < nk, kt + 4 < nk, kt + 4);
;     __syncthreads();
	ds_read_b128 v[180:183], v98 offset:55296
	ds_read_b128 v[184:187], v98 offset:59904
	ds_read_b128 v[188:191], v97 offset:36864
	ds_read_b128 v[220:223], v97 offset:41472
	v_mfma_f32_32x32x16_bf16 v[0:15], v[116:119], v[100:103], v[0:15]
	v_mfma_f32_32x32x16_bf16 v[32:47], v[116:119], v[108:111], v[32:47]
	v_mfma_f32_32x32x16_bf16 v[48:63], v[124:127], v[100:103], v[48:63]
	v_mfma_f32_32x32x16_bf16 v[16:31], v[124:127], v[108:111], v[16:31]
	global_load_dwordx4 v[100:103], v[80:81], off offset:1920
	s_nop 0
	global_load_dwordx4 v[80:83], v[82:83], off offset:1920
	s_nop 0
	global_load_dwordx4 v[104:107], v[84:85], off offset:1920
	s_nop 0
	global_load_dwordx4 v[84:87], v[86:87], off offset:1920
	s_nop 0
	global_load_dwordx4 v[108:111], v[88:89], off offset:1920
	s_nop 0
	global_load_dwordx4 v[88:91], v[90:91], off offset:1920
	s_nop 0
	global_load_dwordx4 v[112:115], v[92:93], off offset:1920
	s_nop 0
	global_load_dwordx4 v[92:95], v[94:95], off offset:1920
	s_waitcnt lgkmcnt(1)
	v_mfma_f32_32x32x16_bf16 v[0:15], v[188:191], v[180:183], v[0:15]
	v_mfma_f32_32x32x16_bf16 v[32:47], v[188:191], v[184:187], v[32:47]
	s_waitcnt lgkmcnt(0)
	v_mfma_f32_32x32x16_bf16 v[48:63], v[220:223], v[180:183], v[48:63]
	ds_read_b128 v[116:119], v98 offset:55328
	ds_read_b128 v[124:127], v98 offset:59936
	ds_read_b128 v[152:155], v97 offset:36896
	ds_read_b128 v[156:159], v97 offset:41504
	v_mfma_f32_32x32x16_bf16 v[16:31], v[220:223], v[184:187], v[16:31]
	s_waitcnt lgkmcnt(1)
	v_mfma_f32_32x32x16_bf16 v[0:15], v[152:155], v[116:119], v[0:15]
	v_mfma_f32_32x32x16_bf16 v[32:47], v[152:155], v[124:127], v[32:47]
	s_waitcnt lgkmcnt(0)
	v_mfma_f32_32x32x16_bf16 v[48:63], v[156:159], v[116:119], v[48:63]
	ds_read_b128 v[116:119], v98 offset:55360
	ds_read_b128 v[120:123], v98 offset:59968
	ds_read_b128 v[128:131], v97 offset:36928
	ds_read_b128 v[152:155], v97 offset:41536
	s_waitcnt vmcnt(15)
	ds_write_b128 v96, v[64:67]
	s_waitcnt vmcnt(13)
	ds_write_b128 v96, v[72:75] offset:4608
	s_waitcnt vmcnt(11)
	ds_write_b128 v96, v[132:135] offset:9216
	s_waitcnt vmcnt(9)
	ds_write_b128 v96, v[140:143] offset:13824
	v_mfma_f32_32x32x16_bf16 v[16:31], v[156:159], v[124:127], v[16:31]
	s_waitcnt lgkmcnt(5)
	v_mfma_f32_32x32x16_bf16 v[0:15], v[128:131], v[116:119], v[0:15]
	s_waitcnt lgkmcnt(4)
	v_mfma_f32_32x32x16_bf16 v[48:63], v[152:155], v[116:119], v[48:63]
	ds_read_b128 v[64:67], v98 offset:55392
	ds_read_b128 v[72:75], v98 offset:60000
	ds_read_b128 v[116:119], v97 offset:36960
	ds_read_b128 v[124:127], v97 offset:41568
	ds_write_b128 v96, v[68:71] offset:18432
	ds_write_b128 v96, v[76:79] offset:23040
	ds_write_b128 v96, v[136:139] offset:27648
	s_waitcnt vmcnt(8)
	ds_write_b128 v96, v[148:151] offset:32256
	v_mfma_f32_32x32x16_bf16 v[32:47], v[128:131], v[120:123], v[32:47]
	v_mfma_f32_32x32x16_bf16 v[16:31], v[152:155], v[120:123], v[16:31]
	s_waitcnt lgkmcnt(0)
	s_barrier
	ds_read_b128 v[180:183], v98 offset:18432
	ds_read_b128 v[184:187], v98 offset:23040
	ds_read_b128 v[188:191], v97
	ds_read_b128 v[220:223], v97 offset:4608
	v_mfma_f32_32x32x16_bf16 v[0:15], v[116:119], v[64:67], v[0:15]
	v_mfma_f32_32x32x16_bf16 v[32:47], v[116:119], v[72:75], v[32:47]
	v_mfma_f32_32x32x16_bf16 v[48:63], v[124:127], v[64:67], v[48:63]
	v_mfma_f32_32x32x16_bf16 v[16:31], v[124:127], v[72:75], v[16:31]
	s_waitcnt lgkmcnt(1)
	v_mfma_f32_32x32x16_bf16 v[0:15], v[188:191], v[180:183], v[0:15]
	v_mfma_f32_32x32x16_bf16 v[32:47], v[188:191], v[184:187], v[32:47]
	s_waitcnt lgkmcnt(0)
	v_mfma_f32_32x32x16_bf16 v[48:63], v[220:223], v[180:183], v[48:63]
	ds_read_b128 v[64:67], v98 offset:18464
	ds_read_b128 v[72:75], v98 offset:23072
	ds_read_b128 v[116:119], v97 offset:32
	ds_read_b128 v[120:123], v97 offset:4640
	v_mfma_f32_32x32x16_bf16 v[16:31], v[220:223], v[184:187], v[16:31]
	s_waitcnt lgkmcnt(1)
	v_mfma_f32_32x32x16_bf16 v[0:15], v[116:119], v[64:67], v[0:15]
	v_mfma_f32_32x32x16_bf16 v[32:47], v[116:119], v[72:75], v[32:47]
	s_waitcnt lgkmcnt(0)
	v_mfma_f32_32x32x16_bf16 v[48:63], v[120:123], v[64:67], v[48:63]
	ds_read_b128 v[64:67], v98 offset:18496
	ds_read_b128 v[68:71], v98 offset:23104
	ds_read_b128 v[76:79], v97 offset:64
	ds_read_b128 v[116:119], v97 offset:4672
	s_waitcnt vmcnt(7)
	ds_write_b128 v96, v[100:103] offset:36864
	s_waitcnt vmcnt(5)
	ds_write_b128 v96, v[104:107] offset:41472
	s_waitcnt vmcnt(3)
	ds_write_b128 v96, v[108:111] offset:46080
	s_waitcnt vmcnt(1)
	ds_write_b128 v96, v[112:115] offset:50688
	v_mfma_f32_32x32x16_bf16 v[16:31], v[120:123], v[72:75], v[16:31]
	s_waitcnt lgkmcnt(5)
	v_mfma_f32_32x32x16_bf16 v[0:15], v[76:79], v[64:67], v[0:15]
	v_mfma_f32_32x32x16_bf16 v[32:47], v[76:79], v[68:71], v[32:47]
	s_waitcnt lgkmcnt(4)
	v_mfma_f32_32x32x16_bf16 v[48:63], v[116:119], v[64:67], v[48:63]
	ds_read_b128 v[64:67], v98 offset:18528
	ds_read_b128 v[72:75], v98 offset:23136
	ds_read_b128 v[76:79], v97 offset:96
	ds_read_b128 v[100:103], v97 offset:4704
	ds_write_b128 v96, v[80:83] offset:55296
	ds_write_b128 v96, v[84:87] offset:59904
	ds_write_b128 v96, v[88:91] offset:64512
	s_waitcnt vmcnt(0)
	ds_write_b128 v99, v[92:95] offset:13824
	v_mfma_f32_32x32x16_bf16 v[16:31], v[116:119], v[68:71], v[16:31]
	s_waitcnt lgkmcnt(0)
	s_barrier
; DI float bf2f(bf16_t v) { return __uint_as_float(((unsigned)v) << 16); }
; DI int crow(int r, int h) { return (r & 3) + 8 * (r >> 2) + 4 * h; }
; template <bool SWAP>
; DI void gemm_tile(const bf16_t* __restrict__ A, int lda, const bf16_t* __restrict__ Bt, int ldb, int K, f32x16 (&acc)[2][2], bf16_t* As, bf16_t* Bs_unused) {
;     ...
;   auto step = [&](int buf, u32x4 (&ra)[4], u32x4 (&rb)[4], bool do_write, bool do_load, int tload) __attribute__((always_inline)) {
;     const bf16_t* pa = As + buf * 2 * GT_IMG + pao; const bf16_t* pb = As + buf * 2 * GT_IMG + pbo;
;     bf16_t* Ad = As + (buf ^ 1) * 2 * GT_IMG; bf16_t* Bd = Ad + GT_IMG;
;     bf16x8 F0[4], F1[4];
;     frag_read(F0, pa, pb, 0);
;     __builtin_amdgcn_sched_barrier(0);
;     frag_read(F1, pa, pb, 16);
;     mfma4(F0);
;     __builtin_amdgcn_sched_barrier(0);
;     frag_read(F0, pa, pb, 32);
;     mfma4(F1);
;     if (do_write) {
; #pragma unroll
;       for (int i = 0; i < 4; ++i) *(u32x4*)(Ad + (lr + 32 * i) * 72 + lc) = ra[i];
;     }
;     __builtin_amdgcn_sched_barrier(0);
;     frag_read(F1, pa, pb, 48);
;     mfma4(F0);
;     if (do_write) {
; #pragma unroll
;       for (int i = 0; i < 4; ++i) *(u32x4*)(Bd + (lr + 32 * i) * 72 + lc) = rb[i];
;     }
;     __builtin_amdgcn_sched_barrier(0);
;     mfma4(F1);
;     if (do_load) load_stage(ra, rb, tload);
;     __builtin_amdgcn_sched_barrier(0);
;   };
; DI void phase_merge(const Params& p, int g, char* smem, int bid, int nb) {
;     ...
;     const bf16_t* pt = proj + (size_t)mt * 128 * NPROJ; bf16_t* mgt = mg + (size_t)mt * 128 * 1024;
; #pragma unroll
;     for (int mi = 0; mi < 2; ++mi)
; #pragma unroll
;       for (int ni = 0; ni < 2; ++ni)
; #pragma unroll
;         for (int r = 0; r < 16; ++r) {
;           const int off = (wm * 64 + mi * 32 + crow(r, h)) * NPROJ + nt * 128 + wn * 64 + ni * 32 + l31;
;           const float sga = bf2f(pt[off + PGA]), sgb = fmaxf(bf2f(pt[off + PGB]), 1e-20f);
;           acc[mi][ni][r] *= sga * __builtin_amdgcn_rcpf(sgb);
;           if (r == 15) asm volatile("" ::: "memory");
;         }
	ds_read_b128 v[180:183], v98 offset:55296
	ds_read_b128 v[184:187], v98 offset:59904
	ds_read_b128 v[188:191], v97 offset:36864
	ds_read_b128 v[220:223], v97 offset:41472
	v_mfma_f32_32x32x16_bf16 v[0:15], v[76:79], v[64:67], v[0:15]
	v_mfma_f32_32x32x16_bf16 v[32:47], v[76:79], v[72:75], v[32:47]
	v_mfma_f32_32x32x16_bf16 v[48:63], v[100:103], v[64:67], v[48:63]
	v_mfma_f32_32x32x16_bf16 v[16:31], v[100:103], v[72:75], v[16:31]
	s_waitcnt lgkmcnt(1)
	v_mfma_f32_32x32x16_bf16 v[0:15], v[188:191], v[180:183], v[0:15]
	v_mfma_f32_32x32x16_bf16 v[32:47], v[188:191], v[184:187], v[32:47]
	s_waitcnt lgkmcnt(0)
	v_mfma_f32_32x32x16_bf16 v[48:63], v[220:223], v[180:183], v[48:63]
	ds_read_b128 v[64:67], v98 offset:55328
	ds_read_b128 v[72:75], v98 offset:59936
	ds_read_b128 v[80:83], v97 offset:36896
	ds_read_b128 v[84:87], v97 offset:41504
	v_mfma_f32_32x32x16_bf16 v[16:31], v[220:223], v[184:187], v[16:31]
	s_waitcnt lgkmcnt(1)
	v_mfma_f32_32x32x16_bf16 v[0:15], v[80:83], v[64:67], v[0:15]
	v_mfma_f32_32x32x16_bf16 v[32:47], v[80:83], v[72:75], v[32:47]
	s_waitcnt lgkmcnt(0)
	v_mfma_f32_32x32x16_bf16 v[48:63], v[84:87], v[64:67], v[48:63]
	v_mfma_f32_32x32x16_bf16 v[16:31], v[84:87], v[72:75], v[16:31]
	ds_read_b128 v[64:67], v97 offset:41536
	ds_read_b128 v[68:71], v98 offset:59968
	ds_read_b128 v[72:75], v98 offset:55360
	ds_read_b128 v[76:79], v97 offset:36928
	s_waitcnt lgkmcnt(0)
	v_mfma_f32_32x32x16_bf16 v[0:15], v[76:79], v[72:75], v[0:15]
	v_mfma_f32_32x32x16_bf16 v[32:47], v[76:79], v[68:71], v[32:47]
	v_mfma_f32_32x32x16_bf16 v[48:63], v[64:67], v[72:75], v[48:63]
	v_mfma_f32_32x32x16_bf16 v[16:31], v[64:67], v[68:71], v[16:31]
	ds_read_b128 v[64:67], v97 offset:41568
	ds_read_b128 v[68:71], v98 offset:60000
	ds_read_b128 v[72:75], v98 offset:55392
	ds_read_b128 v[76:79], v97 offset:36960
	s_waitcnt lgkmcnt(0)
	v_mfma_f32_32x32x16_bf16 v[0:15], v[76:79], v[72:75], v[0:15]
	v_mfma_f32_32x32x16_bf16 v[32:47], v[76:79], v[68:71], v[32:47]
	v_mfma_f32_32x32x16_bf16 v[48:63], v[64:67], v[72:75], v[48:63]
	v_mfma_f32_32x32x16_bf16 v[16:31], v[64:67], v[68:71], v[16:31]
	v_mov_b32_e32 v148, v144
	s_mov_b32 s11, 0x50000
	s_barrier
	v_mov_b32_e32 v149, v145
	v_mov_b32_e32 v150, v146
	s_mul_hi_i32 s7, s6, 0x140000
	s_mul_i32 s6, s6, 0x140000
	v_mul_lo_u32 v64, v148, s11
	s_movk_i32 s11, 0x5000
	s_add_u32 s6, s94, s6
	v_mad_u64_u32 v[64:65], s[16:17], v150, s11, v[64:65]
	v_mov_b32_e32 v151, v147
	s_addc_u32 s7, s95, s7
	s_lshl_b32 s10, s10, 7
	v_lshlrev_b32_e32 v65, 6, v149
	v_add_u32_e32 v79, 0x1400, v64
	v_add3_u32 v65, v65, s10, v151
	v_add_u32_e32 v66, v64, v65
	v_ashrrev_i32_e32 v67, 31, v66
	v_lshl_add_u64 v[66:67], v[66:67], 1, s[6:7]
	v_add_u32_e32 v70, v79, v65
	v_add_co_u32_e32 v68, vcc, s75, v66
	v_ashrrev_i32_e32 v71, 31, v70
	s_nop 0
	v_addc_co_u32_e32 v69, vcc, 0, v67, vcc
	v_lshl_add_u64 v[70:71], v[70:71], 1, s[6:7]
	v_add_co_u32_e32 v72, vcc, s75, v70
	global_load_ushort v68, v[68:69], off
	s_nop 0
	v_addc_co_u32_e32 v73, vcc, 0, v71, vcc
	v_add_co_u32_e32 v70, vcc, s81, v70
	v_add_u32_e32 v80, 0x2800, v64
	s_nop 0
	v_addc_co_u32_e32 v71, vcc, 0, v71, vcc
	v_add_co_u32_e32 v66, vcc, s81, v66
	global_load_ushort v70, v[70:71], off offset:2048
	s_nop 0
	v_addc_co_u32_e32 v67, vcc, 0, v67, vcc
	global_load_ushort v66, v[66:67], off offset:2048
	v_add_u32_e32 v81, 0x3c00, v64
	global_load_ushort v69, v[72:73], off
	v_mov_b32_e32 v155, v195
	s_add_u32 s16, s63, s0
	s_addc_u32 s17, s70, s1
	v_readlane_b32 s11, v233, 1
	s_add_u32 s8, s11, s8
	v_readlane_b32 s11, v233, 2
	s_addc_u32 s9, s11, s9
	s_waitcnt vmcnt(3)
	v_lshlrev_b32_e32 v68, 16, v68
	v_max_f32_e32 v68, v68, v68
	v_max_f32_e32 v68, 0x1e3ce508, v68
	v_rcp_f32_e32 v68, v68
	s_waitcnt vmcnt(2)
	v_lshlrev_b32_e32 v67, 16, v70
	v_add_u32_e32 v70, v81, v65
	v_ashrrev_i32_e32 v71, 31, v70
	s_waitcnt vmcnt(1)
	v_lshlrev_b32_e32 v66, 16, v66
	v_lshl_add_u64 v[70:71], v[70:71], 1, s[6:7]
	s_waitcnt vmcnt(0)
	v_lshlrev_b32_e32 v69, 16, v69
	v_max_f32_e32 v69, v69, v69
	v_max_f32_e32 v69, 0x1e3ce508, v69
	v_rcp_f32_e32 v69, v69
	s_nop 0
	v_pk_mul_f32 v[66:67], v[68:69], v[66:67]
	s_nop 0
	v_pk_mul_f32 v[0:1], v[0:1], v[66:67]
	v_add_u32_e32 v66, v80, v65
	v_ashrrev_i32_e32 v67, 31, v66
	v_lshl_add_u64 v[66:67], v[66:67], 1, s[6:7]
	v_add_co_u32_e32 v68, vcc, s75, v66
	s_nop 1
	v_addc_co_u32_e32 v69, vcc, 0, v67, vcc
	v_add_co_u32_e32 v72, vcc, s75, v70
	global_load_ushort v68, v[68:69], off
	s_nop 0
	v_addc_co_u32_e32 v73, vcc, 0, v71, vcc
	global_load_ushort v69, v[72:73], off
	v_add_co_u32_e32 v66, vcc, s81, v66
	s_waitcnt vmcnt(1)
	v_lshlrev_b32_e32 v68, 16, v68
	v_addc_co_u32_e32 v67, vcc, 0, v67, vcc
	global_load_ushort v72, v[66:67], off offset:2048
	v_add_co_u32_e32 v66, vcc, s81, v70
	s_waitcnt vmcnt(1)
	v_lshlrev_b32_e32 v69, 16, v69
	v_addc_co_u32_e32 v67, vcc, 0, v71, vcc
	global_load_ushort v66, v[66:67], off offset:2048
	v_max_f32_e32 v68, v68, v68
	v_max_f32_e32 v69, v69, v69
	v_max_f32_e32 v68, 0x1e3ce508, v68
	v_max_f32_e32 v69, 0x1e3ce508, v69
	v_rcp_f32_e32 v68, v68
	v_rcp_f32_e32 v69, v69
	s_waitcnt vmcnt(0)
	v_lshlrev_b32_e32 v67, 16, v66
	v_lshlrev_b32_e32 v66, 16, v72
	v_pk_mul_f32 v[66:67], v[68:69], v[66:67]
	s_nop 0
	v_pk_mul_f32 v[2:3], v[2:3], v[66:67]
	v_add_u32_e32 v66, 0xa000, v64
	v_add_u32_e32 v68, v66, v65
	v_ashrrev_i32_e32 v69, 31, v68
	v_lshl_add_u64 v[68:69], v[68:69], 1, s[6:7]
	v_add_co_u32_e32 v70, vcc, s75, v68
	s_nop 1
	v_addc_co_u32_e32 v71, vcc, 0, v69, vcc
	global_load_ushort v67, v[70:71], off
	s_waitcnt vmcnt(0)
; DI float bf2f(bf16_t v) { return __uint_as_float(((unsigned)v) << 16); }
; DI int crow(int r, int h) { return (r & 3) + 8 * (r >> 2) + 4 * h; }
; DI void phase_merge(const Params& p, int g, char* smem, int bid, int nb) {
;     ...
;     const bf16_t* pt = proj + (size_t)mt * 128 * NPROJ; bf16_t* mgt = mg + (size_t)mt * 128 * 1024;
; #pragma unroll
;     for (int mi = 0; mi < 2; ++mi)
; #pragma unroll
;       for (int ni = 0; ni < 2; ++ni)
; #pragma unroll
;         for (int r = 0; r < 16; ++r) {
;           const int off = (wm * 64 + mi * 32 + crow(r, h)) * NPROJ + nt * 128 + wn * 64 + ni * 32 + l31;
;           const float sga = bf2f(pt[off + PGA]), sgb = fmaxf(bf2f(pt[off + PGB]), 1e-20f);
;           acc[mi][ni][r] *= sga * __builtin_amdgcn_rcpf(sgb);
;           if (r == 15) asm volatile("" ::: "memory");
;         }
	v_lshlrev_b32_e32 v67, 16, v67
	v_max_f32_e32 v67, v67, v67
	v_max_f32_e32 v67, 0x1e3ce508, v67
	v_rcp_f32_e32 v70, v67
	v_add_u32_e32 v67, 0xb400, v64
	v_add_u32_e32 v72, v67, v65
	v_ashrrev_i32_e32 v73, 31, v72
	v_lshl_add_u64 v[72:73], v[72:73], 1, s[6:7]
	v_add_co_u32_e32 v74, vcc, s75, v72
	s_nop 1
	v_addc_co_u32_e32 v75, vcc, 0, v73, vcc
	global_load_ushort v71, v[74:75], off
	v_add_co_u32_e32 v68, vcc, s81, v68
	s_waitcnt vmcnt(0)
	v_lshlrev_b32_e32 v71, 16, v71
	v_addc_co_u32_e32 v69, vcc, 0, v69, vcc
	global_load_ushort v74, v[68:69], off offset:2048
	v_add_co_u32_e32 v68, vcc, s81, v72
	v_max_f32_e32 v71, v71, v71
	s_nop 0
	v_addc_co_u32_e32 v69, vcc, 0, v73, vcc
	global_load_ushort v68, v[68:69], off offset:2048
	v_max_f32_e32 v71, 0x1e3ce508, v71
	v_rcp_f32_e32 v71, v71
	s_waitcnt vmcnt(0)
	v_lshlrev_b32_e32 v69, 16, v68
	v_lshlrev_b32_e32 v68, 16, v74
	v_pk_mul_f32 v[68:69], v[70:71], v[68:69]
	s_nop 0
	v_pk_mul_f32 v[4:5], v[4:5], v[68:69]
	v_add_u32_e32 v68, 0xc800, v64
	v_add_u32_e32 v70, v68, v65
	v_ashrrev_i32_e32 v71, 31, v70
	v_lshl_add_u64 v[70:71], v[70:71], 1, s[6:7]
	v_add_co_u32_e32 v72, vcc, s75, v70
	s_nop 1
	v_addc_co_u32_e32 v73, vcc, 0, v71, vcc
	global_load_ushort v69, v[72:73], off
	s_waitcnt vmcnt(0)
	v_lshlrev_b32_e32 v69, 16, v69
	v_max_f32_e32 v69, v69, v69
	v_max_f32_e32 v69, 0x1e3ce508, v69
	v_rcp_f32_e32 v72, v69
	v_add_u32_e32 v69, 0xdc00, v64
	v_add_u32_e32 v74, v69, v65
	v_ashrrev_i32_e32 v75, 31, v74
	v_lshl_add_u64 v[74:75], v[74:75], 1, s[6:7]
	v_add_co_u32_e32 v76, vcc, s75, v74
	s_nop 1
	v_addc_co_u32_e32 v77, vcc, 0, v75, vcc
	global_load_ushort v73, v[76:77], off
	v_add_co_u32_e32 v70, vcc, s81, v70
	s_waitcnt vmcnt(0)
	v_lshlrev_b32_e32 v73, 16, v73
	v_addc_co_u32_e32 v71, vcc, 0, v71, vcc
	global_load_ushort v76, v[70:71], off offset:2048
	v_add_co_u32_e32 v70, vcc, s81, v74
	v_max_f32_e32 v73, v73, v73
	s_nop 0
	v_addc_co_u32_e32 v71, vcc, 0, v75, vcc
	global_load_ushort v70, v[70:71], off offset:2048
	v_max_f32_e32 v73, 0x1e3ce508, v73
	v_rcp_f32_e32 v73, v73
	v_add_u32_e32 v74, 0x14000, v64
	v_add_u32_e32 v75, 0x15400, v64
	s_waitcnt vmcnt(0)
	v_lshlrev_b32_e32 v71, 16, v70
	v_lshlrev_b32_e32 v70, 16, v76
	v_pk_mul_f32 v[70:71], v[72:73], v[70:71]
	v_add_u32_e32 v76, v75, v65
	v_pk_mul_f32 v[6:7], v[6:7], v[70:71]
	v_add_u32_e32 v70, v74, v65
	v_ashrrev_i32_e32 v71, 31, v70
	v_lshl_add_u64 v[70:71], v[70:71], 1, s[6:7]
	v_add_co_u32_e32 v72, vcc, s75, v70
	v_ashrrev_i32_e32 v77, 31, v76
	s_nop 0
	v_addc_co_u32_e32 v73, vcc, 0, v71, vcc
	v_lshl_add_u64 v[76:77], v[76:77], 1, s[6:7]
	v_add_co_u32_e32 v82, vcc, s75, v76
	global_load_ushort v72, v[72:73], off
	s_nop 0
	v_addc_co_u32_e32 v83, vcc, 0, v77, vcc
	v_add_co_u32_e32 v70, vcc, s81, v70
	s_nop 1
	v_addc_co_u32_e32 v71, vcc, 0, v71, vcc
	global_load_ushort v78, v[70:71], off offset:2048
	global_load_ushort v73, v[82:83], off
	v_add_co_u32_e32 v70, vcc, s81, v76
	v_add_u32_e32 v76, 0x16800, v64
	s_nop 0
	v_addc_co_u32_e32 v71, vcc, 0, v77, vcc
	global_load_ushort v70, v[70:71], off offset:2048
	v_add_u32_e32 v77, 0x17c00, v64
	v_add_u32_e32 v82, v77, v65
	v_ashrrev_i32_e32 v83, 31, v82
	v_lshl_add_u64 v[82:83], v[82:83], 1, s[6:7]
	s_waitcnt vmcnt(3)
	v_lshlrev_b32_e32 v72, 16, v72
	v_max_f32_e32 v72, v72, v72
	v_max_f32_e32 v72, 0x1e3ce508, v72
	v_rcp_f32_e32 v72, v72
	s_waitcnt vmcnt(1)
	v_lshlrev_b32_e32 v73, 16, v73
	v_max_f32_e32 v73, v73, v73
	v_max_f32_e32 v73, 0x1e3ce508, v73
	v_rcp_f32_e32 v73, v73
	s_waitcnt vmcnt(0)
	v_lshlrev_b32_e32 v71, 16, v70
	v_lshlrev_b32_e32 v70, 16, v78
	v_pk_mul_f32 v[70:71], v[72:73], v[70:71]
	s_nop 0
	v_pk_mul_f32 v[8:9], v[8:9], v[70:71]
	v_add_u32_e32 v70, v76, v65
	v_ashrrev_i32_e32 v71, 31, v70
	v_lshl_add_u64 v[70:71], v[70:71], 1, s[6:7]
	v_add_co_u32_e32 v72, vcc, s75, v70
	s_nop 1
	v_addc_co_u32_e32 v73, vcc, 0, v71, vcc
	v_add_co_u32_e32 v84, vcc, s75, v82
	global_load_ushort v72, v[72:73], off
	s_nop 0
	v_addc_co_u32_e32 v85, vcc, 0, v83, vcc
	v_add_co_u32_e32 v70, vcc, s81, v70
	s_nop 1
	v_addc_co_u32_e32 v71, vcc, 0, v71, vcc
	global_load_ushort v78, v[70:71], off offset:2048
	global_load_ushort v73, v[84:85], off
	v_add_co_u32_e32 v70, vcc, s81, v82
	s_waitcnt vmcnt(2)
	v_lshlrev_b32_e32 v72, 16, v72
	v_addc_co_u32_e32 v71, vcc, 0, v83, vcc
	global_load_ushort v70, v[70:71], off offset:2048
	v_max_f32_e32 v72, v72, v72
	v_max_f32_e32 v72, 0x1e3ce508, v72
	v_rcp_f32_e32 v72, v72
	s_waitcnt vmcnt(1)
	v_lshlrev_b32_e32 v73, 16, v73
	v_max_f32_e32 v73, v73, v73
	v_max_f32_e32 v73, 0x1e3ce508, v73
	v_rcp_f32_e32 v73, v73
	s_waitcnt vmcnt(0)
	v_lshlrev_b32_e32 v71, 16, v70
	v_lshlrev_b32_e32 v70, 16, v78
	v_pk_mul_f32 v[70:71], v[72:73], v[70:71]
	v_add_u32_e32 v78, 0x1e000, v64
	v_pk_mul_f32 v[10:11], v[10:11], v[70:71]
	v_add_u32_e32 v70, v78, v65
	v_ashrrev_i32_e32 v71, 31, v70
	v_lshl_add_u64 v[70:71], v[70:71], 1, s[6:7]
	v_add_co_u32_e32 v72, vcc, s75, v70
	s_nop 1
	v_addc_co_u32_e32 v73, vcc, 0, v71, vcc
	global_load_ushort v72, v[72:73], off
	s_waitcnt vmcnt(0)
	v_lshlrev_b32_e32 v72, 16, v72
	v_max_f32_e32 v72, v72, v72
	v_max_f32_e32 v72, 0x1e3ce508, v72
	v_rcp_f32_e32 v82, v72
	v_add_u32_e32 v72, 0x1f400, v64
	v_add_u32_e32 v84, v72, v65
	v_ashrrev_i32_e32 v85, 31, v84
	v_lshl_add_u64 v[84:85], v[84:85], 1, s[6:7]
	v_add_co_u32_e32 v86, vcc, s75, v84
	s_nop 1
	v_addc_co_u32_e32 v87, vcc, 0, v85, vcc
	global_load_ushort v73, v[86:87], off
	v_add_co_u32_e32 v70, vcc, s81, v70
	s_waitcnt vmcnt(0)
; DI float bf2f(bf16_t v) { return __uint_as_float(((unsigned)v) << 16); }
; DI int crow(int r, int h) { return (r & 3) + 8 * (r >> 2) + 4 * h; }
; DI void phase_merge(const Params& p, int g, char* smem, int bid, int nb) {
;     ...
;     const bf16_t* pt = proj + (size_t)mt * 128 * NPROJ; bf16_t* mgt = mg + (size_t)mt * 128 * 1024;
; #pragma unroll
;     for (int mi = 0; mi < 2; ++mi)
; #pragma unroll
;       for (int ni = 0; ni < 2; ++ni)
; #pragma unroll
;         for (int r = 0; r < 16; ++r) {
;           const int off = (wm * 64 + mi * 32 + crow(r, h)) * NPROJ + nt * 128 + wn * 64 + ni * 32 + l31;
;           const float sga = bf2f(pt[off + PGA]), sgb = fmaxf(bf2f(pt[off + PGB]), 1e-20f);
;           acc[mi][ni][r] *= sga * __builtin_amdgcn_rcpf(sgb);
;           if (r == 15) asm volatile("" ::: "memory");
;         }
	v_lshlrev_b32_e32 v73, 16, v73
	v_max_f32_e32 v73, v73, v73
	v_max_f32_e32 v73, 0x1e3ce508, v73
	v_addc_co_u32_e32 v71, vcc, 0, v71, vcc
	v_rcp_f32_e32 v83, v73
	global_load_ushort v73, v[70:71], off offset:2048
	v_add_co_u32_e32 v70, vcc, s81, v84
	s_nop 1
	v_addc_co_u32_e32 v71, vcc, 0, v85, vcc
	global_load_ushort v70, v[70:71], off offset:2048
	s_waitcnt vmcnt(0)
	v_lshlrev_b32_e32 v71, 16, v70
	v_lshlrev_b32_e32 v70, 16, v73
	v_pk_mul_f32 v[70:71], v[82:83], v[70:71]
	v_add_u32_e32 v73, 0x20800, v64
	v_pk_mul_f32 v[12:13], v[12:13], v[70:71]
	v_add_u32_e32 v70, v73, v65
	v_ashrrev_i32_e32 v71, 31, v70
	v_lshl_add_u64 v[82:83], v[70:71], 1, s[6:7]
	v_add_co_u32_e32 v70, vcc, s75, v82
	s_nop 1
	v_addc_co_u32_e32 v71, vcc, 0, v83, vcc
	global_load_ushort v70, v[70:71], off
	v_add_u32_e32 v71, 0x21c00, v64
	v_add_u32_e32 v86, v71, v65
	v_ashrrev_i32_e32 v87, 31, v86
	v_lshl_add_u64 v[86:87], v[86:87], 1, s[6:7]
	v_add_co_u32_e32 v88, vcc, s75, v86
	s_waitcnt vmcnt(0)
	v_lshlrev_b32_e32 v70, 16, v70
	v_max_f32_e32 v70, v70, v70
	v_max_f32_e32 v70, 0x1e3ce508, v70
	v_addc_co_u32_e32 v89, vcc, 0, v87, vcc
	v_rcp_f32_e32 v84, v70
	global_load_ushort v70, v[88:89], off
	v_add_co_u32_e32 v82, vcc, s81, v82
	s_waitcnt vmcnt(0)
	v_lshlrev_b32_e32 v70, 16, v70
	v_max_f32_e32 v70, v70, v70
	v_max_f32_e32 v70, 0x1e3ce508, v70
	v_addc_co_u32_e32 v83, vcc, 0, v83, vcc
	v_rcp_f32_e32 v85, v70
	global_load_ushort v70, v[82:83], off offset:2048
	v_add_co_u32_e32 v82, vcc, s81, v86
	s_nop 1
	v_addc_co_u32_e32 v83, vcc, 0, v87, vcc
	global_load_ushort v82, v[82:83], off offset:2048
	s_waitcnt vmcnt(0)
	v_lshlrev_b32_e32 v83, 16, v82
	v_lshlrev_b32_e32 v82, 16, v70
	v_pk_mul_f32 v[82:83], v[84:85], v[82:83]
	v_add_u32_e32 v70, 32, v65
	v_pk_mul_f32 v[14:15], v[14:15], v[82:83]
	v_add_u32_e32 v82, v70, v64
	v_ashrrev_i32_e32 v83, 31, v82
	v_lshl_add_u64 v[82:83], v[82:83], 1, s[6:7]
	v_add_u32_e32 v86, v79, v70
	v_add_co_u32_e32 v84, vcc, s75, v82
	v_ashrrev_i32_e32 v87, 31, v86
	s_nop 0
	v_addc_co_u32_e32 v85, vcc, 0, v83, vcc
	v_lshl_add_u64 v[86:87], v[86:87], 1, s[6:7]
	v_add_co_u32_e32 v88, vcc, s75, v86
	global_load_ushort v84, v[84:85], off
	s_nop 0
	v_addc_co_u32_e32 v89, vcc, 0, v87, vcc
	global_load_ushort v79, v[88:89], off
	v_add_co_u32_e32 v82, vcc, s81, v82
	s_waitcnt vmcnt(1)
	v_lshlrev_b32_e32 v84, 16, v84
	v_addc_co_u32_e32 v83, vcc, 0, v83, vcc
	s_waitcnt vmcnt(0)
	v_lshlrev_b32_e32 v79, 16, v79
	v_max_f32_e32 v79, v79, v79
	v_max_f32_e32 v79, 0x1e3ce508, v79
	v_rcp_f32_e32 v85, v79
	global_load_ushort v79, v[82:83], off offset:2048
	v_add_co_u32_e32 v82, vcc, s81, v86
	v_max_f32_e32 v84, v84, v84
	s_nop 0
	v_addc_co_u32_e32 v83, vcc, 0, v87, vcc
	global_load_ushort v82, v[82:83], off offset:2048
	v_max_f32_e32 v84, 0x1e3ce508, v84
	v_rcp_f32_e32 v84, v84
	s_waitcnt vmcnt(0)
	v_lshlrev_b32_e32 v83, 16, v82
	v_lshlrev_b32_e32 v82, 16, v79
	v_pk_mul_f32 v[82:83], v[84:85], v[82:83]
	s_nop 0
	v_pk_mul_f32 v[32:33], v[32:33], v[82:83]
	v_add_u32_e32 v82, v80, v70
	v_ashrrev_i32_e32 v83, 31, v82
	v_lshl_add_u64 v[82:83], v[82:83], 1, s[6:7]
	v_add_co_u32_e32 v84, vcc, s75, v82
	s_nop 1
	v_addc_co_u32_e32 v85, vcc, 0, v83, vcc
	global_load_ushort v79, v[84:85], off
	v_add_u32_e32 v84, v81, v70
	v_ashrrev_i32_e32 v85, 31, v84
	v_lshl_add_u64 v[84:85], v[84:85], 1, s[6:7]
	v_add_co_u32_e32 v86, vcc, s75, v84
	s_waitcnt vmcnt(0)
	v_lshlrev_b32_e32 v79, 16, v79
	v_max_f32_e32 v79, v79, v79
	v_max_f32_e32 v79, 0x1e3ce508, v79
	v_addc_co_u32_e32 v87, vcc, 0, v85, vcc
	v_rcp_f32_e32 v80, v79
	global_load_ushort v79, v[86:87], off
	v_add_co_u32_e32 v82, vcc, s81, v82
	s_waitcnt vmcnt(0)
	v_lshlrev_b32_e32 v79, 16, v79
	v_max_f32_e32 v79, v79, v79
	v_max_f32_e32 v79, 0x1e3ce508, v79
	v_addc_co_u32_e32 v83, vcc, 0, v83, vcc
	v_rcp_f32_e32 v81, v79
	global_load_ushort v79, v[82:83], off offset:2048
	v_add_co_u32_e32 v82, vcc, s81, v84
	s_nop 1
	v_addc_co_u32_e32 v83, vcc, 0, v85, vcc
	global_load_ushort v82, v[82:83], off offset:2048
	s_waitcnt vmcnt(0)
	v_lshlrev_b32_e32 v83, 16, v82
	v_lshlrev_b32_e32 v82, 16, v79
	v_pk_mul_f32 v[80:81], v[80:81], v[82:83]
	s_nop 0
	v_pk_mul_f32 v[34:35], v[34:35], v[80:81]
	v_add_u32_e32 v80, v66, v70
	v_ashrrev_i32_e32 v81, 31, v80
	v_lshl_add_u64 v[80:81], v[80:81], 1, s[6:7]
	v_add_co_u32_e32 v82, vcc, s75, v80
	s_nop 1
	v_addc_co_u32_e32 v83, vcc, 0, v81, vcc
	global_load_ushort v66, v[82:83], off
	v_add_u32_e32 v82, v67, v70
	v_ashrrev_i32_e32 v83, 31, v82
	v_lshl_add_u64 v[82:83], v[82:83], 1, s[6:7]
	v_add_co_u32_e32 v84, vcc, s75, v82
	s_waitcnt vmcnt(0)
	v_lshlrev_b32_e32 v66, 16, v66
	v_addc_co_u32_e32 v85, vcc, 0, v83, vcc
	global_load_ushort v67, v[84:85], off
	v_add_co_u32_e32 v80, vcc, s81, v80
	v_max_f32_e32 v66, v66, v66
	s_nop 0
	v_addc_co_u32_e32 v81, vcc, 0, v81, vcc
	global_load_ushort v79, v[80:81], off offset:2048
	v_add_co_u32_e32 v80, vcc, s81, v82
	v_max_f32_e32 v66, 0x1e3ce508, v66
	s_nop 0
	v_addc_co_u32_e32 v81, vcc, 0, v83, vcc
	global_load_ushort v80, v[80:81], off offset:2048
	v_rcp_f32_e32 v66, v66
	s_waitcnt vmcnt(2)
	v_lshlrev_b32_e32 v67, 16, v67
	v_max_f32_e32 v67, v67, v67
	v_max_f32_e32 v67, 0x1e3ce508, v67
	v_rcp_f32_e32 v67, v67
	s_waitcnt vmcnt(0)
	v_lshlrev_b32_e32 v81, 16, v80
	v_lshlrev_b32_e32 v80, 16, v79
	v_pk_mul_f32 v[66:67], v[66:67], v[80:81]
	s_nop 0
	v_pk_mul_f32 v[36:37], v[36:37], v[66:67]
	v_add_u32_e32 v66, v68, v70
	v_ashrrev_i32_e32 v67, 31, v66
	v_lshl_add_u64 v[66:67], v[66:67], 1, s[6:7]
	v_add_co_u32_e32 v80, vcc, s75, v66
	s_nop 1
	v_addc_co_u32_e32 v81, vcc, 0, v67, vcc
	global_load_ushort v68, v[80:81], off
	v_add_u32_e32 v80, v69, v70
	v_ashrrev_i32_e32 v81, 31, v80
	v_lshl_add_u64 v[80:81], v[80:81], 1, s[6:7]
	v_add_co_u32_e32 v82, vcc, s75, v80
	s_waitcnt vmcnt(0)
; DI float bf2f(bf16_t v) { return __uint_as_float(((unsigned)v) << 16); }
; DI int crow(int r, int h) { return (r & 3) + 8 * (r >> 2) + 4 * h; }
; DI void phase_merge(const Params& p, int g, char* smem, int bid, int nb) {
;     ...
;     const bf16_t* pt = proj + (size_t)mt * 128 * NPROJ; bf16_t* mgt = mg + (size_t)mt * 128 * 1024;
; #pragma unroll
;     for (int mi = 0; mi < 2; ++mi)
; #pragma unroll
;       for (int ni = 0; ni < 2; ++ni)
; #pragma unroll
;         for (int r = 0; r < 16; ++r) {
;           const int off = (wm * 64 + mi * 32 + crow(r, h)) * NPROJ + nt * 128 + wn * 64 + ni * 32 + l31;
;           const float sga = bf2f(pt[off + PGA]), sgb = fmaxf(bf2f(pt[off + PGB]), 1e-20f);
;           acc[mi][ni][r] *= sga * __builtin_amdgcn_rcpf(sgb);
;           if (r == 15) asm volatile("" ::: "memory");
;         }
	v_lshlrev_b32_e32 v68, 16, v68
	v_addc_co_u32_e32 v83, vcc, 0, v81, vcc
	global_load_ushort v69, v[82:83], off
	v_add_co_u32_e32 v66, vcc, s81, v66
	v_max_f32_e32 v68, v68, v68
	s_nop 0
	v_addc_co_u32_e32 v67, vcc, 0, v67, vcc
	global_load_ushort v79, v[66:67], off offset:2048
	v_add_co_u32_e32 v66, vcc, s81, v80
	v_max_f32_e32 v68, 0x1e3ce508, v68
	s_nop 0
	v_addc_co_u32_e32 v67, vcc, 0, v81, vcc
	global_load_ushort v66, v[66:67], off offset:2048
	v_rcp_f32_e32 v68, v68
	s_waitcnt vmcnt(2)
	v_lshlrev_b32_e32 v69, 16, v69
	v_max_f32_e32 v69, v69, v69
	v_max_f32_e32 v69, 0x1e3ce508, v69
	v_rcp_f32_e32 v69, v69
	s_waitcnt vmcnt(0)
	v_lshlrev_b32_e32 v67, 16, v66
	v_lshlrev_b32_e32 v66, 16, v79
	v_pk_mul_f32 v[66:67], v[68:69], v[66:67]
	s_nop 0
	v_pk_mul_f32 v[38:39], v[38:39], v[66:67]
	v_add_u32_e32 v66, v74, v70
	v_ashrrev_i32_e32 v67, 31, v66
	v_lshl_add_u64 v[66:67], v[66:67], 1, s[6:7]
	v_add_u32_e32 v74, v75, v70
	v_add_co_u32_e32 v68, vcc, s75, v66
	v_ashrrev_i32_e32 v75, 31, v74
	s_nop 0
	v_addc_co_u32_e32 v69, vcc, 0, v67, vcc
	v_lshl_add_u64 v[74:75], v[74:75], 1, s[6:7]
	v_add_co_u32_e32 v80, vcc, s75, v74
	global_load_ushort v68, v[68:69], off
	s_nop 0
	v_addc_co_u32_e32 v81, vcc, 0, v75, vcc
	v_add_co_u32_e32 v66, vcc, s81, v66
	s_nop 1
	v_addc_co_u32_e32 v67, vcc, 0, v67, vcc
	global_load_ushort v79, v[66:67], off offset:2048
	global_load_ushort v69, v[80:81], off
	v_add_co_u32_e32 v66, vcc, s81, v74
	v_add_u32_e32 v74, v77, v70
	s_nop 0
	v_addc_co_u32_e32 v67, vcc, 0, v75, vcc
	global_load_ushort v66, v[66:67], off offset:2048
	v_ashrrev_i32_e32 v75, 31, v74
	v_lshl_add_u64 v[74:75], v[74:75], 1, s[6:7]
	s_waitcnt vmcnt(3)
	v_lshlrev_b32_e32 v68, 16, v68
	v_max_f32_e32 v68, v68, v68
	v_max_f32_e32 v68, 0x1e3ce508, v68
	v_rcp_f32_e32 v68, v68
	s_waitcnt vmcnt(1)
	v_lshlrev_b32_e32 v69, 16, v69
	v_max_f32_e32 v69, v69, v69
	v_max_f32_e32 v69, 0x1e3ce508, v69
	v_rcp_f32_e32 v69, v69
	s_waitcnt vmcnt(0)
	v_lshlrev_b32_e32 v67, 16, v66
	v_lshlrev_b32_e32 v66, 16, v79
	v_pk_mul_f32 v[66:67], v[68:69], v[66:67]
	s_nop 0
	v_pk_mul_f32 v[40:41], v[40:41], v[66:67]
	v_add_u32_e32 v66, v76, v70
	v_ashrrev_i32_e32 v67, 31, v66
	v_lshl_add_u64 v[66:67], v[66:67], 1, s[6:7]
	v_add_co_u32_e32 v68, vcc, s75, v66
	s_nop 1
	v_addc_co_u32_e32 v69, vcc, 0, v67, vcc
	v_add_co_u32_e32 v76, vcc, s75, v74
	global_load_ushort v68, v[68:69], off
	s_nop 0
	v_addc_co_u32_e32 v77, vcc, 0, v75, vcc
	global_load_ushort v69, v[76:77], off
	v_add_co_u32_e32 v66, vcc, s81, v66
	s_waitcnt vmcnt(1)
	v_lshlrev_b32_e32 v68, 16, v68
	v_addc_co_u32_e32 v67, vcc, 0, v67, vcc
	global_load_ushort v76, v[66:67], off offset:2048
	v_add_co_u32_e32 v66, vcc, s81, v74
	s_waitcnt vmcnt(1)
	v_lshlrev_b32_e32 v69, 16, v69
	v_addc_co_u32_e32 v67, vcc, 0, v75, vcc
	global_load_ushort v66, v[66:67], off offset:2048
	v_max_f32_e32 v68, v68, v68
	v_max_f32_e32 v69, v69, v69
	v_max_f32_e32 v68, 0x1e3ce508, v68
	v_max_f32_e32 v69, 0x1e3ce508, v69
	v_rcp_f32_e32 v68, v68
	v_rcp_f32_e32 v69, v69
	v_add_u32_e32 v74, v72, v70
	v_ashrrev_i32_e32 v75, 31, v74
	v_lshl_add_u64 v[74:75], v[74:75], 1, s[6:7]
	s_waitcnt vmcnt(0)
	v_lshlrev_b32_e32 v67, 16, v66
	v_lshlrev_b32_e32 v66, 16, v76
	v_pk_mul_f32 v[66:67], v[68:69], v[66:67]
	s_nop 0
	v_pk_mul_f32 v[42:43], v[42:43], v[66:67]
	v_add_u32_e32 v66, v78, v70
	v_ashrrev_i32_e32 v67, 31, v66
	v_lshl_add_u64 v[66:67], v[66:67], 1, s[6:7]
	v_add_co_u32_e32 v68, vcc, s75, v66
	s_nop 1
	v_addc_co_u32_e32 v69, vcc, 0, v67, vcc
	v_add_co_u32_e32 v76, vcc, s75, v74
	global_load_ushort v68, v[68:69], off
	s_nop 0
	v_addc_co_u32_e32 v77, vcc, 0, v75, vcc
	v_add_co_u32_e32 v66, vcc, s81, v66
	s_nop 1
	v_addc_co_u32_e32 v67, vcc, 0, v67, vcc
	global_load_ushort v72, v[66:67], off offset:2048
	global_load_ushort v69, v[76:77], off
	v_add_co_u32_e32 v66, vcc, s81, v74
	s_waitcnt vmcnt(2)
	v_lshlrev_b32_e32 v68, 16, v68
	v_addc_co_u32_e32 v67, vcc, 0, v75, vcc
	global_load_ushort v66, v[66:67], off offset:2048
	v_max_f32_e32 v68, v68, v68
	v_max_f32_e32 v68, 0x1e3ce508, v68
	v_rcp_f32_e32 v68, v68
	s_waitcnt vmcnt(1)
	v_lshlrev_b32_e32 v69, 16, v69
	v_max_f32_e32 v69, v69, v69
	v_max_f32_e32 v69, 0x1e3ce508, v69
	v_rcp_f32_e32 v69, v69
	s_waitcnt vmcnt(0)
	v_lshlrev_b32_e32 v67, 16, v66
	v_lshlrev_b32_e32 v66, 16, v72
	v_pk_mul_f32 v[66:67], v[68:69], v[66:67]
	v_add_u32_e32 v72, v71, v70
	v_pk_mul_f32 v[44:45], v[44:45], v[66:67]
	v_add_u32_e32 v66, v73, v70
	v_ashrrev_i32_e32 v67, 31, v66
	v_lshl_add_u64 v[66:67], v[66:67], 1, s[6:7]
	v_add_co_u32_e32 v68, vcc, s75, v66
	v_ashrrev_i32_e32 v73, 31, v72
	s_nop 0
	v_addc_co_u32_e32 v69, vcc, 0, v67, vcc
	v_lshl_add_u64 v[72:73], v[72:73], 1, s[6:7]
	v_add_co_u32_e32 v74, vcc, s75, v72
	global_load_ushort v68, v[68:69], off
	s_nop 0
	v_addc_co_u32_e32 v75, vcc, 0, v73, vcc
	v_add_co_u32_e32 v66, vcc, s81, v66
	s_nop 1
	v_addc_co_u32_e32 v67, vcc, 0, v67, vcc
	global_load_ushort v71, v[66:67], off offset:2048
	global_load_ushort v69, v[74:75], off
	v_add_co_u32_e32 v66, vcc, s81, v72
	s_waitcnt vmcnt(2)
	v_lshlrev_b32_e32 v68, 16, v68
	v_addc_co_u32_e32 v67, vcc, 0, v73, vcc
	global_load_ushort v66, v[66:67], off offset:2048
	v_max_f32_e32 v68, v68, v68
	v_max_f32_e32 v68, 0x1e3ce508, v68
	v_rcp_f32_e32 v68, v68
	s_waitcnt vmcnt(1)
	v_lshlrev_b32_e32 v69, 16, v69
	v_max_f32_e32 v69, v69, v69
	v_max_f32_e32 v69, 0x1e3ce508, v69
	v_rcp_f32_e32 v69, v69
	s_waitcnt vmcnt(0)
	v_lshlrev_b32_e32 v67, 16, v66
	v_lshlrev_b32_e32 v66, 16, v71
	v_pk_mul_f32 v[66:67], v[68:69], v[66:67]
	s_nop 0
	v_pk_mul_f32 v[46:47], v[46:47], v[66:67]
	v_add_u32_e32 v66, 0x28000, v64
	v_add_u32_e32 v68, v66, v65
	v_ashrrev_i32_e32 v69, 31, v68
	v_lshl_add_u64 v[68:69], v[68:69], 1, s[6:7]
	v_add_co_u32_e32 v72, vcc, s75, v68
	s_nop 1
	v_addc_co_u32_e32 v73, vcc, 0, v69, vcc
	global_load_ushort v67, v[72:73], off
	s_waitcnt vmcnt(0)
; DI float bf2f(bf16_t v) { return __uint_as_float(((unsigned)v) << 16); }
; DI int crow(int r, int h) { return (r & 3) + 8 * (r >> 2) + 4 * h; }
; DI void phase_merge(const Params& p, int g, char* smem, int bid, int nb) {
;     ...
;     const bf16_t* pt = proj + (size_t)mt * 128 * NPROJ; bf16_t* mgt = mg + (size_t)mt * 128 * 1024;
; #pragma unroll
;     for (int mi = 0; mi < 2; ++mi)
; #pragma unroll
;       for (int ni = 0; ni < 2; ++ni)
; #pragma unroll
;         for (int r = 0; r < 16; ++r) {
;           const int off = (wm * 64 + mi * 32 + crow(r, h)) * NPROJ + nt * 128 + wn * 64 + ni * 32 + l31;
;           const float sga = bf2f(pt[off + PGA]), sgb = fmaxf(bf2f(pt[off + PGB]), 1e-20f);
;           acc[mi][ni][r] *= sga * __builtin_amdgcn_rcpf(sgb);
;           if (r == 15) asm volatile("" ::: "memory");
;         }
	v_lshlrev_b32_e32 v67, 16, v67
	v_max_f32_e32 v67, v67, v67
	v_max_f32_e32 v67, 0x1e3ce508, v67
	v_rcp_f32_e32 v72, v67
	v_add_u32_e32 v67, 0x29400, v64
	v_add_u32_e32 v74, v67, v65
	v_ashrrev_i32_e32 v75, 31, v74
	v_lshl_add_u64 v[74:75], v[74:75], 1, s[6:7]
	v_add_co_u32_e32 v76, vcc, s75, v74
	s_nop 1
	v_addc_co_u32_e32 v77, vcc, 0, v75, vcc
	global_load_ushort v71, v[76:77], off
	v_add_co_u32_e32 v68, vcc, s81, v68
	s_waitcnt vmcnt(0)
	v_lshlrev_b32_e32 v71, 16, v71
	v_max_f32_e32 v71, v71, v71
	v_max_f32_e32 v71, 0x1e3ce508, v71
	v_addc_co_u32_e32 v69, vcc, 0, v69, vcc
	v_rcp_f32_e32 v73, v71
	global_load_ushort v71, v[68:69], off offset:2048
	v_add_co_u32_e32 v68, vcc, s81, v74
	s_nop 1
	v_addc_co_u32_e32 v69, vcc, 0, v75, vcc
	global_load_ushort v68, v[68:69], off offset:2048
	s_waitcnt vmcnt(0)
	v_lshlrev_b32_e32 v69, 16, v68
	v_lshlrev_b32_e32 v68, 16, v71
	v_pk_mul_f32 v[68:69], v[72:73], v[68:69]
	s_nop 0
	v_pk_mul_f32 v[48:49], v[48:49], v[68:69]
	v_add_u32_e32 v68, 0x2a800, v64
	v_add_u32_e32 v72, v68, v65
	v_ashrrev_i32_e32 v73, 31, v72
	v_lshl_add_u64 v[72:73], v[72:73], 1, s[6:7]
	v_add_co_u32_e32 v74, vcc, s75, v72
	s_nop 1
	v_addc_co_u32_e32 v75, vcc, 0, v73, vcc
	global_load_ushort v69, v[74:75], off
	s_waitcnt vmcnt(0)
	v_lshlrev_b32_e32 v69, 16, v69
	v_max_f32_e32 v69, v69, v69
	v_max_f32_e32 v69, 0x1e3ce508, v69
	v_rcp_f32_e32 v74, v69
	v_add_u32_e32 v69, 0x2bc00, v64
	v_add_u32_e32 v76, v69, v65
	v_ashrrev_i32_e32 v77, 31, v76
	v_lshl_add_u64 v[76:77], v[76:77], 1, s[6:7]
	v_add_co_u32_e32 v78, vcc, s75, v76
	s_nop 1
	v_addc_co_u32_e32 v79, vcc, 0, v77, vcc
	global_load_ushort v71, v[78:79], off
	v_add_co_u32_e32 v72, vcc, s81, v72
	s_waitcnt vmcnt(0)
	v_lshlrev_b32_e32 v71, 16, v71
	v_max_f32_e32 v71, v71, v71
	v_max_f32_e32 v71, 0x1e3ce508, v71
	v_addc_co_u32_e32 v73, vcc, 0, v73, vcc
	v_rcp_f32_e32 v75, v71
	global_load_ushort v71, v[72:73], off offset:2048
	v_add_co_u32_e32 v72, vcc, s81, v76
	s_nop 1
	v_addc_co_u32_e32 v73, vcc, 0, v77, vcc
	global_load_ushort v72, v[72:73], off offset:2048
	s_waitcnt vmcnt(0)
	v_lshlrev_b32_e32 v73, 16, v72
	v_lshlrev_b32_e32 v72, 16, v71
	v_pk_mul_f32 v[72:73], v[74:75], v[72:73]
	v_add_u32_e32 v75, 0x32000, v64
	v_pk_mul_f32 v[50:51], v[50:51], v[72:73]
	v_add_u32_e32 v72, v75, v65
	v_ashrrev_i32_e32 v73, 31, v72
	v_lshl_add_u64 v[72:73], v[72:73], 1, s[6:7]
	v_add_co_u32_e32 v76, vcc, s75, v72
	s_nop 1
	v_addc_co_u32_e32 v77, vcc, 0, v73, vcc
	global_load_ushort v71, v[76:77], off
	v_add_u32_e32 v77, 0x33400, v64
	v_add_u32_e32 v80, v77, v65
	v_ashrrev_i32_e32 v81, 31, v80
	v_lshl_add_u64 v[80:81], v[80:81], 1, s[6:7]
	v_add_co_u32_e32 v82, vcc, s75, v80
	v_add_u32_e32 v76, 0x35c00, v64
	s_nop 0
	v_addc_co_u32_e32 v83, vcc, 0, v81, vcc
	v_add_co_u32_e32 v72, vcc, s81, v72
	s_waitcnt vmcnt(0)
	v_lshlrev_b32_e32 v71, 16, v71
	v_max_f32_e32 v71, v71, v71
	v_max_f32_e32 v71, 0x1e3ce508, v71
	v_rcp_f32_e32 v78, v71
	global_load_ushort v71, v[82:83], off
	v_addc_co_u32_e32 v73, vcc, 0, v73, vcc
	v_add_u32_e32 v82, v76, v65
	v_ashrrev_i32_e32 v83, 31, v82
	v_lshl_add_u64 v[82:83], v[82:83], 1, s[6:7]
	s_waitcnt vmcnt(0)
	v_lshlrev_b32_e32 v71, 16, v71
	v_max_f32_e32 v71, v71, v71
	v_max_f32_e32 v71, 0x1e3ce508, v71
	v_rcp_f32_e32 v79, v71
	global_load_ushort v71, v[72:73], off offset:2048
	v_add_co_u32_e32 v72, vcc, s81, v80
	s_nop 1
	v_addc_co_u32_e32 v73, vcc, 0, v81, vcc
	global_load_ushort v72, v[72:73], off offset:2048
	s_waitcnt vmcnt(0)
	v_lshlrev_b32_e32 v73, 16, v72
	v_lshlrev_b32_e32 v72, 16, v71
	v_pk_mul_f32 v[72:73], v[78:79], v[72:73]
	v_add_u32_e32 v78, 0x34800, v64
	v_pk_mul_f32 v[52:53], v[52:53], v[72:73]
	v_add_u32_e32 v72, v78, v65
	v_ashrrev_i32_e32 v73, 31, v72
	v_lshl_add_u64 v[72:73], v[72:73], 1, s[6:7]
	v_add_co_u32_e32 v80, vcc, s75, v72
	s_nop 1
	v_addc_co_u32_e32 v81, vcc, 0, v73, vcc
	global_load_ushort v71, v[80:81], off
	v_add_co_u32_e32 v84, vcc, s75, v82
	s_waitcnt vmcnt(0)
	v_lshlrev_b32_e32 v71, 16, v71
	v_max_f32_e32 v71, v71, v71
	v_max_f32_e32 v71, 0x1e3ce508, v71
	v_addc_co_u32_e32 v85, vcc, 0, v83, vcc
	v_rcp_f32_e32 v80, v71
	global_load_ushort v71, v[84:85], off
	v_add_co_u32_e32 v72, vcc, s81, v72
	s_waitcnt vmcnt(0)
	v_lshlrev_b32_e32 v71, 16, v71
	v_max_f32_e32 v71, v71, v71
	v_max_f32_e32 v71, 0x1e3ce508, v71
	v_addc_co_u32_e32 v73, vcc, 0, v73, vcc
	v_rcp_f32_e32 v81, v71
	global_load_ushort v71, v[72:73], off offset:2048
	v_add_co_u32_e32 v72, vcc, s81, v82
	s_nop 1
	v_addc_co_u32_e32 v73, vcc, 0, v83, vcc
	global_load_ushort v72, v[72:73], off offset:2048
	s_waitcnt vmcnt(0)
	v_lshlrev_b32_e32 v73, 16, v72
	v_lshlrev_b32_e32 v72, 16, v71
	v_pk_mul_f32 v[72:73], v[80:81], v[72:73]
	s_nop 0
	v_pk_mul_f32 v[54:55], v[54:55], v[72:73]
	v_add_u32_e32 v72, 0x3c000, v64
	v_add_u32_e32 v80, v72, v65
	v_ashrrev_i32_e32 v81, 31, v80
	v_lshl_add_u64 v[80:81], v[80:81], 1, s[6:7]
	v_add_co_u32_e32 v82, vcc, s75, v80
	s_nop 1
	v_addc_co_u32_e32 v83, vcc, 0, v81, vcc
	global_load_ushort v71, v[82:83], off
	s_waitcnt vmcnt(0)
	v_lshlrev_b32_e32 v71, 16, v71
	v_max_f32_e32 v71, v71, v71
	v_max_f32_e32 v71, 0x1e3ce508, v71
	v_rcp_f32_e32 v82, v71
	v_add_u32_e32 v71, 0x3d400, v64
	v_add_u32_e32 v84, v71, v65
	v_ashrrev_i32_e32 v85, 31, v84
	v_lshl_add_u64 v[84:85], v[84:85], 1, s[6:7]
	v_add_co_u32_e32 v86, vcc, s75, v84
	s_nop 1
	v_addc_co_u32_e32 v87, vcc, 0, v85, vcc
	global_load_ushort v73, v[86:87], off
	v_add_co_u32_e32 v80, vcc, s81, v80
	s_waitcnt vmcnt(0)
; DI float bf2f(bf16_t v) { return __uint_as_float(((unsigned)v) << 16); }
; DI int crow(int r, int h) { return (r & 3) + 8 * (r >> 2) + 4 * h; }
; DI void phase_merge(const Params& p, int g, char* smem, int bid, int nb) {
;     ...
;     const bf16_t* pt = proj + (size_t)mt * 128 * NPROJ; bf16_t* mgt = mg + (size_t)mt * 128 * 1024;
; #pragma unroll
;     for (int mi = 0; mi < 2; ++mi)
; #pragma unroll
;       for (int ni = 0; ni < 2; ++ni)
; #pragma unroll
;         for (int r = 0; r < 16; ++r) {
;           const int off = (wm * 64 + mi * 32 + crow(r, h)) * NPROJ + nt * 128 + wn * 64 + ni * 32 + l31;
;           const float sga = bf2f(pt[off + PGA]), sgb = fmaxf(bf2f(pt[off + PGB]), 1e-20f);
;           acc[mi][ni][r] *= sga * __builtin_amdgcn_rcpf(sgb);
;           if (r == 15) asm volatile("" ::: "memory");
;         }
	v_lshlrev_b32_e32 v73, 16, v73
	v_max_f32_e32 v73, v73, v73
	v_max_f32_e32 v73, 0x1e3ce508, v73
	v_addc_co_u32_e32 v81, vcc, 0, v81, vcc
	v_rcp_f32_e32 v83, v73
	global_load_ushort v73, v[80:81], off offset:2048
	v_add_co_u32_e32 v80, vcc, s81, v84
	s_nop 1
	v_addc_co_u32_e32 v81, vcc, 0, v85, vcc
	global_load_ushort v74, v[80:81], off offset:2048
	s_waitcnt vmcnt(1)
	v_lshlrev_b32_e32 v80, 16, v73
	v_add_u32_e32 v73, 0x3e800, v64
	s_waitcnt vmcnt(0)
	v_lshlrev_b32_e32 v81, 16, v74
	v_pk_mul_f32 v[80:81], v[82:83], v[80:81]
	s_nop 0
	v_pk_mul_f32 v[56:57], v[56:57], v[80:81]
	v_add_u32_e32 v80, v73, v65
	v_ashrrev_i32_e32 v81, 31, v80
	v_lshl_add_u64 v[80:81], v[80:81], 1, s[6:7]
	v_add_co_u32_e32 v82, vcc, s75, v80
	s_nop 1
	v_addc_co_u32_e32 v83, vcc, 0, v81, vcc
	global_load_ushort v74, v[82:83], off
	s_waitcnt vmcnt(0)
	v_lshlrev_b32_e32 v74, 16, v74
	v_max_f32_e32 v74, v74, v74
	v_max_f32_e32 v74, 0x1e3ce508, v74
	v_rcp_f32_e32 v82, v74
	v_add_u32_e32 v74, 0x3fc00, v64
	v_add_u32_e32 v84, v74, v65
	v_ashrrev_i32_e32 v85, 31, v84
	v_lshl_add_u64 v[84:85], v[84:85], 1, s[6:7]
	v_add_co_u32_e32 v86, vcc, s75, v84
	s_nop 1
	v_addc_co_u32_e32 v87, vcc, 0, v85, vcc
	global_load_ushort v79, v[86:87], off
	v_add_co_u32_e32 v80, vcc, s81, v80
	s_waitcnt vmcnt(0)
	v_lshlrev_b32_e32 v79, 16, v79
	v_max_f32_e32 v79, v79, v79
	v_max_f32_e32 v79, 0x1e3ce508, v79
	v_addc_co_u32_e32 v81, vcc, 0, v81, vcc
	v_rcp_f32_e32 v83, v79
	global_load_ushort v79, v[80:81], off offset:2048
	v_add_co_u32_e32 v80, vcc, s81, v84
	s_nop 1
	v_addc_co_u32_e32 v81, vcc, 0, v85, vcc
	global_load_ushort v80, v[80:81], off offset:2048
	s_waitcnt vmcnt(0)
	v_lshlrev_b32_e32 v81, 16, v80
	v_lshlrev_b32_e32 v80, 16, v79
	v_pk_mul_f32 v[80:81], v[82:83], v[80:81]
	v_add_u32_e32 v79, 0x46000, v64
	v_pk_mul_f32 v[58:59], v[58:59], v[80:81]
	v_add_u32_e32 v80, v79, v65
	v_ashrrev_i32_e32 v81, 31, v80
	v_lshl_add_u64 v[82:83], v[80:81], 1, s[6:7]
	v_add_co_u32_e32 v80, vcc, s75, v82
	s_nop 1
	v_addc_co_u32_e32 v81, vcc, 0, v83, vcc
	global_load_ushort v80, v[80:81], off
	s_waitcnt vmcnt(0)
	v_lshlrev_b32_e32 v80, 16, v80
	v_max_f32_e32 v80, v80, v80
	v_max_f32_e32 v80, 0x1e3ce508, v80
	v_rcp_f32_e32 v84, v80
	v_add_u32_e32 v80, 0x47400, v64
	v_add_u32_e32 v86, v80, v65
	v_ashrrev_i32_e32 v87, 31, v86
	v_lshl_add_u64 v[86:87], v[86:87], 1, s[6:7]
	v_add_co_u32_e32 v88, vcc, s75, v86
	s_nop 1
	v_addc_co_u32_e32 v89, vcc, 0, v87, vcc
	global_load_ushort v81, v[88:89], off
	v_add_co_u32_e32 v82, vcc, s81, v82
	s_waitcnt vmcnt(0)
	v_lshlrev_b32_e32 v81, 16, v81
	v_max_f32_e32 v81, v81, v81
	v_max_f32_e32 v81, 0x1e3ce508, v81
	v_addc_co_u32_e32 v83, vcc, 0, v83, vcc
	v_rcp_f32_e32 v85, v81
	global_load_ushort v81, v[82:83], off offset:2048
	v_add_co_u32_e32 v82, vcc, s81, v86
	s_nop 1
	v_addc_co_u32_e32 v83, vcc, 0, v87, vcc
	global_load_ushort v82, v[82:83], off offset:2048
	s_waitcnt vmcnt(0)
	v_lshlrev_b32_e32 v83, 16, v82
	v_lshlrev_b32_e32 v82, 16, v81
	v_pk_mul_f32 v[82:83], v[84:85], v[82:83]
	v_add_u32_e32 v81, 0x48800, v64
	v_pk_mul_f32 v[60:61], v[60:61], v[82:83]
	v_add_u32_e32 v82, v81, v65
	v_ashrrev_i32_e32 v83, 31, v82
	v_lshl_add_u64 v[84:85], v[82:83], 1, s[6:7]
	v_add_co_u32_e32 v82, vcc, s75, v84
	s_nop 1
	v_addc_co_u32_e32 v83, vcc, 0, v85, vcc
	global_load_ushort v82, v[82:83], off
	s_waitcnt vmcnt(0)
	v_lshlrev_b32_e32 v82, 16, v82
	v_max_f32_e32 v82, v82, v82
	v_max_f32_e32 v82, 0x1e3ce508, v82
	v_rcp_f32_e32 v86, v82
	v_add_u32_e32 v82, 0x49c00, v64
	v_add_u32_e32 v64, v82, v65
	v_ashrrev_i32_e32 v65, 31, v64
	v_lshl_add_u64 v[64:65], v[64:65], 1, s[6:7]
	v_add_co_u32_e32 v88, vcc, s75, v64
	s_nop 1
	v_addc_co_u32_e32 v89, vcc, 0, v65, vcc
	global_load_ushort v83, v[88:89], off
	v_add_co_u32_e32 v84, vcc, s81, v84
	s_waitcnt vmcnt(0)
	v_lshlrev_b32_e32 v83, 16, v83
	v_addc_co_u32_e32 v85, vcc, 0, v85, vcc
	v_max_f32_e32 v83, v83, v83
	v_add_co_u32_e32 v64, vcc, s81, v64
	v_max_f32_e32 v83, 0x1e3ce508, v83
	s_nop 0
	v_addc_co_u32_e32 v65, vcc, 0, v65, vcc
	v_rcp_f32_e32 v87, v83
	global_load_ushort v83, v[84:85], off offset:2048
	s_nop 0
	global_load_ushort v64, v[64:65], off offset:2048
	s_waitcnt vmcnt(0)
	v_lshlrev_b32_e32 v65, 16, v64
	v_lshlrev_b32_e32 v64, 16, v83
	v_pk_mul_f32 v[64:65], v[86:87], v[64:65]
	s_nop 0
	v_pk_mul_f32 v[62:63], v[62:63], v[64:65]
	v_add_u32_e32 v64, v66, v70
	v_ashrrev_i32_e32 v65, 31, v64
	v_lshl_add_u64 v[64:65], v[64:65], 1, s[6:7]
	v_add_co_u32_e32 v84, vcc, s75, v64
	s_nop 1
	v_addc_co_u32_e32 v85, vcc, 0, v65, vcc
	global_load_ushort v66, v[84:85], off
	v_add_u32_e32 v84, v67, v70
	v_ashrrev_i32_e32 v85, 31, v84
	v_lshl_add_u64 v[84:85], v[84:85], 1, s[6:7]
	v_add_co_u32_e32 v86, vcc, s75, v84
	s_waitcnt vmcnt(0)
	v_lshlrev_b32_e32 v66, 16, v66
	v_addc_co_u32_e32 v87, vcc, 0, v85, vcc
	global_load_ushort v67, v[86:87], off
	v_add_co_u32_e32 v64, vcc, s81, v64
	v_max_f32_e32 v66, v66, v66
	s_nop 0
	v_addc_co_u32_e32 v65, vcc, 0, v65, vcc
	global_load_ushort v83, v[64:65], off offset:2048
	v_add_co_u32_e32 v64, vcc, s81, v84
	v_max_f32_e32 v66, 0x1e3ce508, v66
	s_nop 0
	v_addc_co_u32_e32 v65, vcc, 0, v85, vcc
	global_load_ushort v64, v[64:65], off offset:2048
	v_rcp_f32_e32 v66, v66
	s_waitcnt vmcnt(2)
	v_lshlrev_b32_e32 v67, 16, v67
	v_max_f32_e32 v67, v67, v67
	v_max_f32_e32 v67, 0x1e3ce508, v67
	v_rcp_f32_e32 v67, v67
	s_waitcnt vmcnt(0)
; DI float bf2f(bf16_t v) { return __uint_as_float(((unsigned)v) << 16); }
; DI int crow(int r, int h) { return (r & 3) + 8 * (r >> 2) + 4 * h; }
; DI void phase_merge(const Params& p, int g, char* smem, int bid, int nb) {
;     ...
;         for (int r = 0; r < 16; ++r) {
;           const int off = (wm * 64 + mi * 32 + crow(r, h)) * NPROJ + nt * 128 + wn * 64 + ni * 32 + l31;
;           const float sga = bf2f(pt[off + PGA]), sgb = fmaxf(bf2f(pt[off + PGB]), 1e-20f);
;           acc[mi][ni][r] *= sga * __builtin_amdgcn_rcpf(sgb);
;           if (r == 15) asm volatile("" ::: "memory");
;         }
	v_lshlrev_b32_e32 v65, 16, v64
	v_lshlrev_b32_e32 v64, 16, v83
	v_pk_mul_f32 v[64:65], v[66:67], v[64:65]
	s_nop 0
	v_pk_mul_f32 v[16:17], v[16:17], v[64:65]
	v_add_u32_e32 v64, v68, v70
	v_ashrrev_i32_e32 v65, 31, v64
	v_lshl_add_u64 v[64:65], v[64:65], 1, s[6:7]
	v_add_u32_e32 v68, v69, v70
	v_add_co_u32_e32 v66, vcc, s75, v64
	v_ashrrev_i32_e32 v69, 31, v68
	s_nop 0
	v_addc_co_u32_e32 v67, vcc, 0, v65, vcc
	v_lshl_add_u64 v[68:69], v[68:69], 1, s[6:7]
	v_add_co_u32_e32 v84, vcc, s75, v68
	global_load_ushort v66, v[66:67], off
	s_nop 0
	v_addc_co_u32_e32 v85, vcc, 0, v69, vcc
	v_add_co_u32_e32 v64, vcc, s81, v64
	s_nop 1
	v_addc_co_u32_e32 v65, vcc, 0, v65, vcc
	global_load_ushort v83, v[64:65], off offset:2048
	global_load_ushort v67, v[84:85], off
	v_add_co_u32_e32 v64, vcc, s81, v68
	v_add_u32_e32 v68, v77, v70
	s_nop 0
	v_addc_co_u32_e32 v65, vcc, 0, v69, vcc
	global_load_ushort v64, v[64:65], off offset:2048
	v_ashrrev_i32_e32 v69, 31, v68
	v_lshl_add_u64 v[68:69], v[68:69], 1, s[6:7]
	s_waitcnt vmcnt(3)
	v_lshlrev_b32_e32 v66, 16, v66
	v_max_f32_e32 v66, v66, v66
	v_max_f32_e32 v66, 0x1e3ce508, v66
	v_rcp_f32_e32 v66, v66
	s_waitcnt vmcnt(1)
	v_lshlrev_b32_e32 v67, 16, v67
	v_max_f32_e32 v67, v67, v67
	v_max_f32_e32 v67, 0x1e3ce508, v67
	v_rcp_f32_e32 v67, v67
	s_waitcnt vmcnt(0)
	v_lshlrev_b32_e32 v65, 16, v64
	v_lshlrev_b32_e32 v64, 16, v83
	v_pk_mul_f32 v[64:65], v[66:67], v[64:65]
	s_nop 0
	v_pk_mul_f32 v[18:19], v[18:19], v[64:65]
	v_add_u32_e32 v64, v75, v70
	v_ashrrev_i32_e32 v65, 31, v64
	v_lshl_add_u64 v[64:65], v[64:65], 1, s[6:7]
	v_add_co_u32_e32 v66, vcc, s75, v64
	s_nop 1
	v_addc_co_u32_e32 v67, vcc, 0, v65, vcc
	v_add_co_u32_e32 v84, vcc, s75, v68
	global_load_ushort v66, v[66:67], off
	s_nop 0
	v_addc_co_u32_e32 v85, vcc, 0, v69, vcc
	v_add_co_u32_e32 v64, vcc, s81, v64
	s_nop 1
	v_addc_co_u32_e32 v65, vcc, 0, v65, vcc
	global_load_ushort v75, v[64:65], off offset:2048
	global_load_ushort v67, v[84:85], off
	v_add_co_u32_e32 v64, vcc, s81, v68
	v_add_u32_e32 v68, v76, v70
	s_nop 0
	v_addc_co_u32_e32 v65, vcc, 0, v69, vcc
	global_load_ushort v64, v[64:65], off offset:2048
	v_ashrrev_i32_e32 v69, 31, v68
	v_lshl_add_u64 v[68:69], v[68:69], 1, s[6:7]
	s_waitcnt vmcnt(3)
	v_lshlrev_b32_e32 v66, 16, v66
	v_max_f32_e32 v66, v66, v66
	v_max_f32_e32 v66, 0x1e3ce508, v66
	v_rcp_f32_e32 v66, v66
	s_waitcnt vmcnt(1)
	v_lshlrev_b32_e32 v67, 16, v67
	v_max_f32_e32 v67, v67, v67
	v_max_f32_e32 v67, 0x1e3ce508, v67
	v_rcp_f32_e32 v67, v67
	s_waitcnt vmcnt(0)
	v_lshlrev_b32_e32 v65, 16, v64
	v_lshlrev_b32_e32 v64, 16, v75
	v_pk_mul_f32 v[64:65], v[66:67], v[64:65]
	s_nop 0
	v_pk_mul_f32 v[20:21], v[20:21], v[64:65]
	v_add_u32_e32 v64, v78, v70
	v_ashrrev_i32_e32 v65, 31, v64
	v_lshl_add_u64 v[66:67], v[64:65], 1, s[6:7]
	v_add_co_u32_e32 v64, vcc, s75, v66
	s_nop 1
	v_addc_co_u32_e32 v65, vcc, 0, v67, vcc
	v_add_co_u32_e32 v76, vcc, s75, v68
	global_load_ushort v64, v[64:65], off
	s_nop 0
	v_addc_co_u32_e32 v77, vcc, 0, v69, vcc
	v_add_co_u32_e32 v66, vcc, s81, v66
	s_nop 1
	v_addc_co_u32_e32 v67, vcc, 0, v67, vcc
	global_load_ushort v75, v[66:67], off offset:2048
	global_load_ushort v65, v[76:77], off
	v_add_co_u32_e32 v66, vcc, s81, v68
	v_add_u32_e32 v68, v71, v70
	s_nop 0
	v_addc_co_u32_e32 v67, vcc, 0, v69, vcc
	global_load_ushort v66, v[66:67], off offset:2048
	v_ashrrev_i32_e32 v69, 31, v68
	v_lshl_add_u64 v[68:69], v[68:69], 1, s[6:7]
	s_waitcnt vmcnt(3)
	v_lshlrev_b32_e32 v64, 16, v64
	v_max_f32_e32 v64, v64, v64
	v_max_f32_e32 v64, 0x1e3ce508, v64
	v_rcp_f32_e32 v64, v64
	s_waitcnt vmcnt(1)
	v_lshlrev_b32_e32 v65, 16, v65
	v_max_f32_e32 v65, v65, v65
	v_max_f32_e32 v65, 0x1e3ce508, v65
	v_rcp_f32_e32 v65, v65
	s_waitcnt vmcnt(0)
	v_lshlrev_b32_e32 v67, 16, v66
	v_lshlrev_b32_e32 v66, 16, v75
	v_pk_mul_f32 v[64:65], v[64:65], v[66:67]
	s_nop 0
	v_pk_mul_f32 v[22:23], v[22:23], v[64:65]
	v_add_u32_e32 v64, v72, v70
	v_ashrrev_i32_e32 v65, 31, v64
	v_lshl_add_u64 v[64:65], v[64:65], 1, s[6:7]
	v_add_co_u32_e32 v66, vcc, s75, v64
	s_nop 1
	v_addc_co_u32_e32 v67, vcc, 0, v65, vcc
	v_add_co_u32_e32 v76, vcc, s75, v68
	global_load_ushort v66, v[66:67], off
	s_nop 0
	v_addc_co_u32_e32 v77, vcc, 0, v69, vcc
	v_add_co_u32_e32 v64, vcc, s81, v64
	s_nop 1
	v_addc_co_u32_e32 v65, vcc, 0, v65, vcc
	global_load_ushort v71, v[64:65], off offset:2048
	global_load_ushort v67, v[76:77], off
	v_add_co_u32_e32 v64, vcc, s81, v68
	v_add_u32_e32 v68, v74, v70
	s_nop 0
	v_addc_co_u32_e32 v65, vcc, 0, v69, vcc
	global_load_ushort v64, v[64:65], off offset:2048
	v_ashrrev_i32_e32 v69, 31, v68
	v_lshl_add_u64 v[68:69], v[68:69], 1, s[6:7]
	s_waitcnt vmcnt(3)
	v_lshlrev_b32_e32 v66, 16, v66
	v_max_f32_e32 v66, v66, v66
	v_max_f32_e32 v66, 0x1e3ce508, v66
	v_rcp_f32_e32 v66, v66
	s_waitcnt vmcnt(1)
	v_lshlrev_b32_e32 v67, 16, v67
	v_max_f32_e32 v67, v67, v67
	v_max_f32_e32 v67, 0x1e3ce508, v67
	v_rcp_f32_e32 v67, v67
	s_waitcnt vmcnt(0)
	v_lshlrev_b32_e32 v65, 16, v64
	v_lshlrev_b32_e32 v64, 16, v71
	v_pk_mul_f32 v[64:65], v[66:67], v[64:65]
	s_nop 0
	v_pk_mul_f32 v[24:25], v[24:25], v[64:65]
	v_add_u32_e32 v64, v73, v70
	v_ashrrev_i32_e32 v65, 31, v64
	v_lshl_add_u64 v[64:65], v[64:65], 1, s[6:7]
	v_add_co_u32_e32 v66, vcc, s75, v64
	s_nop 1
	v_addc_co_u32_e32 v67, vcc, 0, v65, vcc
	v_add_co_u32_e32 v72, vcc, s75, v68
	global_load_ushort v66, v[66:67], off
	s_nop 0
	v_addc_co_u32_e32 v73, vcc, 0, v69, vcc
	v_add_co_u32_e32 v64, vcc, s81, v64
	s_nop 1
	v_addc_co_u32_e32 v65, vcc, 0, v65, vcc
	global_load_ushort v71, v[64:65], off offset:2048
	global_load_ushort v67, v[72:73], off
	v_add_co_u32_e32 v64, vcc, s81, v68
	v_add_u32_e32 v68, v80, v70
	s_nop 0
	v_addc_co_u32_e32 v65, vcc, 0, v69, vcc
	global_load_ushort v64, v[64:65], off offset:2048
	v_ashrrev_i32_e32 v69, 31, v68
	v_lshl_add_u64 v[68:69], v[68:69], 1, s[6:7]
	s_waitcnt vmcnt(3)
; template <bool SWAP>
; DI void gemm_tile(const bf16_t* __restrict__ A, int lda, const bf16_t* __restrict__ Bt, int ldb, int K, f32x16 (&acc)[2][2], bf16_t* As, bf16_t* Bs_unused) {
;     ...
;   const int tid = TID(), lane = tid & 63, wave = tid >> 6, wm = wave >> 1, wn = wave & 1;
;   const int lr = tid >> 3, lc = (tid & 7) * 8;
;   const bf16_t* ga = A + (size_t)lr * lda + lc;
;   const bf16_t* gb = Bt + (size_t)lr * ldb + lc;
;   u32x4 ra0[4], rb0[4], ra1[4], rb1[4];
;   auto load_stage = [&](u32x4 (&ra)[4], u32x4 (&rb)[4], int t) __attribute__((always_inline)) {
; #pragma unroll
;     for (int i = 0; i < 4; ++i) { ra[i] = *(const u32x4*)(ga + (size_t)(32 * i) * lda + t * 64); rb[i] = *(const u32x4*)(gb + (size_t)(32 * i) * ldb + t * 64); }
;   };
;   auto write_stage = [&](const u32x4 (&ra)[4], const u32x4 (&rb)[4], int buf) __attribute__((always_inline)) {
;     bf16_t* Ad = As + buf * 2 * GT_IMG; bf16_t* Bd = Ad + GT_IMG;
; #pragma unroll
;     for (int i = 0; i < 4; ++i) { *(u32x4*)(Ad + (lr + 32 * i) * 72 + lc) = ra[i]; *(u32x4*)(Bd + (lr + 32 * i) * 72 + lc) = rb[i]; }
;   };
;   const int fr = lane & 31, fk = (lane >> 5) * 8;
;   const int pao = (wm * 64 + fr) * 72 + fk, pbo = GT_IMG + (wn * 64 + fr) * 72 + fk;
;   auto frag_read = [&](bf16x8 (&f)[4], const bf16_t* pa, const bf16_t* pb, int so) __attribute__((always_inline)) {
;     f[0] = *(const bf16x8*)(pa + so); f[1] = *(const bf16x8*)(pb + so); f[2] = *(const bf16x8*)(pb + 32 * 72 + so); f[3] = *(const bf16x8*)(pa + 32 * 72 + so);
;   };
;   auto mfma4 = [&](const bf16x8 (&f)[4]) __attribute__((always_inline)) {
;     if (SWAP) {
;       acc[0][0] = MFMA32(f[1], f[0], acc[0][0]); acc[0][1] = MFMA32(f[2], f[0], acc[0][1]);
;       acc[1][0] = MFMA32(f[1], f[3], acc[1][0]); acc[1][1] = MFMA32(f[2], f[3], acc[1][1]);
;     } else {
;       acc[0][0] = MFMA32(f[0], f[1], acc[0][0]); acc[0][1] = MFMA32(f[0], f[2], acc[0][1]);
; DI void phase_merge(const Params& p, int g, char* smem, int bid, int nb) {
;     ...
;         for (int r = 0; r < 16; ++r) {
;           const int off = (wm * 64 + mi * 32 + crow(r, h)) * NPROJ + nt * 128 + wn * 64 + ni * 32 + l31;
;           const float sga = bf2f(pt[off + PGA]), sgb = fmaxf(bf2f(pt[off + PGB]), 1e-20f);
;           acc[mi][ni][r] *= sga * __builtin_amdgcn_rcpf(sgb);
;           if (r == 15) asm volatile("" ::: "memory");
;         }
	v_lshlrev_b32_e32 v66, 16, v66
	v_max_f32_e32 v66, v66, v66
	v_max_f32_e32 v66, 0x1e3ce508, v66
	v_rcp_f32_e32 v66, v66
	s_waitcnt vmcnt(1)
	v_lshlrev_b32_e32 v67, 16, v67
	v_max_f32_e32 v67, v67, v67
	v_max_f32_e32 v67, 0x1e3ce508, v67
	v_rcp_f32_e32 v67, v67
	s_waitcnt vmcnt(0)
	v_lshlrev_b32_e32 v65, 16, v64
	v_lshlrev_b32_e32 v64, 16, v71
	v_pk_mul_f32 v[64:65], v[66:67], v[64:65]
	s_nop 0
	v_pk_mul_f32 v[26:27], v[26:27], v[64:65]
	v_add_u32_e32 v64, v79, v70
	v_ashrrev_i32_e32 v65, 31, v64
	v_lshl_add_u64 v[64:65], v[64:65], 1, s[6:7]
	v_add_co_u32_e32 v66, vcc, s75, v64
	s_nop 1
	v_addc_co_u32_e32 v67, vcc, 0, v65, vcc
	v_add_co_u32_e32 v72, vcc, s75, v68
	global_load_ushort v66, v[66:67], off
	s_nop 0
	v_addc_co_u32_e32 v73, vcc, 0, v69, vcc
	v_add_co_u32_e32 v64, vcc, s81, v64
	s_nop 1
	v_addc_co_u32_e32 v65, vcc, 0, v65, vcc
	global_load_ushort v71, v[64:65], off offset:2048
	global_load_ushort v67, v[72:73], off
	v_add_co_u32_e32 v64, vcc, s81, v68
	v_add_u32_e32 v68, v82, v70
	s_nop 0
	v_addc_co_u32_e32 v65, vcc, 0, v69, vcc
	global_load_ushort v64, v[64:65], off offset:2048
	v_ashrrev_i32_e32 v69, 31, v68
	v_lshl_add_u64 v[68:69], v[68:69], 1, s[6:7]
	s_waitcnt vmcnt(3)
	v_lshlrev_b32_e32 v66, 16, v66
	v_max_f32_e32 v66, v66, v66
	v_max_f32_e32 v66, 0x1e3ce508, v66
	v_rcp_f32_e32 v66, v66
	s_waitcnt vmcnt(1)
	v_lshlrev_b32_e32 v67, 16, v67
	v_max_f32_e32 v67, v67, v67
	v_max_f32_e32 v67, 0x1e3ce508, v67
	v_rcp_f32_e32 v67, v67
	s_waitcnt vmcnt(0)
	v_lshlrev_b32_e32 v65, 16, v64
	v_lshlrev_b32_e32 v64, 16, v71
	v_pk_mul_f32 v[64:65], v[66:67], v[64:65]
	s_nop 0
	v_pk_mul_f32 v[28:29], v[28:29], v[64:65]
	v_add_u32_e32 v64, v81, v70
	v_ashrrev_i32_e32 v65, 31, v64
	v_lshl_add_u64 v[64:65], v[64:65], 1, s[6:7]
	v_add_co_u32_e32 v66, vcc, s75, v64
	s_nop 1
	v_addc_co_u32_e32 v67, vcc, 0, v65, vcc
	v_add_co_u32_e32 v70, vcc, s75, v68
	global_load_ushort v66, v[66:67], off
	s_nop 0
	v_addc_co_u32_e32 v71, vcc, 0, v69, vcc
	global_load_ushort v67, v[70:71], off
	v_add_co_u32_e32 v64, vcc, s81, v64
	s_waitcnt vmcnt(1)
	v_lshlrev_b32_e32 v66, 16, v66
	v_addc_co_u32_e32 v65, vcc, 0, v65, vcc
	global_load_ushort v70, v[64:65], off offset:2048
	v_add_co_u32_e32 v64, vcc, s81, v68
	s_waitcnt vmcnt(1)
	v_lshlrev_b32_e32 v67, 16, v67
	v_addc_co_u32_e32 v65, vcc, 0, v69, vcc
	global_load_ushort v64, v[64:65], off offset:2048
	v_max_f32_e32 v66, v66, v66
	v_max_f32_e32 v67, v67, v67
	v_max_f32_e32 v66, 0x1e3ce508, v66
	v_max_f32_e32 v67, 0x1e3ce508, v67
	v_rcp_f32_e32 v66, v66
	v_rcp_f32_e32 v67, v67
	s_waitcnt vmcnt(0)
	v_lshlrev_b32_e32 v65, 16, v64
	v_lshlrev_b32_e32 v64, 16, v70
	v_ashrrev_i32_e32 v152, 3, v155
	v_pk_mul_f32 v[64:65], v[66:67], v[64:65]
	v_ashrrev_i32_e32 v153, 31, v152
	v_pk_mul_f32 v[30:31], v[30:31], v[64:65]
	v_lshlrev_b64 v[64:65], 11, v[152:153]
	v_lshlrev_b32_e32 v68, 4, v155
	v_lshl_add_u64 v[66:67], s[16:17], 0, v[64:65]
	v_and_b32_e32 v192, 0x70, v68
	v_lshl_add_u64 v[128:129], v[66:67], 0, v[192:193]
	v_lshl_add_u64 v[64:65], s[8:9], 0, v[64:65]
	v_add_co_u32_e32 v132, vcc, s18, v128
	v_lshl_add_u64 v[130:131], v[64:65], 0, v[192:193]
	s_nop 0
	v_addc_co_u32_e32 v133, vcc, 0, v129, vcc
	v_add_co_u32_e32 v134, vcc, s18, v130
	global_load_dwordx4 v[64:67], v[128:129], off
	global_load_dwordx4 v[68:71], v[130:131], off
	v_addc_co_u32_e32 v135, vcc, 0, v131, vcc
	v_add_co_u32_e32 v136, vcc, s19, v128
	global_load_dwordx4 v[72:75], v[132:133], off
	global_load_dwordx4 v[76:79], v[134:135], off
	v_addc_co_u32_e32 v137, vcc, 0, v129, vcc
	v_add_co_u32_e32 v138, vcc, s19, v130
	global_load_dwordx4 v[80:83], v[136:137], off
	s_nop 0
	v_addc_co_u32_e32 v139, vcc, 0, v131, vcc
	v_add_co_u32_e32 v140, vcc, s20, v128
	global_load_dwordx4 v[84:87], v[138:139], off
	s_nop 0
	v_addc_co_u32_e32 v141, vcc, 0, v129, vcc
	global_load_dwordx4 v[88:91], v[140:141], off
	v_add_co_u32_e32 v142, vcc, s20, v130
	v_mul_lo_u32 v152, v152, s71
	s_nop 0
	v_addc_co_u32_e32 v143, vcc, 0, v131, vcc
	global_load_dwordx4 v[92:95], v[142:143], off
	global_load_dwordx4 v[112:115], v[128:129], off offset:128
	global_load_dwordx4 v[96:99], v[130:131], off offset:128
	global_load_dwordx4 v[116:119], v[132:133], off offset:128
	global_load_dwordx4 v[100:103], v[134:135], off offset:128
	global_load_dwordx4 v[120:123], v[136:137], off offset:128
	global_load_dwordx4 v[104:107], v[138:139], off offset:128
	global_load_dwordx4 v[124:127], v[140:141], off offset:128
	global_load_dwordx4 v[108:111], v[142:143], off offset:128
	v_add3_u32 v152, 32, v152, v192
	s_barrier
	s_waitcnt vmcnt(15)
	ds_write_b128 v152, v[64:67]
	s_waitcnt vmcnt(14)
	ds_write_b128 v152, v[68:71] offset:18432
	s_waitcnt vmcnt(13)
	ds_write_b128 v152, v[72:75] offset:4608
	s_waitcnt vmcnt(12)
	ds_write_b128 v152, v[76:79] offset:23040
	s_waitcnt vmcnt(11)
	ds_write_b128 v152, v[80:83] offset:9216
	s_waitcnt vmcnt(10)
	ds_write_b128 v152, v[84:87] offset:27648
	s_waitcnt vmcnt(9)
	ds_write_b128 v152, v[88:91] offset:13824
	s_waitcnt vmcnt(8)
	ds_write_b128 v152, v[92:95] offset:32256
	global_load_dwordx4 v[80:83], v[128:129], off offset:256
	global_load_dwordx4 v[64:67], v[130:131], off offset:256
	global_load_dwordx4 v[84:87], v[132:133], off offset:256
	global_load_dwordx4 v[68:71], v[134:135], off offset:256
	global_load_dwordx4 v[88:91], v[136:137], off offset:256
	global_load_dwordx4 v[72:75], v[138:139], off offset:256
	global_load_dwordx4 v[92:95], v[140:141], off offset:256
	global_load_dwordx4 v[76:79], v[142:143], off offset:256
	v_lshrrev_b32_e32 v153, 2, v155
	v_and_b32_e32 v158, 0x5f, v155
	v_and_b32_e32 v154, 8, v153
	v_lshrrev_b32_e32 v153, 1, v155
	v_and_b32_e32 v155, 31, v155
	v_and_or_b32 v153, v153, s80, v155
	v_mad_u64_u32 v[156:157], s[8:9], v153, s72, v[154:155]
	v_lshl_add_u32 v153, v156, 1, 32
	v_mad_u32_u24 v154, v158, s72, v154
	s_waitcnt lgkmcnt(0)
	s_barrier
; template <bool SWAP>
; DI void gemm_tile(const bf16_t* __restrict__ A, int lda, const bf16_t* __restrict__ Bt, int ldb, int K, f32x16 (&acc)[2][2], bf16_t* As, bf16_t* Bs_unused) {
;     ...
;   auto step = [&](int buf, u32x4 (&ra)[4], u32x4 (&rb)[4], bool do_write, bool do_load, int tload) __attribute__((always_inline)) {
;     const bf16_t* pa = As + buf * 2 * GT_IMG + pao; const bf16_t* pb = As + buf * 2 * GT_IMG + pbo;
;     bf16_t* Ad = As + (buf ^ 1) * 2 * GT_IMG; bf16_t* Bd = Ad + GT_IMG;
;     bf16x8 F0[4], F1[4];
;     frag_read(F0, pa, pb, 0);
;     __builtin_amdgcn_sched_barrier(0);
;     frag_read(F1, pa, pb, 16);
;     mfma4(F0);
;     __builtin_amdgcn_sched_barrier(0);
;     frag_read(F0, pa, pb, 32);
;     mfma4(F1);
;     if (do_write) {
; #pragma unroll
;       for (int i = 0; i < 4; ++i) *(u32x4*)(Ad + (lr + 32 * i) * 72 + lc) = ra[i];
;     }
;     __builtin_amdgcn_sched_barrier(0);
;     frag_read(F1, pa, pb, 48);
;     mfma4(F0);
;     if (do_write) {
; #pragma unroll
;       for (int i = 0; i < 4; ++i) *(u32x4*)(Bd + (lr + 32 * i) * 72 + lc) = rb[i];
;     }
;     __builtin_amdgcn_sched_barrier(0);
;     mfma4(F1);
;     if (do_load) load_stage(ra, rb, tload);
;     __builtin_amdgcn_sched_barrier(0);
;   };
;   const int nk = K >> 6;
;   load_stage(ra0, rb0, 0); load_stage(ra1, rb1, 1);
;   __syncthreads();
;   write_stage(ra0, rb0, 0);
;   load_stage(ra0, rb0, 2);
;   __syncthreads();
;   for (int kt = 0; kt < nk; kt += 2) {
;     step(0, ra1, rb1, true, kt + 3 < nk, kt + 3);
;     __syncthreads();
;     step(1, ra0, rb0, kt + 2 < nk, kt + 4 < nk, kt + 4);
;     __syncthreads();
	v_lshl_add_u32 v154, v154, 1, 32
	ds_read_b128 v[156:159], v153
	ds_read_b128 v[160:163], v154 offset:18432
	ds_read_b128 v[164:167], v154 offset:23040
	ds_read_b128 v[168:171], v153 offset:4608
	v_add_u32_e32 v155, 0xd800, v152
	s_waitcnt lgkmcnt(2)
	v_mfma_f32_32x32x16_bf16 v[0:15], v[156:159], v[160:163], v[0:15]
	s_waitcnt lgkmcnt(1)
	v_mfma_f32_32x32x16_bf16 v[32:47], v[156:159], v[164:167], v[32:47]
	s_waitcnt lgkmcnt(0)
	v_mfma_f32_32x32x16_bf16 v[48:63], v[168:171], v[160:163], v[48:63]
	ds_read_b128 v[156:159], v154 offset:18464
	ds_read_b128 v[160:163], v154 offset:23072
	ds_read_b128 v[172:175], v153 offset:32
	ds_read_b128 v[176:179], v153 offset:4640
	v_mfma_f32_32x32x16_bf16 v[16:31], v[168:171], v[164:167], v[16:31]
	s_waitcnt lgkmcnt(1)
	v_mfma_f32_32x32x16_bf16 v[0:15], v[172:175], v[156:159], v[0:15]
	v_mfma_f32_32x32x16_bf16 v[32:47], v[172:175], v[160:163], v[32:47]
	s_waitcnt lgkmcnt(0)
	v_mfma_f32_32x32x16_bf16 v[48:63], v[176:179], v[156:159], v[48:63]
	ds_read_b128 v[156:159], v154 offset:18496
	ds_read_b128 v[164:167], v154 offset:23104
	ds_read_b128 v[168:171], v153 offset:64
	ds_read_b128 v[172:175], v153 offset:4672
	s_waitcnt vmcnt(15)
	ds_write_b128 v152, v[112:115] offset:36864
	s_waitcnt vmcnt(13)
	ds_write_b128 v152, v[116:119] offset:41472
	s_waitcnt vmcnt(11)
	ds_write_b128 v152, v[120:123] offset:46080
	s_waitcnt vmcnt(9)
	ds_write_b128 v152, v[124:127] offset:50688
	v_mfma_f32_32x32x16_bf16 v[16:31], v[176:179], v[160:163], v[16:31]
	ds_read_b128 v[112:115], v154 offset:18528
	ds_read_b128 v[116:119], v154 offset:23136
	ds_read_b128 v[120:123], v153 offset:96
	ds_read_b128 v[124:127], v153 offset:4704
	s_waitcnt lgkmcnt(9)
	v_mfma_f32_32x32x16_bf16 v[0:15], v[168:171], v[156:159], v[0:15]
	ds_write_b128 v152, v[96:99] offset:55296
	ds_write_b128 v152, v[100:103] offset:59904
	ds_write_b128 v152, v[104:107] offset:64512
	s_waitcnt vmcnt(8)
	ds_write_b128 v155, v[108:111] offset:13824
	v_mfma_f32_32x32x16_bf16 v[32:47], v[168:171], v[164:167], v[32:47]
	s_waitcnt lgkmcnt(12)
	v_mfma_f32_32x32x16_bf16 v[48:63], v[172:175], v[156:159], v[48:63]
	v_mfma_f32_32x32x16_bf16 v[16:31], v[172:175], v[164:167], v[16:31]
	s_waitcnt lgkmcnt(0)
	s_barrier
	ds_read_b128 v[156:159], v154 offset:55296
	ds_read_b128 v[160:163], v154 offset:59904
	ds_read_b128 v[164:167], v153 offset:36864
	ds_read_b128 v[168:171], v153 offset:41472
	v_mfma_f32_32x32x16_bf16 v[0:15], v[120:123], v[112:115], v[0:15]
	v_mfma_f32_32x32x16_bf16 v[32:47], v[120:123], v[116:119], v[32:47]
	v_mfma_f32_32x32x16_bf16 v[48:63], v[124:127], v[112:115], v[48:63]
	v_mfma_f32_32x32x16_bf16 v[16:31], v[124:127], v[116:119], v[16:31]
	global_load_dwordx4 v[96:99], v[128:129], off offset:384
	global_load_dwordx4 v[100:103], v[130:131], off offset:384
	global_load_dwordx4 v[104:107], v[132:133], off offset:384
	global_load_dwordx4 v[108:111], v[134:135], off offset:384
	global_load_dwordx4 v[112:115], v[136:137], off offset:384
	global_load_dwordx4 v[116:119], v[138:139], off offset:384
	global_load_dwordx4 v[120:123], v[140:141], off offset:384
	global_load_dwordx4 v[124:127], v[142:143], off offset:384
	s_waitcnt lgkmcnt(1)
	v_mfma_f32_32x32x16_bf16 v[0:15], v[164:167], v[156:159], v[0:15]
	v_mfma_f32_32x32x16_bf16 v[32:47], v[164:167], v[160:163], v[32:47]
	s_waitcnt lgkmcnt(0)
	v_mfma_f32_32x32x16_bf16 v[48:63], v[168:171], v[156:159], v[48:63]
	ds_read_b128 v[156:159], v154 offset:55328
	ds_read_b128 v[164:167], v154 offset:59936
	ds_read_b128 v[172:175], v153 offset:36896
	ds_read_b128 v[176:179], v153 offset:41504
	v_mfma_f32_32x32x16_bf16 v[16:31], v[168:171], v[160:163], v[16:31]
	s_waitcnt lgkmcnt(1)
	v_mfma_f32_32x32x16_bf16 v[0:15], v[172:175], v[156:159], v[0:15]
	v_mfma_f32_32x32x16_bf16 v[32:47], v[172:175], v[164:167], v[32:47]
	s_waitcnt lgkmcnt(0)
	v_mfma_f32_32x32x16_bf16 v[48:63], v[176:179], v[156:159], v[48:63]
	ds_read_b128 v[156:159], v154 offset:55360
	ds_read_b128 v[160:163], v154 offset:59968
	ds_read_b128 v[168:171], v153 offset:36928
	ds_read_b128 v[172:175], v153 offset:41536
	s_waitcnt vmcnt(15)
	ds_write_b128 v152, v[80:83]
	s_waitcnt vmcnt(13)
	ds_write_b128 v152, v[84:87] offset:4608
	s_waitcnt vmcnt(11)
	ds_write_b128 v152, v[88:91] offset:9216
	s_waitcnt vmcnt(9)
	ds_write_b128 v152, v[92:95] offset:13824
	v_mfma_f32_32x32x16_bf16 v[16:31], v[176:179], v[164:167], v[16:31]
	ds_read_b128 v[80:83], v154 offset:55392
	ds_read_b128 v[84:87], v154 offset:60000
	ds_read_b128 v[88:91], v153 offset:36960
	ds_read_b128 v[92:95], v153 offset:41568
	s_waitcnt lgkmcnt(9)
	v_mfma_f32_32x32x16_bf16 v[0:15], v[168:171], v[156:159], v[0:15]
	ds_write_b128 v152, v[64:67] offset:18432
	ds_write_b128 v152, v[68:71] offset:23040
	ds_write_b128 v152, v[72:75] offset:27648
	s_waitcnt vmcnt(8)
	ds_write_b128 v152, v[76:79] offset:32256
	v_mfma_f32_32x32x16_bf16 v[32:47], v[168:171], v[160:163], v[32:47]
	s_waitcnt lgkmcnt(12)
	v_mfma_f32_32x32x16_bf16 v[48:63], v[172:175], v[156:159], v[48:63]
	v_mfma_f32_32x32x16_bf16 v[16:31], v[172:175], v[160:163], v[16:31]
	s_waitcnt lgkmcnt(0)
	s_barrier
; template <bool SWAP>
; DI void gemm_tile(const bf16_t* __restrict__ A, int lda, const bf16_t* __restrict__ Bt, int ldb, int K, f32x16 (&acc)[2][2], bf16_t* As, bf16_t* Bs_unused) {
;     ...
;   auto step = [&](int buf, u32x4 (&ra)[4], u32x4 (&rb)[4], bool do_write, bool do_load, int tload) __attribute__((always_inline)) {
;     const bf16_t* pa = As + buf * 2 * GT_IMG + pao; const bf16_t* pb = As + buf * 2 * GT_IMG + pbo;
;     bf16_t* Ad = As + (buf ^ 1) * 2 * GT_IMG; bf16_t* Bd = Ad + GT_IMG;
;     bf16x8 F0[4], F1[4];
;     frag_read(F0, pa, pb, 0);
;     __builtin_amdgcn_sched_barrier(0);
;     frag_read(F1, pa, pb, 16);
;     mfma4(F0);
;     __builtin_amdgcn_sched_barrier(0);
;     frag_read(F0, pa, pb, 32);
;     mfma4(F1);
;     if (do_write) {
; #pragma unroll
;       for (int i = 0; i < 4; ++i) *(u32x4*)(Ad + (lr + 32 * i) * 72 + lc) = ra[i];
;     }
;     __builtin_amdgcn_sched_barrier(0);
;     frag_read(F1, pa, pb, 48);
;     mfma4(F0);
;     if (do_write) {
; #pragma unroll
;       for (int i = 0; i < 4; ++i) *(u32x4*)(Bd + (lr + 32 * i) * 72 + lc) = rb[i];
;     }
;     __builtin_amdgcn_sched_barrier(0);
;     mfma4(F1);
;     if (do_load) load_stage(ra, rb, tload);
;     __builtin_amdgcn_sched_barrier(0);
;   };
;   const int nk = K >> 6;
;   load_stage(ra0, rb0, 0); load_stage(ra1, rb1, 1);
;   __syncthreads();
;   write_stage(ra0, rb0, 0);
;   load_stage(ra0, rb0, 2);
;   __syncthreads();
;   for (int kt = 0; kt < nk; kt += 2) {
;     step(0, ra1, rb1, true, kt + 3 < nk, kt + 3);
;     __syncthreads();
;     step(1, ra0, rb0, kt + 2 < nk, kt + 4 < nk, kt + 4);
;     __syncthreads();
	ds_read_b128 v[156:159], v154 offset:18432
	ds_read_b128 v[160:163], v154 offset:23040
	ds_read_b128 v[164:167], v153
	ds_read_b128 v[168:171], v153 offset:4608
	v_mfma_f32_32x32x16_bf16 v[0:15], v[88:91], v[80:83], v[0:15]
	v_mfma_f32_32x32x16_bf16 v[32:47], v[88:91], v[84:87], v[32:47]
	v_mfma_f32_32x32x16_bf16 v[48:63], v[92:95], v[80:83], v[48:63]
	v_mfma_f32_32x32x16_bf16 v[16:31], v[92:95], v[84:87], v[16:31]
	global_load_dwordx4 v[64:67], v[128:129], off offset:512
	global_load_dwordx4 v[68:71], v[130:131], off offset:512
	global_load_dwordx4 v[72:75], v[132:133], off offset:512
	global_load_dwordx4 v[76:79], v[134:135], off offset:512
	global_load_dwordx4 v[80:83], v[136:137], off offset:512
	global_load_dwordx4 v[84:87], v[138:139], off offset:512
	global_load_dwordx4 v[88:91], v[140:141], off offset:512
	global_load_dwordx4 v[92:95], v[142:143], off offset:512
	s_waitcnt lgkmcnt(1)
	v_mfma_f32_32x32x16_bf16 v[0:15], v[164:167], v[156:159], v[0:15]
	v_mfma_f32_32x32x16_bf16 v[32:47], v[164:167], v[160:163], v[32:47]
	s_waitcnt lgkmcnt(0)
	v_mfma_f32_32x32x16_bf16 v[48:63], v[168:171], v[156:159], v[48:63]
	ds_read_b128 v[156:159], v154 offset:18464
	ds_read_b128 v[164:167], v154 offset:23072
	ds_read_b128 v[172:175], v153 offset:32
	ds_read_b128 v[176:179], v153 offset:4640
	v_mfma_f32_32x32x16_bf16 v[16:31], v[168:171], v[160:163], v[16:31]
	s_waitcnt lgkmcnt(1)
	v_mfma_f32_32x32x16_bf16 v[0:15], v[172:175], v[156:159], v[0:15]
	v_mfma_f32_32x32x16_bf16 v[32:47], v[172:175], v[164:167], v[32:47]
	s_waitcnt lgkmcnt(0)
	v_mfma_f32_32x32x16_bf16 v[48:63], v[176:179], v[156:159], v[48:63]
	ds_read_b128 v[156:159], v154 offset:18496
	ds_read_b128 v[160:163], v154 offset:23104
	ds_read_b128 v[168:171], v153 offset:64
	ds_read_b128 v[172:175], v153 offset:4672
	s_waitcnt vmcnt(15)
	ds_write_b128 v152, v[96:99] offset:36864
	s_waitcnt vmcnt(13)
	ds_write_b128 v152, v[104:107] offset:41472
	s_waitcnt vmcnt(11)
	ds_write_b128 v152, v[112:115] offset:46080
	s_waitcnt vmcnt(9)
	ds_write_b128 v152, v[120:123] offset:50688
	v_mfma_f32_32x32x16_bf16 v[16:31], v[176:179], v[164:167], v[16:31]
	ds_read_b128 v[96:99], v154 offset:18528
	ds_read_b128 v[104:107], v154 offset:23136
	ds_read_b128 v[112:115], v153 offset:96
	ds_read_b128 v[120:123], v153 offset:4704
	s_waitcnt lgkmcnt(9)
	v_mfma_f32_32x32x16_bf16 v[0:15], v[168:171], v[156:159], v[0:15]
	ds_write_b128 v152, v[100:103] offset:55296
	ds_write_b128 v152, v[108:111] offset:59904
	ds_write_b128 v152, v[116:119] offset:64512
	s_waitcnt vmcnt(8)
	ds_write_b128 v155, v[124:127] offset:13824
	v_mfma_f32_32x32x16_bf16 v[32:47], v[168:171], v[160:163], v[32:47]
	s_waitcnt lgkmcnt(12)
	v_mfma_f32_32x32x16_bf16 v[48:63], v[172:175], v[156:159], v[48:63]
	v_mfma_f32_32x32x16_bf16 v[16:31], v[172:175], v[160:163], v[16:31]
	s_waitcnt lgkmcnt(0)
	s_barrier
	ds_read_b128 v[156:159], v154 offset:55296
	ds_read_b128 v[160:163], v154 offset:59904
	ds_read_b128 v[164:167], v153 offset:36864
	ds_read_b128 v[168:171], v153 offset:41472
	v_mfma_f32_32x32x16_bf16 v[0:15], v[112:115], v[96:99], v[0:15]
	v_mfma_f32_32x32x16_bf16 v[32:47], v[112:115], v[104:107], v[32:47]
	v_mfma_f32_32x32x16_bf16 v[48:63], v[120:123], v[96:99], v[48:63]
	v_mfma_f32_32x32x16_bf16 v[16:31], v[120:123], v[104:107], v[16:31]
	global_load_dwordx4 v[96:99], v[128:129], off offset:640
	global_load_dwordx4 v[100:103], v[130:131], off offset:640
	global_load_dwordx4 v[104:107], v[132:133], off offset:640
	global_load_dwordx4 v[108:111], v[134:135], off offset:640
	global_load_dwordx4 v[112:115], v[136:137], off offset:640
	global_load_dwordx4 v[116:119], v[138:139], off offset:640
	global_load_dwordx4 v[120:123], v[140:141], off offset:640
	global_load_dwordx4 v[124:127], v[142:143], off offset:640
	s_waitcnt lgkmcnt(1)
	v_mfma_f32_32x32x16_bf16 v[0:15], v[164:167], v[156:159], v[0:15]
	v_mfma_f32_32x32x16_bf16 v[32:47], v[164:167], v[160:163], v[32:47]
	s_waitcnt lgkmcnt(0)
	v_mfma_f32_32x32x16_bf16 v[48:63], v[168:171], v[156:159], v[48:63]
	ds_read_b128 v[156:159], v154 offset:55328
	ds_read_b128 v[164:167], v154 offset:59936
	ds_read_b128 v[172:175], v153 offset:36896
	ds_read_b128 v[176:179], v153 offset:41504
	v_mfma_f32_32x32x16_bf16 v[16:31], v[168:171], v[160:163], v[16:31]
	s_waitcnt lgkmcnt(1)
	v_mfma_f32_32x32x16_bf16 v[0:15], v[172:175], v[156:159], v[0:15]
	v_mfma_f32_32x32x16_bf16 v[32:47], v[172:175], v[164:167], v[32:47]
	s_waitcnt lgkmcnt(0)
	v_mfma_f32_32x32x16_bf16 v[48:63], v[176:179], v[156:159], v[48:63]
	ds_read_b128 v[156:159], v154 offset:55360
	ds_read_b128 v[160:163], v154 offset:59968
	ds_read_b128 v[168:171], v153 offset:36928
	ds_read_b128 v[172:175], v153 offset:41536
	s_waitcnt vmcnt(15)
	ds_write_b128 v152, v[64:67]
	s_waitcnt vmcnt(13)
	ds_write_b128 v152, v[72:75] offset:4608
	s_waitcnt vmcnt(11)
	ds_write_b128 v152, v[80:83] offset:9216
	s_waitcnt vmcnt(9)
	ds_write_b128 v152, v[88:91] offset:13824
	v_mfma_f32_32x32x16_bf16 v[16:31], v[176:179], v[164:167], v[16:31]
	ds_read_b128 v[64:67], v154 offset:55392
	ds_read_b128 v[72:75], v154 offset:60000
	ds_read_b128 v[80:83], v153 offset:36960
	ds_read_b128 v[88:91], v153 offset:41568
	s_waitcnt lgkmcnt(9)
	v_mfma_f32_32x32x16_bf16 v[0:15], v[168:171], v[156:159], v[0:15]
	ds_write_b128 v152, v[68:71] offset:18432
	ds_write_b128 v152, v[76:79] offset:23040
	ds_write_b128 v152, v[84:87] offset:27648
	s_waitcnt vmcnt(8)
	ds_write_b128 v152, v[92:95] offset:32256
	v_mfma_f32_32x32x16_bf16 v[32:47], v[168:171], v[160:163], v[32:47]
	s_waitcnt lgkmcnt(12)
	v_mfma_f32_32x32x16_bf16 v[48:63], v[172:175], v[156:159], v[48:63]
	v_mfma_f32_32x32x16_bf16 v[16:31], v[172:175], v[160:163], v[16:31]
	s_waitcnt lgkmcnt(0)
	s_barrier
; template <bool SWAP>
; DI void gemm_tile(const bf16_t* __restrict__ A, int lda, const bf16_t* __restrict__ Bt, int ldb, int K, f32x16 (&acc)[2][2], bf16_t* As, bf16_t* Bs_unused) {
;     ...
;   auto step = [&](int buf, u32x4 (&ra)[4], u32x4 (&rb)[4], bool do_write, bool do_load, int tload) __attribute__((always_inline)) {
;     const bf16_t* pa = As + buf * 2 * GT_IMG + pao; const bf16_t* pb = As + buf * 2 * GT_IMG + pbo;
;     bf16_t* Ad = As + (buf ^ 1) * 2 * GT_IMG; bf16_t* Bd = Ad + GT_IMG;
;     bf16x8 F0[4], F1[4];
;     frag_read(F0, pa, pb, 0);
;     __builtin_amdgcn_sched_barrier(0);
;     frag_read(F1, pa, pb, 16);
;     mfma4(F0);
;     __builtin_amdgcn_sched_barrier(0);
;     frag_read(F0, pa, pb, 32);
;     mfma4(F1);
;     if (do_write) {
; #pragma unroll
;       for (int i = 0; i < 4; ++i) *(u32x4*)(Ad + (lr + 32 * i) * 72 + lc) = ra[i];
;     }
;     __builtin_amdgcn_sched_barrier(0);
;     frag_read(F1, pa, pb, 48);
;     mfma4(F0);
;     if (do_write) {
; #pragma unroll
;       for (int i = 0; i < 4; ++i) *(u32x4*)(Bd + (lr + 32 * i) * 72 + lc) = rb[i];
;     }
;     __builtin_amdgcn_sched_barrier(0);
;     mfma4(F1);
;     if (do_load) load_stage(ra, rb, tload);
;     __builtin_amdgcn_sched_barrier(0);
;   };
;   const int nk = K >> 6;
;   load_stage(ra0, rb0, 0); load_stage(ra1, rb1, 1);
;   __syncthreads();
;   write_stage(ra0, rb0, 0);
;   load_stage(ra0, rb0, 2);
;   __syncthreads();
;   for (int kt = 0; kt < nk; kt += 2) {
;     step(0, ra1, rb1, true, kt + 3 < nk, kt + 3);
;     __syncthreads();
;     step(1, ra0, rb0, kt + 2 < nk, kt + 4 < nk, kt + 4);
;     __syncthreads();
	ds_read_b128 v[156:159], v154 offset:18432
	ds_read_b128 v[160:163], v154 offset:23040
	ds_read_b128 v[164:167], v153
	ds_read_b128 v[168:171], v153 offset:4608
	v_mfma_f32_32x32x16_bf16 v[0:15], v[80:83], v[64:67], v[0:15]
	v_mfma_f32_32x32x16_bf16 v[32:47], v[80:83], v[72:75], v[32:47]
	v_mfma_f32_32x32x16_bf16 v[48:63], v[88:91], v[64:67], v[48:63]
	v_mfma_f32_32x32x16_bf16 v[16:31], v[88:91], v[72:75], v[16:31]
	global_load_dwordx4 v[64:67], v[128:129], off offset:768
	global_load_dwordx4 v[68:71], v[130:131], off offset:768
	global_load_dwordx4 v[72:75], v[132:133], off offset:768
	global_load_dwordx4 v[76:79], v[134:135], off offset:768
	global_load_dwordx4 v[80:83], v[136:137], off offset:768
	global_load_dwordx4 v[84:87], v[138:139], off offset:768
	global_load_dwordx4 v[88:91], v[140:141], off offset:768
	global_load_dwordx4 v[92:95], v[142:143], off offset:768
	s_waitcnt lgkmcnt(1)
	v_mfma_f32_32x32x16_bf16 v[0:15], v[164:167], v[156:159], v[0:15]
	v_mfma_f32_32x32x16_bf16 v[32:47], v[164:167], v[160:163], v[32:47]
	s_waitcnt lgkmcnt(0)
	v_mfma_f32_32x32x16_bf16 v[48:63], v[168:171], v[156:159], v[48:63]
	ds_read_b128 v[156:159], v154 offset:18464
	ds_read_b128 v[164:167], v154 offset:23072
	ds_read_b128 v[172:175], v153 offset:32
	ds_read_b128 v[176:179], v153 offset:4640
	v_mfma_f32_32x32x16_bf16 v[16:31], v[168:171], v[160:163], v[16:31]
	s_waitcnt lgkmcnt(1)
	v_mfma_f32_32x32x16_bf16 v[0:15], v[172:175], v[156:159], v[0:15]
	v_mfma_f32_32x32x16_bf16 v[32:47], v[172:175], v[164:167], v[32:47]
	s_waitcnt lgkmcnt(0)
	v_mfma_f32_32x32x16_bf16 v[48:63], v[176:179], v[156:159], v[48:63]
	ds_read_b128 v[156:159], v154 offset:18496
	ds_read_b128 v[160:163], v154 offset:23104
	ds_read_b128 v[168:171], v153 offset:64
	ds_read_b128 v[172:175], v153 offset:4672
	s_waitcnt vmcnt(15)
	ds_write_b128 v152, v[96:99] offset:36864
	s_waitcnt vmcnt(13)
	ds_write_b128 v152, v[104:107] offset:41472
	s_waitcnt vmcnt(11)
	ds_write_b128 v152, v[112:115] offset:46080
	s_waitcnt vmcnt(9)
	ds_write_b128 v152, v[120:123] offset:50688
	v_mfma_f32_32x32x16_bf16 v[16:31], v[176:179], v[164:167], v[16:31]
	ds_read_b128 v[96:99], v154 offset:18528
	ds_read_b128 v[104:107], v154 offset:23136
	ds_read_b128 v[112:115], v153 offset:96
	ds_read_b128 v[120:123], v153 offset:4704
	s_waitcnt lgkmcnt(9)
	v_mfma_f32_32x32x16_bf16 v[0:15], v[168:171], v[156:159], v[0:15]
	ds_write_b128 v152, v[100:103] offset:55296
	ds_write_b128 v152, v[108:111] offset:59904
	ds_write_b128 v152, v[116:119] offset:64512
	s_waitcnt vmcnt(8)
	ds_write_b128 v155, v[124:127] offset:13824
	v_mfma_f32_32x32x16_bf16 v[32:47], v[168:171], v[160:163], v[32:47]
	s_waitcnt lgkmcnt(12)
	v_mfma_f32_32x32x16_bf16 v[48:63], v[172:175], v[156:159], v[48:63]
	v_mfma_f32_32x32x16_bf16 v[16:31], v[172:175], v[160:163], v[16:31]
	s_waitcnt lgkmcnt(0)
	s_barrier
	ds_read_b128 v[156:159], v154 offset:55296
	ds_read_b128 v[160:163], v154 offset:59904
	ds_read_b128 v[164:167], v153 offset:36864
	ds_read_b128 v[168:171], v153 offset:41472
	v_mfma_f32_32x32x16_bf16 v[0:15], v[112:115], v[96:99], v[0:15]
	v_mfma_f32_32x32x16_bf16 v[32:47], v[112:115], v[104:107], v[32:47]
	v_mfma_f32_32x32x16_bf16 v[48:63], v[120:123], v[96:99], v[48:63]
	v_mfma_f32_32x32x16_bf16 v[16:31], v[120:123], v[104:107], v[16:31]
	global_load_dwordx4 v[96:99], v[128:129], off offset:896
	global_load_dwordx4 v[100:103], v[130:131], off offset:896
	global_load_dwordx4 v[104:107], v[132:133], off offset:896
	global_load_dwordx4 v[108:111], v[134:135], off offset:896
	global_load_dwordx4 v[112:115], v[136:137], off offset:896
	global_load_dwordx4 v[116:119], v[138:139], off offset:896
	global_load_dwordx4 v[120:123], v[140:141], off offset:896
	global_load_dwordx4 v[124:127], v[142:143], off offset:896
	s_waitcnt lgkmcnt(1)
	v_mfma_f32_32x32x16_bf16 v[0:15], v[164:167], v[156:159], v[0:15]
	v_mfma_f32_32x32x16_bf16 v[32:47], v[164:167], v[160:163], v[32:47]
	s_waitcnt lgkmcnt(0)
	v_mfma_f32_32x32x16_bf16 v[48:63], v[168:171], v[156:159], v[48:63]
	ds_read_b128 v[156:159], v154 offset:55328
	ds_read_b128 v[164:167], v154 offset:59936
	ds_read_b128 v[172:175], v153 offset:36896
	ds_read_b128 v[176:179], v153 offset:41504
	v_mfma_f32_32x32x16_bf16 v[16:31], v[168:171], v[160:163], v[16:31]
	s_waitcnt lgkmcnt(1)
	v_mfma_f32_32x32x16_bf16 v[0:15], v[172:175], v[156:159], v[0:15]
	v_mfma_f32_32x32x16_bf16 v[32:47], v[172:175], v[164:167], v[32:47]
	s_waitcnt lgkmcnt(0)
	v_mfma_f32_32x32x16_bf16 v[48:63], v[176:179], v[156:159], v[48:63]
	ds_read_b128 v[156:159], v154 offset:55360
	ds_read_b128 v[160:163], v154 offset:59968
	ds_read_b128 v[168:171], v153 offset:36928
	ds_read_b128 v[172:175], v153 offset:41536
	s_waitcnt vmcnt(15)
	ds_write_b128 v152, v[64:67]
	s_waitcnt vmcnt(13)
	ds_write_b128 v152, v[72:75] offset:4608
	s_waitcnt vmcnt(11)
	ds_write_b128 v152, v[80:83] offset:9216
	s_waitcnt vmcnt(9)
	ds_write_b128 v152, v[88:91] offset:13824
	v_mfma_f32_32x32x16_bf16 v[16:31], v[176:179], v[164:167], v[16:31]
	ds_read_b128 v[64:67], v154 offset:55392
	ds_read_b128 v[72:75], v154 offset:60000
	ds_read_b128 v[80:83], v153 offset:36960
	ds_read_b128 v[88:91], v153 offset:41568
	s_waitcnt lgkmcnt(9)
	v_mfma_f32_32x32x16_bf16 v[0:15], v[168:171], v[156:159], v[0:15]
	ds_write_b128 v152, v[68:71] offset:18432
	ds_write_b128 v152, v[76:79] offset:23040
	ds_write_b128 v152, v[84:87] offset:27648
	s_waitcnt vmcnt(8)
	ds_write_b128 v152, v[92:95] offset:32256
	v_mfma_f32_32x32x16_bf16 v[32:47], v[168:171], v[160:163], v[32:47]
	s_waitcnt lgkmcnt(12)
	v_mfma_f32_32x32x16_bf16 v[48:63], v[172:175], v[156:159], v[48:63]
	v_mfma_f32_32x32x16_bf16 v[16:31], v[172:175], v[160:163], v[16:31]
	s_waitcnt lgkmcnt(0)
	s_barrier
; template <bool SWAP>
; DI void gemm_tile(const bf16_t* __restrict__ A, int lda, const bf16_t* __restrict__ Bt, int ldb, int K, f32x16 (&acc)[2][2], bf16_t* As, bf16_t* Bs_unused) {
;     ...
;   auto step = [&](int buf, u32x4 (&ra)[4], u32x4 (&rb)[4], bool do_write, bool do_load, int tload) __attribute__((always_inline)) {
;     const bf16_t* pa = As + buf * 2 * GT_IMG + pao; const bf16_t* pb = As + buf * 2 * GT_IMG + pbo;
;     bf16_t* Ad = As + (buf ^ 1) * 2 * GT_IMG; bf16_t* Bd = Ad + GT_IMG;
;     bf16x8 F0[4], F1[4];
;     frag_read(F0, pa, pb, 0);
;     __builtin_amdgcn_sched_barrier(0);
;     frag_read(F1, pa, pb, 16);
;     mfma4(F0);
;     __builtin_amdgcn_sched_barrier(0);
;     frag_read(F0, pa, pb, 32);
;     mfma4(F1);
;     if (do_write) {
; #pragma unroll
;       for (int i = 0; i < 4; ++i) *(u32x4*)(Ad + (lr + 32 * i) * 72 + lc) = ra[i];
;     }
;     __builtin_amdgcn_sched_barrier(0);
;     frag_read(F1, pa, pb, 48);
;     mfma4(F0);
;     if (do_write) {
; #pragma unroll
;       for (int i = 0; i < 4; ++i) *(u32x4*)(Bd + (lr + 32 * i) * 72 + lc) = rb[i];
;     }
;     __builtin_amdgcn_sched_barrier(0);
;     mfma4(F1);
;     if (do_load) load_stage(ra, rb, tload);
;     __builtin_amdgcn_sched_barrier(0);
;   };
;   const int nk = K >> 6;
;   load_stage(ra0, rb0, 0); load_stage(ra1, rb1, 1);
;   __syncthreads();
;   write_stage(ra0, rb0, 0);
;   load_stage(ra0, rb0, 2);
;   __syncthreads();
;   for (int kt = 0; kt < nk; kt += 2) {
;     step(0, ra1, rb1, true, kt + 3 < nk, kt + 3);
;     __syncthreads();
;     step(1, ra0, rb0, kt + 2 < nk, kt + 4 < nk, kt + 4);
;     __syncthreads();
	ds_read_b128 v[156:159], v154 offset:18432
	ds_read_b128 v[160:163], v154 offset:23040
	ds_read_b128 v[164:167], v153
	ds_read_b128 v[168:171], v153 offset:4608
	v_mfma_f32_32x32x16_bf16 v[0:15], v[80:83], v[64:67], v[0:15]
	v_mfma_f32_32x32x16_bf16 v[32:47], v[80:83], v[72:75], v[32:47]
	v_mfma_f32_32x32x16_bf16 v[48:63], v[88:91], v[64:67], v[48:63]
	v_mfma_f32_32x32x16_bf16 v[16:31], v[88:91], v[72:75], v[16:31]
	global_load_dwordx4 v[64:67], v[128:129], off offset:1024
	global_load_dwordx4 v[68:71], v[130:131], off offset:1024
	global_load_dwordx4 v[72:75], v[132:133], off offset:1024
	global_load_dwordx4 v[76:79], v[134:135], off offset:1024
	global_load_dwordx4 v[80:83], v[136:137], off offset:1024
	global_load_dwordx4 v[84:87], v[138:139], off offset:1024
	global_load_dwordx4 v[88:91], v[140:141], off offset:1024
	global_load_dwordx4 v[92:95], v[142:143], off offset:1024
	s_waitcnt lgkmcnt(1)
	v_mfma_f32_32x32x16_bf16 v[0:15], v[164:167], v[156:159], v[0:15]
	v_mfma_f32_32x32x16_bf16 v[32:47], v[164:167], v[160:163], v[32:47]
	s_waitcnt lgkmcnt(0)
	v_mfma_f32_32x32x16_bf16 v[48:63], v[168:171], v[156:159], v[48:63]
	ds_read_b128 v[156:159], v154 offset:18464
	ds_read_b128 v[164:167], v154 offset:23072
	ds_read_b128 v[172:175], v153 offset:32
	ds_read_b128 v[176:179], v153 offset:4640
	v_mfma_f32_32x32x16_bf16 v[16:31], v[168:171], v[160:163], v[16:31]
	s_waitcnt lgkmcnt(1)
	v_mfma_f32_32x32x16_bf16 v[0:15], v[172:175], v[156:159], v[0:15]
	v_mfma_f32_32x32x16_bf16 v[32:47], v[172:175], v[164:167], v[32:47]
	s_waitcnt lgkmcnt(0)
	v_mfma_f32_32x32x16_bf16 v[48:63], v[176:179], v[156:159], v[48:63]
	ds_read_b128 v[156:159], v154 offset:18496
	ds_read_b128 v[160:163], v154 offset:23104
	ds_read_b128 v[168:171], v153 offset:64
	ds_read_b128 v[172:175], v153 offset:4672
	s_waitcnt vmcnt(15)
	ds_write_b128 v152, v[96:99] offset:36864
	s_waitcnt vmcnt(13)
	ds_write_b128 v152, v[104:107] offset:41472
	s_waitcnt vmcnt(11)
	ds_write_b128 v152, v[112:115] offset:46080
	s_waitcnt vmcnt(9)
	ds_write_b128 v152, v[120:123] offset:50688
	v_mfma_f32_32x32x16_bf16 v[16:31], v[176:179], v[164:167], v[16:31]
	ds_read_b128 v[96:99], v154 offset:18528
	ds_read_b128 v[104:107], v154 offset:23136
	ds_read_b128 v[112:115], v153 offset:96
	ds_read_b128 v[120:123], v153 offset:4704
	s_waitcnt lgkmcnt(9)
	v_mfma_f32_32x32x16_bf16 v[0:15], v[168:171], v[156:159], v[0:15]
	ds_write_b128 v152, v[100:103] offset:55296
	ds_write_b128 v152, v[108:111] offset:59904
	ds_write_b128 v152, v[116:119] offset:64512
	s_waitcnt vmcnt(8)
	ds_write_b128 v155, v[124:127] offset:13824
	v_mfma_f32_32x32x16_bf16 v[32:47], v[168:171], v[160:163], v[32:47]
	s_waitcnt lgkmcnt(12)
	v_mfma_f32_32x32x16_bf16 v[48:63], v[172:175], v[156:159], v[48:63]
	v_mfma_f32_32x32x16_bf16 v[16:31], v[172:175], v[160:163], v[16:31]
	s_waitcnt lgkmcnt(0)
	s_barrier
	ds_read_b128 v[156:159], v154 offset:55296
	ds_read_b128 v[160:163], v154 offset:59904
	ds_read_b128 v[164:167], v153 offset:36864
	ds_read_b128 v[168:171], v153 offset:41472
	v_mfma_f32_32x32x16_bf16 v[0:15], v[112:115], v[96:99], v[0:15]
	v_mfma_f32_32x32x16_bf16 v[32:47], v[112:115], v[104:107], v[32:47]
	v_mfma_f32_32x32x16_bf16 v[48:63], v[120:123], v[96:99], v[48:63]
	v_mfma_f32_32x32x16_bf16 v[16:31], v[120:123], v[104:107], v[16:31]
	global_load_dwordx4 v[96:99], v[128:129], off offset:1152
	global_load_dwordx4 v[100:103], v[130:131], off offset:1152
	global_load_dwordx4 v[104:107], v[132:133], off offset:1152
	global_load_dwordx4 v[108:111], v[134:135], off offset:1152
	global_load_dwordx4 v[112:115], v[136:137], off offset:1152
	global_load_dwordx4 v[116:119], v[138:139], off offset:1152
	global_load_dwordx4 v[120:123], v[140:141], off offset:1152
	global_load_dwordx4 v[124:127], v[142:143], off offset:1152
	s_waitcnt lgkmcnt(1)
	v_mfma_f32_32x32x16_bf16 v[0:15], v[164:167], v[156:159], v[0:15]
	v_mfma_f32_32x32x16_bf16 v[32:47], v[164:167], v[160:163], v[32:47]
	s_waitcnt lgkmcnt(0)
	v_mfma_f32_32x32x16_bf16 v[48:63], v[168:171], v[156:159], v[48:63]
	ds_read_b128 v[156:159], v154 offset:55328
	ds_read_b128 v[164:167], v154 offset:59936
	ds_read_b128 v[172:175], v153 offset:36896
	ds_read_b128 v[176:179], v153 offset:41504
	v_mfma_f32_32x32x16_bf16 v[16:31], v[168:171], v[160:163], v[16:31]
	s_waitcnt lgkmcnt(1)
	v_mfma_f32_32x32x16_bf16 v[0:15], v[172:175], v[156:159], v[0:15]
	v_mfma_f32_32x32x16_bf16 v[32:47], v[172:175], v[164:167], v[32:47]
	s_waitcnt lgkmcnt(0)
	v_mfma_f32_32x32x16_bf16 v[48:63], v[176:179], v[156:159], v[48:63]
	ds_read_b128 v[156:159], v154 offset:55360
	ds_read_b128 v[160:163], v154 offset:59968
	ds_read_b128 v[168:171], v153 offset:36928
	ds_read_b128 v[172:175], v153 offset:41536
	s_waitcnt vmcnt(15)
	ds_write_b128 v152, v[64:67]
	s_waitcnt vmcnt(13)
	ds_write_b128 v152, v[72:75] offset:4608
	s_waitcnt vmcnt(11)
	ds_write_b128 v152, v[80:83] offset:9216
	s_waitcnt vmcnt(9)
	ds_write_b128 v152, v[88:91] offset:13824
	v_mfma_f32_32x32x16_bf16 v[16:31], v[176:179], v[164:167], v[16:31]
	ds_read_b128 v[64:67], v154 offset:55392
	ds_read_b128 v[72:75], v154 offset:60000
	ds_read_b128 v[80:83], v153 offset:36960
	ds_read_b128 v[88:91], v153 offset:41568
	s_waitcnt lgkmcnt(9)
	v_mfma_f32_32x32x16_bf16 v[0:15], v[168:171], v[156:159], v[0:15]
	ds_write_b128 v152, v[68:71] offset:18432
	ds_write_b128 v152, v[76:79] offset:23040
	ds_write_b128 v152, v[84:87] offset:27648
	s_waitcnt vmcnt(8)
	ds_write_b128 v152, v[92:95] offset:32256
	v_mfma_f32_32x32x16_bf16 v[32:47], v[168:171], v[160:163], v[32:47]
	s_waitcnt lgkmcnt(12)
	v_mfma_f32_32x32x16_bf16 v[48:63], v[172:175], v[156:159], v[48:63]
	v_mfma_f32_32x32x16_bf16 v[16:31], v[172:175], v[160:163], v[16:31]
	s_waitcnt lgkmcnt(0)
	s_barrier
; template <bool SWAP>
; DI void gemm_tile(const bf16_t* __restrict__ A, int lda, const bf16_t* __restrict__ Bt, int ldb, int K, f32x16 (&acc)[2][2], bf16_t* As, bf16_t* Bs_unused) {
;     ...
;   auto step = [&](int buf, u32x4 (&ra)[4], u32x4 (&rb)[4], bool do_write, bool do_load, int tload) __attribute__((always_inline)) {
;     const bf16_t* pa = As + buf * 2 * GT_IMG + pao; const bf16_t* pb = As + buf * 2 * GT_IMG + pbo;
;     bf16_t* Ad = As + (buf ^ 1) * 2 * GT_IMG; bf16_t* Bd = Ad + GT_IMG;
;     bf16x8 F0[4], F1[4];
;     frag_read(F0, pa, pb, 0);
;     __builtin_amdgcn_sched_barrier(0);
;     frag_read(F1, pa, pb, 16);
;     mfma4(F0);
;     __builtin_amdgcn_sched_barrier(0);
;     frag_read(F0, pa, pb, 32);
;     mfma4(F1);
;     if (do_write) {
; #pragma unroll
;       for (int i = 0; i < 4; ++i) *(u32x4*)(Ad + (lr + 32 * i) * 72 + lc) = ra[i];
;     }
;     __builtin_amdgcn_sched_barrier(0);
;     frag_read(F1, pa, pb, 48);
;     mfma4(F0);
;     if (do_write) {
; #pragma unroll
;       for (int i = 0; i < 4; ++i) *(u32x4*)(Bd + (lr + 32 * i) * 72 + lc) = rb[i];
;     }
;     __builtin_amdgcn_sched_barrier(0);
;     mfma4(F1);
;     if (do_load) load_stage(ra, rb, tload);
;     __builtin_amdgcn_sched_barrier(0);
;   };
;   const int nk = K >> 6;
;   load_stage(ra0, rb0, 0); load_stage(ra1, rb1, 1);
;   __syncthreads();
;   write_stage(ra0, rb0, 0);
;   load_stage(ra0, rb0, 2);
;   __syncthreads();
;   for (int kt = 0; kt < nk; kt += 2) {
;     step(0, ra1, rb1, true, kt + 3 < nk, kt + 3);
;     __syncthreads();
;     step(1, ra0, rb0, kt + 2 < nk, kt + 4 < nk, kt + 4);
;     __syncthreads();
	ds_read_b128 v[156:159], v154 offset:18432
	ds_read_b128 v[160:163], v154 offset:23040
	ds_read_b128 v[164:167], v153
	ds_read_b128 v[168:171], v153 offset:4608
	v_mfma_f32_32x32x16_bf16 v[0:15], v[80:83], v[64:67], v[0:15]
	v_mfma_f32_32x32x16_bf16 v[32:47], v[80:83], v[72:75], v[32:47]
	v_mfma_f32_32x32x16_bf16 v[48:63], v[88:91], v[64:67], v[48:63]
	v_mfma_f32_32x32x16_bf16 v[16:31], v[88:91], v[72:75], v[16:31]
	global_load_dwordx4 v[64:67], v[128:129], off offset:1280
	global_load_dwordx4 v[68:71], v[130:131], off offset:1280
	global_load_dwordx4 v[72:75], v[132:133], off offset:1280
	global_load_dwordx4 v[76:79], v[134:135], off offset:1280
	global_load_dwordx4 v[80:83], v[136:137], off offset:1280
	global_load_dwordx4 v[84:87], v[138:139], off offset:1280
	global_load_dwordx4 v[88:91], v[140:141], off offset:1280
	global_load_dwordx4 v[92:95], v[142:143], off offset:1280
	s_waitcnt lgkmcnt(1)
	v_mfma_f32_32x32x16_bf16 v[0:15], v[164:167], v[156:159], v[0:15]
	v_mfma_f32_32x32x16_bf16 v[32:47], v[164:167], v[160:163], v[32:47]
	s_waitcnt lgkmcnt(0)
	v_mfma_f32_32x32x16_bf16 v[48:63], v[168:171], v[156:159], v[48:63]
	ds_read_b128 v[156:159], v154 offset:18464
	ds_read_b128 v[164:167], v154 offset:23072
	ds_read_b128 v[172:175], v153 offset:32
	ds_read_b128 v[176:179], v153 offset:4640
	v_mfma_f32_32x32x16_bf16 v[16:31], v[168:171], v[160:163], v[16:31]
	s_waitcnt lgkmcnt(1)
	v_mfma_f32_32x32x16_bf16 v[0:15], v[172:175], v[156:159], v[0:15]
	v_mfma_f32_32x32x16_bf16 v[32:47], v[172:175], v[164:167], v[32:47]
	s_waitcnt lgkmcnt(0)
	v_mfma_f32_32x32x16_bf16 v[48:63], v[176:179], v[156:159], v[48:63]
	ds_read_b128 v[156:159], v154 offset:18496
	ds_read_b128 v[160:163], v154 offset:23104
	ds_read_b128 v[168:171], v153 offset:64
	ds_read_b128 v[172:175], v153 offset:4672
	s_waitcnt vmcnt(15)
	ds_write_b128 v152, v[96:99] offset:36864
	s_waitcnt vmcnt(13)
	ds_write_b128 v152, v[104:107] offset:41472
	s_waitcnt vmcnt(11)
	ds_write_b128 v152, v[112:115] offset:46080
	s_waitcnt vmcnt(9)
	ds_write_b128 v152, v[120:123] offset:50688
	v_mfma_f32_32x32x16_bf16 v[16:31], v[176:179], v[164:167], v[16:31]
	ds_read_b128 v[96:99], v154 offset:18528
	ds_read_b128 v[104:107], v154 offset:23136
	ds_read_b128 v[112:115], v153 offset:96
	ds_read_b128 v[120:123], v153 offset:4704
	s_waitcnt lgkmcnt(9)
	v_mfma_f32_32x32x16_bf16 v[0:15], v[168:171], v[156:159], v[0:15]
	ds_write_b128 v152, v[100:103] offset:55296
	ds_write_b128 v152, v[108:111] offset:59904
	ds_write_b128 v152, v[116:119] offset:64512
	s_waitcnt vmcnt(8)
	ds_write_b128 v155, v[124:127] offset:13824
	v_mfma_f32_32x32x16_bf16 v[32:47], v[168:171], v[160:163], v[32:47]
	s_waitcnt lgkmcnt(12)
	v_mfma_f32_32x32x16_bf16 v[48:63], v[172:175], v[156:159], v[48:63]
	v_mfma_f32_32x32x16_bf16 v[16:31], v[172:175], v[160:163], v[16:31]
	s_waitcnt lgkmcnt(0)
	s_barrier
	ds_read_b128 v[156:159], v154 offset:55296
	ds_read_b128 v[160:163], v154 offset:59904
	ds_read_b128 v[164:167], v153 offset:36864
	ds_read_b128 v[168:171], v153 offset:41472
	v_mfma_f32_32x32x16_bf16 v[0:15], v[112:115], v[96:99], v[0:15]
	v_mfma_f32_32x32x16_bf16 v[32:47], v[112:115], v[104:107], v[32:47]
	v_mfma_f32_32x32x16_bf16 v[48:63], v[120:123], v[96:99], v[48:63]
	v_mfma_f32_32x32x16_bf16 v[16:31], v[120:123], v[104:107], v[16:31]
	global_load_dwordx4 v[96:99], v[128:129], off offset:1408
	global_load_dwordx4 v[100:103], v[130:131], off offset:1408
	global_load_dwordx4 v[104:107], v[132:133], off offset:1408
	global_load_dwordx4 v[108:111], v[134:135], off offset:1408
	global_load_dwordx4 v[112:115], v[136:137], off offset:1408
	global_load_dwordx4 v[116:119], v[138:139], off offset:1408
	global_load_dwordx4 v[120:123], v[140:141], off offset:1408
	global_load_dwordx4 v[124:127], v[142:143], off offset:1408
	s_waitcnt lgkmcnt(1)
	v_mfma_f32_32x32x16_bf16 v[0:15], v[164:167], v[156:159], v[0:15]
	v_mfma_f32_32x32x16_bf16 v[32:47], v[164:167], v[160:163], v[32:47]
	s_waitcnt lgkmcnt(0)
	v_mfma_f32_32x32x16_bf16 v[48:63], v[168:171], v[156:159], v[48:63]
	ds_read_b128 v[156:159], v154 offset:55328
	ds_read_b128 v[164:167], v154 offset:59936
	ds_read_b128 v[172:175], v153 offset:36896
	ds_read_b128 v[176:179], v153 offset:41504
	v_mfma_f32_32x32x16_bf16 v[16:31], v[168:171], v[160:163], v[16:31]
	s_waitcnt lgkmcnt(1)
	v_mfma_f32_32x32x16_bf16 v[0:15], v[172:175], v[156:159], v[0:15]
	v_mfma_f32_32x32x16_bf16 v[32:47], v[172:175], v[164:167], v[32:47]
	s_waitcnt lgkmcnt(0)
	v_mfma_f32_32x32x16_bf16 v[48:63], v[176:179], v[156:159], v[48:63]
	ds_read_b128 v[156:159], v154 offset:55360
	ds_read_b128 v[160:163], v154 offset:59968
	ds_read_b128 v[168:171], v153 offset:36928
	ds_read_b128 v[172:175], v153 offset:41536
	s_waitcnt vmcnt(15)
	ds_write_b128 v152, v[64:67]
	s_waitcnt vmcnt(13)
	ds_write_b128 v152, v[72:75] offset:4608
	s_waitcnt vmcnt(11)
	ds_write_b128 v152, v[80:83] offset:9216
	s_waitcnt vmcnt(9)
	ds_write_b128 v152, v[88:91] offset:13824
	v_mfma_f32_32x32x16_bf16 v[16:31], v[176:179], v[164:167], v[16:31]
	ds_read_b128 v[64:67], v154 offset:55392
	ds_read_b128 v[72:75], v154 offset:60000
	ds_read_b128 v[80:83], v153 offset:36960
	ds_read_b128 v[88:91], v153 offset:41568
	s_waitcnt lgkmcnt(9)
	v_mfma_f32_32x32x16_bf16 v[0:15], v[168:171], v[156:159], v[0:15]
	ds_write_b128 v152, v[68:71] offset:18432
	ds_write_b128 v152, v[76:79] offset:23040
	ds_write_b128 v152, v[84:87] offset:27648
	s_waitcnt vmcnt(8)
	ds_write_b128 v152, v[92:95] offset:32256
	v_mfma_f32_32x32x16_bf16 v[32:47], v[168:171], v[160:163], v[32:47]
	s_waitcnt lgkmcnt(12)
	v_mfma_f32_32x32x16_bf16 v[48:63], v[172:175], v[156:159], v[48:63]
	v_mfma_f32_32x32x16_bf16 v[16:31], v[172:175], v[160:163], v[16:31]
	s_waitcnt lgkmcnt(0)
	s_barrier
; template <bool SWAP>
; DI void gemm_tile(const bf16_t* __restrict__ A, int lda, const bf16_t* __restrict__ Bt, int ldb, int K, f32x16 (&acc)[2][2], bf16_t* As, bf16_t* Bs_unused) {
;     ...
;   auto step = [&](int buf, u32x4 (&ra)[4], u32x4 (&rb)[4], bool do_write, bool do_load, int tload) __attribute__((always_inline)) {
;     const bf16_t* pa = As + buf * 2 * GT_IMG + pao; const bf16_t* pb = As + buf * 2 * GT_IMG + pbo;
;     bf16_t* Ad = As + (buf ^ 1) * 2 * GT_IMG; bf16_t* Bd = Ad + GT_IMG;
;     bf16x8 F0[4], F1[4];
;     frag_read(F0, pa, pb, 0);
;     __builtin_amdgcn_sched_barrier(0);
;     frag_read(F1, pa, pb, 16);
;     mfma4(F0);
;     __builtin_amdgcn_sched_barrier(0);
;     frag_read(F0, pa, pb, 32);
;     mfma4(F1);
;     if (do_write) {
; #pragma unroll
;       for (int i = 0; i < 4; ++i) *(u32x4*)(Ad + (lr + 32 * i) * 72 + lc) = ra[i];
;     }
;     __builtin_amdgcn_sched_barrier(0);
;     frag_read(F1, pa, pb, 48);
;     mfma4(F0);
;     if (do_write) {
; #pragma unroll
;       for (int i = 0; i < 4; ++i) *(u32x4*)(Bd + (lr + 32 * i) * 72 + lc) = rb[i];
;     }
;     __builtin_amdgcn_sched_barrier(0);
;     mfma4(F1);
;     if (do_load) load_stage(ra, rb, tload);
;     __builtin_amdgcn_sched_barrier(0);
;   };
;   const int nk = K >> 6;
;   load_stage(ra0, rb0, 0); load_stage(ra1, rb1, 1);
;   __syncthreads();
;   write_stage(ra0, rb0, 0);
;   load_stage(ra0, rb0, 2);
;   __syncthreads();
;   for (int kt = 0; kt < nk; kt += 2) {
;     step(0, ra1, rb1, true, kt + 3 < nk, kt + 3);
;     __syncthreads();
;     step(1, ra0, rb0, kt + 2 < nk, kt + 4 < nk, kt + 4);
;     __syncthreads();
	ds_read_b128 v[156:159], v154 offset:18432
	ds_read_b128 v[160:163], v154 offset:23040
	ds_read_b128 v[164:167], v153
	ds_read_b128 v[168:171], v153 offset:4608
	v_mfma_f32_32x32x16_bf16 v[0:15], v[80:83], v[64:67], v[0:15]
	v_mfma_f32_32x32x16_bf16 v[32:47], v[80:83], v[72:75], v[32:47]
	v_mfma_f32_32x32x16_bf16 v[48:63], v[88:91], v[64:67], v[48:63]
	v_mfma_f32_32x32x16_bf16 v[16:31], v[88:91], v[72:75], v[16:31]
	global_load_dwordx4 v[64:67], v[128:129], off offset:1536
	global_load_dwordx4 v[68:71], v[130:131], off offset:1536
	global_load_dwordx4 v[72:75], v[132:133], off offset:1536
	global_load_dwordx4 v[76:79], v[134:135], off offset:1536
	global_load_dwordx4 v[80:83], v[136:137], off offset:1536
	global_load_dwordx4 v[84:87], v[138:139], off offset:1536
	global_load_dwordx4 v[88:91], v[140:141], off offset:1536
	global_load_dwordx4 v[92:95], v[142:143], off offset:1536
	s_waitcnt lgkmcnt(1)
	v_mfma_f32_32x32x16_bf16 v[0:15], v[164:167], v[156:159], v[0:15]
	v_mfma_f32_32x32x16_bf16 v[32:47], v[164:167], v[160:163], v[32:47]
	s_waitcnt lgkmcnt(0)
	v_mfma_f32_32x32x16_bf16 v[48:63], v[168:171], v[156:159], v[48:63]
	ds_read_b128 v[156:159], v154 offset:18464
	ds_read_b128 v[164:167], v154 offset:23072
	ds_read_b128 v[172:175], v153 offset:32
	ds_read_b128 v[176:179], v153 offset:4640
	v_mfma_f32_32x32x16_bf16 v[16:31], v[168:171], v[160:163], v[16:31]
	s_waitcnt lgkmcnt(1)
	v_mfma_f32_32x32x16_bf16 v[0:15], v[172:175], v[156:159], v[0:15]
	v_mfma_f32_32x32x16_bf16 v[32:47], v[172:175], v[164:167], v[32:47]
	s_waitcnt lgkmcnt(0)
	v_mfma_f32_32x32x16_bf16 v[48:63], v[176:179], v[156:159], v[48:63]
	ds_read_b128 v[156:159], v154 offset:18496
	ds_read_b128 v[160:163], v154 offset:23104
	ds_read_b128 v[168:171], v153 offset:64
	ds_read_b128 v[172:175], v153 offset:4672
	s_waitcnt vmcnt(15)
	ds_write_b128 v152, v[96:99] offset:36864
	s_waitcnt vmcnt(13)
	ds_write_b128 v152, v[104:107] offset:41472
	s_waitcnt vmcnt(11)
	ds_write_b128 v152, v[112:115] offset:46080
	s_waitcnt vmcnt(9)
	ds_write_b128 v152, v[120:123] offset:50688
	v_mfma_f32_32x32x16_bf16 v[16:31], v[176:179], v[164:167], v[16:31]
	ds_read_b128 v[96:99], v154 offset:18528
	ds_read_b128 v[104:107], v154 offset:23136
	ds_read_b128 v[112:115], v153 offset:96
	ds_read_b128 v[120:123], v153 offset:4704
	s_waitcnt lgkmcnt(9)
	v_mfma_f32_32x32x16_bf16 v[0:15], v[168:171], v[156:159], v[0:15]
	ds_write_b128 v152, v[100:103] offset:55296
	ds_write_b128 v152, v[108:111] offset:59904
	ds_write_b128 v152, v[116:119] offset:64512
	s_waitcnt vmcnt(8)
	ds_write_b128 v155, v[124:127] offset:13824
	v_mfma_f32_32x32x16_bf16 v[32:47], v[168:171], v[160:163], v[32:47]
	s_waitcnt lgkmcnt(12)
	v_mfma_f32_32x32x16_bf16 v[48:63], v[172:175], v[156:159], v[48:63]
	v_mfma_f32_32x32x16_bf16 v[16:31], v[172:175], v[160:163], v[16:31]
	s_waitcnt lgkmcnt(0)
	s_barrier
	ds_read_b128 v[156:159], v154 offset:55296
	ds_read_b128 v[160:163], v154 offset:59904
	ds_read_b128 v[164:167], v153 offset:36864
	ds_read_b128 v[168:171], v153 offset:41472
	v_mfma_f32_32x32x16_bf16 v[0:15], v[112:115], v[96:99], v[0:15]
	v_mfma_f32_32x32x16_bf16 v[32:47], v[112:115], v[104:107], v[32:47]
	v_mfma_f32_32x32x16_bf16 v[48:63], v[120:123], v[96:99], v[48:63]
	v_mfma_f32_32x32x16_bf16 v[16:31], v[120:123], v[104:107], v[16:31]
	global_load_dwordx4 v[96:99], v[128:129], off offset:1664
	global_load_dwordx4 v[100:103], v[130:131], off offset:1664
	global_load_dwordx4 v[104:107], v[132:133], off offset:1664
	global_load_dwordx4 v[108:111], v[134:135], off offset:1664
	global_load_dwordx4 v[112:115], v[136:137], off offset:1664
	global_load_dwordx4 v[116:119], v[138:139], off offset:1664
	global_load_dwordx4 v[120:123], v[140:141], off offset:1664
	global_load_dwordx4 v[124:127], v[142:143], off offset:1664
	s_waitcnt lgkmcnt(1)
	v_mfma_f32_32x32x16_bf16 v[0:15], v[164:167], v[156:159], v[0:15]
	v_mfma_f32_32x32x16_bf16 v[32:47], v[164:167], v[160:163], v[32:47]
	s_waitcnt lgkmcnt(0)
	v_mfma_f32_32x32x16_bf16 v[48:63], v[168:171], v[156:159], v[48:63]
	ds_read_b128 v[156:159], v154 offset:55328
	ds_read_b128 v[164:167], v154 offset:59936
	ds_read_b128 v[172:175], v153 offset:36896
	ds_read_b128 v[176:179], v153 offset:41504
	v_mfma_f32_32x32x16_bf16 v[16:31], v[168:171], v[160:163], v[16:31]
	s_waitcnt lgkmcnt(1)
	v_mfma_f32_32x32x16_bf16 v[0:15], v[172:175], v[156:159], v[0:15]
	v_mfma_f32_32x32x16_bf16 v[32:47], v[172:175], v[164:167], v[32:47]
	s_waitcnt lgkmcnt(0)
	v_mfma_f32_32x32x16_bf16 v[48:63], v[176:179], v[156:159], v[48:63]
	ds_read_b128 v[156:159], v154 offset:55360
	ds_read_b128 v[160:163], v154 offset:59968
	ds_read_b128 v[168:171], v153 offset:36928
	ds_read_b128 v[172:175], v153 offset:41536
	s_waitcnt vmcnt(15)
	ds_write_b128 v152, v[64:67]
	s_waitcnt vmcnt(13)
	ds_write_b128 v152, v[72:75] offset:4608
	s_waitcnt vmcnt(11)
	ds_write_b128 v152, v[80:83] offset:9216
	s_waitcnt vmcnt(9)
	ds_write_b128 v152, v[88:91] offset:13824
	v_mfma_f32_32x32x16_bf16 v[16:31], v[176:179], v[164:167], v[16:31]
	ds_read_b128 v[64:67], v154 offset:55392
	ds_read_b128 v[72:75], v154 offset:60000
	ds_read_b128 v[80:83], v153 offset:36960
	ds_read_b128 v[88:91], v153 offset:41568
	s_waitcnt lgkmcnt(9)
	v_mfma_f32_32x32x16_bf16 v[0:15], v[168:171], v[156:159], v[0:15]
	ds_write_b128 v152, v[68:71] offset:18432
	ds_write_b128 v152, v[76:79] offset:23040
	ds_write_b128 v152, v[84:87] offset:27648
	s_waitcnt vmcnt(8)
	ds_write_b128 v152, v[92:95] offset:32256
	v_mfma_f32_32x32x16_bf16 v[32:47], v[168:171], v[160:163], v[32:47]
	s_waitcnt lgkmcnt(12)
	v_mfma_f32_32x32x16_bf16 v[48:63], v[172:175], v[156:159], v[48:63]
	v_mfma_f32_32x32x16_bf16 v[16:31], v[172:175], v[160:163], v[16:31]
	s_waitcnt lgkmcnt(0)
	s_barrier
; template <bool SWAP>
; DI void gemm_tile(const bf16_t* __restrict__ A, int lda, const bf16_t* __restrict__ Bt, int ldb, int K, f32x16 (&acc)[2][2], bf16_t* As, bf16_t* Bs_unused) {
;     ...
;   auto step = [&](int buf, u32x4 (&ra)[4], u32x4 (&rb)[4], bool do_write, bool do_load, int tload) __attribute__((always_inline)) {
;     const bf16_t* pa = As + buf * 2 * GT_IMG + pao; const bf16_t* pb = As + buf * 2 * GT_IMG + pbo;
;     bf16_t* Ad = As + (buf ^ 1) * 2 * GT_IMG; bf16_t* Bd = Ad + GT_IMG;
;     bf16x8 F0[4], F1[4];
;     frag_read(F0, pa, pb, 0);
;     __builtin_amdgcn_sched_barrier(0);
;     frag_read(F1, pa, pb, 16);
;     mfma4(F0);
;     __builtin_amdgcn_sched_barrier(0);
;     frag_read(F0, pa, pb, 32);
;     mfma4(F1);
;     if (do_write) {
; #pragma unroll
;       for (int i = 0; i < 4; ++i) *(u32x4*)(Ad + (lr + 32 * i) * 72 + lc) = ra[i];
;     }
;     __builtin_amdgcn_sched_barrier(0);
;     frag_read(F1, pa, pb, 48);
;     mfma4(F0);
;     if (do_write) {
; #pragma unroll
;       for (int i = 0; i < 4; ++i) *(u32x4*)(Bd + (lr + 32 * i) * 72 + lc) = rb[i];
;     }
;     __builtin_amdgcn_sched_barrier(0);
;     mfma4(F1);
;     if (do_load) load_stage(ra, rb, tload);
;     __builtin_amdgcn_sched_barrier(0);
;   };
;   const int nk = K >> 6;
;   load_stage(ra0, rb0, 0); load_stage(ra1, rb1, 1);
;   __syncthreads();
;   write_stage(ra0, rb0, 0);
;   load_stage(ra0, rb0, 2);
;   __syncthreads();
;   for (int kt = 0; kt < nk; kt += 2) {
;     step(0, ra1, rb1, true, kt + 3 < nk, kt + 3);
;     __syncthreads();
;     step(1, ra0, rb0, kt + 2 < nk, kt + 4 < nk, kt + 4);
;     __syncthreads();
	ds_read_b128 v[156:159], v154 offset:18432
	ds_read_b128 v[160:163], v154 offset:23040
	ds_read_b128 v[164:167], v153
	ds_read_b128 v[168:171], v153 offset:4608
	v_mfma_f32_32x32x16_bf16 v[0:15], v[80:83], v[64:67], v[0:15]
	v_mfma_f32_32x32x16_bf16 v[32:47], v[80:83], v[72:75], v[32:47]
	v_mfma_f32_32x32x16_bf16 v[48:63], v[88:91], v[64:67], v[48:63]
	v_mfma_f32_32x32x16_bf16 v[16:31], v[88:91], v[72:75], v[16:31]
	global_load_dwordx4 v[64:67], v[128:129], off offset:1792
	global_load_dwordx4 v[68:71], v[130:131], off offset:1792
	global_load_dwordx4 v[72:75], v[132:133], off offset:1792
	global_load_dwordx4 v[76:79], v[134:135], off offset:1792
	global_load_dwordx4 v[80:83], v[136:137], off offset:1792
	global_load_dwordx4 v[84:87], v[138:139], off offset:1792
	global_load_dwordx4 v[88:91], v[140:141], off offset:1792
	global_load_dwordx4 v[92:95], v[142:143], off offset:1792
	s_waitcnt lgkmcnt(1)
	v_mfma_f32_32x32x16_bf16 v[0:15], v[164:167], v[156:159], v[0:15]
	v_mfma_f32_32x32x16_bf16 v[32:47], v[164:167], v[160:163], v[32:47]
	s_waitcnt lgkmcnt(0)
	v_mfma_f32_32x32x16_bf16 v[48:63], v[168:171], v[156:159], v[48:63]
	ds_read_b128 v[156:159], v154 offset:18464
	ds_read_b128 v[164:167], v154 offset:23072
	ds_read_b128 v[172:175], v153 offset:32
	ds_read_b128 v[176:179], v153 offset:4640
	v_mfma_f32_32x32x16_bf16 v[16:31], v[168:171], v[160:163], v[16:31]
	s_waitcnt lgkmcnt(1)
	v_mfma_f32_32x32x16_bf16 v[0:15], v[172:175], v[156:159], v[0:15]
	v_mfma_f32_32x32x16_bf16 v[32:47], v[172:175], v[164:167], v[32:47]
	s_waitcnt lgkmcnt(0)
	v_mfma_f32_32x32x16_bf16 v[48:63], v[176:179], v[156:159], v[48:63]
	ds_read_b128 v[156:159], v154 offset:18496
	ds_read_b128 v[160:163], v154 offset:23104
	ds_read_b128 v[168:171], v153 offset:64
	ds_read_b128 v[172:175], v153 offset:4672
	s_waitcnt vmcnt(15)
	ds_write_b128 v152, v[96:99] offset:36864
	s_waitcnt vmcnt(13)
	ds_write_b128 v152, v[104:107] offset:41472
	s_waitcnt vmcnt(11)
	ds_write_b128 v152, v[112:115] offset:46080
	s_waitcnt vmcnt(9)
	ds_write_b128 v152, v[120:123] offset:50688
	v_mfma_f32_32x32x16_bf16 v[16:31], v[176:179], v[164:167], v[16:31]
	ds_read_b128 v[96:99], v154 offset:18528
	ds_read_b128 v[104:107], v154 offset:23136
	ds_read_b128 v[112:115], v153 offset:96
	ds_read_b128 v[120:123], v153 offset:4704
	s_waitcnt lgkmcnt(9)
	v_mfma_f32_32x32x16_bf16 v[0:15], v[168:171], v[156:159], v[0:15]
	ds_write_b128 v152, v[100:103] offset:55296
	ds_write_b128 v152, v[108:111] offset:59904
	ds_write_b128 v152, v[116:119] offset:64512
	s_waitcnt vmcnt(8)
	ds_write_b128 v155, v[124:127] offset:13824
	v_mfma_f32_32x32x16_bf16 v[32:47], v[168:171], v[160:163], v[32:47]
	s_waitcnt lgkmcnt(12)
	v_mfma_f32_32x32x16_bf16 v[48:63], v[172:175], v[156:159], v[48:63]
	v_mfma_f32_32x32x16_bf16 v[16:31], v[172:175], v[160:163], v[16:31]
	s_waitcnt lgkmcnt(0)
	s_barrier
	ds_read_b128 v[180:183], v154 offset:55296
	ds_read_b128 v[184:187], v154 offset:59904
	ds_read_b128 v[188:191], v153 offset:36864
	ds_read_b128 v[220:223], v153 offset:41472
	v_mfma_f32_32x32x16_bf16 v[0:15], v[112:115], v[96:99], v[0:15]
	v_mfma_f32_32x32x16_bf16 v[32:47], v[112:115], v[104:107], v[32:47]
	v_mfma_f32_32x32x16_bf16 v[48:63], v[120:123], v[96:99], v[48:63]
	v_mfma_f32_32x32x16_bf16 v[16:31], v[120:123], v[104:107], v[16:31]
	global_load_dwordx4 v[96:99], v[128:129], off offset:1920
	global_load_dwordx4 v[100:103], v[130:131], off offset:1920
	global_load_dwordx4 v[104:107], v[132:133], off offset:1920
	global_load_dwordx4 v[108:111], v[134:135], off offset:1920
	global_load_dwordx4 v[112:115], v[136:137], off offset:1920
	global_load_dwordx4 v[116:119], v[138:139], off offset:1920
	global_load_dwordx4 v[120:123], v[140:141], off offset:1920
	global_load_dwordx4 v[124:127], v[142:143], off offset:1920
	s_waitcnt lgkmcnt(1)
	v_mfma_f32_32x32x16_bf16 v[0:15], v[188:191], v[180:183], v[0:15]
	v_mfma_f32_32x32x16_bf16 v[32:47], v[188:191], v[184:187], v[32:47]
	s_waitcnt lgkmcnt(0)
	v_mfma_f32_32x32x16_bf16 v[48:63], v[220:223], v[180:183], v[48:63]
	ds_read_b128 v[128:131], v154 offset:55328
	ds_read_b128 v[136:139], v154 offset:59936
	ds_read_b128 v[156:159], v153 offset:36896
	ds_read_b128 v[160:163], v153 offset:41504
	v_mfma_f32_32x32x16_bf16 v[16:31], v[220:223], v[184:187], v[16:31]
	s_waitcnt lgkmcnt(1)
	v_mfma_f32_32x32x16_bf16 v[0:15], v[156:159], v[128:131], v[0:15]
	v_mfma_f32_32x32x16_bf16 v[32:47], v[156:159], v[136:139], v[32:47]
	s_waitcnt lgkmcnt(0)
	v_mfma_f32_32x32x16_bf16 v[48:63], v[160:163], v[128:131], v[48:63]
	ds_read_b128 v[128:131], v154 offset:55360
	ds_read_b128 v[132:135], v154 offset:59968
	ds_read_b128 v[140:143], v153 offset:36928
	ds_read_b128 v[156:159], v153 offset:41536
	s_waitcnt vmcnt(15)
	ds_write_b128 v152, v[64:67]
	s_waitcnt vmcnt(13)
	ds_write_b128 v152, v[72:75] offset:4608
	s_waitcnt vmcnt(11)
	ds_write_b128 v152, v[80:83] offset:9216
	s_waitcnt vmcnt(9)
	ds_write_b128 v152, v[88:91] offset:13824
	v_mfma_f32_32x32x16_bf16 v[16:31], v[160:163], v[136:139], v[16:31]
	ds_read_b128 v[64:67], v154 offset:55392
	ds_read_b128 v[72:75], v154 offset:60000
	ds_read_b128 v[80:83], v153 offset:36960
	ds_read_b128 v[88:91], v153 offset:41568
	s_waitcnt lgkmcnt(9)
	v_mfma_f32_32x32x16_bf16 v[0:15], v[140:143], v[128:131], v[0:15]
	ds_write_b128 v152, v[68:71] offset:18432
	ds_write_b128 v152, v[76:79] offset:23040
	ds_write_b128 v152, v[84:87] offset:27648
	s_waitcnt vmcnt(8)
	ds_write_b128 v152, v[92:95] offset:32256
	v_mfma_f32_32x32x16_bf16 v[32:47], v[140:143], v[132:135], v[32:47]
	s_waitcnt lgkmcnt(12)
	v_mfma_f32_32x32x16_bf16 v[48:63], v[156:159], v[128:131], v[48:63]
	v_mfma_f32_32x32x16_bf16 v[16:31], v[156:159], v[132:135], v[16:31]
	s_waitcnt lgkmcnt(0)
	s_barrier
; template <bool SWAP>
; DI void gemm_tile(const bf16_t* __restrict__ A, int lda, const bf16_t* __restrict__ Bt, int ldb, int K, f32x16 (&acc)[2][2], bf16_t* As, bf16_t* Bs_unused) {
;     ...
;   auto step = [&](int buf, u32x4 (&ra)[4], u32x4 (&rb)[4], bool do_write, bool do_load, int tload) __attribute__((always_inline)) {
;     const bf16_t* pa = As + buf * 2 * GT_IMG + pao; const bf16_t* pb = As + buf * 2 * GT_IMG + pbo;
;     bf16_t* Ad = As + (buf ^ 1) * 2 * GT_IMG; bf16_t* Bd = Ad + GT_IMG;
;     bf16x8 F0[4], F1[4];
;     frag_read(F0, pa, pb, 0);
;     __builtin_amdgcn_sched_barrier(0);
;     frag_read(F1, pa, pb, 16);
;     mfma4(F0);
;     __builtin_amdgcn_sched_barrier(0);
;     frag_read(F0, pa, pb, 32);
;     mfma4(F1);
;     if (do_write) {
; #pragma unroll
;       for (int i = 0; i < 4; ++i) *(u32x4*)(Ad + (lr + 32 * i) * 72 + lc) = ra[i];
;     }
;     __builtin_amdgcn_sched_barrier(0);
;     frag_read(F1, pa, pb, 48);
;     mfma4(F0);
;     if (do_write) {
; #pragma unroll
;       for (int i = 0; i < 4; ++i) *(u32x4*)(Bd + (lr + 32 * i) * 72 + lc) = rb[i];
;     }
;     __builtin_amdgcn_sched_barrier(0);
;     mfma4(F1);
;     if (do_load) load_stage(ra, rb, tload);
;     __builtin_amdgcn_sched_barrier(0);
;   };
;   const int nk = K >> 6;
;   load_stage(ra0, rb0, 0); load_stage(ra1, rb1, 1);
;   __syncthreads();
;   write_stage(ra0, rb0, 0);
;   load_stage(ra0, rb0, 2);
;   __syncthreads();
;   for (int kt = 0; kt < nk; kt += 2) {
;     step(0, ra1, rb1, true, kt + 3 < nk, kt + 3);
;     __syncthreads();
;     step(1, ra0, rb0, kt + 2 < nk, kt + 4 < nk, kt + 4);
;     __syncthreads();
;   }
	ds_read_b128 v[180:183], v154 offset:18432
	ds_read_b128 v[184:187], v154 offset:23040
	ds_read_b128 v[188:191], v153
	ds_read_b128 v[220:223], v153 offset:4608
	v_mfma_f32_32x32x16_bf16 v[0:15], v[80:83], v[64:67], v[0:15]
	v_mfma_f32_32x32x16_bf16 v[32:47], v[80:83], v[72:75], v[32:47]
	v_mfma_f32_32x32x16_bf16 v[48:63], v[88:91], v[64:67], v[48:63]
	v_mfma_f32_32x32x16_bf16 v[16:31], v[88:91], v[72:75], v[16:31]
	s_waitcnt lgkmcnt(1)
	v_mfma_f32_32x32x16_bf16 v[0:15], v[188:191], v[180:183], v[0:15]
	v_mfma_f32_32x32x16_bf16 v[32:47], v[188:191], v[184:187], v[32:47]
	s_waitcnt lgkmcnt(0)
	v_mfma_f32_32x32x16_bf16 v[48:63], v[220:223], v[180:183], v[48:63]
	ds_read_b128 v[64:67], v154 offset:18464
	ds_read_b128 v[72:75], v154 offset:23072
	ds_read_b128 v[80:83], v153 offset:32
	ds_read_b128 v[84:87], v153 offset:4640
	v_mfma_f32_32x32x16_bf16 v[16:31], v[220:223], v[184:187], v[16:31]
	s_waitcnt lgkmcnt(1)
	v_mfma_f32_32x32x16_bf16 v[0:15], v[80:83], v[64:67], v[0:15]
	v_mfma_f32_32x32x16_bf16 v[32:47], v[80:83], v[72:75], v[32:47]
	s_waitcnt lgkmcnt(0)
	v_mfma_f32_32x32x16_bf16 v[48:63], v[84:87], v[64:67], v[48:63]
	ds_read_b128 v[64:67], v154 offset:18496
	ds_read_b128 v[68:71], v154 offset:23104
	ds_read_b128 v[76:79], v153 offset:64
	ds_read_b128 v[80:83], v153 offset:4672
	s_waitcnt vmcnt(7)
	ds_write_b128 v152, v[96:99] offset:36864
	s_waitcnt vmcnt(5)
	ds_write_b128 v152, v[104:107] offset:41472
	s_waitcnt vmcnt(3)
	ds_write_b128 v152, v[112:115] offset:46080
	s_waitcnt vmcnt(1)
	ds_write_b128 v152, v[120:123] offset:50688
	v_mfma_f32_32x32x16_bf16 v[16:31], v[84:87], v[72:75], v[16:31]
	s_waitcnt lgkmcnt(5)
	v_mfma_f32_32x32x16_bf16 v[0:15], v[76:79], v[64:67], v[0:15]
	v_mfma_f32_32x32x16_bf16 v[32:47], v[76:79], v[68:71], v[32:47]
	s_waitcnt lgkmcnt(4)
	v_mfma_f32_32x32x16_bf16 v[48:63], v[80:83], v[64:67], v[48:63]
	ds_read_b128 v[64:67], v154 offset:18528
	ds_read_b128 v[72:75], v154 offset:23136
	ds_read_b128 v[76:79], v153 offset:96
	ds_read_b128 v[84:87], v153 offset:4704
	ds_write_b128 v152, v[100:103] offset:55296
	ds_write_b128 v152, v[108:111] offset:59904
	ds_write_b128 v152, v[116:119] offset:64512
	s_waitcnt vmcnt(0)
	ds_write_b128 v155, v[124:127] offset:13824
	v_mfma_f32_32x32x16_bf16 v[16:31], v[80:83], v[68:71], v[16:31]
	s_waitcnt lgkmcnt(0)
	s_barrier
	ds_read_b128 v[180:183], v154 offset:55296
	ds_read_b128 v[184:187], v154 offset:59904
	ds_read_b128 v[188:191], v153 offset:36864
	ds_read_b128 v[220:223], v153 offset:41472
	v_mfma_f32_32x32x16_bf16 v[0:15], v[76:79], v[64:67], v[0:15]
	v_mfma_f32_32x32x16_bf16 v[32:47], v[76:79], v[72:75], v[32:47]
	v_mfma_f32_32x32x16_bf16 v[48:63], v[84:87], v[64:67], v[48:63]
	v_mfma_f32_32x32x16_bf16 v[16:31], v[84:87], v[72:75], v[16:31]
	s_waitcnt lgkmcnt(1)
	v_mfma_f32_32x32x16_bf16 v[0:15], v[188:191], v[180:183], v[0:15]
	v_mfma_f32_32x32x16_bf16 v[32:47], v[188:191], v[184:187], v[32:47]
	s_waitcnt lgkmcnt(0)
	v_mfma_f32_32x32x16_bf16 v[48:63], v[220:223], v[180:183], v[48:63]
	ds_read_b128 v[64:67], v154 offset:55328
	ds_read_b128 v[72:75], v154 offset:59936
	ds_read_b128 v[80:83], v153 offset:36896
	ds_read_b128 v[84:87], v153 offset:41504
	v_mfma_f32_32x32x16_bf16 v[16:31], v[220:223], v[184:187], v[16:31]
	s_waitcnt lgkmcnt(1)
	v_mfma_f32_32x32x16_bf16 v[0:15], v[80:83], v[64:67], v[0:15]
	v_mfma_f32_32x32x16_bf16 v[32:47], v[80:83], v[72:75], v[32:47]
	s_waitcnt lgkmcnt(0)
	v_mfma_f32_32x32x16_bf16 v[48:63], v[84:87], v[64:67], v[48:63]
	v_mfma_f32_32x32x16_bf16 v[16:31], v[84:87], v[72:75], v[16:31]
	ds_read_b128 v[64:67], v153 offset:41536
	ds_read_b128 v[68:71], v154 offset:59968
	ds_read_b128 v[72:75], v154 offset:55360
	ds_read_b128 v[76:79], v153 offset:36928
	s_waitcnt lgkmcnt(0)
	v_mfma_f32_32x32x16_bf16 v[0:15], v[76:79], v[72:75], v[0:15]
	v_mfma_f32_32x32x16_bf16 v[32:47], v[76:79], v[68:71], v[32:47]
	v_mfma_f32_32x32x16_bf16 v[48:63], v[64:67], v[72:75], v[48:63]
	v_mfma_f32_32x32x16_bf16 v[16:31], v[64:67], v[68:71], v[16:31]
	ds_read_b128 v[64:67], v153 offset:41568
	ds_read_b128 v[68:71], v154 offset:60000
	ds_read_b128 v[72:75], v154 offset:55392
	ds_read_b128 v[76:79], v153 offset:36960
	s_waitcnt lgkmcnt(0)
	v_mfma_f32_32x32x16_bf16 v[0:15], v[76:79], v[72:75], v[0:15]
	v_mfma_f32_32x32x16_bf16 v[32:47], v[76:79], v[68:71], v[32:47]
	v_mfma_f32_32x32x16_bf16 v[48:63], v[64:67], v[72:75], v[48:63]
	v_mfma_f32_32x32x16_bf16 v[16:31], v[64:67], v[68:71], v[16:31]
	s_barrier
; DI float bf2f(bf16_t v) { return __uint_as_float(((unsigned)v) << 16); }
; DI bf16_t f2bf(float x) { return (bf16_t)(pk_bf16(x, 0.f) & 0xffffu); }
; DI int crow(int r, int h) { return (r & 3) + 8 * (r >> 2) + 4 * h; }
; DI void phase_merge(const Params& p, int g, char* smem, int bid, int nb) {
;     ...
; #pragma unroll
;     for (int mi = 0; mi < 2; ++mi)
; #pragma unroll
;       for (int ni = 0; ni < 2; ++ni)
;       {
;         bf16_t gb16[16];
; #pragma unroll
;         for (int r = 0; r < 16; ++r) gb16[r] = pt[(wm * 64 + mi * 32 + crow(r, h)) * NPROJ + nt * 128 + wn * 64 + ni * 32 + l31 + PGB];
; #pragma unroll
;         for (int r = 0; r < 16; ++r) {
;           const int rl = wm * 64 + mi * 32 + crow(r, h), cl = nt * 128 + wn * 64 + ni * 32 + l31;
;           mgt[rl * 1024 + cl] = f2bf(acc[mi][ni][r] * fmaxf(bf2f(gb16[r]), 1e-20f));
;         }
	s_movk_i32 s8, 0x1400
	v_lshlrev_b32_e32 v64, 6, v148
	v_lshl_add_u32 v65, v150, 2, v64
	v_lshlrev_b32_e32 v64, 6, v149
	v_mul_lo_u32 v66, v65, s8
	v_add3_u32 v64, v64, s10, v151
	v_add_u32_e32 v68, v66, v64
	v_ashrrev_i32_e32 v69, 31, v68
	v_lshl_add_u64 v[68:69], v[68:69], 1, s[6:7]
	v_add_co_u32_e32 v68, vcc, s75, v68
	v_add_u32_e32 v98, 0x1400, v66
	s_nop 0
	v_addc_co_u32_e32 v69, vcc, 0, v69, vcc
	global_load_ushort v101, v[68:69], off
	v_add_u32_e32 v70, v98, v64
	v_ashrrev_i32_e32 v71, 31, v70
	v_lshl_add_u64 v[70:71], v[70:71], 1, s[6:7]
	v_add_co_u32_e32 v70, vcc, s75, v70
	v_add_u32_e32 v67, 0x2800, v66
	s_nop 0
	v_addc_co_u32_e32 v71, vcc, 0, v71, vcc
	global_load_ushort v113, v[70:71], off
	v_add_u32_e32 v72, v67, v64
	v_ashrrev_i32_e32 v73, 31, v72
	v_add_u32_e32 v99, 0x3c00, v66
	v_lshl_add_u64 v[72:73], v[72:73], 1, s[6:7]
	v_add_u32_e32 v74, v99, v64
	v_ashrrev_i32_e32 v75, 31, v74
	v_add_co_u32_e32 v70, vcc, s75, v72
	v_lshl_add_u64 v[74:75], v[74:75], 1, s[6:7]
	s_nop 0
	v_addc_co_u32_e32 v71, vcc, 0, v73, vcc
	v_add_co_u32_e32 v72, vcc, s75, v74
	v_add_u32_e32 v100, 0xa000, v66
	s_nop 0
	v_addc_co_u32_e32 v73, vcc, 0, v75, vcc
	global_load_ushort v114, v[70:71], off
	global_load_ushort v115, v[72:73], off
	v_add_u32_e32 v76, v100, v64
	v_ashrrev_i32_e32 v77, 31, v76
	v_add_u32_e32 v102, 0xb400, v66
	v_lshl_add_u64 v[76:77], v[76:77], 1, s[6:7]
	v_add_u32_e32 v68, v102, v64
	v_ashrrev_i32_e32 v69, 31, v68
	v_add_u32_e32 v103, 0xc800, v66
	v_add_co_u32_e32 v70, vcc, s75, v76
	v_lshl_add_u64 v[68:69], v[68:69], 1, s[6:7]
	v_add_u32_e32 v78, v103, v64
	v_addc_co_u32_e32 v71, vcc, 0, v77, vcc
	v_ashrrev_i32_e32 v79, 31, v78
	v_add_u32_e32 v104, 0xdc00, v66
	v_add_co_u32_e32 v68, vcc, s75, v68
	v_lshl_add_u64 v[78:79], v[78:79], 1, s[6:7]
	v_add_u32_e32 v80, v104, v64
	v_addc_co_u32_e32 v69, vcc, 0, v69, vcc
	v_ashrrev_i32_e32 v81, 31, v80
	v_add_co_u32_e32 v72, vcc, s75, v78
	v_lshl_add_u64 v[80:81], v[80:81], 1, s[6:7]
	s_nop 0
	v_addc_co_u32_e32 v73, vcc, 0, v79, vcc
	v_add_co_u32_e32 v74, vcc, s75, v80
	v_add_u32_e32 v105, 0x14000, v66
	s_nop 0
	v_addc_co_u32_e32 v75, vcc, 0, v81, vcc
	global_load_ushort v116, v[70:71], off
	global_load_ushort v117, v[68:69], off
	global_load_ushort v118, v[72:73], off
	global_load_ushort v119, v[74:75], off
	v_add_u32_e32 v82, v105, v64
	v_ashrrev_i32_e32 v83, 31, v82
	v_add_u32_e32 v106, 0x15400, v66
	v_lshl_add_u64 v[82:83], v[82:83], 1, s[6:7]
	v_add_u32_e32 v84, v106, v64
	v_ashrrev_i32_e32 v85, 31, v84
	v_add_u32_e32 v107, 0x16800, v66
	v_add_co_u32_e32 v70, vcc, s75, v82
	v_lshl_add_u64 v[84:85], v[84:85], 1, s[6:7]
	v_add_u32_e32 v86, v107, v64
	v_addc_co_u32_e32 v71, vcc, 0, v83, vcc
	v_ashrrev_i32_e32 v87, 31, v86
	v_add_u32_e32 v108, 0x17c00, v66
	v_lshl_add_u64 v[86:87], v[86:87], 1, s[6:7]
	v_add_u32_e32 v88, v108, v64
	v_ashrrev_i32_e32 v89, 31, v88
	v_add_u32_e32 v109, 0x1e000, v66
	v_lshl_add_u64 v[88:89], v[88:89], 1, s[6:7]
	s_waitcnt vmcnt(7)
	v_lshlrev_b32_e32 v68, 16, v101
	global_load_ushort v101, v[70:71], off
	v_add_co_u32_e32 v70, vcc, s75, v84
	v_add_u32_e32 v90, v109, v64
	s_nop 0
	v_addc_co_u32_e32 v71, vcc, 0, v85, vcc
	v_add_co_u32_e32 v72, vcc, s75, v86
	v_ashrrev_i32_e32 v91, 31, v90
	s_nop 0
	v_addc_co_u32_e32 v73, vcc, 0, v87, vcc
	v_add_u32_e32 v110, 0x1f400, v66
	v_add_co_u32_e32 v74, vcc, s75, v88
	v_lshl_add_u64 v[90:91], v[90:91], 1, s[6:7]
	v_add_u32_e32 v92, v110, v64
	v_addc_co_u32_e32 v75, vcc, 0, v89, vcc
	v_ashrrev_i32_e32 v93, 31, v92
	v_add_u32_e32 v111, 0x20800, v66
	v_add_co_u32_e32 v76, vcc, s75, v90
	v_lshl_add_u64 v[92:93], v[92:93], 1, s[6:7]
	v_add_u32_e32 v94, v111, v64
	v_addc_co_u32_e32 v77, vcc, 0, v91, vcc
	v_ashrrev_i32_e32 v95, 31, v94
	v_add_u32_e32 v112, 0x21c00, v66
	v_add_co_u32_e32 v78, vcc, s75, v92
	v_lshl_add_u64 v[94:95], v[94:95], 1, s[6:7]
	v_add_u32_e32 v96, v112, v64
	v_addc_co_u32_e32 v79, vcc, 0, v93, vcc
	v_ashrrev_i32_e32 v97, 31, v96
	v_add_co_u32_e32 v80, vcc, s75, v94
	v_lshl_add_u64 v[96:97], v[96:97], 1, s[6:7]
	s_nop 0
	v_addc_co_u32_e32 v81, vcc, 0, v95, vcc
	v_add_co_u32_e32 v82, vcc, s75, v96
	v_max_f32_e32 v68, v68, v68
	s_nop 0
	v_addc_co_u32_e32 v83, vcc, 0, v97, vcc
	global_load_ushort v70, v[70:71], off
	s_nop 0
	global_load_ushort v71, v[72:73], off
	s_nop 0
	global_load_ushort v72, v[74:75], off
	global_load_ushort v73, v[76:77], off
	s_nop 0
	global_load_ushort v74, v[78:79], off
	global_load_ushort v75, v[80:81], off
	global_load_ushort v76, v[82:83], off
	v_max_f32_e32 v68, 0x1e3ce508, v68
	v_lshlrev_b32_e32 v65, 10, v65
	s_add_u32 s0, s4, s0
	v_mul_f32_e32 v0, v0, v68
	v_add_u32_e32 v68, v65, v64
	s_addc_u32 s1, s5, s1
	v_ashrrev_i32_e32 v69, 31, v68
	v_cvt_pk_bf16_f32 v0, v0, s0
	v_lshl_add_u64 v[68:69], v[68:69], 1, s[0:1]
	global_store_short v[68:69], v0, off
	s_waitcnt vmcnt(15)
	v_lshlrev_b32_e32 v0, 16, v113
	v_max_f32_e32 v0, v0, v0
	v_max_f32_e32 v0, 0x1e3ce508, v0
	v_mul_f32_e32 v0, v1, v0
	v_or_b32_e32 v84, 0x400, v65
	v_cvt_pk_bf16_f32 v68, v0, s0
	v_add_u32_e32 v0, v84, v64
	v_ashrrev_i32_e32 v1, 31, v0
	v_lshl_add_u64 v[0:1], v[0:1], 1, s[0:1]
	global_store_short v[0:1], v68, off
	s_waitcnt vmcnt(15)
	v_lshlrev_b32_e32 v0, 16, v114
	v_max_f32_e32 v0, v0, v0
	v_max_f32_e32 v0, 0x1e3ce508, v0
	v_mul_f32_e32 v0, v2, v0
	v_or_b32_e32 v85, 0x800, v65
	v_cvt_pk_bf16_f32 v2, v0, s0
	v_add_u32_e32 v0, v85, v64
	v_ashrrev_i32_e32 v1, 31, v0
	v_lshl_add_u64 v[0:1], v[0:1], 1, s[0:1]
	global_store_short v[0:1], v2, off
	s_waitcnt vmcnt(15)
; DI float bf2f(bf16_t v) { return __uint_as_float(((unsigned)v) << 16); }
; DI bf16_t f2bf(float x) { return (bf16_t)(pk_bf16(x, 0.f) & 0xffffu); }
; DI int crow(int r, int h) { return (r & 3) + 8 * (r >> 2) + 4 * h; }
; DI void phase_merge(const Params& p, int g, char* smem, int bid, int nb) {
;     ...
; #pragma unroll
;     for (int mi = 0; mi < 2; ++mi)
; #pragma unroll
;       for (int ni = 0; ni < 2; ++ni)
;       {
;         bf16_t gb16[16];
; #pragma unroll
;         for (int r = 0; r < 16; ++r) gb16[r] = pt[(wm * 64 + mi * 32 + crow(r, h)) * NPROJ + nt * 128 + wn * 64 + ni * 32 + l31 + PGB];
; #pragma unroll
;         for (int r = 0; r < 16; ++r) {
;           const int rl = wm * 64 + mi * 32 + crow(r, h), cl = nt * 128 + wn * 64 + ni * 32 + l31;
;           mgt[rl * 1024 + cl] = f2bf(acc[mi][ni][r] * fmaxf(bf2f(gb16[r]), 1e-20f));
;         }
	v_lshlrev_b32_e32 v0, 16, v115
	v_max_f32_e32 v0, v0, v0
	v_max_f32_e32 v0, 0x1e3ce508, v0
	v_mul_f32_e32 v0, v3, v0
	v_or_b32_e32 v86, 0xc00, v65
	v_cvt_pk_bf16_f32 v2, v0, s0
	v_add_u32_e32 v0, v86, v64
	v_ashrrev_i32_e32 v1, 31, v0
	v_lshl_add_u64 v[0:1], v[0:1], 1, s[0:1]
	global_store_short v[0:1], v2, off
	s_waitcnt vmcnt(15)
	v_lshlrev_b32_e32 v0, 16, v116
	v_max_f32_e32 v0, v0, v0
	v_max_f32_e32 v0, 0x1e3ce508, v0
	v_mul_f32_e32 v0, v4, v0
	v_add_u32_e32 v87, 0x2000, v65
	v_cvt_pk_bf16_f32 v2, v0, s0
	v_add_u32_e32 v0, v87, v64
	v_ashrrev_i32_e32 v1, 31, v0
	v_lshl_add_u64 v[0:1], v[0:1], 1, s[0:1]
	global_store_short v[0:1], v2, off
	s_waitcnt vmcnt(15)
	v_lshlrev_b32_e32 v0, 16, v117
	v_max_f32_e32 v0, v0, v0
	v_max_f32_e32 v0, 0x1e3ce508, v0
	v_mul_f32_e32 v0, v5, v0
	v_add_u32_e32 v88, 0x2400, v65
	v_cvt_pk_bf16_f32 v2, v0, s0
	v_add_u32_e32 v0, v88, v64
	v_ashrrev_i32_e32 v1, 31, v0
	v_lshl_add_u64 v[0:1], v[0:1], 1, s[0:1]
	global_store_short v[0:1], v2, off
	s_waitcnt vmcnt(15)
	v_lshlrev_b32_e32 v0, 16, v118
	v_max_f32_e32 v0, v0, v0
	v_max_f32_e32 v0, 0x1e3ce508, v0
	v_mul_f32_e32 v0, v6, v0
	v_add_u32_e32 v89, 0x2800, v65
	v_cvt_pk_bf16_f32 v2, v0, s0
	v_add_u32_e32 v0, v89, v64
	v_ashrrev_i32_e32 v1, 31, v0
	v_lshl_add_u64 v[0:1], v[0:1], 1, s[0:1]
	global_store_short v[0:1], v2, off
	s_waitcnt vmcnt(15)
	v_lshlrev_b32_e32 v0, 16, v119
	v_max_f32_e32 v0, v0, v0
	v_max_f32_e32 v0, 0x1e3ce508, v0
	v_mul_f32_e32 v0, v7, v0
	v_add_u32_e32 v90, 0x2c00, v65
	v_cvt_pk_bf16_f32 v2, v0, s0
	v_add_u32_e32 v0, v90, v64
	v_ashrrev_i32_e32 v1, 31, v0
	v_lshl_add_u64 v[0:1], v[0:1], 1, s[0:1]
	global_store_short v[0:1], v2, off
	s_waitcnt vmcnt(15)
	v_lshlrev_b32_e32 v0, 16, v101
	v_max_f32_e32 v0, v0, v0
	v_max_f32_e32 v0, 0x1e3ce508, v0
	v_mul_f32_e32 v0, v8, v0
	v_add_u32_e32 v91, 0x4000, v65
	v_cvt_pk_bf16_f32 v2, v0, s0
	v_add_u32_e32 v0, v91, v64
	v_ashrrev_i32_e32 v1, 31, v0
	v_lshl_add_u64 v[0:1], v[0:1], 1, s[0:1]
	global_store_short v[0:1], v2, off
	s_waitcnt vmcnt(15)
	v_lshlrev_b32_e32 v0, 16, v70
	v_max_f32_e32 v0, v0, v0
	v_max_f32_e32 v0, 0x1e3ce508, v0
	v_mul_f32_e32 v0, v9, v0
	v_add_u32_e32 v92, 0x4400, v65
	v_cvt_pk_bf16_f32 v2, v0, s0
	v_add_u32_e32 v0, v92, v64
	v_ashrrev_i32_e32 v1, 31, v0
	v_lshl_add_u64 v[0:1], v[0:1], 1, s[0:1]
	global_store_short v[0:1], v2, off
	s_waitcnt vmcnt(15)
	v_lshlrev_b32_e32 v0, 16, v71
	v_max_f32_e32 v0, v0, v0
	v_max_f32_e32 v0, 0x1e3ce508, v0
	v_mul_f32_e32 v0, v10, v0
	v_add_u32_e32 v93, 0x4800, v65
	v_cvt_pk_bf16_f32 v2, v0, s0
	v_add_u32_e32 v0, v93, v64
	v_ashrrev_i32_e32 v1, 31, v0
	v_lshl_add_u64 v[0:1], v[0:1], 1, s[0:1]
	global_store_short v[0:1], v2, off
	s_waitcnt vmcnt(15)
	v_lshlrev_b32_e32 v0, 16, v72
	v_max_f32_e32 v0, v0, v0
	v_max_f32_e32 v0, 0x1e3ce508, v0
	v_mul_f32_e32 v0, v11, v0
	v_add_u32_e32 v94, 0x4c00, v65
	v_cvt_pk_bf16_f32 v2, v0, s0
	v_add_u32_e32 v0, v94, v64
	v_ashrrev_i32_e32 v1, 31, v0
	v_lshl_add_u64 v[0:1], v[0:1], 1, s[0:1]
	global_store_short v[0:1], v2, off
	s_waitcnt vmcnt(15)
	v_lshlrev_b32_e32 v0, 16, v73
	v_max_f32_e32 v0, v0, v0
	v_max_f32_e32 v0, 0x1e3ce508, v0
	v_mul_f32_e32 v0, v12, v0
	v_add_u32_e32 v95, 0x6000, v65
	v_cvt_pk_bf16_f32 v2, v0, s0
	v_add_u32_e32 v0, v95, v64
	v_ashrrev_i32_e32 v1, 31, v0
	v_lshl_add_u64 v[0:1], v[0:1], 1, s[0:1]
	global_store_short v[0:1], v2, off
	s_waitcnt vmcnt(15)
	v_lshlrev_b32_e32 v0, 16, v74
	v_max_f32_e32 v0, v0, v0
	v_max_f32_e32 v0, 0x1e3ce508, v0
	v_mul_f32_e32 v0, v13, v0
	v_add_u32_e32 v96, 0x6400, v65
	v_cvt_pk_bf16_f32 v2, v0, s0
	v_add_u32_e32 v0, v96, v64
	v_ashrrev_i32_e32 v1, 31, v0
	v_lshl_add_u64 v[0:1], v[0:1], 1, s[0:1]
	global_store_short v[0:1], v2, off
	s_waitcnt vmcnt(15)
	v_lshlrev_b32_e32 v0, 16, v75
	v_max_f32_e32 v0, v0, v0
	v_max_f32_e32 v0, 0x1e3ce508, v0
	v_mul_f32_e32 v0, v14, v0
	v_add_u32_e32 v97, 0x6800, v65
	v_cvt_pk_bf16_f32 v2, v0, s0
	v_add_u32_e32 v0, v97, v64
	v_ashrrev_i32_e32 v1, 31, v0
	v_lshl_add_u64 v[0:1], v[0:1], 1, s[0:1]
	global_store_short v[0:1], v2, off
	s_waitcnt vmcnt(15)
	v_lshlrev_b32_e32 v0, 16, v76
	v_max_f32_e32 v0, v0, v0
	v_max_f32_e32 v0, 0x1e3ce508, v0
	v_mul_f32_e32 v0, v15, v0
	v_add_u32_e32 v101, 0x6c00, v65
	v_cvt_pk_bf16_f32 v2, v0, s0
	v_add_u32_e32 v0, v101, v64
	v_ashrrev_i32_e32 v1, 31, v0
	v_lshl_add_u64 v[0:1], v[0:1], 1, s[0:1]
	global_store_short v[0:1], v2, off
	v_add_u32_e32 v0, 32, v64
	v_add_u32_e32 v2, v0, v66
	v_ashrrev_i32_e32 v3, 31, v2
	v_lshl_add_u64 v[2:3], v[2:3], 1, s[6:7]
	v_add_co_u32_e32 v2, vcc, s75, v2
	v_add_u32_e32 v4, v98, v0
	s_nop 0
	v_addc_co_u32_e32 v3, vcc, 0, v3, vcc
	global_load_ushort v1, v[2:3], off
	v_ashrrev_i32_e32 v5, 31, v4
	v_lshl_add_u64 v[2:3], v[4:5], 1, s[6:7]
	v_add_co_u32_e32 v2, vcc, s75, v2
	v_add_u32_e32 v4, v67, v0
	s_nop 0
	v_addc_co_u32_e32 v3, vcc, 0, v3, vcc
	global_load_ushort v67, v[2:3], off
	v_ashrrev_i32_e32 v5, 31, v4
	v_lshl_add_u64 v[4:5], v[4:5], 1, s[6:7]
	v_add_u32_e32 v6, v99, v0
	v_ashrrev_i32_e32 v7, 31, v6
	v_add_co_u32_e32 v2, vcc, s75, v4
	v_lshl_add_u64 v[6:7], v[6:7], 1, s[6:7]
	s_nop 0
	v_addc_co_u32_e32 v3, vcc, 0, v5, vcc
	v_add_co_u32_e32 v4, vcc, s75, v6
	v_add_u32_e32 v8, v100, v0
	s_nop 0
	v_addc_co_u32_e32 v5, vcc, 0, v7, vcc
	global_load_ushort v98, v[2:3], off
	global_load_ushort v99, v[4:5], off
	v_ashrrev_i32_e32 v9, 31, v8
	v_lshl_add_u64 v[8:9], v[8:9], 1, s[6:7]
	v_add_u32_e32 v10, v102, v0
	v_ashrrev_i32_e32 v11, 31, v10
	v_add_co_u32_e32 v2, vcc, s75, v8
	v_lshl_add_u64 v[10:11], v[10:11], 1, s[6:7]
	v_add_u32_e32 v12, v103, v0
	v_addc_co_u32_e32 v3, vcc, 0, v9, vcc
	v_ashrrev_i32_e32 v13, 31, v12
	v_add_co_u32_e32 v4, vcc, s75, v10
; DI float bf2f(bf16_t v) { return __uint_as_float(((unsigned)v) << 16); }
; DI bf16_t f2bf(float x) { return (bf16_t)(pk_bf16(x, 0.f) & 0xffffu); }
; DI int crow(int r, int h) { return (r & 3) + 8 * (r >> 2) + 4 * h; }
; DI void phase_merge(const Params& p, int g, char* smem, int bid, int nb) {
;     ...
; #pragma unroll
;     for (int mi = 0; mi < 2; ++mi)
; #pragma unroll
;       for (int ni = 0; ni < 2; ++ni)
;       {
;         bf16_t gb16[16];
; #pragma unroll
;         for (int r = 0; r < 16; ++r) gb16[r] = pt[(wm * 64 + mi * 32 + crow(r, h)) * NPROJ + nt * 128 + wn * 64 + ni * 32 + l31 + PGB];
; #pragma unroll
;         for (int r = 0; r < 16; ++r) {
;           const int rl = wm * 64 + mi * 32 + crow(r, h), cl = nt * 128 + wn * 64 + ni * 32 + l31;
;           mgt[rl * 1024 + cl] = f2bf(acc[mi][ni][r] * fmaxf(bf2f(gb16[r]), 1e-20f));
;         }
	v_lshl_add_u64 v[12:13], v[12:13], 1, s[6:7]
	v_add_u32_e32 v14, v104, v0
	v_addc_co_u32_e32 v5, vcc, 0, v11, vcc
	v_ashrrev_i32_e32 v15, 31, v14
	v_add_co_u32_e32 v6, vcc, s75, v12
	v_lshl_add_u64 v[14:15], v[14:15], 1, s[6:7]
	s_nop 0
	v_addc_co_u32_e32 v7, vcc, 0, v13, vcc
	v_add_co_u32_e32 v8, vcc, s75, v14
	v_add_u32_e32 v68, v105, v0
	s_nop 0
	v_addc_co_u32_e32 v9, vcc, 0, v15, vcc
	global_load_ushort v100, v[2:3], off
	global_load_ushort v102, v[4:5], off
	global_load_ushort v103, v[6:7], off
	global_load_ushort v104, v[8:9], off
	v_ashrrev_i32_e32 v69, 31, v68
	v_lshl_add_u64 v[68:69], v[68:69], 1, s[6:7]
	v_add_u32_e32 v70, v106, v0
	v_ashrrev_i32_e32 v71, 31, v70
	v_add_co_u32_e32 v4, vcc, s75, v68
	v_lshl_add_u64 v[70:71], v[70:71], 1, s[6:7]
	v_add_u32_e32 v72, v107, v0
	v_addc_co_u32_e32 v5, vcc, 0, v69, vcc
	v_ashrrev_i32_e32 v73, 31, v72
	v_lshl_add_u64 v[72:73], v[72:73], 1, s[6:7]
	v_add_u32_e32 v74, v108, v0
	v_ashrrev_i32_e32 v75, 31, v74
	v_lshl_add_u64 v[74:75], v[74:75], 1, s[6:7]
	v_add_u32_e32 v76, v109, v0
	v_ashrrev_i32_e32 v77, 31, v76
	v_lshl_add_u64 v[76:77], v[76:77], 1, s[6:7]
	v_add_u32_e32 v78, v110, v0
	v_ashrrev_i32_e32 v79, 31, v78
	v_lshl_add_u64 v[78:79], v[78:79], 1, s[6:7]
	v_add_u32_e32 v80, v111, v0
	v_ashrrev_i32_e32 v81, 31, v80
	v_lshl_add_u64 v[80:81], v[80:81], 1, s[6:7]
	v_add_u32_e32 v82, v112, v0
	v_ashrrev_i32_e32 v83, 31, v82
	v_lshl_add_u64 v[82:83], v[82:83], 1, s[6:7]
	s_waitcnt vmcnt(7)
	v_lshlrev_b32_e32 v1, 16, v1
	v_max_f32_e32 v1, v1, v1
	v_max_f32_e32 v1, 0x1e3ce508, v1
	v_mul_f32_e32 v1, v32, v1
	global_load_ushort v32, v[4:5], off
	v_add_co_u32_e32 v4, vcc, s75, v70
	v_add_u32_e32 v2, v0, v65
	s_nop 0
	v_addc_co_u32_e32 v5, vcc, 0, v71, vcc
	v_add_co_u32_e32 v6, vcc, s75, v72
	v_ashrrev_i32_e32 v3, 31, v2
	s_nop 0
	v_addc_co_u32_e32 v7, vcc, 0, v73, vcc
	v_add_co_u32_e32 v8, vcc, s75, v74
	v_cvt_pk_bf16_f32 v1, v1, s0
	s_nop 0
	v_addc_co_u32_e32 v9, vcc, 0, v75, vcc
	v_add_co_u32_e32 v10, vcc, s75, v76
	v_lshl_add_u64 v[2:3], v[2:3], 1, s[0:1]
	s_nop 0
	v_addc_co_u32_e32 v11, vcc, 0, v77, vcc
	v_add_co_u32_e32 v12, vcc, s75, v78
	v_add_u32_e32 v70, 0x32000, v66
	s_nop 0
	v_addc_co_u32_e32 v13, vcc, 0, v79, vcc
	v_add_co_u32_e32 v14, vcc, s75, v80
	v_add_u32_e32 v72, 0x33400, v66
	s_nop 0
	v_addc_co_u32_e32 v15, vcc, 0, v81, vcc
	v_add_co_u32_e32 v68, vcc, s75, v82
	v_add_u32_e32 v73, 0x34800, v66
	s_nop 0
	v_addc_co_u32_e32 v69, vcc, 0, v83, vcc
	global_load_ushort v4, v[4:5], off
	s_nop 0
	global_load_ushort v5, v[6:7], off
	s_nop 0
	global_load_ushort v6, v[8:9], off
	global_load_ushort v7, v[10:11], off
	s_nop 0
	global_load_ushort v8, v[12:13], off
	global_load_ushort v9, v[14:15], off
	global_load_ushort v10, v[68:69], off
	v_add_u32_e32 v68, 0x2a800, v66
	global_store_short v[2:3], v1, off
	s_waitcnt vmcnt(15)
	v_lshlrev_b32_e32 v1, 16, v67
	v_max_f32_e32 v1, v1, v1
	v_max_f32_e32 v1, 0x1e3ce508, v1
	v_add_u32_e32 v2, v84, v0
	v_mul_f32_e32 v1, v33, v1
	v_ashrrev_i32_e32 v3, 31, v2
	v_cvt_pk_bf16_f32 v1, v1, s0
	v_lshl_add_u64 v[2:3], v[2:3], 1, s[0:1]
	global_store_short v[2:3], v1, off
	s_waitcnt vmcnt(15)
	v_lshlrev_b32_e32 v1, 16, v98
	v_max_f32_e32 v1, v1, v1
	v_max_f32_e32 v1, 0x1e3ce508, v1
	v_add_u32_e32 v2, v85, v0
	v_mul_f32_e32 v1, v34, v1
	v_ashrrev_i32_e32 v3, 31, v2
	v_cvt_pk_bf16_f32 v1, v1, s0
	v_lshl_add_u64 v[2:3], v[2:3], 1, s[0:1]
	global_store_short v[2:3], v1, off
	s_waitcnt vmcnt(15)
	v_lshlrev_b32_e32 v1, 16, v99
	v_max_f32_e32 v1, v1, v1
	v_max_f32_e32 v1, 0x1e3ce508, v1
	v_add_u32_e32 v2, v86, v0
	v_mul_f32_e32 v1, v35, v1
	v_ashrrev_i32_e32 v3, 31, v2
	v_cvt_pk_bf16_f32 v1, v1, s0
	v_lshl_add_u64 v[2:3], v[2:3], 1, s[0:1]
	global_store_short v[2:3], v1, off
	s_waitcnt vmcnt(15)
	v_lshlrev_b32_e32 v1, 16, v100
	v_max_f32_e32 v1, v1, v1
	v_max_f32_e32 v1, 0x1e3ce508, v1
	v_add_u32_e32 v2, v87, v0
	v_mul_f32_e32 v1, v36, v1
	v_ashrrev_i32_e32 v3, 31, v2
	v_cvt_pk_bf16_f32 v1, v1, s0
	v_lshl_add_u64 v[2:3], v[2:3], 1, s[0:1]
	global_store_short v[2:3], v1, off
	s_waitcnt vmcnt(15)
	v_lshlrev_b32_e32 v1, 16, v102
	v_max_f32_e32 v1, v1, v1
	v_max_f32_e32 v1, 0x1e3ce508, v1
	v_add_u32_e32 v2, v88, v0
	v_mul_f32_e32 v1, v37, v1
	v_ashrrev_i32_e32 v3, 31, v2
	v_cvt_pk_bf16_f32 v1, v1, s0
	v_lshl_add_u64 v[2:3], v[2:3], 1, s[0:1]
	global_store_short v[2:3], v1, off
	s_waitcnt vmcnt(15)
	v_lshlrev_b32_e32 v1, 16, v103
	v_max_f32_e32 v1, v1, v1
	v_max_f32_e32 v1, 0x1e3ce508, v1
	v_add_u32_e32 v2, v89, v0
	v_mul_f32_e32 v1, v38, v1
	v_ashrrev_i32_e32 v3, 31, v2
	v_cvt_pk_bf16_f32 v1, v1, s0
	v_lshl_add_u64 v[2:3], v[2:3], 1, s[0:1]
	global_store_short v[2:3], v1, off
	s_waitcnt vmcnt(15)
	v_lshlrev_b32_e32 v1, 16, v104
	v_max_f32_e32 v1, v1, v1
	v_max_f32_e32 v1, 0x1e3ce508, v1
	v_add_u32_e32 v2, v90, v0
	v_mul_f32_e32 v1, v39, v1
	v_ashrrev_i32_e32 v3, 31, v2
	v_cvt_pk_bf16_f32 v1, v1, s0
	v_lshl_add_u64 v[2:3], v[2:3], 1, s[0:1]
	global_store_short v[2:3], v1, off
	s_waitcnt vmcnt(15)
	v_lshlrev_b32_e32 v1, 16, v32
	v_max_f32_e32 v1, v1, v1
	v_max_f32_e32 v1, 0x1e3ce508, v1
	v_add_u32_e32 v2, v91, v0
	v_mul_f32_e32 v1, v40, v1
	v_ashrrev_i32_e32 v3, 31, v2
	v_cvt_pk_bf16_f32 v1, v1, s0
	v_lshl_add_u64 v[2:3], v[2:3], 1, s[0:1]
	global_store_short v[2:3], v1, off
	s_waitcnt vmcnt(15)
	v_lshlrev_b32_e32 v1, 16, v4
	v_max_f32_e32 v1, v1, v1
	v_max_f32_e32 v1, 0x1e3ce508, v1
	v_add_u32_e32 v2, v92, v0
	v_mul_f32_e32 v1, v41, v1
	v_ashrrev_i32_e32 v3, 31, v2
	v_cvt_pk_bf16_f32 v1, v1, s0
	v_lshl_add_u64 v[2:3], v[2:3], 1, s[0:1]
	global_store_short v[2:3], v1, off
	s_waitcnt vmcnt(15)
; DI float bf2f(bf16_t v) { return __uint_as_float(((unsigned)v) << 16); }
; DI bf16_t f2bf(float x) { return (bf16_t)(pk_bf16(x, 0.f) & 0xffffu); }
; DI int crow(int r, int h) { return (r & 3) + 8 * (r >> 2) + 4 * h; }
; DI void phase_merge(const Params& p, int g, char* smem, int bid, int nb) {
;     ...
; #pragma unroll
;     for (int mi = 0; mi < 2; ++mi)
; #pragma unroll
;       for (int ni = 0; ni < 2; ++ni)
;       {
;         bf16_t gb16[16];
; #pragma unroll
;         for (int r = 0; r < 16; ++r) gb16[r] = pt[(wm * 64 + mi * 32 + crow(r, h)) * NPROJ + nt * 128 + wn * 64 + ni * 32 + l31 + PGB];
; #pragma unroll
;         for (int r = 0; r < 16; ++r) {
;           const int rl = wm * 64 + mi * 32 + crow(r, h), cl = nt * 128 + wn * 64 + ni * 32 + l31;
;           mgt[rl * 1024 + cl] = f2bf(acc[mi][ni][r] * fmaxf(bf2f(gb16[r]), 1e-20f));
;         }
	v_lshlrev_b32_e32 v1, 16, v5
	v_max_f32_e32 v1, v1, v1
	v_max_f32_e32 v1, 0x1e3ce508, v1
	v_add_u32_e32 v2, v93, v0
	v_mul_f32_e32 v1, v42, v1
	v_ashrrev_i32_e32 v3, 31, v2
	v_cvt_pk_bf16_f32 v1, v1, s0
	v_lshl_add_u64 v[2:3], v[2:3], 1, s[0:1]
	global_store_short v[2:3], v1, off
	s_waitcnt vmcnt(15)
	v_lshlrev_b32_e32 v1, 16, v6
	v_max_f32_e32 v1, v1, v1
	v_max_f32_e32 v1, 0x1e3ce508, v1
	v_add_u32_e32 v2, v94, v0
	v_mul_f32_e32 v1, v43, v1
	v_ashrrev_i32_e32 v3, 31, v2
	v_cvt_pk_bf16_f32 v1, v1, s0
	v_lshl_add_u64 v[2:3], v[2:3], 1, s[0:1]
	global_store_short v[2:3], v1, off
	s_waitcnt vmcnt(15)
	v_lshlrev_b32_e32 v1, 16, v7
	v_max_f32_e32 v1, v1, v1
	v_max_f32_e32 v1, 0x1e3ce508, v1
	v_add_u32_e32 v2, v95, v0
	v_mul_f32_e32 v1, v44, v1
	v_ashrrev_i32_e32 v3, 31, v2
	v_cvt_pk_bf16_f32 v1, v1, s0
	v_lshl_add_u64 v[2:3], v[2:3], 1, s[0:1]
	global_store_short v[2:3], v1, off
	s_waitcnt vmcnt(15)
	v_lshlrev_b32_e32 v1, 16, v8
	v_max_f32_e32 v1, v1, v1
	v_max_f32_e32 v1, 0x1e3ce508, v1
	v_add_u32_e32 v2, v96, v0
	v_mul_f32_e32 v1, v45, v1
	v_ashrrev_i32_e32 v3, 31, v2
	v_cvt_pk_bf16_f32 v1, v1, s0
	v_lshl_add_u64 v[2:3], v[2:3], 1, s[0:1]
	global_store_short v[2:3], v1, off
	s_waitcnt vmcnt(15)
	v_lshlrev_b32_e32 v1, 16, v9
	v_max_f32_e32 v1, v1, v1
	v_max_f32_e32 v1, 0x1e3ce508, v1
	v_add_u32_e32 v2, v97, v0
	v_mul_f32_e32 v1, v46, v1
	v_ashrrev_i32_e32 v3, 31, v2
	v_cvt_pk_bf16_f32 v1, v1, s0
	v_lshl_add_u64 v[2:3], v[2:3], 1, s[0:1]
	global_store_short v[2:3], v1, off
	s_waitcnt vmcnt(15)
	v_lshlrev_b32_e32 v1, 16, v10
	v_max_f32_e32 v1, v1, v1
	v_max_f32_e32 v1, 0x1e3ce508, v1
	v_add_u32_e32 v2, v101, v0
	v_mul_f32_e32 v1, v47, v1
	v_ashrrev_i32_e32 v3, 31, v2
	v_cvt_pk_bf16_f32 v1, v1, s0
	v_lshl_add_u64 v[2:3], v[2:3], 1, s[0:1]
	global_store_short v[2:3], v1, off
	v_add_u32_e32 v1, 0x28000, v66
	v_add_u32_e32 v2, v1, v64
	v_ashrrev_i32_e32 v3, 31, v2
	v_lshl_add_u64 v[2:3], v[2:3], 1, s[6:7]
	v_add_co_u32_e32 v2, vcc, s75, v2
	v_add_u32_e32 v67, 0x29400, v66
	s_nop 0
	v_addc_co_u32_e32 v3, vcc, 0, v3, vcc
	global_load_ushort v71, v[2:3], off
	v_add_u32_e32 v4, v67, v64
	v_ashrrev_i32_e32 v5, 31, v4
	v_lshl_add_u64 v[4:5], v[4:5], 1, s[6:7]
	v_add_co_u32_e32 v4, vcc, s75, v4
	v_add_u32_e32 v6, v68, v64
	s_nop 0
	v_addc_co_u32_e32 v5, vcc, 0, v5, vcc
	global_load_ushort v82, v[4:5], off
	v_ashrrev_i32_e32 v7, 31, v6
	v_add_u32_e32 v69, 0x2bc00, v66
	v_lshl_add_u64 v[6:7], v[6:7], 1, s[6:7]
	v_add_u32_e32 v8, v69, v64
	v_ashrrev_i32_e32 v9, 31, v8
	v_add_co_u32_e32 v4, vcc, s75, v6
	v_lshl_add_u64 v[8:9], v[8:9], 1, s[6:7]
	s_nop 0
	v_addc_co_u32_e32 v5, vcc, 0, v7, vcc
	v_add_co_u32_e32 v6, vcc, s75, v8
	v_add_u32_e32 v10, v70, v64
	s_nop 0
	v_addc_co_u32_e32 v7, vcc, 0, v9, vcc
	global_load_ushort v83, v[4:5], off
	global_load_ushort v84, v[6:7], off
	v_ashrrev_i32_e32 v11, 31, v10
	v_lshl_add_u64 v[10:11], v[10:11], 1, s[6:7]
	v_add_u32_e32 v2, v72, v64
	v_ashrrev_i32_e32 v3, 31, v2
	v_add_co_u32_e32 v4, vcc, s75, v10
	v_lshl_add_u64 v[2:3], v[2:3], 1, s[6:7]
	v_add_u32_e32 v12, v73, v64
	v_addc_co_u32_e32 v5, vcc, 0, v11, vcc
	v_ashrrev_i32_e32 v13, 31, v12
	v_add_u32_e32 v74, 0x35c00, v66
	v_add_co_u32_e32 v2, vcc, s75, v2
	v_lshl_add_u64 v[12:13], v[12:13], 1, s[6:7]
	v_add_u32_e32 v14, v74, v64
	v_addc_co_u32_e32 v3, vcc, 0, v3, vcc
	v_ashrrev_i32_e32 v15, 31, v14
	v_add_co_u32_e32 v6, vcc, s75, v12
	v_lshl_add_u64 v[14:15], v[14:15], 1, s[6:7]
	s_nop 0
	v_addc_co_u32_e32 v7, vcc, 0, v13, vcc
	v_add_co_u32_e32 v8, vcc, s75, v14
	v_add_u32_e32 v75, 0x3c000, v66
	s_nop 0
	v_addc_co_u32_e32 v9, vcc, 0, v15, vcc
	global_load_ushort v85, v[4:5], off
	global_load_ushort v86, v[2:3], off
	global_load_ushort v87, v[6:7], off
	global_load_ushort v88, v[8:9], off
	v_add_u32_e32 v32, v75, v64
	v_ashrrev_i32_e32 v33, 31, v32
	v_add_u32_e32 v76, 0x3d400, v66
	v_lshl_add_u64 v[32:33], v[32:33], 1, s[6:7]
	v_add_u32_e32 v34, v76, v64
	v_ashrrev_i32_e32 v35, 31, v34
	v_add_u32_e32 v77, 0x3e800, v66
	v_add_co_u32_e32 v4, vcc, s75, v32
	v_lshl_add_u64 v[34:35], v[34:35], 1, s[6:7]
	v_add_u32_e32 v36, v77, v64
	v_addc_co_u32_e32 v5, vcc, 0, v33, vcc
	v_ashrrev_i32_e32 v37, 31, v36
	v_add_u32_e32 v78, 0x3fc00, v66
	global_load_ushort v89, v[4:5], off
	v_add_co_u32_e32 v4, vcc, s75, v34
	v_lshl_add_u64 v[36:37], v[36:37], 1, s[6:7]
	v_add_u32_e32 v38, v78, v64
	v_addc_co_u32_e32 v5, vcc, 0, v35, vcc
	v_ashrrev_i32_e32 v39, 31, v38
	v_add_u32_e32 v79, 0x46000, v66
	v_add_co_u32_e32 v6, vcc, s75, v36
	v_lshl_add_u64 v[38:39], v[38:39], 1, s[6:7]
	v_add_u32_e32 v40, v79, v64
	v_addc_co_u32_e32 v7, vcc, 0, v37, vcc
	v_ashrrev_i32_e32 v41, 31, v40
	v_add_u32_e32 v80, 0x47400, v66
	v_add_co_u32_e32 v8, vcc, s75, v38
	v_lshl_add_u64 v[40:41], v[40:41], 1, s[6:7]
	v_add_u32_e32 v42, v80, v64
	v_addc_co_u32_e32 v9, vcc, 0, v39, vcc
	v_ashrrev_i32_e32 v43, 31, v42
	v_add_u32_e32 v81, 0x48800, v66
	v_add_co_u32_e32 v10, vcc, s75, v40
	v_lshl_add_u64 v[42:43], v[42:43], 1, s[6:7]
	v_add_u32_e32 v44, v81, v64
	v_addc_co_u32_e32 v11, vcc, 0, v41, vcc
	v_ashrrev_i32_e32 v45, 31, v44
	v_add_u32_e32 v66, 0x49c00, v66
	v_add_co_u32_e32 v12, vcc, s75, v42
	v_lshl_add_u64 v[44:45], v[44:45], 1, s[6:7]
	v_add_u32_e32 v46, v66, v64
	v_addc_co_u32_e32 v13, vcc, 0, v43, vcc
	v_ashrrev_i32_e32 v47, 31, v46
	v_add_co_u32_e32 v14, vcc, s75, v44
	v_lshl_add_u64 v[46:47], v[46:47], 1, s[6:7]
	s_nop 0
	v_addc_co_u32_e32 v15, vcc, 0, v45, vcc
	v_add_co_u32_e32 v32, vcc, s75, v46
	s_waitcnt vmcnt(8)
; DI float bf2f(bf16_t v) { return __uint_as_float(((unsigned)v) << 16); }
; DI bf16_t f2bf(float x) { return (bf16_t)(pk_bf16(x, 0.f) & 0xffffu); }
; DI int crow(int r, int h) { return (r & 3) + 8 * (r >> 2) + 4 * h; }
; DI void phase_merge(const Params& p, int g, char* smem, int bid, int nb) {
;     ...
; #pragma unroll
;     for (int mi = 0; mi < 2; ++mi)
; #pragma unroll
;       for (int ni = 0; ni < 2; ++ni)
;       {
;         bf16_t gb16[16];
; #pragma unroll
;         for (int r = 0; r < 16; ++r) gb16[r] = pt[(wm * 64 + mi * 32 + crow(r, h)) * NPROJ + nt * 128 + wn * 64 + ni * 32 + l31 + PGB];
; #pragma unroll
;         for (int r = 0; r < 16; ++r) {
;           const int rl = wm * 64 + mi * 32 + crow(r, h), cl = nt * 128 + wn * 64 + ni * 32 + l31;
;           mgt[rl * 1024 + cl] = f2bf(acc[mi][ni][r] * fmaxf(bf2f(gb16[r]), 1e-20f));
;         }
	v_lshlrev_b32_e32 v2, 16, v71
	v_addc_co_u32_e32 v33, vcc, 0, v47, vcc
	global_load_ushort v4, v[4:5], off
	s_nop 0
	global_load_ushort v5, v[6:7], off
	s_nop 0
	global_load_ushort v6, v[8:9], off
	global_load_ushort v7, v[10:11], off
	s_nop 0
	global_load_ushort v8, v[12:13], off
	global_load_ushort v9, v[14:15], off
	global_load_ushort v10, v[32:33], off
	v_max_f32_e32 v2, v2, v2
	v_max_f32_e32 v2, 0x1e3ce508, v2
	v_mul_f32_e32 v2, v48, v2
	v_add_u32_e32 v71, 0x8000, v65
	v_cvt_pk_bf16_f32 v48, v2, s0
	v_add_u32_e32 v2, v71, v64
	v_ashrrev_i32_e32 v3, 31, v2
	v_lshl_add_u64 v[2:3], v[2:3], 1, s[0:1]
	global_store_short v[2:3], v48, off
	s_waitcnt vmcnt(15)
	v_lshlrev_b32_e32 v2, 16, v82
	v_max_f32_e32 v2, v2, v2
	v_max_f32_e32 v2, 0x1e3ce508, v2
	v_mul_f32_e32 v2, v49, v2
	v_add_u32_e32 v48, 0x8400, v65
	v_cvt_pk_bf16_f32 v11, v2, s0
	v_add_u32_e32 v2, v48, v64
	v_ashrrev_i32_e32 v3, 31, v2
	v_lshl_add_u64 v[2:3], v[2:3], 1, s[0:1]
	global_store_short v[2:3], v11, off
	s_waitcnt vmcnt(15)
	v_lshlrev_b32_e32 v2, 16, v83
	v_max_f32_e32 v2, v2, v2
	v_max_f32_e32 v2, 0x1e3ce508, v2
	v_mul_f32_e32 v2, v50, v2
	v_add_u32_e32 v49, 0x8800, v65
	v_cvt_pk_bf16_f32 v11, v2, s0
	v_add_u32_e32 v2, v49, v64
	v_ashrrev_i32_e32 v3, 31, v2
	v_lshl_add_u64 v[2:3], v[2:3], 1, s[0:1]
	global_store_short v[2:3], v11, off
	s_waitcnt vmcnt(15)
	v_lshlrev_b32_e32 v2, 16, v84
	v_max_f32_e32 v2, v2, v2
	v_max_f32_e32 v2, 0x1e3ce508, v2
	v_mul_f32_e32 v2, v51, v2
	v_add_u32_e32 v50, 0x8c00, v65
	v_cvt_pk_bf16_f32 v11, v2, s0
	v_add_u32_e32 v2, v50, v64
	v_ashrrev_i32_e32 v3, 31, v2
	v_lshl_add_u64 v[2:3], v[2:3], 1, s[0:1]
	global_store_short v[2:3], v11, off
	s_waitcnt vmcnt(15)
	v_lshlrev_b32_e32 v2, 16, v85
	v_max_f32_e32 v2, v2, v2
	v_max_f32_e32 v2, 0x1e3ce508, v2
	v_mul_f32_e32 v2, v52, v2
	v_add_u32_e32 v51, 0xa000, v65
	v_cvt_pk_bf16_f32 v11, v2, s0
	v_add_u32_e32 v2, v51, v64
	v_ashrrev_i32_e32 v3, 31, v2
	v_lshl_add_u64 v[2:3], v[2:3], 1, s[0:1]
	global_store_short v[2:3], v11, off
	s_waitcnt vmcnt(15)
	v_lshlrev_b32_e32 v2, 16, v86
	v_max_f32_e32 v2, v2, v2
	v_max_f32_e32 v2, 0x1e3ce508, v2
	v_mul_f32_e32 v2, v53, v2
	v_add_u32_e32 v52, 0xa400, v65
	v_cvt_pk_bf16_f32 v11, v2, s0
	v_add_u32_e32 v2, v52, v64
	v_ashrrev_i32_e32 v3, 31, v2
	v_lshl_add_u64 v[2:3], v[2:3], 1, s[0:1]
	global_store_short v[2:3], v11, off
	s_waitcnt vmcnt(15)
	v_lshlrev_b32_e32 v2, 16, v87
	v_max_f32_e32 v2, v2, v2
	v_max_f32_e32 v2, 0x1e3ce508, v2
	v_mul_f32_e32 v2, v54, v2
	v_add_u32_e32 v53, 0xa800, v65
	v_cvt_pk_bf16_f32 v11, v2, s0
	v_add_u32_e32 v2, v53, v64
	v_ashrrev_i32_e32 v3, 31, v2
	v_lshl_add_u64 v[2:3], v[2:3], 1, s[0:1]
	global_store_short v[2:3], v11, off
	s_waitcnt vmcnt(15)
	v_lshlrev_b32_e32 v2, 16, v88
	v_max_f32_e32 v2, v2, v2
	v_max_f32_e32 v2, 0x1e3ce508, v2
	v_mul_f32_e32 v2, v55, v2
	v_add_u32_e32 v54, 0xac00, v65
	v_cvt_pk_bf16_f32 v11, v2, s0
	v_add_u32_e32 v2, v54, v64
	v_ashrrev_i32_e32 v3, 31, v2
	v_lshl_add_u64 v[2:3], v[2:3], 1, s[0:1]
	global_store_short v[2:3], v11, off
	s_waitcnt vmcnt(15)
	v_lshlrev_b32_e32 v2, 16, v89
	v_max_f32_e32 v2, v2, v2
	v_max_f32_e32 v2, 0x1e3ce508, v2
	v_mul_f32_e32 v2, v56, v2
	v_add_u32_e32 v55, 0xc000, v65
	v_cvt_pk_bf16_f32 v11, v2, s0
	v_add_u32_e32 v2, v55, v64
	v_ashrrev_i32_e32 v3, 31, v2
	v_lshl_add_u64 v[2:3], v[2:3], 1, s[0:1]
	global_store_short v[2:3], v11, off
	s_waitcnt vmcnt(15)
	v_lshlrev_b32_e32 v2, 16, v4
	v_max_f32_e32 v2, v2, v2
	v_max_f32_e32 v2, 0x1e3ce508, v2
	v_mul_f32_e32 v2, v57, v2
	v_add_u32_e32 v56, 0xc400, v65
	v_cvt_pk_bf16_f32 v4, v2, s0
	v_add_u32_e32 v2, v56, v64
	v_ashrrev_i32_e32 v3, 31, v2
	v_lshl_add_u64 v[2:3], v[2:3], 1, s[0:1]
	global_store_short v[2:3], v4, off
	s_waitcnt vmcnt(15)
	v_lshlrev_b32_e32 v2, 16, v5
	v_max_f32_e32 v2, v2, v2
	v_max_f32_e32 v2, 0x1e3ce508, v2
	v_mul_f32_e32 v2, v58, v2
	v_add_u32_e32 v57, 0xc800, v65
	v_cvt_pk_bf16_f32 v4, v2, s0
	v_add_u32_e32 v2, v57, v64
	v_ashrrev_i32_e32 v3, 31, v2
	v_lshl_add_u64 v[2:3], v[2:3], 1, s[0:1]
	global_store_short v[2:3], v4, off
	s_waitcnt vmcnt(15)
	v_lshlrev_b32_e32 v2, 16, v6
	v_max_f32_e32 v2, v2, v2
	v_max_f32_e32 v2, 0x1e3ce508, v2
	v_mul_f32_e32 v2, v59, v2
	v_add_u32_e32 v58, 0xcc00, v65
	v_cvt_pk_bf16_f32 v4, v2, s0
	v_add_u32_e32 v2, v58, v64
	v_ashrrev_i32_e32 v3, 31, v2
	v_lshl_add_u64 v[2:3], v[2:3], 1, s[0:1]
	global_store_short v[2:3], v4, off
	s_waitcnt vmcnt(15)
	v_lshlrev_b32_e32 v2, 16, v7
	v_max_f32_e32 v2, v2, v2
	v_max_f32_e32 v2, 0x1e3ce508, v2
	v_mul_f32_e32 v2, v60, v2
	v_add_u32_e32 v59, 0xe000, v65
	v_cvt_pk_bf16_f32 v4, v2, s0
	v_add_u32_e32 v2, v59, v64
	v_ashrrev_i32_e32 v3, 31, v2
	v_lshl_add_u64 v[2:3], v[2:3], 1, s[0:1]
	global_store_short v[2:3], v4, off
	s_waitcnt vmcnt(15)
	v_lshlrev_b32_e32 v2, 16, v8
	v_max_f32_e32 v2, v2, v2
	v_max_f32_e32 v2, 0x1e3ce508, v2
	v_mul_f32_e32 v2, v61, v2
	v_add_u32_e32 v60, 0xe400, v65
	v_cvt_pk_bf16_f32 v4, v2, s0
	v_add_u32_e32 v2, v60, v64
	v_ashrrev_i32_e32 v3, 31, v2
	v_lshl_add_u64 v[2:3], v[2:3], 1, s[0:1]
	global_store_short v[2:3], v4, off
	s_waitcnt vmcnt(15)
	v_lshlrev_b32_e32 v2, 16, v9
	v_max_f32_e32 v2, v2, v2
	v_max_f32_e32 v2, 0x1e3ce508, v2
	v_mul_f32_e32 v2, v62, v2
	v_add_u32_e32 v61, 0xe800, v65
	v_cvt_pk_bf16_f32 v4, v2, s0
	v_add_u32_e32 v2, v61, v64
	v_ashrrev_i32_e32 v3, 31, v2
	v_lshl_add_u64 v[2:3], v[2:3], 1, s[0:1]
	global_store_short v[2:3], v4, off
	s_waitcnt vmcnt(15)
; DI float bf2f(bf16_t v) { return __uint_as_float(((unsigned)v) << 16); }
; DI bf16_t f2bf(float x) { return (bf16_t)(pk_bf16(x, 0.f) & 0xffffu); }
; DI int crow(int r, int h) { return (r & 3) + 8 * (r >> 2) + 4 * h; }
; DI void phase_merge(const Params& p, int g, char* smem, int bid, int nb) {
;     ...
; #pragma unroll
;     for (int mi = 0; mi < 2; ++mi)
; #pragma unroll
;       for (int ni = 0; ni < 2; ++ni)
;       {
;         bf16_t gb16[16];
; #pragma unroll
;         for (int r = 0; r < 16; ++r) gb16[r] = pt[(wm * 64 + mi * 32 + crow(r, h)) * NPROJ + nt * 128 + wn * 64 + ni * 32 + l31 + PGB];
; #pragma unroll
;         for (int r = 0; r < 16; ++r) {
;           const int rl = wm * 64 + mi * 32 + crow(r, h), cl = nt * 128 + wn * 64 + ni * 32 + l31;
;           mgt[rl * 1024 + cl] = f2bf(acc[mi][ni][r] * fmaxf(bf2f(gb16[r]), 1e-20f));
;         }
	v_lshlrev_b32_e32 v2, 16, v10
	v_max_f32_e32 v2, v2, v2
	v_max_f32_e32 v2, 0x1e3ce508, v2
	v_mul_f32_e32 v2, v63, v2
	v_add_u32_e32 v62, 0xec00, v65
	v_cvt_pk_bf16_f32 v4, v2, s0
	v_add_u32_e32 v2, v62, v64
	v_ashrrev_i32_e32 v3, 31, v2
	v_lshl_add_u64 v[2:3], v[2:3], 1, s[0:1]
	global_store_short v[2:3], v4, off
	v_add_u32_e32 v2, v1, v0
	v_ashrrev_i32_e32 v3, 31, v2
	v_lshl_add_u64 v[2:3], v[2:3], 1, s[6:7]
	v_add_co_u32_e32 v2, vcc, s75, v2
	v_add_u32_e32 v4, v67, v0
	s_nop 0
	v_addc_co_u32_e32 v3, vcc, 0, v3, vcc
	global_load_ushort v1, v[2:3], off
	v_ashrrev_i32_e32 v5, 31, v4
	v_lshl_add_u64 v[2:3], v[4:5], 1, s[6:7]
	v_add_co_u32_e32 v2, vcc, s75, v2
	v_add_u32_e32 v4, v68, v0
	s_nop 0
	v_addc_co_u32_e32 v3, vcc, 0, v3, vcc
	global_load_ushort v63, v[2:3], off
	v_ashrrev_i32_e32 v5, 31, v4
	v_lshl_add_u64 v[4:5], v[4:5], 1, s[6:7]
	v_add_u32_e32 v6, v69, v0
	v_ashrrev_i32_e32 v7, 31, v6
	v_add_co_u32_e32 v2, vcc, s75, v4
	v_lshl_add_u64 v[6:7], v[6:7], 1, s[6:7]
	s_nop 0
	v_addc_co_u32_e32 v3, vcc, 0, v5, vcc
	v_add_co_u32_e32 v4, vcc, s75, v6
	v_add_u32_e32 v8, v70, v0
	s_nop 0
	v_addc_co_u32_e32 v5, vcc, 0, v7, vcc
	global_load_ushort v64, v[2:3], off
	global_load_ushort v65, v[4:5], off
	v_ashrrev_i32_e32 v9, 31, v8
	v_lshl_add_u64 v[8:9], v[8:9], 1, s[6:7]
	v_add_u32_e32 v10, v72, v0
	v_ashrrev_i32_e32 v11, 31, v10
	v_add_co_u32_e32 v2, vcc, s75, v8
	v_lshl_add_u64 v[10:11], v[10:11], 1, s[6:7]
	v_add_u32_e32 v12, v73, v0
	v_addc_co_u32_e32 v3, vcc, 0, v9, vcc
	v_ashrrev_i32_e32 v13, 31, v12
	v_add_co_u32_e32 v4, vcc, s75, v10
	v_lshl_add_u64 v[12:13], v[12:13], 1, s[6:7]
	v_add_u32_e32 v14, v74, v0
	v_addc_co_u32_e32 v5, vcc, 0, v11, vcc
	v_ashrrev_i32_e32 v15, 31, v14
	v_add_co_u32_e32 v6, vcc, s75, v12
	v_lshl_add_u64 v[14:15], v[14:15], 1, s[6:7]
	s_nop 0
	v_addc_co_u32_e32 v7, vcc, 0, v13, vcc
	v_add_co_u32_e32 v8, vcc, s75, v14
	v_add_u32_e32 v46, v66, v0
	s_nop 0
	v_addc_co_u32_e32 v9, vcc, 0, v15, vcc
	global_load_ushort v66, v[2:3], off
	global_load_ushort v67, v[4:5], off
	global_load_ushort v68, v[6:7], off
	global_load_ushort v69, v[8:9], off
	v_add_u32_e32 v32, v75, v0
	v_ashrrev_i32_e32 v33, 31, v32
	v_lshl_add_u64 v[32:33], v[32:33], 1, s[6:7]
	v_add_u32_e32 v34, v76, v0
	v_ashrrev_i32_e32 v35, 31, v34
	v_add_co_u32_e32 v4, vcc, s75, v32
	v_lshl_add_u64 v[34:35], v[34:35], 1, s[6:7]
	v_add_u32_e32 v36, v77, v0
	v_addc_co_u32_e32 v5, vcc, 0, v33, vcc
	v_ashrrev_i32_e32 v37, 31, v36
	v_lshl_add_u64 v[36:37], v[36:37], 1, s[6:7]
	v_add_u32_e32 v38, v78, v0
	v_ashrrev_i32_e32 v39, 31, v38
	v_lshl_add_u64 v[38:39], v[38:39], 1, s[6:7]
	v_add_u32_e32 v40, v79, v0
	v_ashrrev_i32_e32 v41, 31, v40
	v_lshl_add_u64 v[40:41], v[40:41], 1, s[6:7]
	v_add_u32_e32 v42, v80, v0
	v_ashrrev_i32_e32 v43, 31, v42
	v_lshl_add_u64 v[42:43], v[42:43], 1, s[6:7]
	v_add_u32_e32 v44, v81, v0
	v_ashrrev_i32_e32 v45, 31, v44
	v_lshl_add_u64 v[44:45], v[44:45], 1, s[6:7]
	v_ashrrev_i32_e32 v47, 31, v46
	v_lshl_add_u64 v[46:47], v[46:47], 1, s[6:7]
	s_waitcnt vmcnt(7)
	v_lshlrev_b32_e32 v1, 16, v1
	v_max_f32_e32 v1, v1, v1
	v_max_f32_e32 v1, 0x1e3ce508, v1
	v_mul_f32_e32 v1, v16, v1
	global_load_ushort v16, v[4:5], off
	v_add_co_u32_e32 v4, vcc, s75, v34
	v_add_u32_e32 v2, v71, v0
	s_nop 0
	v_addc_co_u32_e32 v5, vcc, 0, v35, vcc
	v_add_co_u32_e32 v6, vcc, s75, v36
	v_ashrrev_i32_e32 v3, 31, v2
	s_nop 0
	v_addc_co_u32_e32 v7, vcc, 0, v37, vcc
	v_add_co_u32_e32 v8, vcc, s75, v38
	v_cvt_pk_bf16_f32 v1, v1, s0
	s_nop 0
	v_addc_co_u32_e32 v9, vcc, 0, v39, vcc
	v_add_co_u32_e32 v10, vcc, s75, v40
	v_lshl_add_u64 v[2:3], v[2:3], 1, s[0:1]
	s_nop 0
	v_addc_co_u32_e32 v11, vcc, 0, v41, vcc
	v_add_co_u32_e32 v12, vcc, s75, v42
	s_cmp_ge_i32 s13, s15
	s_nop 0
	v_addc_co_u32_e32 v13, vcc, 0, v43, vcc
	v_add_co_u32_e32 v14, vcc, s75, v44
	s_nop 1
	v_addc_co_u32_e32 v15, vcc, 0, v45, vcc
	v_add_co_u32_e32 v32, vcc, s75, v46
	s_nop 1
	v_addc_co_u32_e32 v33, vcc, 0, v47, vcc
	global_load_ushort v4, v[4:5], off
	s_nop 0
	global_load_ushort v5, v[6:7], off
	s_nop 0
	global_load_ushort v6, v[8:9], off
	global_load_ushort v7, v[10:11], off
	s_nop 0
	global_load_ushort v8, v[12:13], off
	global_load_ushort v9, v[14:15], off
	global_load_ushort v10, v[32:33], off
	s_nop 0
	global_store_short v[2:3], v1, off
	s_waitcnt vmcnt(15)
; DI float bf2f(bf16_t v) { return __uint_as_float(((unsigned)v) << 16); }
; DI bf16_t f2bf(float x) { return (bf16_t)(pk_bf16(x, 0.f) & 0xffffu); }
; DI int crow(int r, int h) { return (r & 3) + 8 * (r >> 2) + 4 * h; }
; DI void phase_merge(const Params& p, int g, char* smem, int bid, int nb) {
;     ...
; #pragma unroll
;     for (int mi = 0; mi < 2; ++mi)
; #pragma unroll
;       for (int ni = 0; ni < 2; ++ni)
;       {
;         bf16_t gb16[16];
; #pragma unroll
;         for (int r = 0; r < 16; ++r) gb16[r] = pt[(wm * 64 + mi * 32 + crow(r, h)) * NPROJ + nt * 128 + wn * 64 + ni * 32 + l31 + PGB];
; #pragma unroll
;         for (int r = 0; r < 16; ++r) {
;           const int rl = wm * 64 + mi * 32 + crow(r, h), cl = nt * 128 + wn * 64 + ni * 32 + l31;
;           mgt[rl * 1024 + cl] = f2bf(acc[mi][ni][r] * fmaxf(bf2f(gb16[r]), 1e-20f));
;         }
	v_lshlrev_b32_e32 v1, 16, v63
	v_max_f32_e32 v1, v1, v1
	v_max_f32_e32 v1, 0x1e3ce508, v1
	v_add_u32_e32 v2, v48, v0
	v_mul_f32_e32 v1, v17, v1
	v_ashrrev_i32_e32 v3, 31, v2
	v_cvt_pk_bf16_f32 v1, v1, s0
	v_lshl_add_u64 v[2:3], v[2:3], 1, s[0:1]
	global_store_short v[2:3], v1, off
	s_waitcnt vmcnt(15)
	v_lshlrev_b32_e32 v1, 16, v64
	v_max_f32_e32 v1, v1, v1
	v_max_f32_e32 v1, 0x1e3ce508, v1
	v_add_u32_e32 v2, v49, v0
	v_mul_f32_e32 v1, v18, v1
	v_ashrrev_i32_e32 v3, 31, v2
	v_cvt_pk_bf16_f32 v1, v1, s0
	v_lshl_add_u64 v[2:3], v[2:3], 1, s[0:1]
	global_store_short v[2:3], v1, off
	s_waitcnt vmcnt(15)
	v_lshlrev_b32_e32 v1, 16, v65
	v_max_f32_e32 v1, v1, v1
	v_max_f32_e32 v1, 0x1e3ce508, v1
	v_add_u32_e32 v2, v50, v0
	v_mul_f32_e32 v1, v19, v1
	v_ashrrev_i32_e32 v3, 31, v2
	v_cvt_pk_bf16_f32 v1, v1, s0
	v_lshl_add_u64 v[2:3], v[2:3], 1, s[0:1]
	global_store_short v[2:3], v1, off
	s_waitcnt vmcnt(15)
	v_lshlrev_b32_e32 v1, 16, v66
	v_max_f32_e32 v1, v1, v1
	v_max_f32_e32 v1, 0x1e3ce508, v1
	v_add_u32_e32 v2, v51, v0
	v_mul_f32_e32 v1, v20, v1
	v_ashrrev_i32_e32 v3, 31, v2
	v_cvt_pk_bf16_f32 v1, v1, s0
	v_lshl_add_u64 v[2:3], v[2:3], 1, s[0:1]
	global_store_short v[2:3], v1, off
	s_waitcnt vmcnt(15)
	v_lshlrev_b32_e32 v1, 16, v67
	v_max_f32_e32 v1, v1, v1
	v_max_f32_e32 v1, 0x1e3ce508, v1
	v_add_u32_e32 v2, v52, v0
	v_mul_f32_e32 v1, v21, v1
	v_ashrrev_i32_e32 v3, 31, v2
	v_cvt_pk_bf16_f32 v1, v1, s0
	v_lshl_add_u64 v[2:3], v[2:3], 1, s[0:1]
	global_store_short v[2:3], v1, off
	s_waitcnt vmcnt(15)
	v_lshlrev_b32_e32 v1, 16, v68
	v_max_f32_e32 v1, v1, v1
	v_max_f32_e32 v1, 0x1e3ce508, v1
	v_add_u32_e32 v2, v53, v0
	v_mul_f32_e32 v1, v22, v1
	v_ashrrev_i32_e32 v3, 31, v2
	v_cvt_pk_bf16_f32 v1, v1, s0
	v_lshl_add_u64 v[2:3], v[2:3], 1, s[0:1]
	global_store_short v[2:3], v1, off
	s_waitcnt vmcnt(15)
	v_lshlrev_b32_e32 v1, 16, v69
	v_max_f32_e32 v1, v1, v1
	v_max_f32_e32 v1, 0x1e3ce508, v1
	v_add_u32_e32 v2, v54, v0
	v_mul_f32_e32 v1, v23, v1
	v_ashrrev_i32_e32 v3, 31, v2
	v_cvt_pk_bf16_f32 v1, v1, s0
	v_lshl_add_u64 v[2:3], v[2:3], 1, s[0:1]
	global_store_short v[2:3], v1, off
	s_waitcnt vmcnt(15)
	v_lshlrev_b32_e32 v1, 16, v16
	v_max_f32_e32 v1, v1, v1
	v_max_f32_e32 v1, 0x1e3ce508, v1
	v_add_u32_e32 v2, v55, v0
	v_mul_f32_e32 v1, v24, v1
	v_ashrrev_i32_e32 v3, 31, v2
	v_cvt_pk_bf16_f32 v1, v1, s0
	v_lshl_add_u64 v[2:3], v[2:3], 1, s[0:1]
	global_store_short v[2:3], v1, off
	s_waitcnt vmcnt(15)
	v_lshlrev_b32_e32 v1, 16, v4
	v_max_f32_e32 v1, v1, v1
	v_max_f32_e32 v1, 0x1e3ce508, v1
	v_add_u32_e32 v2, v56, v0
	v_mul_f32_e32 v1, v25, v1
	v_ashrrev_i32_e32 v3, 31, v2
	v_cvt_pk_bf16_f32 v1, v1, s0
	v_lshl_add_u64 v[2:3], v[2:3], 1, s[0:1]
	global_store_short v[2:3], v1, off
	s_waitcnt vmcnt(15)
	v_lshlrev_b32_e32 v1, 16, v5
	v_max_f32_e32 v1, v1, v1
	v_max_f32_e32 v1, 0x1e3ce508, v1
	v_add_u32_e32 v2, v57, v0
	v_mul_f32_e32 v1, v26, v1
	v_ashrrev_i32_e32 v3, 31, v2
	v_cvt_pk_bf16_f32 v1, v1, s0
	v_lshl_add_u64 v[2:3], v[2:3], 1, s[0:1]
	global_store_short v[2:3], v1, off
	s_waitcnt vmcnt(15)
	v_lshlrev_b32_e32 v1, 16, v6
	v_max_f32_e32 v1, v1, v1
	v_max_f32_e32 v1, 0x1e3ce508, v1
	v_add_u32_e32 v2, v58, v0
	v_mul_f32_e32 v1, v27, v1
	v_ashrrev_i32_e32 v3, 31, v2
	v_cvt_pk_bf16_f32 v1, v1, s0
	v_lshl_add_u64 v[2:3], v[2:3], 1, s[0:1]
	global_store_short v[2:3], v1, off
	s_waitcnt vmcnt(15)
	v_lshlrev_b32_e32 v1, 16, v7
	v_max_f32_e32 v1, v1, v1
	v_max_f32_e32 v1, 0x1e3ce508, v1
	v_add_u32_e32 v2, v59, v0
	v_mul_f32_e32 v1, v28, v1
	v_ashrrev_i32_e32 v3, 31, v2
	v_cvt_pk_bf16_f32 v1, v1, s0
	v_lshl_add_u64 v[2:3], v[2:3], 1, s[0:1]
	global_store_short v[2:3], v1, off
	s_waitcnt vmcnt(15)
	v_lshlrev_b32_e32 v1, 16, v8
	v_max_f32_e32 v1, v1, v1
	v_max_f32_e32 v1, 0x1e3ce508, v1
	v_add_u32_e32 v2, v60, v0
	v_mul_f32_e32 v1, v29, v1
	v_ashrrev_i32_e32 v3, 31, v2
	v_cvt_pk_bf16_f32 v1, v1, s0
	v_lshl_add_u64 v[2:3], v[2:3], 1, s[0:1]
	global_store_short v[2:3], v1, off
	s_waitcnt vmcnt(15)
	v_lshlrev_b32_e32 v1, 16, v9
	v_max_f32_e32 v1, v1, v1
	v_max_f32_e32 v1, 0x1e3ce508, v1
	v_add_u32_e32 v2, v61, v0
	v_mul_f32_e32 v1, v30, v1
	v_ashrrev_i32_e32 v3, 31, v2
	v_cvt_pk_bf16_f32 v1, v1, s0
	v_lshl_add_u64 v[2:3], v[2:3], 1, s[0:1]
	global_store_short v[2:3], v1, off
	s_waitcnt vmcnt(15)
	v_lshlrev_b32_e32 v1, 16, v10
	v_max_f32_e32 v1, v1, v1
	v_max_f32_e32 v1, 0x1e3ce508, v1
	v_mul_f32_e32 v1, v31, v1
	v_add_u32_e32 v0, v62, v0
	v_cvt_pk_bf16_f32 v2, v1, s0
	v_ashrrev_i32_e32 v1, 31, v0
	v_lshl_add_u64 v[0:1], v[0:1], 1, s[0:1]
	global_store_short v[0:1], v2, off
	s_cbranch_scc1 .LBB0_227

; template <bool SWAP>
; DI void gemm_tile(const bf16_t* __restrict__ A, int lda, const bf16_t* __restrict__ Bt, int ldb, int K, f32x16 (&acc)[2][2], bf16_t* As, bf16_t* Bs_unused) {
;     ...
;   const int tid = TID(), lane = tid & 63, wave = tid >> 6, wm = wave >> 1, wn = wave & 1;
;   const int lr = tid >> 3, lc = (tid & 7) * 8;
;   const bf16_t* ga = A + (size_t)lr * lda + lc;
;   const bf16_t* gb = Bt + (size_t)lr * ldb + lc;
;   u32x4 ra0[4], rb0[4], ra1[4], rb1[4];
;   auto load_stage = [&](u32x4 (&ra)[4], u32x4 (&rb)[4], int t) __attribute__((always_inline)) {
; #pragma unroll
;     for (int i = 0; i < 4; ++i) { ra[i] = *(const u32x4*)(ga + (size_t)(32 * i) * lda + t * 64); rb[i] = *(const u32x4*)(gb + (size_t)(32 * i) * ldb + t * 64); }
;   };
;   auto write_stage = [&](const u32x4 (&ra)[4], const u32x4 (&rb)[4], int buf) __attribute__((always_inline)) {
;     bf16_t* Ad = As + buf * 2 * GT_IMG; bf16_t* Bd = Ad + GT_IMG;
; #pragma unroll
;     for (int i = 0; i < 4; ++i) { *(u32x4*)(Ad + (lr + 32 * i) * 72 + lc) = ra[i]; *(u32x4*)(Bd + (lr + 32 * i) * 72 + lc) = rb[i]; }
;   };
;   const int fr = lane & 31, fk = (lane >> 5) * 8;
;   const int pao = (wm * 64 + fr) * 72 + fk, pbo = GT_IMG + (wn * 64 + fr) * 72 + fk;
;   auto frag_read = [&](bf16x8 (&f)[4], const bf16_t* pa, const bf16_t* pb, int so) __attribute__((always_inline)) {
;     f[0] = *(const bf16x8*)(pa + so); f[1] = *(const bf16x8*)(pb + so); f[2] = *(const bf16x8*)(pb + 32 * 72 + so); f[3] = *(const bf16x8*)(pa + 32 * 72 + so);
;   };
;   auto mfma4 = [&](const bf16x8 (&f)[4]) __attribute__((always_inline)) {
;     if (SWAP) {
;       acc[0][0] = MFMA32(f[1], f[0], acc[0][0]); acc[0][1] = MFMA32(f[2], f[0], acc[0][1]);
;       acc[1][0] = MFMA32(f[1], f[3], acc[1][0]); acc[1][1] = MFMA32(f[2], f[3], acc[1][1]);
;     } else {
;       acc[0][0] = MFMA32(f[0], f[1], acc[0][0]); acc[0][1] = MFMA32(f[0], f[2], acc[0][1]);
;       acc[1][0] = MFMA32(f[3], f[1], acc[1][0]); acc[1][1] = MFMA32(f[3], f[2], acc[1][1]);
;     }
;   };
;   auto step = [&](int buf, u32x4 (&ra)[4], u32x4 (&rb)[4], bool do_write, bool do_load, int tload) __attribute__((always_inline)) {
;     const bf16_t* pa = As + buf * 2 * GT_IMG + pao; const bf16_t* pb = As + buf * 2 * GT_IMG + pbo;
;     bf16_t* Ad = As + (buf ^ 1) * 2 * GT_IMG; bf16_t* Bd = Ad + GT_IMG;
;     bf16x8 F0[4], F1[4];
;     frag_read(F0, pa, pb, 0);
.LBB0_367:
	s_andn2_b64 vcc, exec, s[14:15]
	s_cbranch_vccnz .LBB0_369
	v_mov_b32_e32 v34, v195
	s_nop 0
	v_ashrrev_i32_e32 v32, 3, v34
	v_ashrrev_i32_e32 v33, 31, v32
	v_lshlrev_b64 v[0:1], 11, v[32:33]
	s_waitcnt lgkmcnt(0)
	v_lshlrev_b32_e32 v4, 4, v34
	v_lshl_add_u64 v[2:3], s[0:1], 0, v[0:1]
	v_and_b32_e32 v192, 0x70, v4
	v_lshl_add_u64 v[84:85], v[2:3], 0, v[192:193]
	v_lshl_add_u64 v[0:1], s[6:7], 0, v[0:1]
	v_add_co_u32_e32 v88, vcc, 0x10000, v84
	v_lshl_add_u64 v[86:87], v[0:1], 0, v[192:193]
	s_nop 0
	v_addc_co_u32_e32 v89, vcc, 0, v85, vcc
	v_add_co_u32_e32 v90, vcc, 0x10000, v86
	global_load_dwordx4 v[0:3], v[84:85], off
	global_load_dwordx4 v[4:7], v[86:87], off
	v_addc_co_u32_e32 v91, vcc, 0, v87, vcc
	v_add_co_u32_e32 v92, vcc, 0x20000, v84
	global_load_dwordx4 v[8:11], v[88:89], off
	global_load_dwordx4 v[12:15], v[90:91], off
	v_addc_co_u32_e32 v93, vcc, 0, v85, vcc
	v_add_co_u32_e32 v94, vcc, 0x20000, v86
	global_load_dwordx4 v[16:19], v[92:93], off
	s_nop 0
	v_addc_co_u32_e32 v95, vcc, 0, v87, vcc
	v_add_co_u32_e32 v96, vcc, 0x30000, v84
	global_load_dwordx4 v[20:23], v[94:95], off
	s_nop 0
	v_addc_co_u32_e32 v97, vcc, 0, v85, vcc
	global_load_dwordx4 v[24:27], v[96:97], off
	v_add_co_u32_e32 v98, vcc, 0x30000, v86
	v_mul_lo_u32 v32, v32, s71
	s_nop 0
	v_addc_co_u32_e32 v99, vcc, 0, v87, vcc
	global_load_dwordx4 v[28:31], v[98:99], off
	global_load_dwordx4 v[104:107], v[84:85], off offset:128
	global_load_dwordx4 v[80:83], v[86:87], off offset:128
	global_load_dwordx4 v[108:111], v[88:89], off offset:128
	global_load_dwordx4 v[112:115], v[90:91], off offset:128
	global_load_dwordx4 v[116:119], v[92:93], off offset:128
	global_load_dwordx4 v[124:127], v[94:95], off offset:128
	global_load_dwordx4 v[128:131], v[96:97], off offset:128
	global_load_dwordx4 v[132:135], v[98:99], off offset:128
	v_add3_u32 v100, 32, v32, v192
	s_waitcnt lgkmcnt(0)
	s_barrier
	v_add_u32_e32 v103, 0xd800, v100
	s_waitcnt vmcnt(15)
	ds_write_b128 v100, v[0:3]
	s_waitcnt vmcnt(14)
	ds_write_b128 v100, v[4:7] offset:18432
	s_waitcnt vmcnt(13)
	ds_write_b128 v100, v[8:11] offset:4608
	s_waitcnt vmcnt(12)
	ds_write_b128 v100, v[12:15] offset:23040
	s_waitcnt vmcnt(11)
	ds_write_b128 v100, v[16:19] offset:9216
	s_waitcnt vmcnt(10)
	ds_write_b128 v100, v[20:23] offset:27648
	s_waitcnt vmcnt(9)
	ds_write_b128 v100, v[24:27] offset:13824
	s_waitcnt vmcnt(8)
	ds_write_b128 v100, v[28:31] offset:32256
	global_load_dwordx4 v[136:139], v[84:85], off offset:256
	global_load_dwordx4 v[64:67], v[86:87], off offset:256
	global_load_dwordx4 v[140:143], v[88:89], off offset:256
	global_load_dwordx4 v[68:71], v[90:91], off offset:256
	global_load_dwordx4 v[144:147], v[92:93], off offset:256
	global_load_dwordx4 v[72:75], v[94:95], off offset:256
	global_load_dwordx4 v[148:151], v[96:97], off offset:256
	global_load_dwordx4 v[76:79], v[98:99], off offset:256
	v_lshrrev_b32_e32 v0, 2, v34
	v_lshrrev_b32_e32 v2, 1, v34
	v_and_b32_e32 v3, 31, v34
	v_and_b32_e32 v1, 0x5f, v34
	v_and_b32_e32 v0, 8, v0
	v_and_or_b32 v2, v2, s80, v3
	v_mad_u64_u32 v[2:3], s[8:9], v2, s72, v[0:1]
	v_lshl_add_u32 v101, v2, 1, 32
	v_mad_u32_u24 v0, v1, s72, v0
	s_waitcnt lgkmcnt(0)
	s_barrier
	v_lshl_add_u32 v102, v0, 1, 32
	ds_read_b128 v[0:3], v101
	ds_read_b128 v[4:7], v102 offset:18432
	ds_read_b128 v[16:19], v102 offset:23040
	ds_read_b128 v[20:23], v101 offset:4608
	s_waitcnt lgkmcnt(2)
	v_mfma_f32_32x32x16_bf16 v[48:63], v[0:3], v[4:7], 0
	ds_read_b128 v[152:155], v102 offset:18464
	ds_read_b128 v[156:159], v102 offset:23072
	ds_read_b128 v[160:163], v101 offset:32
	ds_read_b128 v[164:167], v101 offset:4640
	s_waitcnt lgkmcnt(5)
	v_mfma_f32_32x32x16_bf16 v[32:47], v[0:3], v[16:19], 0
	s_waitcnt lgkmcnt(4)
	v_mfma_f32_32x32x16_bf16 v[0:15], v[20:23], v[4:7], 0
	v_mfma_f32_32x32x16_bf16 v[16:31], v[20:23], v[16:19], 0
	s_waitcnt lgkmcnt(1)
	v_mfma_f32_32x32x16_bf16 v[48:63], v[160:163], v[152:155], v[48:63]
	v_mfma_f32_32x32x16_bf16 v[32:47], v[160:163], v[156:159], v[32:47]
	s_waitcnt lgkmcnt(0)
	v_mfma_f32_32x32x16_bf16 v[0:15], v[164:167], v[152:155], v[0:15]
	ds_read_b128 v[152:155], v102 offset:18496
	ds_read_b128 v[160:163], v102 offset:23104
	ds_read_b128 v[168:171], v101 offset:64
	ds_read_b128 v[172:175], v101 offset:4672
	s_waitcnt vmcnt(15)
	ds_write_b128 v100, v[104:107] offset:36864
	s_waitcnt vmcnt(13)
	ds_write_b128 v100, v[108:111] offset:41472
	s_waitcnt vmcnt(11)
	ds_write_b128 v100, v[116:119] offset:46080
	s_waitcnt vmcnt(9)
	ds_write_b128 v100, v[128:131] offset:50688
	v_mfma_f32_32x32x16_bf16 v[16:31], v[164:167], v[156:159], v[16:31]
	s_waitcnt lgkmcnt(5)
	v_mfma_f32_32x32x16_bf16 v[48:63], v[168:171], v[152:155], v[48:63]
	ds_read_b128 v[104:107], v102 offset:18528
	ds_read_b128 v[108:111], v102 offset:23136
	ds_read_b128 v[116:119], v101 offset:96
	ds_read_b128 v[128:131], v101 offset:4704
	ds_write_b128 v100, v[80:83] offset:55296
	ds_write_b128 v100, v[112:115] offset:59904
	ds_write_b128 v100, v[124:127] offset:64512
	s_waitcnt vmcnt(8)
	ds_write_b128 v103, v[132:135] offset:13824
	v_mfma_f32_32x32x16_bf16 v[32:47], v[168:171], v[160:163], v[32:47]
	s_waitcnt lgkmcnt(12)
	v_mfma_f32_32x32x16_bf16 v[0:15], v[172:175], v[152:155], v[0:15]
	v_mfma_f32_32x32x16_bf16 v[16:31], v[172:175], v[160:163], v[16:31]
	s_waitcnt lgkmcnt(0)
	s_barrier
; template <bool SWAP>
; DI void gemm_tile(const bf16_t* __restrict__ A, int lda, const bf16_t* __restrict__ Bt, int ldb, int K, f32x16 (&acc)[2][2], bf16_t* As, bf16_t* Bs_unused) {
;     ...
;   auto step = [&](int buf, u32x4 (&ra)[4], u32x4 (&rb)[4], bool do_write, bool do_load, int tload) __attribute__((always_inline)) {
;     const bf16_t* pa = As + buf * 2 * GT_IMG + pao; const bf16_t* pb = As + buf * 2 * GT_IMG + pbo;
;     bf16_t* Ad = As + (buf ^ 1) * 2 * GT_IMG; bf16_t* Bd = Ad + GT_IMG;
;     bf16x8 F0[4], F1[4];
;     frag_read(F0, pa, pb, 0);
;     __builtin_amdgcn_sched_barrier(0);
;     frag_read(F1, pa, pb, 16);
;     mfma4(F0);
;     __builtin_amdgcn_sched_barrier(0);
;     frag_read(F0, pa, pb, 32);
;     mfma4(F1);
;     if (do_write) {
; #pragma unroll
;       for (int i = 0; i < 4; ++i) *(u32x4*)(Ad + (lr + 32 * i) * 72 + lc) = ra[i];
;     }
;     __builtin_amdgcn_sched_barrier(0);
;     frag_read(F1, pa, pb, 48);
;     mfma4(F0);
;     if (do_write) {
; #pragma unroll
;       for (int i = 0; i < 4; ++i) *(u32x4*)(Bd + (lr + 32 * i) * 72 + lc) = rb[i];
;     }
;     __builtin_amdgcn_sched_barrier(0);
;     mfma4(F1);
;     if (do_load) load_stage(ra, rb, tload);
;     __builtin_amdgcn_sched_barrier(0);
;   };
;   const int nk = K >> 6;
;   load_stage(ra0, rb0, 0); load_stage(ra1, rb1, 1);
;   __syncthreads();
;   write_stage(ra0, rb0, 0);
;   load_stage(ra0, rb0, 2);
;   __syncthreads();
;   for (int kt = 0; kt < nk; kt += 2) {
;     step(0, ra1, rb1, true, kt + 3 < nk, kt + 3);
;     __syncthreads();
;     step(1, ra0, rb0, kt + 2 < nk, kt + 4 < nk, kt + 4);
;     __syncthreads();
	ds_read_b128 v[152:155], v102 offset:55296
	ds_read_b128 v[156:159], v102 offset:59904
	ds_read_b128 v[160:163], v101 offset:36864
	ds_read_b128 v[164:167], v101 offset:41472
	v_mfma_f32_32x32x16_bf16 v[48:63], v[116:119], v[104:107], v[48:63]
	v_mfma_f32_32x32x16_bf16 v[32:47], v[116:119], v[108:111], v[32:47]
	v_mfma_f32_32x32x16_bf16 v[0:15], v[128:131], v[104:107], v[0:15]
	v_mfma_f32_32x32x16_bf16 v[16:31], v[128:131], v[108:111], v[16:31]
	global_load_dwordx4 v[80:83], v[84:85], off offset:384
	global_load_dwordx4 v[104:107], v[86:87], off offset:384
	global_load_dwordx4 v[108:111], v[88:89], off offset:384
	global_load_dwordx4 v[112:115], v[90:91], off offset:384
	global_load_dwordx4 v[116:119], v[92:93], off offset:384
	global_load_dwordx4 v[124:127], v[94:95], off offset:384
	global_load_dwordx4 v[128:131], v[96:97], off offset:384
	global_load_dwordx4 v[132:135], v[98:99], off offset:384
	s_waitcnt lgkmcnt(1)
	v_mfma_f32_32x32x16_bf16 v[48:63], v[160:163], v[152:155], v[48:63]
	v_mfma_f32_32x32x16_bf16 v[32:47], v[160:163], v[156:159], v[32:47]
	s_waitcnt lgkmcnt(0)
	v_mfma_f32_32x32x16_bf16 v[0:15], v[164:167], v[152:155], v[0:15]
	ds_read_b128 v[152:155], v102 offset:55328
	ds_read_b128 v[160:163], v102 offset:59936
	ds_read_b128 v[168:171], v101 offset:36896
	ds_read_b128 v[172:175], v101 offset:41504
	v_mfma_f32_32x32x16_bf16 v[16:31], v[164:167], v[156:159], v[16:31]
	s_waitcnt lgkmcnt(1)
	v_mfma_f32_32x32x16_bf16 v[48:63], v[168:171], v[152:155], v[48:63]
	v_mfma_f32_32x32x16_bf16 v[32:47], v[168:171], v[160:163], v[32:47]
	s_waitcnt lgkmcnt(0)
	v_mfma_f32_32x32x16_bf16 v[0:15], v[172:175], v[152:155], v[0:15]
	ds_read_b128 v[152:155], v102 offset:55360
	ds_read_b128 v[156:159], v102 offset:59968
	ds_read_b128 v[164:167], v101 offset:36928
	ds_read_b128 v[168:171], v101 offset:41536
	s_waitcnt vmcnt(15)
	ds_write_b128 v100, v[136:139]
	s_waitcnt vmcnt(13)
	ds_write_b128 v100, v[140:143] offset:4608
	s_waitcnt vmcnt(11)
	ds_write_b128 v100, v[144:147] offset:9216
	s_waitcnt vmcnt(9)
	ds_write_b128 v100, v[148:151] offset:13824
	v_mfma_f32_32x32x16_bf16 v[16:31], v[172:175], v[160:163], v[16:31]
	s_waitcnt lgkmcnt(5)
	v_mfma_f32_32x32x16_bf16 v[48:63], v[164:167], v[152:155], v[48:63]
	ds_read_b128 v[136:139], v102 offset:55392
	ds_read_b128 v[140:143], v102 offset:60000
	ds_read_b128 v[144:147], v101 offset:36960
	ds_read_b128 v[148:151], v101 offset:41568
	ds_write_b128 v100, v[64:67] offset:18432
	ds_write_b128 v100, v[68:71] offset:23040
	ds_write_b128 v100, v[72:75] offset:27648
	s_waitcnt vmcnt(8)
	ds_write_b128 v100, v[76:79] offset:32256
	v_mfma_f32_32x32x16_bf16 v[32:47], v[164:167], v[156:159], v[32:47]
	s_waitcnt lgkmcnt(12)
	v_mfma_f32_32x32x16_bf16 v[0:15], v[168:171], v[152:155], v[0:15]
	v_mfma_f32_32x32x16_bf16 v[16:31], v[168:171], v[156:159], v[16:31]
	s_waitcnt lgkmcnt(0)
	s_barrier
	ds_read_b128 v[152:155], v102 offset:18432
	ds_read_b128 v[156:159], v102 offset:23040
	ds_read_b128 v[160:163], v101
	ds_read_b128 v[164:167], v101 offset:4608
	v_mfma_f32_32x32x16_bf16 v[48:63], v[144:147], v[136:139], v[48:63]
	v_mfma_f32_32x32x16_bf16 v[32:47], v[144:147], v[140:143], v[32:47]
	v_mfma_f32_32x32x16_bf16 v[0:15], v[148:151], v[136:139], v[0:15]
	v_mfma_f32_32x32x16_bf16 v[16:31], v[148:151], v[140:143], v[16:31]
	global_load_dwordx4 v[64:67], v[84:85], off offset:512
	global_load_dwordx4 v[68:71], v[86:87], off offset:512
	global_load_dwordx4 v[72:75], v[88:89], off offset:512
	global_load_dwordx4 v[76:79], v[90:91], off offset:512
	global_load_dwordx4 v[136:139], v[92:93], off offset:512
	global_load_dwordx4 v[140:143], v[94:95], off offset:512
	global_load_dwordx4 v[144:147], v[96:97], off offset:512
	global_load_dwordx4 v[148:151], v[98:99], off offset:512
	s_waitcnt lgkmcnt(1)
	v_mfma_f32_32x32x16_bf16 v[48:63], v[160:163], v[152:155], v[48:63]
	v_mfma_f32_32x32x16_bf16 v[32:47], v[160:163], v[156:159], v[32:47]
	s_waitcnt lgkmcnt(0)
	v_mfma_f32_32x32x16_bf16 v[0:15], v[164:167], v[152:155], v[0:15]
	ds_read_b128 v[152:155], v102 offset:18464
	ds_read_b128 v[160:163], v102 offset:23072
	ds_read_b128 v[168:171], v101 offset:32
	ds_read_b128 v[172:175], v101 offset:4640
	v_mfma_f32_32x32x16_bf16 v[16:31], v[164:167], v[156:159], v[16:31]
	s_waitcnt lgkmcnt(1)
	v_mfma_f32_32x32x16_bf16 v[48:63], v[168:171], v[152:155], v[48:63]
	v_mfma_f32_32x32x16_bf16 v[32:47], v[168:171], v[160:163], v[32:47]
	s_waitcnt lgkmcnt(0)
	v_mfma_f32_32x32x16_bf16 v[0:15], v[172:175], v[152:155], v[0:15]
	ds_read_b128 v[152:155], v102 offset:18496
	ds_read_b128 v[156:159], v102 offset:23104
	ds_read_b128 v[164:167], v101 offset:64
	ds_read_b128 v[168:171], v101 offset:4672
	s_waitcnt vmcnt(15)
	ds_write_b128 v100, v[80:83] offset:36864
	s_waitcnt vmcnt(13)
	ds_write_b128 v100, v[108:111] offset:41472
	s_waitcnt vmcnt(11)
	ds_write_b128 v100, v[116:119] offset:46080
	s_waitcnt vmcnt(9)
	ds_write_b128 v100, v[128:131] offset:50688
	v_mfma_f32_32x32x16_bf16 v[16:31], v[172:175], v[160:163], v[16:31]
	s_waitcnt lgkmcnt(5)
	v_mfma_f32_32x32x16_bf16 v[48:63], v[164:167], v[152:155], v[48:63]
	ds_read_b128 v[80:83], v102 offset:18528
	ds_read_b128 v[108:111], v102 offset:23136
	ds_read_b128 v[116:119], v101 offset:96
	ds_read_b128 v[128:131], v101 offset:4704
	ds_write_b128 v100, v[104:107] offset:55296
	ds_write_b128 v100, v[112:115] offset:59904
	ds_write_b128 v100, v[124:127] offset:64512
	s_waitcnt vmcnt(8)
	ds_write_b128 v103, v[132:135] offset:13824
	v_mfma_f32_32x32x16_bf16 v[32:47], v[164:167], v[156:159], v[32:47]
	s_waitcnt lgkmcnt(12)
	v_mfma_f32_32x32x16_bf16 v[0:15], v[168:171], v[152:155], v[0:15]
	v_mfma_f32_32x32x16_bf16 v[16:31], v[168:171], v[156:159], v[16:31]
	s_waitcnt lgkmcnt(0)
	s_barrier
; template <bool SWAP>
; DI void gemm_tile(const bf16_t* __restrict__ A, int lda, const bf16_t* __restrict__ Bt, int ldb, int K, f32x16 (&acc)[2][2], bf16_t* As, bf16_t* Bs_unused) {
;     ...
;   auto step = [&](int buf, u32x4 (&ra)[4], u32x4 (&rb)[4], bool do_write, bool do_load, int tload) __attribute__((always_inline)) {
;     const bf16_t* pa = As + buf * 2 * GT_IMG + pao; const bf16_t* pb = As + buf * 2 * GT_IMG + pbo;
;     bf16_t* Ad = As + (buf ^ 1) * 2 * GT_IMG; bf16_t* Bd = Ad + GT_IMG;
;     bf16x8 F0[4], F1[4];
;     frag_read(F0, pa, pb, 0);
;     __builtin_amdgcn_sched_barrier(0);
;     frag_read(F1, pa, pb, 16);
;     mfma4(F0);
;     __builtin_amdgcn_sched_barrier(0);
;     frag_read(F0, pa, pb, 32);
;     mfma4(F1);
;     if (do_write) {
; #pragma unroll
;       for (int i = 0; i < 4; ++i) *(u32x4*)(Ad + (lr + 32 * i) * 72 + lc) = ra[i];
;     }
;     __builtin_amdgcn_sched_barrier(0);
;     frag_read(F1, pa, pb, 48);
;     mfma4(F0);
;     if (do_write) {
; #pragma unroll
;       for (int i = 0; i < 4; ++i) *(u32x4*)(Bd + (lr + 32 * i) * 72 + lc) = rb[i];
;     }
;     __builtin_amdgcn_sched_barrier(0);
;     mfma4(F1);
;     if (do_load) load_stage(ra, rb, tload);
;     __builtin_amdgcn_sched_barrier(0);
;   };
;   const int nk = K >> 6;
;   load_stage(ra0, rb0, 0); load_stage(ra1, rb1, 1);
;   __syncthreads();
;   write_stage(ra0, rb0, 0);
;   load_stage(ra0, rb0, 2);
;   __syncthreads();
;   for (int kt = 0; kt < nk; kt += 2) {
;     step(0, ra1, rb1, true, kt + 3 < nk, kt + 3);
;     __syncthreads();
;     step(1, ra0, rb0, kt + 2 < nk, kt + 4 < nk, kt + 4);
;     __syncthreads();
	ds_read_b128 v[152:155], v102 offset:55296
	ds_read_b128 v[156:159], v102 offset:59904
	ds_read_b128 v[160:163], v101 offset:36864
	ds_read_b128 v[164:167], v101 offset:41472
	v_mfma_f32_32x32x16_bf16 v[48:63], v[116:119], v[80:83], v[48:63]
	v_mfma_f32_32x32x16_bf16 v[32:47], v[116:119], v[108:111], v[32:47]
	v_mfma_f32_32x32x16_bf16 v[0:15], v[128:131], v[80:83], v[0:15]
	v_mfma_f32_32x32x16_bf16 v[16:31], v[128:131], v[108:111], v[16:31]
	global_load_dwordx4 v[80:83], v[84:85], off offset:640
	global_load_dwordx4 v[104:107], v[86:87], off offset:640
	global_load_dwordx4 v[108:111], v[88:89], off offset:640
	global_load_dwordx4 v[112:115], v[90:91], off offset:640
	global_load_dwordx4 v[116:119], v[92:93], off offset:640
	global_load_dwordx4 v[124:127], v[94:95], off offset:640
	global_load_dwordx4 v[128:131], v[96:97], off offset:640
	global_load_dwordx4 v[132:135], v[98:99], off offset:640
	s_waitcnt lgkmcnt(1)
	v_mfma_f32_32x32x16_bf16 v[48:63], v[160:163], v[152:155], v[48:63]
	v_mfma_f32_32x32x16_bf16 v[32:47], v[160:163], v[156:159], v[32:47]
	s_waitcnt lgkmcnt(0)
	v_mfma_f32_32x32x16_bf16 v[0:15], v[164:167], v[152:155], v[0:15]
	ds_read_b128 v[152:155], v102 offset:55328
	ds_read_b128 v[160:163], v102 offset:59936
	ds_read_b128 v[168:171], v101 offset:36896
	ds_read_b128 v[172:175], v101 offset:41504
	v_mfma_f32_32x32x16_bf16 v[16:31], v[164:167], v[156:159], v[16:31]
	s_waitcnt lgkmcnt(1)
	v_mfma_f32_32x32x16_bf16 v[48:63], v[168:171], v[152:155], v[48:63]
	v_mfma_f32_32x32x16_bf16 v[32:47], v[168:171], v[160:163], v[32:47]
	s_waitcnt lgkmcnt(0)
	v_mfma_f32_32x32x16_bf16 v[0:15], v[172:175], v[152:155], v[0:15]
	ds_read_b128 v[152:155], v102 offset:55360
	ds_read_b128 v[156:159], v102 offset:59968
	ds_read_b128 v[164:167], v101 offset:36928
	ds_read_b128 v[168:171], v101 offset:41536
	s_waitcnt vmcnt(15)
	ds_write_b128 v100, v[64:67]
	s_waitcnt vmcnt(13)
	ds_write_b128 v100, v[72:75] offset:4608
	s_waitcnt vmcnt(11)
	ds_write_b128 v100, v[136:139] offset:9216
	s_waitcnt vmcnt(9)
	ds_write_b128 v100, v[144:147] offset:13824
	v_mfma_f32_32x32x16_bf16 v[16:31], v[172:175], v[160:163], v[16:31]
	s_waitcnt lgkmcnt(5)
	v_mfma_f32_32x32x16_bf16 v[48:63], v[164:167], v[152:155], v[48:63]
	ds_read_b128 v[64:67], v102 offset:55392
	ds_read_b128 v[72:75], v102 offset:60000
	ds_read_b128 v[136:139], v101 offset:36960
	ds_read_b128 v[144:147], v101 offset:41568
	ds_write_b128 v100, v[68:71] offset:18432
	ds_write_b128 v100, v[76:79] offset:23040
	ds_write_b128 v100, v[140:143] offset:27648
	s_waitcnt vmcnt(8)
	ds_write_b128 v100, v[148:151] offset:32256
	v_mfma_f32_32x32x16_bf16 v[32:47], v[164:167], v[156:159], v[32:47]
	s_waitcnt lgkmcnt(12)
	v_mfma_f32_32x32x16_bf16 v[0:15], v[168:171], v[152:155], v[0:15]
	v_mfma_f32_32x32x16_bf16 v[16:31], v[168:171], v[156:159], v[16:31]
	s_waitcnt lgkmcnt(0)
	s_barrier
	ds_read_b128 v[152:155], v102 offset:18432
	ds_read_b128 v[156:159], v102 offset:23040
	ds_read_b128 v[160:163], v101
	ds_read_b128 v[164:167], v101 offset:4608
	v_mfma_f32_32x32x16_bf16 v[48:63], v[136:139], v[64:67], v[48:63]
	v_mfma_f32_32x32x16_bf16 v[32:47], v[136:139], v[72:75], v[32:47]
	v_mfma_f32_32x32x16_bf16 v[0:15], v[144:147], v[64:67], v[0:15]
	v_mfma_f32_32x32x16_bf16 v[16:31], v[144:147], v[72:75], v[16:31]
	global_load_dwordx4 v[64:67], v[84:85], off offset:768
	global_load_dwordx4 v[68:71], v[86:87], off offset:768
	global_load_dwordx4 v[72:75], v[88:89], off offset:768
	global_load_dwordx4 v[76:79], v[90:91], off offset:768
	global_load_dwordx4 v[136:139], v[92:93], off offset:768
	global_load_dwordx4 v[140:143], v[94:95], off offset:768
	global_load_dwordx4 v[144:147], v[96:97], off offset:768
	global_load_dwordx4 v[148:151], v[98:99], off offset:768
	s_waitcnt lgkmcnt(1)
	v_mfma_f32_32x32x16_bf16 v[48:63], v[160:163], v[152:155], v[48:63]
	v_mfma_f32_32x32x16_bf16 v[32:47], v[160:163], v[156:159], v[32:47]
	s_waitcnt lgkmcnt(0)
	v_mfma_f32_32x32x16_bf16 v[0:15], v[164:167], v[152:155], v[0:15]
	ds_read_b128 v[152:155], v102 offset:18464
	ds_read_b128 v[160:163], v102 offset:23072
	ds_read_b128 v[168:171], v101 offset:32
	ds_read_b128 v[172:175], v101 offset:4640
	v_mfma_f32_32x32x16_bf16 v[16:31], v[164:167], v[156:159], v[16:31]
	s_waitcnt lgkmcnt(1)
	v_mfma_f32_32x32x16_bf16 v[48:63], v[168:171], v[152:155], v[48:63]
	v_mfma_f32_32x32x16_bf16 v[32:47], v[168:171], v[160:163], v[32:47]
	s_waitcnt lgkmcnt(0)
	v_mfma_f32_32x32x16_bf16 v[0:15], v[172:175], v[152:155], v[0:15]
	ds_read_b128 v[152:155], v102 offset:18496
	ds_read_b128 v[156:159], v102 offset:23104
	ds_read_b128 v[164:167], v101 offset:64
	ds_read_b128 v[168:171], v101 offset:4672
	s_waitcnt vmcnt(15)
	ds_write_b128 v100, v[80:83] offset:36864
	s_waitcnt vmcnt(13)
	ds_write_b128 v100, v[108:111] offset:41472
	s_waitcnt vmcnt(11)
	ds_write_b128 v100, v[116:119] offset:46080
	s_waitcnt vmcnt(9)
	ds_write_b128 v100, v[128:131] offset:50688
	v_mfma_f32_32x32x16_bf16 v[16:31], v[172:175], v[160:163], v[16:31]
	s_waitcnt lgkmcnt(5)
	v_mfma_f32_32x32x16_bf16 v[48:63], v[164:167], v[152:155], v[48:63]
	ds_read_b128 v[80:83], v102 offset:18528
	ds_read_b128 v[108:111], v102 offset:23136
	ds_read_b128 v[116:119], v101 offset:96
	ds_read_b128 v[128:131], v101 offset:4704
	ds_write_b128 v100, v[104:107] offset:55296
	ds_write_b128 v100, v[112:115] offset:59904
	ds_write_b128 v100, v[124:127] offset:64512
	s_waitcnt vmcnt(8)
	ds_write_b128 v103, v[132:135] offset:13824
	v_mfma_f32_32x32x16_bf16 v[32:47], v[164:167], v[156:159], v[32:47]
	s_waitcnt lgkmcnt(12)
	v_mfma_f32_32x32x16_bf16 v[0:15], v[168:171], v[152:155], v[0:15]
	v_mfma_f32_32x32x16_bf16 v[16:31], v[168:171], v[156:159], v[16:31]
	s_waitcnt lgkmcnt(0)
	s_barrier
; template <bool SWAP>
; DI void gemm_tile(const bf16_t* __restrict__ A, int lda, const bf16_t* __restrict__ Bt, int ldb, int K, f32x16 (&acc)[2][2], bf16_t* As, bf16_t* Bs_unused) {
;     ...
;   auto step = [&](int buf, u32x4 (&ra)[4], u32x4 (&rb)[4], bool do_write, bool do_load, int tload) __attribute__((always_inline)) {
;     const bf16_t* pa = As + buf * 2 * GT_IMG + pao; const bf16_t* pb = As + buf * 2 * GT_IMG + pbo;
;     bf16_t* Ad = As + (buf ^ 1) * 2 * GT_IMG; bf16_t* Bd = Ad + GT_IMG;
;     bf16x8 F0[4], F1[4];
;     frag_read(F0, pa, pb, 0);
;     __builtin_amdgcn_sched_barrier(0);
;     frag_read(F1, pa, pb, 16);
;     mfma4(F0);
;     __builtin_amdgcn_sched_barrier(0);
;     frag_read(F0, pa, pb, 32);
;     mfma4(F1);
;     if (do_write) {
; #pragma unroll
;       for (int i = 0; i < 4; ++i) *(u32x4*)(Ad + (lr + 32 * i) * 72 + lc) = ra[i];
;     }
;     __builtin_amdgcn_sched_barrier(0);
;     frag_read(F1, pa, pb, 48);
;     mfma4(F0);
;     if (do_write) {
; #pragma unroll
;       for (int i = 0; i < 4; ++i) *(u32x4*)(Bd + (lr + 32 * i) * 72 + lc) = rb[i];
;     }
;     __builtin_amdgcn_sched_barrier(0);
;     mfma4(F1);
;     if (do_load) load_stage(ra, rb, tload);
;     __builtin_amdgcn_sched_barrier(0);
;   };
;   const int nk = K >> 6;
;   load_stage(ra0, rb0, 0); load_stage(ra1, rb1, 1);
;   __syncthreads();
;   write_stage(ra0, rb0, 0);
;   load_stage(ra0, rb0, 2);
;   __syncthreads();
;   for (int kt = 0; kt < nk; kt += 2) {
;     step(0, ra1, rb1, true, kt + 3 < nk, kt + 3);
;     __syncthreads();
;     step(1, ra0, rb0, kt + 2 < nk, kt + 4 < nk, kt + 4);
;     __syncthreads();
	ds_read_b128 v[152:155], v102 offset:55296
	ds_read_b128 v[156:159], v102 offset:59904
	ds_read_b128 v[160:163], v101 offset:36864
	ds_read_b128 v[164:167], v101 offset:41472
	v_mfma_f32_32x32x16_bf16 v[48:63], v[116:119], v[80:83], v[48:63]
	v_mfma_f32_32x32x16_bf16 v[32:47], v[116:119], v[108:111], v[32:47]
	v_mfma_f32_32x32x16_bf16 v[0:15], v[128:131], v[80:83], v[0:15]
	v_mfma_f32_32x32x16_bf16 v[16:31], v[128:131], v[108:111], v[16:31]
	global_load_dwordx4 v[80:83], v[84:85], off offset:896
	global_load_dwordx4 v[104:107], v[86:87], off offset:896
	global_load_dwordx4 v[108:111], v[88:89], off offset:896
	global_load_dwordx4 v[112:115], v[90:91], off offset:896
	global_load_dwordx4 v[116:119], v[92:93], off offset:896
	global_load_dwordx4 v[124:127], v[94:95], off offset:896
	global_load_dwordx4 v[128:131], v[96:97], off offset:896
	global_load_dwordx4 v[132:135], v[98:99], off offset:896
	s_waitcnt lgkmcnt(1)
	v_mfma_f32_32x32x16_bf16 v[48:63], v[160:163], v[152:155], v[48:63]
	v_mfma_f32_32x32x16_bf16 v[32:47], v[160:163], v[156:159], v[32:47]
	s_waitcnt lgkmcnt(0)
	v_mfma_f32_32x32x16_bf16 v[0:15], v[164:167], v[152:155], v[0:15]
	ds_read_b128 v[152:155], v102 offset:55328
	ds_read_b128 v[160:163], v102 offset:59936
	ds_read_b128 v[168:171], v101 offset:36896
	ds_read_b128 v[172:175], v101 offset:41504
	v_mfma_f32_32x32x16_bf16 v[16:31], v[164:167], v[156:159], v[16:31]
	s_waitcnt lgkmcnt(1)
	v_mfma_f32_32x32x16_bf16 v[48:63], v[168:171], v[152:155], v[48:63]
	v_mfma_f32_32x32x16_bf16 v[32:47], v[168:171], v[160:163], v[32:47]
	s_waitcnt lgkmcnt(0)
	v_mfma_f32_32x32x16_bf16 v[0:15], v[172:175], v[152:155], v[0:15]
	ds_read_b128 v[152:155], v102 offset:55360
	ds_read_b128 v[156:159], v102 offset:59968
	ds_read_b128 v[164:167], v101 offset:36928
	ds_read_b128 v[168:171], v101 offset:41536
	s_waitcnt vmcnt(15)
	ds_write_b128 v100, v[64:67]
	s_waitcnt vmcnt(13)
	ds_write_b128 v100, v[72:75] offset:4608
	s_waitcnt vmcnt(11)
	ds_write_b128 v100, v[136:139] offset:9216
	s_waitcnt vmcnt(9)
	ds_write_b128 v100, v[144:147] offset:13824
	v_mfma_f32_32x32x16_bf16 v[16:31], v[172:175], v[160:163], v[16:31]
	s_waitcnt lgkmcnt(5)
	v_mfma_f32_32x32x16_bf16 v[48:63], v[164:167], v[152:155], v[48:63]
	ds_read_b128 v[64:67], v102 offset:55392
	ds_read_b128 v[72:75], v102 offset:60000
	ds_read_b128 v[136:139], v101 offset:36960
	ds_read_b128 v[144:147], v101 offset:41568
	ds_write_b128 v100, v[68:71] offset:18432
	ds_write_b128 v100, v[76:79] offset:23040
	ds_write_b128 v100, v[140:143] offset:27648
	s_waitcnt vmcnt(8)
	ds_write_b128 v100, v[148:151] offset:32256
	v_mfma_f32_32x32x16_bf16 v[32:47], v[164:167], v[156:159], v[32:47]
	s_waitcnt lgkmcnt(12)
	v_mfma_f32_32x32x16_bf16 v[0:15], v[168:171], v[152:155], v[0:15]
	v_mfma_f32_32x32x16_bf16 v[16:31], v[168:171], v[156:159], v[16:31]
	s_waitcnt lgkmcnt(0)
	s_barrier
	ds_read_b128 v[152:155], v102 offset:18432
	ds_read_b128 v[156:159], v102 offset:23040
	ds_read_b128 v[160:163], v101
	ds_read_b128 v[164:167], v101 offset:4608
	v_mfma_f32_32x32x16_bf16 v[48:63], v[136:139], v[64:67], v[48:63]
	v_mfma_f32_32x32x16_bf16 v[32:47], v[136:139], v[72:75], v[32:47]
	v_mfma_f32_32x32x16_bf16 v[0:15], v[144:147], v[64:67], v[0:15]
	v_mfma_f32_32x32x16_bf16 v[16:31], v[144:147], v[72:75], v[16:31]
	global_load_dwordx4 v[64:67], v[84:85], off offset:1024
	global_load_dwordx4 v[68:71], v[86:87], off offset:1024
	global_load_dwordx4 v[72:75], v[88:89], off offset:1024
	global_load_dwordx4 v[76:79], v[90:91], off offset:1024
	global_load_dwordx4 v[136:139], v[92:93], off offset:1024
	global_load_dwordx4 v[140:143], v[94:95], off offset:1024
	global_load_dwordx4 v[144:147], v[96:97], off offset:1024
	global_load_dwordx4 v[148:151], v[98:99], off offset:1024
	s_waitcnt lgkmcnt(1)
	v_mfma_f32_32x32x16_bf16 v[48:63], v[160:163], v[152:155], v[48:63]
	v_mfma_f32_32x32x16_bf16 v[32:47], v[160:163], v[156:159], v[32:47]
	s_waitcnt lgkmcnt(0)
	v_mfma_f32_32x32x16_bf16 v[0:15], v[164:167], v[152:155], v[0:15]
	ds_read_b128 v[152:155], v102 offset:18464
	ds_read_b128 v[160:163], v102 offset:23072
	ds_read_b128 v[168:171], v101 offset:32
	ds_read_b128 v[172:175], v101 offset:4640
	v_mfma_f32_32x32x16_bf16 v[16:31], v[164:167], v[156:159], v[16:31]
	s_waitcnt lgkmcnt(1)
	v_mfma_f32_32x32x16_bf16 v[48:63], v[168:171], v[152:155], v[48:63]
	v_mfma_f32_32x32x16_bf16 v[32:47], v[168:171], v[160:163], v[32:47]
	s_waitcnt lgkmcnt(0)
	v_mfma_f32_32x32x16_bf16 v[0:15], v[172:175], v[152:155], v[0:15]
	ds_read_b128 v[152:155], v102 offset:18496
	ds_read_b128 v[156:159], v102 offset:23104
	ds_read_b128 v[164:167], v101 offset:64
	ds_read_b128 v[168:171], v101 offset:4672
	s_waitcnt vmcnt(15)
	ds_write_b128 v100, v[80:83] offset:36864
	s_waitcnt vmcnt(13)
	ds_write_b128 v100, v[108:111] offset:41472
	s_waitcnt vmcnt(11)
	ds_write_b128 v100, v[116:119] offset:46080
	s_waitcnt vmcnt(9)
	ds_write_b128 v100, v[128:131] offset:50688
	v_mfma_f32_32x32x16_bf16 v[16:31], v[172:175], v[160:163], v[16:31]
	s_waitcnt lgkmcnt(5)
	v_mfma_f32_32x32x16_bf16 v[48:63], v[164:167], v[152:155], v[48:63]
	ds_read_b128 v[80:83], v102 offset:18528
	ds_read_b128 v[108:111], v102 offset:23136
	ds_read_b128 v[116:119], v101 offset:96
	ds_read_b128 v[128:131], v101 offset:4704
	ds_write_b128 v100, v[104:107] offset:55296
	ds_write_b128 v100, v[112:115] offset:59904
	ds_write_b128 v100, v[124:127] offset:64512
	s_waitcnt vmcnt(8)
	ds_write_b128 v103, v[132:135] offset:13824
	v_mfma_f32_32x32x16_bf16 v[32:47], v[164:167], v[156:159], v[32:47]
	s_waitcnt lgkmcnt(12)
	v_mfma_f32_32x32x16_bf16 v[0:15], v[168:171], v[152:155], v[0:15]
	v_mfma_f32_32x32x16_bf16 v[16:31], v[168:171], v[156:159], v[16:31]
	s_waitcnt lgkmcnt(0)
	s_barrier
; template <bool SWAP>
; DI void gemm_tile(const bf16_t* __restrict__ A, int lda, const bf16_t* __restrict__ Bt, int ldb, int K, f32x16 (&acc)[2][2], bf16_t* As, bf16_t* Bs_unused) {
;     ...
;   auto step = [&](int buf, u32x4 (&ra)[4], u32x4 (&rb)[4], bool do_write, bool do_load, int tload) __attribute__((always_inline)) {
;     const bf16_t* pa = As + buf * 2 * GT_IMG + pao; const bf16_t* pb = As + buf * 2 * GT_IMG + pbo;
;     bf16_t* Ad = As + (buf ^ 1) * 2 * GT_IMG; bf16_t* Bd = Ad + GT_IMG;
;     bf16x8 F0[4], F1[4];
;     frag_read(F0, pa, pb, 0);
;     __builtin_amdgcn_sched_barrier(0);
;     frag_read(F1, pa, pb, 16);
;     mfma4(F0);
;     __builtin_amdgcn_sched_barrier(0);
;     frag_read(F0, pa, pb, 32);
;     mfma4(F1);
;     if (do_write) {
; #pragma unroll
;       for (int i = 0; i < 4; ++i) *(u32x4*)(Ad + (lr + 32 * i) * 72 + lc) = ra[i];
;     }
;     __builtin_amdgcn_sched_barrier(0);
;     frag_read(F1, pa, pb, 48);
;     mfma4(F0);
;     if (do_write) {
; #pragma unroll
;       for (int i = 0; i < 4; ++i) *(u32x4*)(Bd + (lr + 32 * i) * 72 + lc) = rb[i];
;     }
;     __builtin_amdgcn_sched_barrier(0);
;     mfma4(F1);
;     if (do_load) load_stage(ra, rb, tload);
;     __builtin_amdgcn_sched_barrier(0);
;   };
;   const int nk = K >> 6;
;   load_stage(ra0, rb0, 0); load_stage(ra1, rb1, 1);
;   __syncthreads();
;   write_stage(ra0, rb0, 0);
;   load_stage(ra0, rb0, 2);
;   __syncthreads();
;   for (int kt = 0; kt < nk; kt += 2) {
;     step(0, ra1, rb1, true, kt + 3 < nk, kt + 3);
;     __syncthreads();
;     step(1, ra0, rb0, kt + 2 < nk, kt + 4 < nk, kt + 4);
;     __syncthreads();
	ds_read_b128 v[152:155], v102 offset:55296
	ds_read_b128 v[156:159], v102 offset:59904
	ds_read_b128 v[160:163], v101 offset:36864
	ds_read_b128 v[164:167], v101 offset:41472
	v_mfma_f32_32x32x16_bf16 v[48:63], v[116:119], v[80:83], v[48:63]
	v_mfma_f32_32x32x16_bf16 v[32:47], v[116:119], v[108:111], v[32:47]
	v_mfma_f32_32x32x16_bf16 v[0:15], v[128:131], v[80:83], v[0:15]
	v_mfma_f32_32x32x16_bf16 v[16:31], v[128:131], v[108:111], v[16:31]
	global_load_dwordx4 v[80:83], v[84:85], off offset:1152
	global_load_dwordx4 v[104:107], v[86:87], off offset:1152
	global_load_dwordx4 v[108:111], v[88:89], off offset:1152
	global_load_dwordx4 v[112:115], v[90:91], off offset:1152
	global_load_dwordx4 v[116:119], v[92:93], off offset:1152
	global_load_dwordx4 v[124:127], v[94:95], off offset:1152
	global_load_dwordx4 v[128:131], v[96:97], off offset:1152
	global_load_dwordx4 v[132:135], v[98:99], off offset:1152
	s_waitcnt lgkmcnt(1)
	v_mfma_f32_32x32x16_bf16 v[48:63], v[160:163], v[152:155], v[48:63]
	v_mfma_f32_32x32x16_bf16 v[32:47], v[160:163], v[156:159], v[32:47]
	s_waitcnt lgkmcnt(0)
	v_mfma_f32_32x32x16_bf16 v[0:15], v[164:167], v[152:155], v[0:15]
	ds_read_b128 v[152:155], v102 offset:55328
	ds_read_b128 v[160:163], v102 offset:59936
	ds_read_b128 v[168:171], v101 offset:36896
	ds_read_b128 v[172:175], v101 offset:41504
	v_mfma_f32_32x32x16_bf16 v[16:31], v[164:167], v[156:159], v[16:31]
	s_waitcnt lgkmcnt(1)
	v_mfma_f32_32x32x16_bf16 v[48:63], v[168:171], v[152:155], v[48:63]
	v_mfma_f32_32x32x16_bf16 v[32:47], v[168:171], v[160:163], v[32:47]
	s_waitcnt lgkmcnt(0)
	v_mfma_f32_32x32x16_bf16 v[0:15], v[172:175], v[152:155], v[0:15]
	ds_read_b128 v[152:155], v102 offset:55360
	ds_read_b128 v[156:159], v102 offset:59968
	ds_read_b128 v[164:167], v101 offset:36928
	ds_read_b128 v[168:171], v101 offset:41536
	s_waitcnt vmcnt(15)
	ds_write_b128 v100, v[64:67]
	s_waitcnt vmcnt(13)
	ds_write_b128 v100, v[72:75] offset:4608
	s_waitcnt vmcnt(11)
	ds_write_b128 v100, v[136:139] offset:9216
	s_waitcnt vmcnt(9)
	ds_write_b128 v100, v[144:147] offset:13824
	v_mfma_f32_32x32x16_bf16 v[16:31], v[172:175], v[160:163], v[16:31]
	s_waitcnt lgkmcnt(5)
	v_mfma_f32_32x32x16_bf16 v[48:63], v[164:167], v[152:155], v[48:63]
	ds_read_b128 v[64:67], v102 offset:55392
	ds_read_b128 v[72:75], v102 offset:60000
	ds_read_b128 v[136:139], v101 offset:36960
	ds_read_b128 v[144:147], v101 offset:41568
	ds_write_b128 v100, v[68:71] offset:18432
	ds_write_b128 v100, v[76:79] offset:23040
	ds_write_b128 v100, v[140:143] offset:27648
	s_waitcnt vmcnt(8)
	ds_write_b128 v100, v[148:151] offset:32256
	v_mfma_f32_32x32x16_bf16 v[32:47], v[164:167], v[156:159], v[32:47]
	s_waitcnt lgkmcnt(12)
	v_mfma_f32_32x32x16_bf16 v[0:15], v[168:171], v[152:155], v[0:15]
	v_mfma_f32_32x32x16_bf16 v[16:31], v[168:171], v[156:159], v[16:31]
	s_waitcnt lgkmcnt(0)
	s_barrier
	ds_read_b128 v[152:155], v102 offset:18432
	ds_read_b128 v[156:159], v102 offset:23040
	ds_read_b128 v[160:163], v101
	ds_read_b128 v[164:167], v101 offset:4608
	v_mfma_f32_32x32x16_bf16 v[48:63], v[136:139], v[64:67], v[48:63]
	v_mfma_f32_32x32x16_bf16 v[32:47], v[136:139], v[72:75], v[32:47]
	v_mfma_f32_32x32x16_bf16 v[0:15], v[144:147], v[64:67], v[0:15]
	v_mfma_f32_32x32x16_bf16 v[16:31], v[144:147], v[72:75], v[16:31]
	global_load_dwordx4 v[64:67], v[84:85], off offset:1280
	global_load_dwordx4 v[68:71], v[86:87], off offset:1280
	global_load_dwordx4 v[72:75], v[88:89], off offset:1280
	global_load_dwordx4 v[76:79], v[90:91], off offset:1280
	global_load_dwordx4 v[136:139], v[92:93], off offset:1280
	global_load_dwordx4 v[140:143], v[94:95], off offset:1280
	global_load_dwordx4 v[144:147], v[96:97], off offset:1280
	global_load_dwordx4 v[148:151], v[98:99], off offset:1280
	s_waitcnt lgkmcnt(1)
	v_mfma_f32_32x32x16_bf16 v[48:63], v[160:163], v[152:155], v[48:63]
	v_mfma_f32_32x32x16_bf16 v[32:47], v[160:163], v[156:159], v[32:47]
	s_waitcnt lgkmcnt(0)
	v_mfma_f32_32x32x16_bf16 v[0:15], v[164:167], v[152:155], v[0:15]
	ds_read_b128 v[152:155], v102 offset:18464
	ds_read_b128 v[160:163], v102 offset:23072
	ds_read_b128 v[168:171], v101 offset:32
	ds_read_b128 v[172:175], v101 offset:4640
	v_mfma_f32_32x32x16_bf16 v[16:31], v[164:167], v[156:159], v[16:31]
	s_waitcnt lgkmcnt(1)
	v_mfma_f32_32x32x16_bf16 v[48:63], v[168:171], v[152:155], v[48:63]
	v_mfma_f32_32x32x16_bf16 v[32:47], v[168:171], v[160:163], v[32:47]
	s_waitcnt lgkmcnt(0)
	v_mfma_f32_32x32x16_bf16 v[0:15], v[172:175], v[152:155], v[0:15]
	ds_read_b128 v[152:155], v102 offset:18496
	ds_read_b128 v[156:159], v102 offset:23104
	ds_read_b128 v[164:167], v101 offset:64
	ds_read_b128 v[168:171], v101 offset:4672
	s_waitcnt vmcnt(15)
	ds_write_b128 v100, v[80:83] offset:36864
	s_waitcnt vmcnt(13)
	ds_write_b128 v100, v[108:111] offset:41472
	s_waitcnt vmcnt(11)
	ds_write_b128 v100, v[116:119] offset:46080
	s_waitcnt vmcnt(9)
	ds_write_b128 v100, v[128:131] offset:50688
	v_mfma_f32_32x32x16_bf16 v[16:31], v[172:175], v[160:163], v[16:31]
	s_waitcnt lgkmcnt(5)
	v_mfma_f32_32x32x16_bf16 v[48:63], v[164:167], v[152:155], v[48:63]
	ds_read_b128 v[80:83], v102 offset:18528
	ds_read_b128 v[108:111], v102 offset:23136
	ds_read_b128 v[116:119], v101 offset:96
	ds_read_b128 v[128:131], v101 offset:4704
	ds_write_b128 v100, v[104:107] offset:55296
	ds_write_b128 v100, v[112:115] offset:59904
	ds_write_b128 v100, v[124:127] offset:64512
	s_waitcnt vmcnt(8)
	ds_write_b128 v103, v[132:135] offset:13824
	v_mfma_f32_32x32x16_bf16 v[32:47], v[164:167], v[156:159], v[32:47]
	s_waitcnt lgkmcnt(12)
	v_mfma_f32_32x32x16_bf16 v[0:15], v[168:171], v[152:155], v[0:15]
	v_mfma_f32_32x32x16_bf16 v[16:31], v[168:171], v[156:159], v[16:31]
	s_waitcnt lgkmcnt(0)
	s_barrier
; template <bool SWAP>
; DI void gemm_tile(const bf16_t* __restrict__ A, int lda, const bf16_t* __restrict__ Bt, int ldb, int K, f32x16 (&acc)[2][2], bf16_t* As, bf16_t* Bs_unused) {
;     ...
;   auto step = [&](int buf, u32x4 (&ra)[4], u32x4 (&rb)[4], bool do_write, bool do_load, int tload) __attribute__((always_inline)) {
;     const bf16_t* pa = As + buf * 2 * GT_IMG + pao; const bf16_t* pb = As + buf * 2 * GT_IMG + pbo;
;     bf16_t* Ad = As + (buf ^ 1) * 2 * GT_IMG; bf16_t* Bd = Ad + GT_IMG;
;     bf16x8 F0[4], F1[4];
;     frag_read(F0, pa, pb, 0);
;     __builtin_amdgcn_sched_barrier(0);
;     frag_read(F1, pa, pb, 16);
;     mfma4(F0);
;     __builtin_amdgcn_sched_barrier(0);
;     frag_read(F0, pa, pb, 32);
;     mfma4(F1);
;     if (do_write) {
; #pragma unroll
;       for (int i = 0; i < 4; ++i) *(u32x4*)(Ad + (lr + 32 * i) * 72 + lc) = ra[i];
;     }
;     __builtin_amdgcn_sched_barrier(0);
;     frag_read(F1, pa, pb, 48);
;     mfma4(F0);
;     if (do_write) {
; #pragma unroll
;       for (int i = 0; i < 4; ++i) *(u32x4*)(Bd + (lr + 32 * i) * 72 + lc) = rb[i];
;     }
;     __builtin_amdgcn_sched_barrier(0);
;     mfma4(F1);
;     if (do_load) load_stage(ra, rb, tload);
;     __builtin_amdgcn_sched_barrier(0);
;   };
;   const int nk = K >> 6;
;   load_stage(ra0, rb0, 0); load_stage(ra1, rb1, 1);
;   __syncthreads();
;   write_stage(ra0, rb0, 0);
;   load_stage(ra0, rb0, 2);
;   __syncthreads();
;   for (int kt = 0; kt < nk; kt += 2) {
;     step(0, ra1, rb1, true, kt + 3 < nk, kt + 3);
;     __syncthreads();
;     step(1, ra0, rb0, kt + 2 < nk, kt + 4 < nk, kt + 4);
;     __syncthreads();
	ds_read_b128 v[152:155], v102 offset:55296
	ds_read_b128 v[156:159], v102 offset:59904
	ds_read_b128 v[160:163], v101 offset:36864
	ds_read_b128 v[164:167], v101 offset:41472
	v_mfma_f32_32x32x16_bf16 v[48:63], v[116:119], v[80:83], v[48:63]
	v_mfma_f32_32x32x16_bf16 v[32:47], v[116:119], v[108:111], v[32:47]
	v_mfma_f32_32x32x16_bf16 v[0:15], v[128:131], v[80:83], v[0:15]
	v_mfma_f32_32x32x16_bf16 v[16:31], v[128:131], v[108:111], v[16:31]
	global_load_dwordx4 v[80:83], v[84:85], off offset:1408
	global_load_dwordx4 v[104:107], v[86:87], off offset:1408
	global_load_dwordx4 v[108:111], v[88:89], off offset:1408
	global_load_dwordx4 v[112:115], v[90:91], off offset:1408
	global_load_dwordx4 v[116:119], v[92:93], off offset:1408
	global_load_dwordx4 v[124:127], v[94:95], off offset:1408
	global_load_dwordx4 v[128:131], v[96:97], off offset:1408
	global_load_dwordx4 v[132:135], v[98:99], off offset:1408
	s_waitcnt lgkmcnt(1)
	v_mfma_f32_32x32x16_bf16 v[48:63], v[160:163], v[152:155], v[48:63]
	v_mfma_f32_32x32x16_bf16 v[32:47], v[160:163], v[156:159], v[32:47]
	s_waitcnt lgkmcnt(0)
	v_mfma_f32_32x32x16_bf16 v[0:15], v[164:167], v[152:155], v[0:15]
	ds_read_b128 v[152:155], v102 offset:55328
	ds_read_b128 v[160:163], v102 offset:59936
	ds_read_b128 v[168:171], v101 offset:36896
	ds_read_b128 v[172:175], v101 offset:41504
	v_mfma_f32_32x32x16_bf16 v[16:31], v[164:167], v[156:159], v[16:31]
	s_waitcnt lgkmcnt(1)
	v_mfma_f32_32x32x16_bf16 v[48:63], v[168:171], v[152:155], v[48:63]
	v_mfma_f32_32x32x16_bf16 v[32:47], v[168:171], v[160:163], v[32:47]
	s_waitcnt lgkmcnt(0)
	v_mfma_f32_32x32x16_bf16 v[0:15], v[172:175], v[152:155], v[0:15]
	ds_read_b128 v[152:155], v102 offset:55360
	ds_read_b128 v[156:159], v102 offset:59968
	ds_read_b128 v[164:167], v101 offset:36928
	ds_read_b128 v[168:171], v101 offset:41536
	s_waitcnt vmcnt(15)
	ds_write_b128 v100, v[64:67]
	s_waitcnt vmcnt(13)
	ds_write_b128 v100, v[72:75] offset:4608
	s_waitcnt vmcnt(11)
	ds_write_b128 v100, v[136:139] offset:9216
	s_waitcnt vmcnt(9)
	ds_write_b128 v100, v[144:147] offset:13824
	v_mfma_f32_32x32x16_bf16 v[16:31], v[172:175], v[160:163], v[16:31]
	s_waitcnt lgkmcnt(5)
	v_mfma_f32_32x32x16_bf16 v[48:63], v[164:167], v[152:155], v[48:63]
	ds_read_b128 v[64:67], v102 offset:55392
	ds_read_b128 v[72:75], v102 offset:60000
	ds_read_b128 v[136:139], v101 offset:36960
	ds_read_b128 v[144:147], v101 offset:41568
	ds_write_b128 v100, v[68:71] offset:18432
	ds_write_b128 v100, v[76:79] offset:23040
	ds_write_b128 v100, v[140:143] offset:27648
	s_waitcnt vmcnt(8)
	ds_write_b128 v100, v[148:151] offset:32256
	v_mfma_f32_32x32x16_bf16 v[32:47], v[164:167], v[156:159], v[32:47]
	s_waitcnt lgkmcnt(12)
	v_mfma_f32_32x32x16_bf16 v[0:15], v[168:171], v[152:155], v[0:15]
	v_mfma_f32_32x32x16_bf16 v[16:31], v[168:171], v[156:159], v[16:31]
	s_waitcnt lgkmcnt(0)
	s_barrier
	ds_read_b128 v[152:155], v102 offset:18432
	ds_read_b128 v[156:159], v102 offset:23040
	ds_read_b128 v[160:163], v101
	ds_read_b128 v[164:167], v101 offset:4608
	v_mfma_f32_32x32x16_bf16 v[48:63], v[136:139], v[64:67], v[48:63]
	v_mfma_f32_32x32x16_bf16 v[32:47], v[136:139], v[72:75], v[32:47]
	v_mfma_f32_32x32x16_bf16 v[0:15], v[144:147], v[64:67], v[0:15]
	v_mfma_f32_32x32x16_bf16 v[16:31], v[144:147], v[72:75], v[16:31]
	global_load_dwordx4 v[64:67], v[84:85], off offset:1536
	global_load_dwordx4 v[68:71], v[86:87], off offset:1536
	global_load_dwordx4 v[72:75], v[88:89], off offset:1536
	global_load_dwordx4 v[76:79], v[90:91], off offset:1536
	global_load_dwordx4 v[136:139], v[92:93], off offset:1536
	global_load_dwordx4 v[140:143], v[94:95], off offset:1536
	global_load_dwordx4 v[144:147], v[96:97], off offset:1536
	global_load_dwordx4 v[148:151], v[98:99], off offset:1536
	s_waitcnt lgkmcnt(1)
	v_mfma_f32_32x32x16_bf16 v[48:63], v[160:163], v[152:155], v[48:63]
	v_mfma_f32_32x32x16_bf16 v[32:47], v[160:163], v[156:159], v[32:47]
	s_waitcnt lgkmcnt(0)
	v_mfma_f32_32x32x16_bf16 v[0:15], v[164:167], v[152:155], v[0:15]
	ds_read_b128 v[152:155], v102 offset:18464
	ds_read_b128 v[160:163], v102 offset:23072
	ds_read_b128 v[168:171], v101 offset:32
	ds_read_b128 v[172:175], v101 offset:4640
	v_mfma_f32_32x32x16_bf16 v[16:31], v[164:167], v[156:159], v[16:31]
	s_waitcnt lgkmcnt(1)
	v_mfma_f32_32x32x16_bf16 v[48:63], v[168:171], v[152:155], v[48:63]
	v_mfma_f32_32x32x16_bf16 v[32:47], v[168:171], v[160:163], v[32:47]
	s_waitcnt lgkmcnt(0)
	v_mfma_f32_32x32x16_bf16 v[0:15], v[172:175], v[152:155], v[0:15]
	ds_read_b128 v[152:155], v102 offset:18496
	ds_read_b128 v[156:159], v102 offset:23104
	ds_read_b128 v[164:167], v101 offset:64
	ds_read_b128 v[168:171], v101 offset:4672
	s_waitcnt vmcnt(15)
	ds_write_b128 v100, v[80:83] offset:36864
	s_waitcnt vmcnt(13)
	ds_write_b128 v100, v[108:111] offset:41472
	s_waitcnt vmcnt(11)
	ds_write_b128 v100, v[116:119] offset:46080
	s_waitcnt vmcnt(9)
	ds_write_b128 v100, v[128:131] offset:50688
	v_mfma_f32_32x32x16_bf16 v[16:31], v[172:175], v[160:163], v[16:31]
	s_waitcnt lgkmcnt(5)
	v_mfma_f32_32x32x16_bf16 v[48:63], v[164:167], v[152:155], v[48:63]
	ds_read_b128 v[80:83], v102 offset:18528
	ds_read_b128 v[108:111], v102 offset:23136
	ds_read_b128 v[116:119], v101 offset:96
	ds_read_b128 v[128:131], v101 offset:4704
	ds_write_b128 v100, v[104:107] offset:55296
	ds_write_b128 v100, v[112:115] offset:59904
	ds_write_b128 v100, v[124:127] offset:64512
	s_waitcnt vmcnt(8)
	ds_write_b128 v103, v[132:135] offset:13824
	v_mfma_f32_32x32x16_bf16 v[32:47], v[164:167], v[156:159], v[32:47]
	s_waitcnt lgkmcnt(12)
	v_mfma_f32_32x32x16_bf16 v[0:15], v[168:171], v[152:155], v[0:15]
	v_mfma_f32_32x32x16_bf16 v[16:31], v[168:171], v[156:159], v[16:31]
	s_waitcnt lgkmcnt(0)
	s_barrier
; template <bool SWAP>
; DI void gemm_tile(const bf16_t* __restrict__ A, int lda, const bf16_t* __restrict__ Bt, int ldb, int K, f32x16 (&acc)[2][2], bf16_t* As, bf16_t* Bs_unused) {
;     ...
;   auto step = [&](int buf, u32x4 (&ra)[4], u32x4 (&rb)[4], bool do_write, bool do_load, int tload) __attribute__((always_inline)) {
;     const bf16_t* pa = As + buf * 2 * GT_IMG + pao; const bf16_t* pb = As + buf * 2 * GT_IMG + pbo;
;     bf16_t* Ad = As + (buf ^ 1) * 2 * GT_IMG; bf16_t* Bd = Ad + GT_IMG;
;     bf16x8 F0[4], F1[4];
;     frag_read(F0, pa, pb, 0);
;     __builtin_amdgcn_sched_barrier(0);
;     frag_read(F1, pa, pb, 16);
;     mfma4(F0);
;     __builtin_amdgcn_sched_barrier(0);
;     frag_read(F0, pa, pb, 32);
;     mfma4(F1);
;     if (do_write) {
; #pragma unroll
;       for (int i = 0; i < 4; ++i) *(u32x4*)(Ad + (lr + 32 * i) * 72 + lc) = ra[i];
;     }
;     __builtin_amdgcn_sched_barrier(0);
;     frag_read(F1, pa, pb, 48);
;     mfma4(F0);
;     if (do_write) {
; #pragma unroll
;       for (int i = 0; i < 4; ++i) *(u32x4*)(Bd + (lr + 32 * i) * 72 + lc) = rb[i];
;     }
;     __builtin_amdgcn_sched_barrier(0);
;     mfma4(F1);
;     if (do_load) load_stage(ra, rb, tload);
;     __builtin_amdgcn_sched_barrier(0);
;   };
;   const int nk = K >> 6;
;   load_stage(ra0, rb0, 0); load_stage(ra1, rb1, 1);
;   __syncthreads();
;   write_stage(ra0, rb0, 0);
;   load_stage(ra0, rb0, 2);
;   __syncthreads();
;   for (int kt = 0; kt < nk; kt += 2) {
;     step(0, ra1, rb1, true, kt + 3 < nk, kt + 3);
;     __syncthreads();
;     step(1, ra0, rb0, kt + 2 < nk, kt + 4 < nk, kt + 4);
;     __syncthreads();
	ds_read_b128 v[152:155], v102 offset:55296
	ds_read_b128 v[156:159], v102 offset:59904
	ds_read_b128 v[160:163], v101 offset:36864
	ds_read_b128 v[164:167], v101 offset:41472
	v_mfma_f32_32x32x16_bf16 v[48:63], v[116:119], v[80:83], v[48:63]
	v_mfma_f32_32x32x16_bf16 v[32:47], v[116:119], v[108:111], v[32:47]
	v_mfma_f32_32x32x16_bf16 v[0:15], v[128:131], v[80:83], v[0:15]
	v_mfma_f32_32x32x16_bf16 v[16:31], v[128:131], v[108:111], v[16:31]
	global_load_dwordx4 v[80:83], v[84:85], off offset:1664
	global_load_dwordx4 v[104:107], v[86:87], off offset:1664
	global_load_dwordx4 v[108:111], v[88:89], off offset:1664
	global_load_dwordx4 v[112:115], v[90:91], off offset:1664
	global_load_dwordx4 v[116:119], v[92:93], off offset:1664
	global_load_dwordx4 v[124:127], v[94:95], off offset:1664
	global_load_dwordx4 v[128:131], v[96:97], off offset:1664
	global_load_dwordx4 v[132:135], v[98:99], off offset:1664
	s_waitcnt lgkmcnt(1)
	v_mfma_f32_32x32x16_bf16 v[48:63], v[160:163], v[152:155], v[48:63]
	v_mfma_f32_32x32x16_bf16 v[32:47], v[160:163], v[156:159], v[32:47]
	s_waitcnt lgkmcnt(0)
	v_mfma_f32_32x32x16_bf16 v[0:15], v[164:167], v[152:155], v[0:15]
	ds_read_b128 v[152:155], v102 offset:55328
	ds_read_b128 v[160:163], v102 offset:59936
	ds_read_b128 v[168:171], v101 offset:36896
	ds_read_b128 v[172:175], v101 offset:41504
	v_mfma_f32_32x32x16_bf16 v[16:31], v[164:167], v[156:159], v[16:31]
	s_waitcnt lgkmcnt(1)
	v_mfma_f32_32x32x16_bf16 v[48:63], v[168:171], v[152:155], v[48:63]
	v_mfma_f32_32x32x16_bf16 v[32:47], v[168:171], v[160:163], v[32:47]
	s_waitcnt lgkmcnt(0)
	v_mfma_f32_32x32x16_bf16 v[0:15], v[172:175], v[152:155], v[0:15]
	ds_read_b128 v[152:155], v102 offset:55360
	ds_read_b128 v[156:159], v102 offset:59968
	ds_read_b128 v[164:167], v101 offset:36928
	ds_read_b128 v[168:171], v101 offset:41536
	s_waitcnt vmcnt(15)
	ds_write_b128 v100, v[64:67]
	s_waitcnt vmcnt(13)
	ds_write_b128 v100, v[72:75] offset:4608
	s_waitcnt vmcnt(11)
	ds_write_b128 v100, v[136:139] offset:9216
	s_waitcnt vmcnt(9)
	ds_write_b128 v100, v[144:147] offset:13824
	v_mfma_f32_32x32x16_bf16 v[16:31], v[172:175], v[160:163], v[16:31]
	s_waitcnt lgkmcnt(5)
	v_mfma_f32_32x32x16_bf16 v[48:63], v[164:167], v[152:155], v[48:63]
	ds_read_b128 v[64:67], v102 offset:55392
	ds_read_b128 v[72:75], v102 offset:60000
	ds_read_b128 v[136:139], v101 offset:36960
	ds_read_b128 v[144:147], v101 offset:41568
	ds_write_b128 v100, v[68:71] offset:18432
	ds_write_b128 v100, v[76:79] offset:23040
	ds_write_b128 v100, v[140:143] offset:27648
	s_waitcnt vmcnt(8)
	ds_write_b128 v100, v[148:151] offset:32256
	v_mfma_f32_32x32x16_bf16 v[32:47], v[164:167], v[156:159], v[32:47]
	s_waitcnt lgkmcnt(12)
	v_mfma_f32_32x32x16_bf16 v[0:15], v[168:171], v[152:155], v[0:15]
	v_mfma_f32_32x32x16_bf16 v[16:31], v[168:171], v[156:159], v[16:31]
	s_waitcnt lgkmcnt(0)
	s_barrier
	ds_read_b128 v[152:155], v102 offset:18432
	ds_read_b128 v[156:159], v102 offset:23040
	ds_read_b128 v[160:163], v101
	ds_read_b128 v[164:167], v101 offset:4608
	v_mfma_f32_32x32x16_bf16 v[48:63], v[136:139], v[64:67], v[48:63]
	v_mfma_f32_32x32x16_bf16 v[32:47], v[136:139], v[72:75], v[32:47]
	v_mfma_f32_32x32x16_bf16 v[0:15], v[144:147], v[64:67], v[0:15]
	v_mfma_f32_32x32x16_bf16 v[16:31], v[144:147], v[72:75], v[16:31]
	global_load_dwordx4 v[64:67], v[84:85], off offset:1792
	global_load_dwordx4 v[68:71], v[86:87], off offset:1792
	global_load_dwordx4 v[72:75], v[88:89], off offset:1792
	global_load_dwordx4 v[76:79], v[90:91], off offset:1792
	global_load_dwordx4 v[136:139], v[92:93], off offset:1792
	global_load_dwordx4 v[140:143], v[94:95], off offset:1792
	global_load_dwordx4 v[144:147], v[96:97], off offset:1792
	global_load_dwordx4 v[148:151], v[98:99], off offset:1792
	s_waitcnt lgkmcnt(1)
	v_mfma_f32_32x32x16_bf16 v[48:63], v[160:163], v[152:155], v[48:63]
	v_mfma_f32_32x32x16_bf16 v[32:47], v[160:163], v[156:159], v[32:47]
	s_waitcnt lgkmcnt(0)
	v_mfma_f32_32x32x16_bf16 v[0:15], v[164:167], v[152:155], v[0:15]
	ds_read_b128 v[152:155], v102 offset:18464
	ds_read_b128 v[160:163], v102 offset:23072
	ds_read_b128 v[168:171], v101 offset:32
	ds_read_b128 v[172:175], v101 offset:4640
	v_mfma_f32_32x32x16_bf16 v[16:31], v[164:167], v[156:159], v[16:31]
	s_waitcnt lgkmcnt(1)
	v_mfma_f32_32x32x16_bf16 v[48:63], v[168:171], v[152:155], v[48:63]
	v_mfma_f32_32x32x16_bf16 v[32:47], v[168:171], v[160:163], v[32:47]
	s_waitcnt lgkmcnt(0)
	v_mfma_f32_32x32x16_bf16 v[0:15], v[172:175], v[152:155], v[0:15]
	ds_read_b128 v[152:155], v102 offset:18496
	ds_read_b128 v[156:159], v102 offset:23104
	ds_read_b128 v[164:167], v101 offset:64
	ds_read_b128 v[168:171], v101 offset:4672
	s_waitcnt vmcnt(15)
	ds_write_b128 v100, v[80:83] offset:36864
	s_waitcnt vmcnt(13)
	ds_write_b128 v100, v[108:111] offset:41472
	s_waitcnt vmcnt(11)
	ds_write_b128 v100, v[116:119] offset:46080
	s_waitcnt vmcnt(9)
	ds_write_b128 v100, v[128:131] offset:50688
	v_mfma_f32_32x32x16_bf16 v[16:31], v[172:175], v[160:163], v[16:31]
	s_waitcnt lgkmcnt(5)
	v_mfma_f32_32x32x16_bf16 v[48:63], v[164:167], v[152:155], v[48:63]
	ds_read_b128 v[80:83], v102 offset:18528
	ds_read_b128 v[108:111], v102 offset:23136
	ds_read_b128 v[116:119], v101 offset:96
	ds_read_b128 v[128:131], v101 offset:4704
	ds_write_b128 v100, v[104:107] offset:55296
	ds_write_b128 v100, v[112:115] offset:59904
	ds_write_b128 v100, v[124:127] offset:64512
	s_waitcnt vmcnt(8)
	ds_write_b128 v103, v[132:135] offset:13824
	v_mfma_f32_32x32x16_bf16 v[32:47], v[164:167], v[156:159], v[32:47]
	s_waitcnt lgkmcnt(12)
	v_mfma_f32_32x32x16_bf16 v[0:15], v[168:171], v[152:155], v[0:15]
	v_mfma_f32_32x32x16_bf16 v[16:31], v[168:171], v[156:159], v[16:31]
	s_waitcnt lgkmcnt(0)
	s_barrier
; template <bool SWAP>
; DI void gemm_tile(const bf16_t* __restrict__ A, int lda, const bf16_t* __restrict__ Bt, int ldb, int K, f32x16 (&acc)[2][2], bf16_t* As, bf16_t* Bs_unused) {
;     ...
;   auto step = [&](int buf, u32x4 (&ra)[4], u32x4 (&rb)[4], bool do_write, bool do_load, int tload) __attribute__((always_inline)) {
;     const bf16_t* pa = As + buf * 2 * GT_IMG + pao; const bf16_t* pb = As + buf * 2 * GT_IMG + pbo;
;     bf16_t* Ad = As + (buf ^ 1) * 2 * GT_IMG; bf16_t* Bd = Ad + GT_IMG;
;     bf16x8 F0[4], F1[4];
;     frag_read(F0, pa, pb, 0);
;     __builtin_amdgcn_sched_barrier(0);
;     frag_read(F1, pa, pb, 16);
;     mfma4(F0);
;     __builtin_amdgcn_sched_barrier(0);
;     frag_read(F0, pa, pb, 32);
;     mfma4(F1);
;     if (do_write) {
; #pragma unroll
;       for (int i = 0; i < 4; ++i) *(u32x4*)(Ad + (lr + 32 * i) * 72 + lc) = ra[i];
;     }
;     __builtin_amdgcn_sched_barrier(0);
;     frag_read(F1, pa, pb, 48);
;     mfma4(F0);
;     if (do_write) {
; #pragma unroll
;       for (int i = 0; i < 4; ++i) *(u32x4*)(Bd + (lr + 32 * i) * 72 + lc) = rb[i];
;     }
;     __builtin_amdgcn_sched_barrier(0);
;     mfma4(F1);
;     if (do_load) load_stage(ra, rb, tload);
;     __builtin_amdgcn_sched_barrier(0);
;   };
;   const int nk = K >> 6;
;   load_stage(ra0, rb0, 0); load_stage(ra1, rb1, 1);
;   __syncthreads();
;   write_stage(ra0, rb0, 0);
;   load_stage(ra0, rb0, 2);
;   __syncthreads();
;   for (int kt = 0; kt < nk; kt += 2) {
;     step(0, ra1, rb1, true, kt + 3 < nk, kt + 3);
;     __syncthreads();
;     step(1, ra0, rb0, kt + 2 < nk, kt + 4 < nk, kt + 4);
;     __syncthreads();
	ds_read_b128 v[180:183], v102 offset:55296
	ds_read_b128 v[184:187], v102 offset:59904
	ds_read_b128 v[188:191], v101 offset:36864
	ds_read_b128 v[220:223], v101 offset:41472
	v_mfma_f32_32x32x16_bf16 v[48:63], v[116:119], v[80:83], v[48:63]
	v_mfma_f32_32x32x16_bf16 v[32:47], v[116:119], v[108:111], v[32:47]
	v_mfma_f32_32x32x16_bf16 v[0:15], v[128:131], v[80:83], v[0:15]
	v_mfma_f32_32x32x16_bf16 v[16:31], v[128:131], v[108:111], v[16:31]
	global_load_dwordx4 v[80:83], v[84:85], off offset:1920
	s_nop 0
	global_load_dwordx4 v[84:87], v[86:87], off offset:1920
	s_nop 0
	global_load_dwordx4 v[104:107], v[88:89], off offset:1920
	s_nop 0
	global_load_dwordx4 v[88:91], v[90:91], off offset:1920
	s_nop 0
	global_load_dwordx4 v[108:111], v[92:93], off offset:1920
	s_nop 0
	global_load_dwordx4 v[92:95], v[94:95], off offset:1920
	s_nop 0
	global_load_dwordx4 v[112:115], v[96:97], off offset:1920
	s_nop 0
	global_load_dwordx4 v[96:99], v[98:99], off offset:1920
	s_waitcnt lgkmcnt(1)
	v_mfma_f32_32x32x16_bf16 v[48:63], v[188:191], v[180:183], v[48:63]
	v_mfma_f32_32x32x16_bf16 v[32:47], v[188:191], v[184:187], v[32:47]
	s_waitcnt lgkmcnt(0)
	v_mfma_f32_32x32x16_bf16 v[0:15], v[220:223], v[180:183], v[0:15]
	ds_read_b128 v[116:119], v102 offset:55328
	ds_read_b128 v[128:131], v102 offset:59936
	ds_read_b128 v[152:155], v101 offset:36896
	ds_read_b128 v[156:159], v101 offset:41504
	v_mfma_f32_32x32x16_bf16 v[16:31], v[220:223], v[184:187], v[16:31]
	s_waitcnt lgkmcnt(1)
	v_mfma_f32_32x32x16_bf16 v[48:63], v[152:155], v[116:119], v[48:63]
	v_mfma_f32_32x32x16_bf16 v[32:47], v[152:155], v[128:131], v[32:47]
	s_waitcnt lgkmcnt(0)
	v_mfma_f32_32x32x16_bf16 v[0:15], v[156:159], v[116:119], v[0:15]
	ds_read_b128 v[116:119], v102 offset:55360
	ds_read_b128 v[124:127], v102 offset:59968
	ds_read_b128 v[132:135], v101 offset:36928
	ds_read_b128 v[152:155], v101 offset:41536
	s_waitcnt vmcnt(15)
	ds_write_b128 v100, v[64:67]
	s_waitcnt vmcnt(13)
	ds_write_b128 v100, v[72:75] offset:4608
	s_waitcnt vmcnt(11)
	ds_write_b128 v100, v[136:139] offset:9216
	s_waitcnt vmcnt(9)
	ds_write_b128 v100, v[144:147] offset:13824
	v_mfma_f32_32x32x16_bf16 v[16:31], v[156:159], v[128:131], v[16:31]
	s_waitcnt lgkmcnt(5)
	v_mfma_f32_32x32x16_bf16 v[48:63], v[132:135], v[116:119], v[48:63]
	v_mfma_f32_32x32x16_bf16 v[32:47], v[132:135], v[124:127], v[32:47]
	s_waitcnt lgkmcnt(4)
	v_mfma_f32_32x32x16_bf16 v[0:15], v[152:155], v[116:119], v[0:15]
	ds_read_b128 v[64:67], v102 offset:55392
	ds_read_b128 v[72:75], v102 offset:60000
	ds_read_b128 v[116:119], v101 offset:36960
	ds_read_b128 v[128:131], v101 offset:41568
	ds_write_b128 v100, v[68:71] offset:18432
	ds_write_b128 v100, v[76:79] offset:23040
	ds_write_b128 v100, v[140:143] offset:27648
	s_waitcnt vmcnt(8)
	ds_write_b128 v100, v[148:151] offset:32256
	v_mfma_f32_32x32x16_bf16 v[16:31], v[152:155], v[124:127], v[16:31]
	s_waitcnt lgkmcnt(0)
	s_barrier
	ds_read_b128 v[180:183], v102 offset:18432
	ds_read_b128 v[184:187], v102 offset:23040
	ds_read_b128 v[188:191], v101
	ds_read_b128 v[220:223], v101 offset:4608
	v_mfma_f32_32x32x16_bf16 v[48:63], v[116:119], v[64:67], v[48:63]
	v_mfma_f32_32x32x16_bf16 v[32:47], v[116:119], v[72:75], v[32:47]
	v_mfma_f32_32x32x16_bf16 v[0:15], v[128:131], v[64:67], v[0:15]
	v_mfma_f32_32x32x16_bf16 v[16:31], v[128:131], v[72:75], v[16:31]
	s_waitcnt lgkmcnt(1)
	v_mfma_f32_32x32x16_bf16 v[48:63], v[188:191], v[180:183], v[48:63]
	v_mfma_f32_32x32x16_bf16 v[32:47], v[188:191], v[184:187], v[32:47]
	s_waitcnt lgkmcnt(0)
	v_mfma_f32_32x32x16_bf16 v[0:15], v[220:223], v[180:183], v[0:15]
	ds_read_b128 v[64:67], v102 offset:18464
	ds_read_b128 v[72:75], v102 offset:23072
	ds_read_b128 v[116:119], v101 offset:32
	ds_read_b128 v[124:127], v101 offset:4640
	v_mfma_f32_32x32x16_bf16 v[16:31], v[220:223], v[184:187], v[16:31]
	s_waitcnt lgkmcnt(1)
	v_mfma_f32_32x32x16_bf16 v[48:63], v[116:119], v[64:67], v[48:63]
	v_mfma_f32_32x32x16_bf16 v[32:47], v[116:119], v[72:75], v[32:47]
	s_waitcnt lgkmcnt(0)
	v_mfma_f32_32x32x16_bf16 v[0:15], v[124:127], v[64:67], v[0:15]
	ds_read_b128 v[64:67], v102 offset:18496
	ds_read_b128 v[68:71], v102 offset:23104
	ds_read_b128 v[76:79], v101 offset:64
	ds_read_b128 v[116:119], v101 offset:4672
	s_waitcnt vmcnt(7)
	ds_write_b128 v100, v[80:83] offset:36864
	s_waitcnt vmcnt(5)
	ds_write_b128 v100, v[104:107] offset:41472
	s_waitcnt vmcnt(3)
	ds_write_b128 v100, v[108:111] offset:46080
	s_waitcnt vmcnt(1)
	ds_write_b128 v100, v[112:115] offset:50688
	v_mfma_f32_32x32x16_bf16 v[16:31], v[124:127], v[72:75], v[16:31]
	s_waitcnt lgkmcnt(5)
	v_mfma_f32_32x32x16_bf16 v[48:63], v[76:79], v[64:67], v[48:63]
	v_mfma_f32_32x32x16_bf16 v[32:47], v[76:79], v[68:71], v[32:47]
	s_waitcnt lgkmcnt(4)
	v_mfma_f32_32x32x16_bf16 v[0:15], v[116:119], v[64:67], v[0:15]
	ds_read_b128 v[64:67], v102 offset:18528
	ds_read_b128 v[72:75], v102 offset:23136
	ds_read_b128 v[76:79], v101 offset:96
	ds_read_b128 v[80:83], v101 offset:4704
	ds_write_b128 v100, v[84:87] offset:55296
	ds_write_b128 v100, v[88:91] offset:59904
	ds_write_b128 v100, v[92:95] offset:64512
	s_waitcnt vmcnt(0)
	ds_write_b128 v103, v[96:99] offset:13824
	v_mfma_f32_32x32x16_bf16 v[16:31], v[116:119], v[68:71], v[16:31]
	s_waitcnt lgkmcnt(0)
	s_barrier
; template <bool SWAP>
; DI void gemm_tile(const bf16_t* __restrict__ A, int lda, const bf16_t* __restrict__ Bt, int ldb, int K, f32x16 (&acc)[2][2], bf16_t* As, bf16_t* Bs_unused) {
;     ...
;   const int lr = tid >> 3, lc = (tid & 7) * 8;
;   const bf16_t* ga = A + (size_t)lr * lda + lc;
;   const bf16_t* gb = Bt + (size_t)lr * ldb + lc;
;   u32x4 ra0[4], rb0[4], ra1[4], rb1[4];
;   auto load_stage = [&](u32x4 (&ra)[4], u32x4 (&rb)[4], int t) __attribute__((always_inline)) {
; #pragma unroll
;     for (int i = 0; i < 4; ++i) { ra[i] = *(const u32x4*)(ga + (size_t)(32 * i) * lda + t * 64); rb[i] = *(const u32x4*)(gb + (size_t)(32 * i) * ldb + t * 64); }
;   };
;   auto write_stage = [&](const u32x4 (&ra)[4], const u32x4 (&rb)[4], int buf) __attribute__((always_inline)) {
;     bf16_t* Ad = As + buf * 2 * GT_IMG; bf16_t* Bd = Ad + GT_IMG;
; #pragma unroll
;     ...
;   auto step = [&](int buf, u32x4 (&ra)[4], u32x4 (&rb)[4], bool do_write, bool do_load, int tload) __attribute__((always_inline)) {
;     const bf16_t* pa = As + buf * 2 * GT_IMG + pao; const bf16_t* pb = As + buf * 2 * GT_IMG + pbo;
;     bf16_t* Ad = As + (buf ^ 1) * 2 * GT_IMG; bf16_t* Bd = Ad + GT_IMG;
;     bf16x8 F0[4], F1[4];
;     frag_read(F0, pa, pb, 0);
;     __builtin_amdgcn_sched_barrier(0);
;     frag_read(F1, pa, pb, 16);
;     mfma4(F0);
;     __builtin_amdgcn_sched_barrier(0);
;     frag_read(F0, pa, pb, 32);
;     mfma4(F1);
;     if (do_write) {
; #pragma unroll
;       for (int i = 0; i < 4; ++i) *(u32x4*)(Ad + (lr + 32 * i) * 72 + lc) = ra[i];
;     }
;     __builtin_amdgcn_sched_barrier(0);
;     frag_read(F1, pa, pb, 48);
;     mfma4(F0);
;     if (do_write) {
; #pragma unroll
;       for (int i = 0; i < 4; ++i) *(u32x4*)(Bd + (lr + 32 * i) * 72 + lc) = rb[i];
;     }
;     __builtin_amdgcn_sched_barrier(0);
;     mfma4(F1);
;     if (do_load) load_stage(ra, rb, tload);
;     __builtin_amdgcn_sched_barrier(0);
;   };
;   const int nk = K >> 6;
;   load_stage(ra0, rb0, 0); load_stage(ra1, rb1, 1);
;   __syncthreads();
;   write_stage(ra0, rb0, 0);
;   load_stage(ra0, rb0, 2);
;   __syncthreads();
;   for (int kt = 0; kt < nk; kt += 2) {
;     step(0, ra1, rb1, true, kt + 3 < nk, kt + 3);
;     __syncthreads();
;     step(1, ra0, rb0, kt + 2 < nk, kt + 4 < nk, kt + 4);
;     __syncthreads();
	ds_read_b128 v[180:183], v102 offset:55296
	ds_read_b128 v[184:187], v102 offset:59904
	ds_read_b128 v[188:191], v101 offset:36864
	ds_read_b128 v[220:223], v101 offset:41472
	v_mfma_f32_32x32x16_bf16 v[48:63], v[76:79], v[64:67], v[48:63]
	v_mfma_f32_32x32x16_bf16 v[32:47], v[76:79], v[72:75], v[32:47]
	v_mfma_f32_32x32x16_bf16 v[0:15], v[80:83], v[64:67], v[0:15]
	v_mfma_f32_32x32x16_bf16 v[16:31], v[80:83], v[72:75], v[16:31]
	s_waitcnt lgkmcnt(1)
	v_mfma_f32_32x32x16_bf16 v[48:63], v[188:191], v[180:183], v[48:63]
	v_mfma_f32_32x32x16_bf16 v[32:47], v[188:191], v[184:187], v[32:47]
	s_waitcnt lgkmcnt(0)
	v_mfma_f32_32x32x16_bf16 v[0:15], v[220:223], v[180:183], v[0:15]
	ds_read_b128 v[64:67], v102 offset:55328
	ds_read_b128 v[72:75], v102 offset:59936
	ds_read_b128 v[80:83], v101 offset:36896
	ds_read_b128 v[84:87], v101 offset:41504
	v_mfma_f32_32x32x16_bf16 v[16:31], v[220:223], v[184:187], v[16:31]
	s_waitcnt lgkmcnt(1)
	v_mfma_f32_32x32x16_bf16 v[48:63], v[80:83], v[64:67], v[48:63]
	v_mfma_f32_32x32x16_bf16 v[32:47], v[80:83], v[72:75], v[32:47]
	s_waitcnt lgkmcnt(0)
	v_mfma_f32_32x32x16_bf16 v[0:15], v[84:87], v[64:67], v[0:15]
	v_mfma_f32_32x32x16_bf16 v[16:31], v[84:87], v[72:75], v[16:31]
	ds_read_b128 v[64:67], v101 offset:41536
	ds_read_b128 v[68:71], v102 offset:59968
	ds_read_b128 v[72:75], v102 offset:55360
	ds_read_b128 v[76:79], v101 offset:36928
	s_waitcnt lgkmcnt(0)
	v_mfma_f32_32x32x16_bf16 v[48:63], v[76:79], v[72:75], v[48:63]
	v_mfma_f32_32x32x16_bf16 v[32:47], v[76:79], v[68:71], v[32:47]
	v_mfma_f32_32x32x16_bf16 v[0:15], v[64:67], v[72:75], v[0:15]
	v_mfma_f32_32x32x16_bf16 v[16:31], v[64:67], v[68:71], v[16:31]
	ds_read_b128 v[64:67], v101 offset:41568
	ds_read_b128 v[68:71], v102 offset:60000
	ds_read_b128 v[72:75], v102 offset:55392
	ds_read_b128 v[76:79], v101 offset:36960
	s_waitcnt lgkmcnt(0)
	v_mfma_f32_32x32x16_bf16 v[48:63], v[76:79], v[72:75], v[48:63]
	v_mfma_f32_32x32x16_bf16 v[32:47], v[76:79], v[68:71], v[32:47]
	v_mfma_f32_32x32x16_bf16 v[0:15], v[64:67], v[72:75], v[0:15]
	v_mfma_f32_32x32x16_bf16 v[16:31], v[64:67], v[68:71], v[16:31]
	s_barrier
	s_mov_b64 s[8:9], 0
.LBB0_369:
	v_readlane_b32 s22, v231, 53
	s_andn2_b64 vcc, exec, s[8:9]
	v_readlane_b32 s23, v231, 54
	s_cbranch_vccnz .LBB0_371
	s_waitcnt lgkmcnt(0)
	s_nop 3
	v_mov_b32_e32 v4, v195
	s_nop 0
	v_ashrrev_i32_e32 v32, 3, v4
	v_ashrrev_i32_e32 v33, 31, v32
	v_lshlrev_b64 v[0:1], 11, v[32:33]
	v_lshlrev_b32_e32 v5, 4, v4
	v_lshl_add_u64 v[2:3], s[0:1], 0, v[0:1]
	v_and_b32_e32 v192, 0x70, v5
	v_lshl_add_u64 v[0:1], s[6:7], 0, v[0:1]
	v_lshl_add_u64 v[106:107], v[0:1], 0, v[192:193]
	v_lshrrev_b32_e32 v1, 2, v4
	v_and_b32_e32 v0, 31, v4
	v_and_b32_e32 v34, 8, v1
	v_lshrrev_b32_e32 v1, 1, v4
	v_and_or_b32 v0, v1, s80, v0
	v_mad_u64_u32 v[36:37], s[0:1], v0, s72, v[34:35]
	s_waitcnt vmcnt(0)
	v_lshl_add_u64 v[104:105], v[2:3], 0, v[192:193]
	s_mov_b32 s0, 0x10000
	v_add_co_u32_e32 v108, vcc, s0, v104
	v_and_b32_e32 v33, 0x5f, v4
	s_nop 0
	v_addc_co_u32_e32 v109, vcc, 0, v105, vcc
	v_add_co_u32_e32 v110, vcc, s0, v106
	s_mov_b32 s0, 0x20000
	s_nop 0
	v_addc_co_u32_e32 v111, vcc, 0, v107, vcc
	global_load_dwordx4 v[0:3], v[104:105], off
	global_load_dwordx4 v[4:7], v[106:107], off
	v_add_co_u32_e32 v112, vcc, s0, v104
	global_load_dwordx4 v[8:11], v[108:109], off
	global_load_dwordx4 v[12:15], v[110:111], off
	v_addc_co_u32_e32 v113, vcc, 0, v105, vcc
	v_add_co_u32_e32 v114, vcc, s0, v106
	s_mov_b32 s0, 0x30000
	s_nop 0
	v_addc_co_u32_e32 v115, vcc, 0, v107, vcc
	global_load_dwordx4 v[16:19], v[112:113], off
	global_load_dwordx4 v[20:23], v[114:115], off
	v_add_co_u32_e32 v116, vcc, s0, v104
	v_mul_lo_u32 v32, v32, s71
	s_nop 0
	v_addc_co_u32_e32 v117, vcc, 0, v105, vcc
	global_load_dwordx4 v[24:27], v[116:117], off
	v_add_co_u32_e32 v118, vcc, s0, v106
	v_add3_u32 v125, 32, v32, v192
	s_nop 0
	v_addc_co_u32_e32 v119, vcc, 0, v107, vcc
	global_load_dwordx4 v[28:31], v[118:119], off
	global_load_dwordx4 v[128:131], v[104:105], off offset:128
	global_load_dwordx4 v[80:83], v[106:107], off offset:128
	global_load_dwordx4 v[132:135], v[108:109], off offset:128
	global_load_dwordx4 v[92:95], v[110:111], off offset:128
	global_load_dwordx4 v[136:139], v[112:113], off offset:128
	global_load_dwordx4 v[140:143], v[114:115], off offset:128
	global_load_dwordx4 v[144:147], v[116:117], off offset:128
	global_load_dwordx4 v[148:151], v[118:119], off offset:128
	s_waitcnt lgkmcnt(0)
	s_barrier
	v_lshl_add_u32 v124, v36, 1, 32
	v_add_u32_e32 v127, 0xd800, v125
	s_waitcnt vmcnt(15)
	ds_write_b128 v125, v[0:3]
	s_waitcnt vmcnt(14)
	ds_write_b128 v125, v[4:7] offset:18432
	s_waitcnt vmcnt(13)
	ds_write_b128 v125, v[8:11] offset:4608
	s_waitcnt vmcnt(12)
	ds_write_b128 v125, v[12:15] offset:23040
	s_waitcnt vmcnt(11)
	ds_write_b128 v125, v[16:19] offset:9216
	s_waitcnt vmcnt(10)
	ds_write_b128 v125, v[20:23] offset:27648
	s_waitcnt vmcnt(9)
	ds_write_b128 v125, v[24:27] offset:13824
	s_waitcnt vmcnt(8)
	ds_write_b128 v125, v[28:31] offset:32256
	global_load_dwordx4 v[84:87], v[104:105], off offset:256
	global_load_dwordx4 v[64:67], v[106:107], off offset:256
	global_load_dwordx4 v[88:91], v[108:109], off offset:256
	global_load_dwordx4 v[68:71], v[110:111], off offset:256
	global_load_dwordx4 v[96:99], v[112:113], off offset:256
	global_load_dwordx4 v[72:75], v[114:115], off offset:256
	global_load_dwordx4 v[100:103], v[116:117], off offset:256
	global_load_dwordx4 v[76:79], v[118:119], off offset:256
	v_mad_u32_u24 v0, v33, s72, v34
	s_waitcnt lgkmcnt(0)
	s_barrier
; template <bool SWAP>
; DI void gemm_tile(const bf16_t* __restrict__ A, int lda, const bf16_t* __restrict__ Bt, int ldb, int K, f32x16 (&acc)[2][2], bf16_t* As, bf16_t* Bs_unused) {
;     ...
;   auto step = [&](int buf, u32x4 (&ra)[4], u32x4 (&rb)[4], bool do_write, bool do_load, int tload) __attribute__((always_inline)) {
;     const bf16_t* pa = As + buf * 2 * GT_IMG + pao; const bf16_t* pb = As + buf * 2 * GT_IMG + pbo;
;     bf16_t* Ad = As + (buf ^ 1) * 2 * GT_IMG; bf16_t* Bd = Ad + GT_IMG;
;     bf16x8 F0[4], F1[4];
;     frag_read(F0, pa, pb, 0);
;     __builtin_amdgcn_sched_barrier(0);
;     frag_read(F1, pa, pb, 16);
;     mfma4(F0);
;     __builtin_amdgcn_sched_barrier(0);
;     frag_read(F0, pa, pb, 32);
;     mfma4(F1);
;     if (do_write) {
; #pragma unroll
;       for (int i = 0; i < 4; ++i) *(u32x4*)(Ad + (lr + 32 * i) * 72 + lc) = ra[i];
;     }
;     __builtin_amdgcn_sched_barrier(0);
;     frag_read(F1, pa, pb, 48);
;     mfma4(F0);
;     if (do_write) {
; #pragma unroll
;       for (int i = 0; i < 4; ++i) *(u32x4*)(Bd + (lr + 32 * i) * 72 + lc) = rb[i];
;     }
;     __builtin_amdgcn_sched_barrier(0);
;     mfma4(F1);
;     if (do_load) load_stage(ra, rb, tload);
;     __builtin_amdgcn_sched_barrier(0);
;   };
;   const int nk = K >> 6;
;   load_stage(ra0, rb0, 0); load_stage(ra1, rb1, 1);
;   __syncthreads();
;   write_stage(ra0, rb0, 0);
;   load_stage(ra0, rb0, 2);
;   __syncthreads();
;   for (int kt = 0; kt < nk; kt += 2) {
;     step(0, ra1, rb1, true, kt + 3 < nk, kt + 3);
;     __syncthreads();
;     step(1, ra0, rb0, kt + 2 < nk, kt + 4 < nk, kt + 4);
;     __syncthreads();
	v_lshl_add_u32 v126, v0, 1, 32
	ds_read_b128 v[0:3], v124
	ds_read_b128 v[4:7], v126 offset:18432
	ds_read_b128 v[16:19], v126 offset:23040
	ds_read_b128 v[20:23], v124 offset:4608
	s_waitcnt lgkmcnt(2)
	v_mfma_f32_32x32x16_bf16 v[48:63], v[4:7], v[0:3], 0
	ds_read_b128 v[152:155], v126 offset:18464
	ds_read_b128 v[156:159], v126 offset:23072
	ds_read_b128 v[160:163], v124 offset:32
	ds_read_b128 v[164:167], v124 offset:4640
	s_waitcnt lgkmcnt(5)
	v_mfma_f32_32x32x16_bf16 v[32:47], v[16:19], v[0:3], 0
	s_waitcnt lgkmcnt(4)
	v_mfma_f32_32x32x16_bf16 v[0:15], v[4:7], v[20:23], 0
	v_mfma_f32_32x32x16_bf16 v[16:31], v[16:19], v[20:23], 0
	s_waitcnt lgkmcnt(1)
	v_mfma_f32_32x32x16_bf16 v[48:63], v[152:155], v[160:163], v[48:63]
	v_mfma_f32_32x32x16_bf16 v[32:47], v[156:159], v[160:163], v[32:47]
	s_waitcnt lgkmcnt(0)
	v_mfma_f32_32x32x16_bf16 v[0:15], v[152:155], v[164:167], v[0:15]
	ds_read_b128 v[152:155], v126 offset:18496
	ds_read_b128 v[160:163], v126 offset:23104
	ds_read_b128 v[168:171], v124 offset:64
	ds_read_b128 v[172:175], v124 offset:4672
	s_waitcnt vmcnt(15)
	ds_write_b128 v125, v[128:131] offset:36864
	s_waitcnt vmcnt(13)
	ds_write_b128 v125, v[132:135] offset:41472
	s_waitcnt vmcnt(11)
	ds_write_b128 v125, v[136:139] offset:46080
	s_waitcnt vmcnt(9)
	ds_write_b128 v125, v[144:147] offset:50688
	v_mfma_f32_32x32x16_bf16 v[16:31], v[156:159], v[164:167], v[16:31]
	s_waitcnt lgkmcnt(5)
	v_mfma_f32_32x32x16_bf16 v[48:63], v[152:155], v[168:171], v[48:63]
	ds_read_b128 v[128:131], v126 offset:18528
	ds_read_b128 v[132:135], v126 offset:23136
	ds_read_b128 v[136:139], v124 offset:96
	ds_read_b128 v[144:147], v124 offset:4704
	ds_write_b128 v125, v[80:83] offset:55296
	ds_write_b128 v125, v[92:95] offset:59904
	ds_write_b128 v125, v[140:143] offset:64512
	s_waitcnt vmcnt(8)
	ds_write_b128 v127, v[148:151] offset:13824
	v_mfma_f32_32x32x16_bf16 v[32:47], v[160:163], v[168:171], v[32:47]
	s_waitcnt lgkmcnt(12)
	v_mfma_f32_32x32x16_bf16 v[0:15], v[152:155], v[172:175], v[0:15]
	v_mfma_f32_32x32x16_bf16 v[16:31], v[160:163], v[172:175], v[16:31]
	s_waitcnt lgkmcnt(0)
	s_barrier
	ds_read_b128 v[152:155], v126 offset:55296
	ds_read_b128 v[156:159], v126 offset:59904
	ds_read_b128 v[160:163], v124 offset:36864
	ds_read_b128 v[164:167], v124 offset:41472
	v_mfma_f32_32x32x16_bf16 v[48:63], v[128:131], v[136:139], v[48:63]
	v_mfma_f32_32x32x16_bf16 v[32:47], v[132:135], v[136:139], v[32:47]
	v_mfma_f32_32x32x16_bf16 v[0:15], v[128:131], v[144:147], v[0:15]
	v_mfma_f32_32x32x16_bf16 v[16:31], v[132:135], v[144:147], v[16:31]
	global_load_dwordx4 v[80:83], v[104:105], off offset:384
	global_load_dwordx4 v[92:95], v[106:107], off offset:384
	global_load_dwordx4 v[128:131], v[108:109], off offset:384
	global_load_dwordx4 v[132:135], v[110:111], off offset:384
	global_load_dwordx4 v[136:139], v[112:113], off offset:384
	global_load_dwordx4 v[140:143], v[114:115], off offset:384
	global_load_dwordx4 v[144:147], v[116:117], off offset:384
	global_load_dwordx4 v[148:151], v[118:119], off offset:384
	s_waitcnt lgkmcnt(1)
	v_mfma_f32_32x32x16_bf16 v[48:63], v[152:155], v[160:163], v[48:63]
	v_mfma_f32_32x32x16_bf16 v[32:47], v[156:159], v[160:163], v[32:47]
	s_waitcnt lgkmcnt(0)
	v_mfma_f32_32x32x16_bf16 v[0:15], v[152:155], v[164:167], v[0:15]
	ds_read_b128 v[152:155], v126 offset:55328
	ds_read_b128 v[160:163], v126 offset:59936
	ds_read_b128 v[168:171], v124 offset:36896
	ds_read_b128 v[172:175], v124 offset:41504
	v_mfma_f32_32x32x16_bf16 v[16:31], v[156:159], v[164:167], v[16:31]
	s_waitcnt lgkmcnt(1)
	v_mfma_f32_32x32x16_bf16 v[48:63], v[152:155], v[168:171], v[48:63]
	v_mfma_f32_32x32x16_bf16 v[32:47], v[160:163], v[168:171], v[32:47]
	s_waitcnt lgkmcnt(0)
	v_mfma_f32_32x32x16_bf16 v[0:15], v[152:155], v[172:175], v[0:15]
	ds_read_b128 v[152:155], v126 offset:55360
	ds_read_b128 v[156:159], v126 offset:59968
	ds_read_b128 v[164:167], v124 offset:36928
	ds_read_b128 v[168:171], v124 offset:41536
	s_waitcnt vmcnt(15)
	ds_write_b128 v125, v[84:87]
	s_waitcnt vmcnt(13)
	ds_write_b128 v125, v[88:91] offset:4608
	s_waitcnt vmcnt(11)
	ds_write_b128 v125, v[96:99] offset:9216
	s_waitcnt vmcnt(9)
	ds_write_b128 v125, v[100:103] offset:13824
	v_mfma_f32_32x32x16_bf16 v[16:31], v[160:163], v[172:175], v[16:31]
	s_waitcnt lgkmcnt(5)
	v_mfma_f32_32x32x16_bf16 v[48:63], v[152:155], v[164:167], v[48:63]
	ds_read_b128 v[84:87], v126 offset:55392
	ds_read_b128 v[88:91], v126 offset:60000
	ds_read_b128 v[96:99], v124 offset:36960
	ds_read_b128 v[100:103], v124 offset:41568
	ds_write_b128 v125, v[64:67] offset:18432
	ds_write_b128 v125, v[68:71] offset:23040
	ds_write_b128 v125, v[72:75] offset:27648
	s_waitcnt vmcnt(8)
	ds_write_b128 v125, v[76:79] offset:32256
	v_mfma_f32_32x32x16_bf16 v[32:47], v[156:159], v[164:167], v[32:47]
	s_waitcnt lgkmcnt(12)
	v_mfma_f32_32x32x16_bf16 v[0:15], v[152:155], v[168:171], v[0:15]
	v_mfma_f32_32x32x16_bf16 v[16:31], v[156:159], v[168:171], v[16:31]
	s_waitcnt lgkmcnt(0)
	s_barrier
; template <bool SWAP>
; DI void gemm_tile(const bf16_t* __restrict__ A, int lda, const bf16_t* __restrict__ Bt, int ldb, int K, f32x16 (&acc)[2][2], bf16_t* As, bf16_t* Bs_unused) {
;     ...
;   auto step = [&](int buf, u32x4 (&ra)[4], u32x4 (&rb)[4], bool do_write, bool do_load, int tload) __attribute__((always_inline)) {
;     const bf16_t* pa = As + buf * 2 * GT_IMG + pao; const bf16_t* pb = As + buf * 2 * GT_IMG + pbo;
;     bf16_t* Ad = As + (buf ^ 1) * 2 * GT_IMG; bf16_t* Bd = Ad + GT_IMG;
;     bf16x8 F0[4], F1[4];
;     frag_read(F0, pa, pb, 0);
;     __builtin_amdgcn_sched_barrier(0);
;     frag_read(F1, pa, pb, 16);
;     mfma4(F0);
;     __builtin_amdgcn_sched_barrier(0);
;     frag_read(F0, pa, pb, 32);
;     mfma4(F1);
;     if (do_write) {
; #pragma unroll
;       for (int i = 0; i < 4; ++i) *(u32x4*)(Ad + (lr + 32 * i) * 72 + lc) = ra[i];
;     }
;     __builtin_amdgcn_sched_barrier(0);
;     frag_read(F1, pa, pb, 48);
;     mfma4(F0);
;     if (do_write) {
; #pragma unroll
;       for (int i = 0; i < 4; ++i) *(u32x4*)(Bd + (lr + 32 * i) * 72 + lc) = rb[i];
;     }
;     __builtin_amdgcn_sched_barrier(0);
;     mfma4(F1);
;     if (do_load) load_stage(ra, rb, tload);
;     __builtin_amdgcn_sched_barrier(0);
;   };
;   const int nk = K >> 6;
;   load_stage(ra0, rb0, 0); load_stage(ra1, rb1, 1);
;   __syncthreads();
;   write_stage(ra0, rb0, 0);
;   load_stage(ra0, rb0, 2);
;   __syncthreads();
;   for (int kt = 0; kt < nk; kt += 2) {
;     step(0, ra1, rb1, true, kt + 3 < nk, kt + 3);
;     __syncthreads();
;     step(1, ra0, rb0, kt + 2 < nk, kt + 4 < nk, kt + 4);
;     __syncthreads();
	ds_read_b128 v[152:155], v126 offset:18432
	ds_read_b128 v[156:159], v126 offset:23040
	ds_read_b128 v[160:163], v124
	ds_read_b128 v[164:167], v124 offset:4608
	v_mfma_f32_32x32x16_bf16 v[48:63], v[84:87], v[96:99], v[48:63]
	v_mfma_f32_32x32x16_bf16 v[32:47], v[88:91], v[96:99], v[32:47]
	v_mfma_f32_32x32x16_bf16 v[0:15], v[84:87], v[100:103], v[0:15]
	v_mfma_f32_32x32x16_bf16 v[16:31], v[88:91], v[100:103], v[16:31]
	global_load_dwordx4 v[64:67], v[104:105], off offset:512
	global_load_dwordx4 v[68:71], v[106:107], off offset:512
	global_load_dwordx4 v[72:75], v[108:109], off offset:512
	global_load_dwordx4 v[76:79], v[110:111], off offset:512
	global_load_dwordx4 v[84:87], v[112:113], off offset:512
	global_load_dwordx4 v[88:91], v[114:115], off offset:512
	global_load_dwordx4 v[96:99], v[116:117], off offset:512
	global_load_dwordx4 v[100:103], v[118:119], off offset:512
	s_waitcnt lgkmcnt(1)
	v_mfma_f32_32x32x16_bf16 v[48:63], v[152:155], v[160:163], v[48:63]
	v_mfma_f32_32x32x16_bf16 v[32:47], v[156:159], v[160:163], v[32:47]
	s_waitcnt lgkmcnt(0)
	v_mfma_f32_32x32x16_bf16 v[0:15], v[152:155], v[164:167], v[0:15]
	ds_read_b128 v[152:155], v126 offset:18464
	ds_read_b128 v[160:163], v126 offset:23072
	ds_read_b128 v[168:171], v124 offset:32
	ds_read_b128 v[172:175], v124 offset:4640
	v_mfma_f32_32x32x16_bf16 v[16:31], v[156:159], v[164:167], v[16:31]
	s_waitcnt lgkmcnt(1)
	v_mfma_f32_32x32x16_bf16 v[48:63], v[152:155], v[168:171], v[48:63]
	v_mfma_f32_32x32x16_bf16 v[32:47], v[160:163], v[168:171], v[32:47]
	s_waitcnt lgkmcnt(0)
	v_mfma_f32_32x32x16_bf16 v[0:15], v[152:155], v[172:175], v[0:15]
	ds_read_b128 v[152:155], v126 offset:18496
	ds_read_b128 v[156:159], v126 offset:23104
	ds_read_b128 v[164:167], v124 offset:64
	ds_read_b128 v[168:171], v124 offset:4672
	s_waitcnt vmcnt(15)
	ds_write_b128 v125, v[80:83] offset:36864
	s_waitcnt vmcnt(13)
	ds_write_b128 v125, v[128:131] offset:41472
	s_waitcnt vmcnt(11)
	ds_write_b128 v125, v[136:139] offset:46080
	s_waitcnt vmcnt(9)
	ds_write_b128 v125, v[144:147] offset:50688
	v_mfma_f32_32x32x16_bf16 v[16:31], v[160:163], v[172:175], v[16:31]
	s_waitcnt lgkmcnt(5)
	v_mfma_f32_32x32x16_bf16 v[48:63], v[152:155], v[164:167], v[48:63]
	ds_read_b128 v[80:83], v126 offset:18528
	ds_read_b128 v[128:131], v126 offset:23136
	ds_read_b128 v[136:139], v124 offset:96
	ds_read_b128 v[144:147], v124 offset:4704
	ds_write_b128 v125, v[92:95] offset:55296
	ds_write_b128 v125, v[132:135] offset:59904
	ds_write_b128 v125, v[140:143] offset:64512
	s_waitcnt vmcnt(8)
	ds_write_b128 v127, v[148:151] offset:13824
	v_mfma_f32_32x32x16_bf16 v[32:47], v[156:159], v[164:167], v[32:47]
	s_waitcnt lgkmcnt(12)
	v_mfma_f32_32x32x16_bf16 v[0:15], v[152:155], v[168:171], v[0:15]
	v_mfma_f32_32x32x16_bf16 v[16:31], v[156:159], v[168:171], v[16:31]
	s_waitcnt lgkmcnt(0)
	s_barrier
	ds_read_b128 v[152:155], v126 offset:55296
	ds_read_b128 v[156:159], v126 offset:59904
	ds_read_b128 v[160:163], v124 offset:36864
	ds_read_b128 v[164:167], v124 offset:41472
	v_mfma_f32_32x32x16_bf16 v[48:63], v[80:83], v[136:139], v[48:63]
	v_mfma_f32_32x32x16_bf16 v[32:47], v[128:131], v[136:139], v[32:47]
	v_mfma_f32_32x32x16_bf16 v[0:15], v[80:83], v[144:147], v[0:15]
	v_mfma_f32_32x32x16_bf16 v[16:31], v[128:131], v[144:147], v[16:31]
	global_load_dwordx4 v[80:83], v[104:105], off offset:640
	global_load_dwordx4 v[92:95], v[106:107], off offset:640
	global_load_dwordx4 v[128:131], v[108:109], off offset:640
	global_load_dwordx4 v[132:135], v[110:111], off offset:640
	global_load_dwordx4 v[136:139], v[112:113], off offset:640
	global_load_dwordx4 v[140:143], v[114:115], off offset:640
	global_load_dwordx4 v[144:147], v[116:117], off offset:640
	global_load_dwordx4 v[148:151], v[118:119], off offset:640
	s_waitcnt lgkmcnt(1)
	v_mfma_f32_32x32x16_bf16 v[48:63], v[152:155], v[160:163], v[48:63]
	v_mfma_f32_32x32x16_bf16 v[32:47], v[156:159], v[160:163], v[32:47]
	s_waitcnt lgkmcnt(0)
	v_mfma_f32_32x32x16_bf16 v[0:15], v[152:155], v[164:167], v[0:15]
	ds_read_b128 v[152:155], v126 offset:55328
	ds_read_b128 v[160:163], v126 offset:59936
	ds_read_b128 v[168:171], v124 offset:36896
	ds_read_b128 v[172:175], v124 offset:41504
	v_mfma_f32_32x32x16_bf16 v[16:31], v[156:159], v[164:167], v[16:31]
	s_waitcnt lgkmcnt(1)
	v_mfma_f32_32x32x16_bf16 v[48:63], v[152:155], v[168:171], v[48:63]
	v_mfma_f32_32x32x16_bf16 v[32:47], v[160:163], v[168:171], v[32:47]
	s_waitcnt lgkmcnt(0)
	v_mfma_f32_32x32x16_bf16 v[0:15], v[152:155], v[172:175], v[0:15]
	ds_read_b128 v[152:155], v126 offset:55360
	ds_read_b128 v[156:159], v126 offset:59968
	ds_read_b128 v[164:167], v124 offset:36928
	ds_read_b128 v[168:171], v124 offset:41536
	s_waitcnt vmcnt(15)
	ds_write_b128 v125, v[64:67]
	s_waitcnt vmcnt(13)
	ds_write_b128 v125, v[72:75] offset:4608
	s_waitcnt vmcnt(11)
	ds_write_b128 v125, v[84:87] offset:9216
	s_waitcnt vmcnt(9)
	ds_write_b128 v125, v[96:99] offset:13824
	v_mfma_f32_32x32x16_bf16 v[16:31], v[160:163], v[172:175], v[16:31]
	s_waitcnt lgkmcnt(5)
	v_mfma_f32_32x32x16_bf16 v[48:63], v[152:155], v[164:167], v[48:63]
	ds_read_b128 v[64:67], v126 offset:55392
	ds_read_b128 v[72:75], v126 offset:60000
	ds_read_b128 v[84:87], v124 offset:36960
	ds_read_b128 v[96:99], v124 offset:41568
	ds_write_b128 v125, v[68:71] offset:18432
	ds_write_b128 v125, v[76:79] offset:23040
	ds_write_b128 v125, v[88:91] offset:27648
	s_waitcnt vmcnt(8)
	ds_write_b128 v125, v[100:103] offset:32256
	v_mfma_f32_32x32x16_bf16 v[32:47], v[156:159], v[164:167], v[32:47]
	s_waitcnt lgkmcnt(12)
	v_mfma_f32_32x32x16_bf16 v[0:15], v[152:155], v[168:171], v[0:15]
	v_mfma_f32_32x32x16_bf16 v[16:31], v[156:159], v[168:171], v[16:31]
	s_waitcnt lgkmcnt(0)
	s_barrier
; template <bool SWAP>
; DI void gemm_tile(const bf16_t* __restrict__ A, int lda, const bf16_t* __restrict__ Bt, int ldb, int K, f32x16 (&acc)[2][2], bf16_t* As, bf16_t* Bs_unused) {
;     ...
;   auto step = [&](int buf, u32x4 (&ra)[4], u32x4 (&rb)[4], bool do_write, bool do_load, int tload) __attribute__((always_inline)) {
;     const bf16_t* pa = As + buf * 2 * GT_IMG + pao; const bf16_t* pb = As + buf * 2 * GT_IMG + pbo;
;     bf16_t* Ad = As + (buf ^ 1) * 2 * GT_IMG; bf16_t* Bd = Ad + GT_IMG;
;     bf16x8 F0[4], F1[4];
;     frag_read(F0, pa, pb, 0);
;     __builtin_amdgcn_sched_barrier(0);
;     frag_read(F1, pa, pb, 16);
;     mfma4(F0);
;     __builtin_amdgcn_sched_barrier(0);
;     frag_read(F0, pa, pb, 32);
;     mfma4(F1);
;     if (do_write) {
; #pragma unroll
;       for (int i = 0; i < 4; ++i) *(u32x4*)(Ad + (lr + 32 * i) * 72 + lc) = ra[i];
;     }
;     __builtin_amdgcn_sched_barrier(0);
;     frag_read(F1, pa, pb, 48);
;     mfma4(F0);
;     if (do_write) {
; #pragma unroll
;       for (int i = 0; i < 4; ++i) *(u32x4*)(Bd + (lr + 32 * i) * 72 + lc) = rb[i];
;     }
;     __builtin_amdgcn_sched_barrier(0);
;     mfma4(F1);
;     if (do_load) load_stage(ra, rb, tload);
;     __builtin_amdgcn_sched_barrier(0);
;   };
;   const int nk = K >> 6;
;   load_stage(ra0, rb0, 0); load_stage(ra1, rb1, 1);
;   __syncthreads();
;   write_stage(ra0, rb0, 0);
;   load_stage(ra0, rb0, 2);
;   __syncthreads();
;   for (int kt = 0; kt < nk; kt += 2) {
;     step(0, ra1, rb1, true, kt + 3 < nk, kt + 3);
;     __syncthreads();
;     step(1, ra0, rb0, kt + 2 < nk, kt + 4 < nk, kt + 4);
;     __syncthreads();
	ds_read_b128 v[152:155], v126 offset:18432
	ds_read_b128 v[156:159], v126 offset:23040
	ds_read_b128 v[160:163], v124
	ds_read_b128 v[164:167], v124 offset:4608
	v_mfma_f32_32x32x16_bf16 v[48:63], v[64:67], v[84:87], v[48:63]
	v_mfma_f32_32x32x16_bf16 v[32:47], v[72:75], v[84:87], v[32:47]
	v_mfma_f32_32x32x16_bf16 v[0:15], v[64:67], v[96:99], v[0:15]
	v_mfma_f32_32x32x16_bf16 v[16:31], v[72:75], v[96:99], v[16:31]
	global_load_dwordx4 v[64:67], v[104:105], off offset:768
	global_load_dwordx4 v[68:71], v[106:107], off offset:768
	global_load_dwordx4 v[72:75], v[108:109], off offset:768
	global_load_dwordx4 v[76:79], v[110:111], off offset:768
	global_load_dwordx4 v[84:87], v[112:113], off offset:768
	global_load_dwordx4 v[88:91], v[114:115], off offset:768
	global_load_dwordx4 v[96:99], v[116:117], off offset:768
	global_load_dwordx4 v[100:103], v[118:119], off offset:768
	s_waitcnt lgkmcnt(1)
	v_mfma_f32_32x32x16_bf16 v[48:63], v[152:155], v[160:163], v[48:63]
	v_mfma_f32_32x32x16_bf16 v[32:47], v[156:159], v[160:163], v[32:47]
	s_waitcnt lgkmcnt(0)
	v_mfma_f32_32x32x16_bf16 v[0:15], v[152:155], v[164:167], v[0:15]
	ds_read_b128 v[152:155], v126 offset:18464
	ds_read_b128 v[160:163], v126 offset:23072
	ds_read_b128 v[168:171], v124 offset:32
	ds_read_b128 v[172:175], v124 offset:4640
	v_mfma_f32_32x32x16_bf16 v[16:31], v[156:159], v[164:167], v[16:31]
	s_waitcnt lgkmcnt(1)
	v_mfma_f32_32x32x16_bf16 v[48:63], v[152:155], v[168:171], v[48:63]
	v_mfma_f32_32x32x16_bf16 v[32:47], v[160:163], v[168:171], v[32:47]
	s_waitcnt lgkmcnt(0)
	v_mfma_f32_32x32x16_bf16 v[0:15], v[152:155], v[172:175], v[0:15]
	ds_read_b128 v[152:155], v126 offset:18496
	ds_read_b128 v[156:159], v126 offset:23104
	ds_read_b128 v[164:167], v124 offset:64
	ds_read_b128 v[168:171], v124 offset:4672
	s_waitcnt vmcnt(15)
	ds_write_b128 v125, v[80:83] offset:36864
	s_waitcnt vmcnt(13)
	ds_write_b128 v125, v[128:131] offset:41472
	s_waitcnt vmcnt(11)
	ds_write_b128 v125, v[136:139] offset:46080
	s_waitcnt vmcnt(9)
	ds_write_b128 v125, v[144:147] offset:50688
	v_mfma_f32_32x32x16_bf16 v[16:31], v[160:163], v[172:175], v[16:31]
	s_waitcnt lgkmcnt(5)
	v_mfma_f32_32x32x16_bf16 v[48:63], v[152:155], v[164:167], v[48:63]
	ds_read_b128 v[80:83], v126 offset:18528
	ds_read_b128 v[128:131], v126 offset:23136
	ds_read_b128 v[136:139], v124 offset:96
	ds_read_b128 v[144:147], v124 offset:4704
	ds_write_b128 v125, v[92:95] offset:55296
	ds_write_b128 v125, v[132:135] offset:59904
	ds_write_b128 v125, v[140:143] offset:64512
	s_waitcnt vmcnt(8)
	ds_write_b128 v127, v[148:151] offset:13824
	v_mfma_f32_32x32x16_bf16 v[32:47], v[156:159], v[164:167], v[32:47]
	s_waitcnt lgkmcnt(12)
	v_mfma_f32_32x32x16_bf16 v[0:15], v[152:155], v[168:171], v[0:15]
	v_mfma_f32_32x32x16_bf16 v[16:31], v[156:159], v[168:171], v[16:31]
	s_waitcnt lgkmcnt(0)
	s_barrier
	ds_read_b128 v[152:155], v126 offset:55296
	ds_read_b128 v[156:159], v126 offset:59904
	ds_read_b128 v[160:163], v124 offset:36864
	ds_read_b128 v[164:167], v124 offset:41472
	v_mfma_f32_32x32x16_bf16 v[48:63], v[80:83], v[136:139], v[48:63]
	v_mfma_f32_32x32x16_bf16 v[32:47], v[128:131], v[136:139], v[32:47]
	v_mfma_f32_32x32x16_bf16 v[0:15], v[80:83], v[144:147], v[0:15]
	v_mfma_f32_32x32x16_bf16 v[16:31], v[128:131], v[144:147], v[16:31]
	global_load_dwordx4 v[80:83], v[104:105], off offset:896
	global_load_dwordx4 v[92:95], v[106:107], off offset:896
	global_load_dwordx4 v[128:131], v[108:109], off offset:896
	global_load_dwordx4 v[132:135], v[110:111], off offset:896
	global_load_dwordx4 v[136:139], v[112:113], off offset:896
	global_load_dwordx4 v[140:143], v[114:115], off offset:896
	global_load_dwordx4 v[144:147], v[116:117], off offset:896
	global_load_dwordx4 v[148:151], v[118:119], off offset:896
	s_waitcnt lgkmcnt(1)
	v_mfma_f32_32x32x16_bf16 v[48:63], v[152:155], v[160:163], v[48:63]
	v_mfma_f32_32x32x16_bf16 v[32:47], v[156:159], v[160:163], v[32:47]
	s_waitcnt lgkmcnt(0)
	v_mfma_f32_32x32x16_bf16 v[0:15], v[152:155], v[164:167], v[0:15]
	ds_read_b128 v[152:155], v126 offset:55328
	ds_read_b128 v[160:163], v126 offset:59936
	ds_read_b128 v[168:171], v124 offset:36896
	ds_read_b128 v[172:175], v124 offset:41504
	v_mfma_f32_32x32x16_bf16 v[16:31], v[156:159], v[164:167], v[16:31]
	s_waitcnt lgkmcnt(1)
	v_mfma_f32_32x32x16_bf16 v[48:63], v[152:155], v[168:171], v[48:63]
	v_mfma_f32_32x32x16_bf16 v[32:47], v[160:163], v[168:171], v[32:47]
	s_waitcnt lgkmcnt(0)
	v_mfma_f32_32x32x16_bf16 v[0:15], v[152:155], v[172:175], v[0:15]
	ds_read_b128 v[152:155], v126 offset:55360
	ds_read_b128 v[156:159], v126 offset:59968
	ds_read_b128 v[164:167], v124 offset:36928
	ds_read_b128 v[168:171], v124 offset:41536
	s_waitcnt vmcnt(15)
	ds_write_b128 v125, v[64:67]
	s_waitcnt vmcnt(13)
	ds_write_b128 v125, v[72:75] offset:4608
	s_waitcnt vmcnt(11)
	ds_write_b128 v125, v[84:87] offset:9216
	s_waitcnt vmcnt(9)
	ds_write_b128 v125, v[96:99] offset:13824
	v_mfma_f32_32x32x16_bf16 v[16:31], v[160:163], v[172:175], v[16:31]
	s_waitcnt lgkmcnt(5)
	v_mfma_f32_32x32x16_bf16 v[48:63], v[152:155], v[164:167], v[48:63]
	ds_read_b128 v[64:67], v126 offset:55392
	ds_read_b128 v[72:75], v126 offset:60000
	ds_read_b128 v[84:87], v124 offset:36960
	ds_read_b128 v[96:99], v124 offset:41568
	ds_write_b128 v125, v[68:71] offset:18432
	ds_write_b128 v125, v[76:79] offset:23040
	ds_write_b128 v125, v[88:91] offset:27648
	s_waitcnt vmcnt(8)
	ds_write_b128 v125, v[100:103] offset:32256
	v_mfma_f32_32x32x16_bf16 v[32:47], v[156:159], v[164:167], v[32:47]
	s_waitcnt lgkmcnt(12)
	v_mfma_f32_32x32x16_bf16 v[0:15], v[152:155], v[168:171], v[0:15]
	v_mfma_f32_32x32x16_bf16 v[16:31], v[156:159], v[168:171], v[16:31]
	s_waitcnt lgkmcnt(0)
	s_barrier
; template <bool SWAP>
; DI void gemm_tile(const bf16_t* __restrict__ A, int lda, const bf16_t* __restrict__ Bt, int ldb, int K, f32x16 (&acc)[2][2], bf16_t* As, bf16_t* Bs_unused) {
;     ...
;   auto step = [&](int buf, u32x4 (&ra)[4], u32x4 (&rb)[4], bool do_write, bool do_load, int tload) __attribute__((always_inline)) {
;     const bf16_t* pa = As + buf * 2 * GT_IMG + pao; const bf16_t* pb = As + buf * 2 * GT_IMG + pbo;
;     bf16_t* Ad = As + (buf ^ 1) * 2 * GT_IMG; bf16_t* Bd = Ad + GT_IMG;
;     bf16x8 F0[4], F1[4];
;     frag_read(F0, pa, pb, 0);
;     __builtin_amdgcn_sched_barrier(0);
;     frag_read(F1, pa, pb, 16);
;     mfma4(F0);
;     __builtin_amdgcn_sched_barrier(0);
;     frag_read(F0, pa, pb, 32);
;     mfma4(F1);
;     if (do_write) {
; #pragma unroll
;       for (int i = 0; i < 4; ++i) *(u32x4*)(Ad + (lr + 32 * i) * 72 + lc) = ra[i];
;     }
;     __builtin_amdgcn_sched_barrier(0);
;     frag_read(F1, pa, pb, 48);
;     mfma4(F0);
;     if (do_write) {
; #pragma unroll
;       for (int i = 0; i < 4; ++i) *(u32x4*)(Bd + (lr + 32 * i) * 72 + lc) = rb[i];
;     }
;     __builtin_amdgcn_sched_barrier(0);
;     mfma4(F1);
;     if (do_load) load_stage(ra, rb, tload);
;     __builtin_amdgcn_sched_barrier(0);
;   };
;   const int nk = K >> 6;
;   load_stage(ra0, rb0, 0); load_stage(ra1, rb1, 1);
;   __syncthreads();
;   write_stage(ra0, rb0, 0);
;   load_stage(ra0, rb0, 2);
;   __syncthreads();
;   for (int kt = 0; kt < nk; kt += 2) {
;     step(0, ra1, rb1, true, kt + 3 < nk, kt + 3);
;     __syncthreads();
;     step(1, ra0, rb0, kt + 2 < nk, kt + 4 < nk, kt + 4);
;     __syncthreads();
	ds_read_b128 v[152:155], v126 offset:18432
	ds_read_b128 v[156:159], v126 offset:23040
	ds_read_b128 v[160:163], v124
	ds_read_b128 v[164:167], v124 offset:4608
	v_mfma_f32_32x32x16_bf16 v[48:63], v[64:67], v[84:87], v[48:63]
	v_mfma_f32_32x32x16_bf16 v[32:47], v[72:75], v[84:87], v[32:47]
	v_mfma_f32_32x32x16_bf16 v[0:15], v[64:67], v[96:99], v[0:15]
	v_mfma_f32_32x32x16_bf16 v[16:31], v[72:75], v[96:99], v[16:31]
	global_load_dwordx4 v[64:67], v[104:105], off offset:1024
	global_load_dwordx4 v[68:71], v[106:107], off offset:1024
	global_load_dwordx4 v[72:75], v[108:109], off offset:1024
	global_load_dwordx4 v[76:79], v[110:111], off offset:1024
	global_load_dwordx4 v[84:87], v[112:113], off offset:1024
	global_load_dwordx4 v[88:91], v[114:115], off offset:1024
	global_load_dwordx4 v[96:99], v[116:117], off offset:1024
	global_load_dwordx4 v[100:103], v[118:119], off offset:1024
	s_waitcnt lgkmcnt(1)
	v_mfma_f32_32x32x16_bf16 v[48:63], v[152:155], v[160:163], v[48:63]
	v_mfma_f32_32x32x16_bf16 v[32:47], v[156:159], v[160:163], v[32:47]
	s_waitcnt lgkmcnt(0)
	v_mfma_f32_32x32x16_bf16 v[0:15], v[152:155], v[164:167], v[0:15]
	ds_read_b128 v[152:155], v126 offset:18464
	ds_read_b128 v[160:163], v126 offset:23072
	ds_read_b128 v[168:171], v124 offset:32
	ds_read_b128 v[172:175], v124 offset:4640
	v_mfma_f32_32x32x16_bf16 v[16:31], v[156:159], v[164:167], v[16:31]
	s_waitcnt lgkmcnt(1)
	v_mfma_f32_32x32x16_bf16 v[48:63], v[152:155], v[168:171], v[48:63]
	v_mfma_f32_32x32x16_bf16 v[32:47], v[160:163], v[168:171], v[32:47]
	s_waitcnt lgkmcnt(0)
	v_mfma_f32_32x32x16_bf16 v[0:15], v[152:155], v[172:175], v[0:15]
	ds_read_b128 v[152:155], v126 offset:18496
	ds_read_b128 v[156:159], v126 offset:23104
	ds_read_b128 v[164:167], v124 offset:64
	ds_read_b128 v[168:171], v124 offset:4672
	s_waitcnt vmcnt(15)
	ds_write_b128 v125, v[80:83] offset:36864
	s_waitcnt vmcnt(13)
	ds_write_b128 v125, v[128:131] offset:41472
	s_waitcnt vmcnt(11)
	ds_write_b128 v125, v[136:139] offset:46080
	s_waitcnt vmcnt(9)
	ds_write_b128 v125, v[144:147] offset:50688
	v_mfma_f32_32x32x16_bf16 v[16:31], v[160:163], v[172:175], v[16:31]
	s_waitcnt lgkmcnt(5)
	v_mfma_f32_32x32x16_bf16 v[48:63], v[152:155], v[164:167], v[48:63]
	ds_read_b128 v[80:83], v126 offset:18528
	ds_read_b128 v[128:131], v126 offset:23136
	ds_read_b128 v[136:139], v124 offset:96
	ds_read_b128 v[144:147], v124 offset:4704
	ds_write_b128 v125, v[92:95] offset:55296
	ds_write_b128 v125, v[132:135] offset:59904
	ds_write_b128 v125, v[140:143] offset:64512
	s_waitcnt vmcnt(8)
	ds_write_b128 v127, v[148:151] offset:13824
	v_mfma_f32_32x32x16_bf16 v[32:47], v[156:159], v[164:167], v[32:47]
	s_waitcnt lgkmcnt(12)
	v_mfma_f32_32x32x16_bf16 v[0:15], v[152:155], v[168:171], v[0:15]
	v_mfma_f32_32x32x16_bf16 v[16:31], v[156:159], v[168:171], v[16:31]
	s_waitcnt lgkmcnt(0)
	s_barrier
	ds_read_b128 v[152:155], v126 offset:55296
	ds_read_b128 v[156:159], v126 offset:59904
	ds_read_b128 v[160:163], v124 offset:36864
	ds_read_b128 v[164:167], v124 offset:41472
	v_mfma_f32_32x32x16_bf16 v[48:63], v[80:83], v[136:139], v[48:63]
	v_mfma_f32_32x32x16_bf16 v[32:47], v[128:131], v[136:139], v[32:47]
	v_mfma_f32_32x32x16_bf16 v[0:15], v[80:83], v[144:147], v[0:15]
	v_mfma_f32_32x32x16_bf16 v[16:31], v[128:131], v[144:147], v[16:31]
	global_load_dwordx4 v[80:83], v[104:105], off offset:1152
	global_load_dwordx4 v[92:95], v[106:107], off offset:1152
	global_load_dwordx4 v[128:131], v[108:109], off offset:1152
	global_load_dwordx4 v[132:135], v[110:111], off offset:1152
	global_load_dwordx4 v[136:139], v[112:113], off offset:1152
	global_load_dwordx4 v[140:143], v[114:115], off offset:1152
	global_load_dwordx4 v[144:147], v[116:117], off offset:1152
	global_load_dwordx4 v[148:151], v[118:119], off offset:1152
	s_waitcnt lgkmcnt(1)
	v_mfma_f32_32x32x16_bf16 v[48:63], v[152:155], v[160:163], v[48:63]
	v_mfma_f32_32x32x16_bf16 v[32:47], v[156:159], v[160:163], v[32:47]
	s_waitcnt lgkmcnt(0)
	v_mfma_f32_32x32x16_bf16 v[0:15], v[152:155], v[164:167], v[0:15]
	ds_read_b128 v[152:155], v126 offset:55328
	ds_read_b128 v[160:163], v126 offset:59936
	ds_read_b128 v[168:171], v124 offset:36896
	ds_read_b128 v[172:175], v124 offset:41504
	v_mfma_f32_32x32x16_bf16 v[16:31], v[156:159], v[164:167], v[16:31]
	s_waitcnt lgkmcnt(1)
	v_mfma_f32_32x32x16_bf16 v[48:63], v[152:155], v[168:171], v[48:63]
	v_mfma_f32_32x32x16_bf16 v[32:47], v[160:163], v[168:171], v[32:47]
	s_waitcnt lgkmcnt(0)
	v_mfma_f32_32x32x16_bf16 v[0:15], v[152:155], v[172:175], v[0:15]
	ds_read_b128 v[152:155], v126 offset:55360
	ds_read_b128 v[156:159], v126 offset:59968
	ds_read_b128 v[164:167], v124 offset:36928
	ds_read_b128 v[168:171], v124 offset:41536
	s_waitcnt vmcnt(15)
	ds_write_b128 v125, v[64:67]
	s_waitcnt vmcnt(13)
	ds_write_b128 v125, v[72:75] offset:4608
	s_waitcnt vmcnt(11)
	ds_write_b128 v125, v[84:87] offset:9216
	s_waitcnt vmcnt(9)
	ds_write_b128 v125, v[96:99] offset:13824
	v_mfma_f32_32x32x16_bf16 v[16:31], v[160:163], v[172:175], v[16:31]
	s_waitcnt lgkmcnt(5)
	v_mfma_f32_32x32x16_bf16 v[48:63], v[152:155], v[164:167], v[48:63]
	ds_read_b128 v[64:67], v126 offset:55392
	ds_read_b128 v[72:75], v126 offset:60000
	ds_read_b128 v[84:87], v124 offset:36960
	ds_read_b128 v[96:99], v124 offset:41568
	ds_write_b128 v125, v[68:71] offset:18432
	ds_write_b128 v125, v[76:79] offset:23040
	ds_write_b128 v125, v[88:91] offset:27648
	s_waitcnt vmcnt(8)
	ds_write_b128 v125, v[100:103] offset:32256
	v_mfma_f32_32x32x16_bf16 v[32:47], v[156:159], v[164:167], v[32:47]
	s_waitcnt lgkmcnt(12)
	v_mfma_f32_32x32x16_bf16 v[0:15], v[152:155], v[168:171], v[0:15]
	v_mfma_f32_32x32x16_bf16 v[16:31], v[156:159], v[168:171], v[16:31]
	s_waitcnt lgkmcnt(0)
	s_barrier
; template <bool SWAP>
; DI void gemm_tile(const bf16_t* __restrict__ A, int lda, const bf16_t* __restrict__ Bt, int ldb, int K, f32x16 (&acc)[2][2], bf16_t* As, bf16_t* Bs_unused) {
;     ...
;   auto step = [&](int buf, u32x4 (&ra)[4], u32x4 (&rb)[4], bool do_write, bool do_load, int tload) __attribute__((always_inline)) {
;     const bf16_t* pa = As + buf * 2 * GT_IMG + pao; const bf16_t* pb = As + buf * 2 * GT_IMG + pbo;
;     bf16_t* Ad = As + (buf ^ 1) * 2 * GT_IMG; bf16_t* Bd = Ad + GT_IMG;
;     bf16x8 F0[4], F1[4];
;     frag_read(F0, pa, pb, 0);
;     __builtin_amdgcn_sched_barrier(0);
;     frag_read(F1, pa, pb, 16);
;     mfma4(F0);
;     __builtin_amdgcn_sched_barrier(0);
;     frag_read(F0, pa, pb, 32);
;     mfma4(F1);
;     if (do_write) {
; #pragma unroll
;       for (int i = 0; i < 4; ++i) *(u32x4*)(Ad + (lr + 32 * i) * 72 + lc) = ra[i];
;     }
;     __builtin_amdgcn_sched_barrier(0);
;     frag_read(F1, pa, pb, 48);
;     mfma4(F0);
;     if (do_write) {
; #pragma unroll
;       for (int i = 0; i < 4; ++i) *(u32x4*)(Bd + (lr + 32 * i) * 72 + lc) = rb[i];
;     }
;     __builtin_amdgcn_sched_barrier(0);
;     mfma4(F1);
;     if (do_load) load_stage(ra, rb, tload);
;     __builtin_amdgcn_sched_barrier(0);
;   };
;   const int nk = K >> 6;
;   load_stage(ra0, rb0, 0); load_stage(ra1, rb1, 1);
;   __syncthreads();
;   write_stage(ra0, rb0, 0);
;   load_stage(ra0, rb0, 2);
;   __syncthreads();
;   for (int kt = 0; kt < nk; kt += 2) {
;     step(0, ra1, rb1, true, kt + 3 < nk, kt + 3);
;     __syncthreads();
;     step(1, ra0, rb0, kt + 2 < nk, kt + 4 < nk, kt + 4);
;     __syncthreads();
	ds_read_b128 v[152:155], v126 offset:18432
	ds_read_b128 v[156:159], v126 offset:23040
	ds_read_b128 v[160:163], v124
	ds_read_b128 v[164:167], v124 offset:4608
	v_mfma_f32_32x32x16_bf16 v[48:63], v[64:67], v[84:87], v[48:63]
	v_mfma_f32_32x32x16_bf16 v[32:47], v[72:75], v[84:87], v[32:47]
	v_mfma_f32_32x32x16_bf16 v[0:15], v[64:67], v[96:99], v[0:15]
	v_mfma_f32_32x32x16_bf16 v[16:31], v[72:75], v[96:99], v[16:31]
	global_load_dwordx4 v[64:67], v[104:105], off offset:1280
	global_load_dwordx4 v[68:71], v[106:107], off offset:1280
	global_load_dwordx4 v[72:75], v[108:109], off offset:1280
	global_load_dwordx4 v[76:79], v[110:111], off offset:1280
	global_load_dwordx4 v[84:87], v[112:113], off offset:1280
	global_load_dwordx4 v[88:91], v[114:115], off offset:1280
	global_load_dwordx4 v[96:99], v[116:117], off offset:1280
	global_load_dwordx4 v[100:103], v[118:119], off offset:1280
	s_waitcnt lgkmcnt(1)
	v_mfma_f32_32x32x16_bf16 v[48:63], v[152:155], v[160:163], v[48:63]
	v_mfma_f32_32x32x16_bf16 v[32:47], v[156:159], v[160:163], v[32:47]
	s_waitcnt lgkmcnt(0)
	v_mfma_f32_32x32x16_bf16 v[0:15], v[152:155], v[164:167], v[0:15]
	ds_read_b128 v[152:155], v126 offset:18464
	ds_read_b128 v[160:163], v126 offset:23072
	ds_read_b128 v[168:171], v124 offset:32
	ds_read_b128 v[172:175], v124 offset:4640
	v_mfma_f32_32x32x16_bf16 v[16:31], v[156:159], v[164:167], v[16:31]
	s_waitcnt lgkmcnt(1)
	v_mfma_f32_32x32x16_bf16 v[48:63], v[152:155], v[168:171], v[48:63]
	v_mfma_f32_32x32x16_bf16 v[32:47], v[160:163], v[168:171], v[32:47]
	s_waitcnt lgkmcnt(0)
	v_mfma_f32_32x32x16_bf16 v[0:15], v[152:155], v[172:175], v[0:15]
	ds_read_b128 v[152:155], v126 offset:18496
	ds_read_b128 v[156:159], v126 offset:23104
	ds_read_b128 v[164:167], v124 offset:64
	ds_read_b128 v[168:171], v124 offset:4672
	s_waitcnt vmcnt(15)
	ds_write_b128 v125, v[80:83] offset:36864
	s_waitcnt vmcnt(13)
	ds_write_b128 v125, v[128:131] offset:41472
	s_waitcnt vmcnt(11)
	ds_write_b128 v125, v[136:139] offset:46080
	s_waitcnt vmcnt(9)
	ds_write_b128 v125, v[144:147] offset:50688
	v_mfma_f32_32x32x16_bf16 v[16:31], v[160:163], v[172:175], v[16:31]
	s_waitcnt lgkmcnt(5)
	v_mfma_f32_32x32x16_bf16 v[48:63], v[152:155], v[164:167], v[48:63]
	ds_read_b128 v[80:83], v126 offset:18528
	ds_read_b128 v[128:131], v126 offset:23136
	ds_read_b128 v[136:139], v124 offset:96
	ds_read_b128 v[144:147], v124 offset:4704
	ds_write_b128 v125, v[92:95] offset:55296
	ds_write_b128 v125, v[132:135] offset:59904
	ds_write_b128 v125, v[140:143] offset:64512
	s_waitcnt vmcnt(8)
	ds_write_b128 v127, v[148:151] offset:13824
	v_mfma_f32_32x32x16_bf16 v[32:47], v[156:159], v[164:167], v[32:47]
	s_waitcnt lgkmcnt(12)
	v_mfma_f32_32x32x16_bf16 v[0:15], v[152:155], v[168:171], v[0:15]
	v_mfma_f32_32x32x16_bf16 v[16:31], v[156:159], v[168:171], v[16:31]
	s_waitcnt lgkmcnt(0)
	s_barrier
	ds_read_b128 v[152:155], v126 offset:55296
	ds_read_b128 v[156:159], v126 offset:59904
	ds_read_b128 v[160:163], v124 offset:36864
	ds_read_b128 v[164:167], v124 offset:41472
	v_mfma_f32_32x32x16_bf16 v[48:63], v[80:83], v[136:139], v[48:63]
	v_mfma_f32_32x32x16_bf16 v[32:47], v[128:131], v[136:139], v[32:47]
	v_mfma_f32_32x32x16_bf16 v[0:15], v[80:83], v[144:147], v[0:15]
	v_mfma_f32_32x32x16_bf16 v[16:31], v[128:131], v[144:147], v[16:31]
	global_load_dwordx4 v[80:83], v[104:105], off offset:1408
	global_load_dwordx4 v[92:95], v[106:107], off offset:1408
	global_load_dwordx4 v[128:131], v[108:109], off offset:1408
	global_load_dwordx4 v[132:135], v[110:111], off offset:1408
	global_load_dwordx4 v[136:139], v[112:113], off offset:1408
	global_load_dwordx4 v[140:143], v[114:115], off offset:1408
	global_load_dwordx4 v[144:147], v[116:117], off offset:1408
	global_load_dwordx4 v[148:151], v[118:119], off offset:1408
	s_waitcnt lgkmcnt(1)
	v_mfma_f32_32x32x16_bf16 v[48:63], v[152:155], v[160:163], v[48:63]
	v_mfma_f32_32x32x16_bf16 v[32:47], v[156:159], v[160:163], v[32:47]
	s_waitcnt lgkmcnt(0)
	v_mfma_f32_32x32x16_bf16 v[0:15], v[152:155], v[164:167], v[0:15]
	ds_read_b128 v[152:155], v126 offset:55328
	ds_read_b128 v[160:163], v126 offset:59936
	ds_read_b128 v[168:171], v124 offset:36896
	ds_read_b128 v[172:175], v124 offset:41504
	v_mfma_f32_32x32x16_bf16 v[16:31], v[156:159], v[164:167], v[16:31]
	s_waitcnt lgkmcnt(1)
	v_mfma_f32_32x32x16_bf16 v[48:63], v[152:155], v[168:171], v[48:63]
	v_mfma_f32_32x32x16_bf16 v[32:47], v[160:163], v[168:171], v[32:47]
	s_waitcnt lgkmcnt(0)
	v_mfma_f32_32x32x16_bf16 v[0:15], v[152:155], v[172:175], v[0:15]
	ds_read_b128 v[152:155], v126 offset:55360
	ds_read_b128 v[156:159], v126 offset:59968
	ds_read_b128 v[164:167], v124 offset:36928
	ds_read_b128 v[168:171], v124 offset:41536
	s_waitcnt vmcnt(15)
	ds_write_b128 v125, v[64:67]
	s_waitcnt vmcnt(13)
	ds_write_b128 v125, v[72:75] offset:4608
	s_waitcnt vmcnt(11)
	ds_write_b128 v125, v[84:87] offset:9216
	s_waitcnt vmcnt(9)
	ds_write_b128 v125, v[96:99] offset:13824
	v_mfma_f32_32x32x16_bf16 v[16:31], v[160:163], v[172:175], v[16:31]
	s_waitcnt lgkmcnt(5)
	v_mfma_f32_32x32x16_bf16 v[48:63], v[152:155], v[164:167], v[48:63]
	ds_read_b128 v[64:67], v126 offset:55392
	ds_read_b128 v[72:75], v126 offset:60000
	ds_read_b128 v[84:87], v124 offset:36960
	ds_read_b128 v[96:99], v124 offset:41568
	ds_write_b128 v125, v[68:71] offset:18432
	ds_write_b128 v125, v[76:79] offset:23040
	ds_write_b128 v125, v[88:91] offset:27648
	s_waitcnt vmcnt(8)
	ds_write_b128 v125, v[100:103] offset:32256
	v_mfma_f32_32x32x16_bf16 v[32:47], v[156:159], v[164:167], v[32:47]
	s_waitcnt lgkmcnt(12)
	v_mfma_f32_32x32x16_bf16 v[0:15], v[152:155], v[168:171], v[0:15]
	v_mfma_f32_32x32x16_bf16 v[16:31], v[156:159], v[168:171], v[16:31]
	s_waitcnt lgkmcnt(0)
	s_barrier
; template <bool SWAP>
; DI void gemm_tile(const bf16_t* __restrict__ A, int lda, const bf16_t* __restrict__ Bt, int ldb, int K, f32x16 (&acc)[2][2], bf16_t* As, bf16_t* Bs_unused) {
;     ...
;   auto step = [&](int buf, u32x4 (&ra)[4], u32x4 (&rb)[4], bool do_write, bool do_load, int tload) __attribute__((always_inline)) {
;     const bf16_t* pa = As + buf * 2 * GT_IMG + pao; const bf16_t* pb = As + buf * 2 * GT_IMG + pbo;
;     bf16_t* Ad = As + (buf ^ 1) * 2 * GT_IMG; bf16_t* Bd = Ad + GT_IMG;
;     bf16x8 F0[4], F1[4];
;     frag_read(F0, pa, pb, 0);
;     __builtin_amdgcn_sched_barrier(0);
;     frag_read(F1, pa, pb, 16);
;     mfma4(F0);
;     __builtin_amdgcn_sched_barrier(0);
;     frag_read(F0, pa, pb, 32);
;     mfma4(F1);
;     if (do_write) {
; #pragma unroll
;       for (int i = 0; i < 4; ++i) *(u32x4*)(Ad + (lr + 32 * i) * 72 + lc) = ra[i];
;     }
;     __builtin_amdgcn_sched_barrier(0);
;     frag_read(F1, pa, pb, 48);
;     mfma4(F0);
;     if (do_write) {
; #pragma unroll
;       for (int i = 0; i < 4; ++i) *(u32x4*)(Bd + (lr + 32 * i) * 72 + lc) = rb[i];
;     }
;     __builtin_amdgcn_sched_barrier(0);
;     mfma4(F1);
;     if (do_load) load_stage(ra, rb, tload);
;     __builtin_amdgcn_sched_barrier(0);
;   };
;   const int nk = K >> 6;
;   load_stage(ra0, rb0, 0); load_stage(ra1, rb1, 1);
;   __syncthreads();
;   write_stage(ra0, rb0, 0);
;   load_stage(ra0, rb0, 2);
;   __syncthreads();
;   for (int kt = 0; kt < nk; kt += 2) {
;     step(0, ra1, rb1, true, kt + 3 < nk, kt + 3);
;     __syncthreads();
;     step(1, ra0, rb0, kt + 2 < nk, kt + 4 < nk, kt + 4);
;     __syncthreads();
	ds_read_b128 v[152:155], v126 offset:18432
	ds_read_b128 v[156:159], v126 offset:23040
	ds_read_b128 v[160:163], v124
	ds_read_b128 v[164:167], v124 offset:4608
	v_mfma_f32_32x32x16_bf16 v[48:63], v[64:67], v[84:87], v[48:63]
	v_mfma_f32_32x32x16_bf16 v[32:47], v[72:75], v[84:87], v[32:47]
	v_mfma_f32_32x32x16_bf16 v[0:15], v[64:67], v[96:99], v[0:15]
	v_mfma_f32_32x32x16_bf16 v[16:31], v[72:75], v[96:99], v[16:31]
	global_load_dwordx4 v[64:67], v[104:105], off offset:1536
	global_load_dwordx4 v[68:71], v[106:107], off offset:1536
	global_load_dwordx4 v[72:75], v[108:109], off offset:1536
	global_load_dwordx4 v[76:79], v[110:111], off offset:1536
	global_load_dwordx4 v[84:87], v[112:113], off offset:1536
	global_load_dwordx4 v[88:91], v[114:115], off offset:1536
	global_load_dwordx4 v[96:99], v[116:117], off offset:1536
	global_load_dwordx4 v[100:103], v[118:119], off offset:1536
	s_waitcnt lgkmcnt(1)
	v_mfma_f32_32x32x16_bf16 v[48:63], v[152:155], v[160:163], v[48:63]
	v_mfma_f32_32x32x16_bf16 v[32:47], v[156:159], v[160:163], v[32:47]
	s_waitcnt lgkmcnt(0)
	v_mfma_f32_32x32x16_bf16 v[0:15], v[152:155], v[164:167], v[0:15]
	ds_read_b128 v[152:155], v126 offset:18464
	ds_read_b128 v[160:163], v126 offset:23072
	ds_read_b128 v[168:171], v124 offset:32
	ds_read_b128 v[172:175], v124 offset:4640
	v_mfma_f32_32x32x16_bf16 v[16:31], v[156:159], v[164:167], v[16:31]
	s_waitcnt lgkmcnt(1)
	v_mfma_f32_32x32x16_bf16 v[48:63], v[152:155], v[168:171], v[48:63]
	v_mfma_f32_32x32x16_bf16 v[32:47], v[160:163], v[168:171], v[32:47]
	s_waitcnt lgkmcnt(0)
	v_mfma_f32_32x32x16_bf16 v[0:15], v[152:155], v[172:175], v[0:15]
	ds_read_b128 v[152:155], v126 offset:18496
	ds_read_b128 v[156:159], v126 offset:23104
	ds_read_b128 v[164:167], v124 offset:64
	ds_read_b128 v[168:171], v124 offset:4672
	s_waitcnt vmcnt(15)
	ds_write_b128 v125, v[80:83] offset:36864
	s_waitcnt vmcnt(13)
	ds_write_b128 v125, v[128:131] offset:41472
	s_waitcnt vmcnt(11)
	ds_write_b128 v125, v[136:139] offset:46080
	s_waitcnt vmcnt(9)
	ds_write_b128 v125, v[144:147] offset:50688
	v_mfma_f32_32x32x16_bf16 v[16:31], v[160:163], v[172:175], v[16:31]
	s_waitcnt lgkmcnt(5)
	v_mfma_f32_32x32x16_bf16 v[48:63], v[152:155], v[164:167], v[48:63]
	ds_read_b128 v[80:83], v126 offset:18528
	ds_read_b128 v[128:131], v126 offset:23136
	ds_read_b128 v[136:139], v124 offset:96
	ds_read_b128 v[144:147], v124 offset:4704
	ds_write_b128 v125, v[92:95] offset:55296
	ds_write_b128 v125, v[132:135] offset:59904
	ds_write_b128 v125, v[140:143] offset:64512
	s_waitcnt vmcnt(8)
	ds_write_b128 v127, v[148:151] offset:13824
	v_mfma_f32_32x32x16_bf16 v[32:47], v[156:159], v[164:167], v[32:47]
	s_waitcnt lgkmcnt(12)
	v_mfma_f32_32x32x16_bf16 v[0:15], v[152:155], v[168:171], v[0:15]
	v_mfma_f32_32x32x16_bf16 v[16:31], v[156:159], v[168:171], v[16:31]
	s_waitcnt lgkmcnt(0)
	s_barrier
	ds_read_b128 v[152:155], v126 offset:55296
	ds_read_b128 v[156:159], v126 offset:59904
	ds_read_b128 v[160:163], v124 offset:36864
	ds_read_b128 v[164:167], v124 offset:41472
	v_mfma_f32_32x32x16_bf16 v[48:63], v[80:83], v[136:139], v[48:63]
	v_mfma_f32_32x32x16_bf16 v[32:47], v[128:131], v[136:139], v[32:47]
	v_mfma_f32_32x32x16_bf16 v[0:15], v[80:83], v[144:147], v[0:15]
	v_mfma_f32_32x32x16_bf16 v[16:31], v[128:131], v[144:147], v[16:31]
	global_load_dwordx4 v[80:83], v[104:105], off offset:1664
	global_load_dwordx4 v[92:95], v[106:107], off offset:1664
	global_load_dwordx4 v[128:131], v[108:109], off offset:1664
	global_load_dwordx4 v[132:135], v[110:111], off offset:1664
	global_load_dwordx4 v[136:139], v[112:113], off offset:1664
	global_load_dwordx4 v[140:143], v[114:115], off offset:1664
	global_load_dwordx4 v[144:147], v[116:117], off offset:1664
	global_load_dwordx4 v[148:151], v[118:119], off offset:1664
	s_waitcnt lgkmcnt(1)
	v_mfma_f32_32x32x16_bf16 v[48:63], v[152:155], v[160:163], v[48:63]
	v_mfma_f32_32x32x16_bf16 v[32:47], v[156:159], v[160:163], v[32:47]
	s_waitcnt lgkmcnt(0)
	v_mfma_f32_32x32x16_bf16 v[0:15], v[152:155], v[164:167], v[0:15]
	ds_read_b128 v[152:155], v126 offset:55328
	ds_read_b128 v[160:163], v126 offset:59936
	ds_read_b128 v[168:171], v124 offset:36896
	ds_read_b128 v[172:175], v124 offset:41504
	v_mfma_f32_32x32x16_bf16 v[16:31], v[156:159], v[164:167], v[16:31]
	s_waitcnt lgkmcnt(1)
	v_mfma_f32_32x32x16_bf16 v[48:63], v[152:155], v[168:171], v[48:63]
	v_mfma_f32_32x32x16_bf16 v[32:47], v[160:163], v[168:171], v[32:47]
	s_waitcnt lgkmcnt(0)
	v_mfma_f32_32x32x16_bf16 v[0:15], v[152:155], v[172:175], v[0:15]
	ds_read_b128 v[152:155], v126 offset:55360
	ds_read_b128 v[156:159], v126 offset:59968
	ds_read_b128 v[164:167], v124 offset:36928
	ds_read_b128 v[168:171], v124 offset:41536
	s_waitcnt vmcnt(15)
	ds_write_b128 v125, v[64:67]
	s_waitcnt vmcnt(13)
	ds_write_b128 v125, v[72:75] offset:4608
	s_waitcnt vmcnt(11)
	ds_write_b128 v125, v[84:87] offset:9216
	s_waitcnt vmcnt(9)
	ds_write_b128 v125, v[96:99] offset:13824
	v_mfma_f32_32x32x16_bf16 v[16:31], v[160:163], v[172:175], v[16:31]
	s_waitcnt lgkmcnt(5)
	v_mfma_f32_32x32x16_bf16 v[48:63], v[152:155], v[164:167], v[48:63]
	ds_read_b128 v[64:67], v126 offset:55392
	ds_read_b128 v[72:75], v126 offset:60000
	ds_read_b128 v[84:87], v124 offset:36960
	ds_read_b128 v[96:99], v124 offset:41568
	ds_write_b128 v125, v[68:71] offset:18432
	ds_write_b128 v125, v[76:79] offset:23040
	ds_write_b128 v125, v[88:91] offset:27648
	s_waitcnt vmcnt(8)
	ds_write_b128 v125, v[100:103] offset:32256
	v_mfma_f32_32x32x16_bf16 v[32:47], v[156:159], v[164:167], v[32:47]
	s_waitcnt lgkmcnt(12)
	v_mfma_f32_32x32x16_bf16 v[0:15], v[152:155], v[168:171], v[0:15]
	v_mfma_f32_32x32x16_bf16 v[16:31], v[156:159], v[168:171], v[16:31]
	s_waitcnt lgkmcnt(0)
	s_barrier
; template <bool SWAP>
; DI void gemm_tile(const bf16_t* __restrict__ A, int lda, const bf16_t* __restrict__ Bt, int ldb, int K, f32x16 (&acc)[2][2], bf16_t* As, bf16_t* Bs_unused) {
;     ...
;   auto step = [&](int buf, u32x4 (&ra)[4], u32x4 (&rb)[4], bool do_write, bool do_load, int tload) __attribute__((always_inline)) {
;     const bf16_t* pa = As + buf * 2 * GT_IMG + pao; const bf16_t* pb = As + buf * 2 * GT_IMG + pbo;
;     bf16_t* Ad = As + (buf ^ 1) * 2 * GT_IMG; bf16_t* Bd = Ad + GT_IMG;
;     bf16x8 F0[4], F1[4];
;     frag_read(F0, pa, pb, 0);
;     __builtin_amdgcn_sched_barrier(0);
;     frag_read(F1, pa, pb, 16);
;     mfma4(F0);
;     __builtin_amdgcn_sched_barrier(0);
;     frag_read(F0, pa, pb, 32);
;     mfma4(F1);
;     if (do_write) {
; #pragma unroll
;       for (int i = 0; i < 4; ++i) *(u32x4*)(Ad + (lr + 32 * i) * 72 + lc) = ra[i];
;     }
;     __builtin_amdgcn_sched_barrier(0);
;     frag_read(F1, pa, pb, 48);
;     mfma4(F0);
;     if (do_write) {
; #pragma unroll
;       for (int i = 0; i < 4; ++i) *(u32x4*)(Bd + (lr + 32 * i) * 72 + lc) = rb[i];
;     }
;     __builtin_amdgcn_sched_barrier(0);
;     mfma4(F1);
;     if (do_load) load_stage(ra, rb, tload);
;     __builtin_amdgcn_sched_barrier(0);
;   };
;   const int nk = K >> 6;
;   load_stage(ra0, rb0, 0); load_stage(ra1, rb1, 1);
;   __syncthreads();
;   write_stage(ra0, rb0, 0);
;   load_stage(ra0, rb0, 2);
;   __syncthreads();
;   for (int kt = 0; kt < nk; kt += 2) {
;     step(0, ra1, rb1, true, kt + 3 < nk, kt + 3);
;     __syncthreads();
;     step(1, ra0, rb0, kt + 2 < nk, kt + 4 < nk, kt + 4);
;     __syncthreads();
	ds_read_b128 v[152:155], v126 offset:18432
	ds_read_b128 v[156:159], v126 offset:23040
	ds_read_b128 v[160:163], v124
	ds_read_b128 v[164:167], v124 offset:4608
	v_mfma_f32_32x32x16_bf16 v[48:63], v[64:67], v[84:87], v[48:63]
	v_mfma_f32_32x32x16_bf16 v[32:47], v[72:75], v[84:87], v[32:47]
	v_mfma_f32_32x32x16_bf16 v[0:15], v[64:67], v[96:99], v[0:15]
	v_mfma_f32_32x32x16_bf16 v[16:31], v[72:75], v[96:99], v[16:31]
	global_load_dwordx4 v[64:67], v[104:105], off offset:1792
	global_load_dwordx4 v[68:71], v[106:107], off offset:1792
	global_load_dwordx4 v[72:75], v[108:109], off offset:1792
	global_load_dwordx4 v[76:79], v[110:111], off offset:1792
	global_load_dwordx4 v[84:87], v[112:113], off offset:1792
	global_load_dwordx4 v[88:91], v[114:115], off offset:1792
	global_load_dwordx4 v[96:99], v[116:117], off offset:1792
	global_load_dwordx4 v[100:103], v[118:119], off offset:1792
	s_waitcnt lgkmcnt(1)
	v_mfma_f32_32x32x16_bf16 v[48:63], v[152:155], v[160:163], v[48:63]
	v_mfma_f32_32x32x16_bf16 v[32:47], v[156:159], v[160:163], v[32:47]
	s_waitcnt lgkmcnt(0)
	v_mfma_f32_32x32x16_bf16 v[0:15], v[152:155], v[164:167], v[0:15]
	ds_read_b128 v[152:155], v126 offset:18464
	ds_read_b128 v[160:163], v126 offset:23072
	ds_read_b128 v[168:171], v124 offset:32
	ds_read_b128 v[172:175], v124 offset:4640
	v_mfma_f32_32x32x16_bf16 v[16:31], v[156:159], v[164:167], v[16:31]
	s_waitcnt lgkmcnt(1)
	v_mfma_f32_32x32x16_bf16 v[48:63], v[152:155], v[168:171], v[48:63]
	v_mfma_f32_32x32x16_bf16 v[32:47], v[160:163], v[168:171], v[32:47]
	s_waitcnt lgkmcnt(0)
	v_mfma_f32_32x32x16_bf16 v[0:15], v[152:155], v[172:175], v[0:15]
	ds_read_b128 v[152:155], v126 offset:18496
	ds_read_b128 v[156:159], v126 offset:23104
	ds_read_b128 v[164:167], v124 offset:64
	ds_read_b128 v[168:171], v124 offset:4672
	s_waitcnt vmcnt(15)
	ds_write_b128 v125, v[80:83] offset:36864
	s_waitcnt vmcnt(13)
	ds_write_b128 v125, v[128:131] offset:41472
	s_waitcnt vmcnt(11)
	ds_write_b128 v125, v[136:139] offset:46080
	s_waitcnt vmcnt(9)
	ds_write_b128 v125, v[144:147] offset:50688
	v_mfma_f32_32x32x16_bf16 v[16:31], v[160:163], v[172:175], v[16:31]
	s_waitcnt lgkmcnt(5)
	v_mfma_f32_32x32x16_bf16 v[48:63], v[152:155], v[164:167], v[48:63]
	ds_read_b128 v[80:83], v126 offset:18528
	ds_read_b128 v[128:131], v126 offset:23136
	ds_read_b128 v[136:139], v124 offset:96
	ds_read_b128 v[144:147], v124 offset:4704
	ds_write_b128 v125, v[92:95] offset:55296
	ds_write_b128 v125, v[132:135] offset:59904
	ds_write_b128 v125, v[140:143] offset:64512
	s_waitcnt vmcnt(8)
	ds_write_b128 v127, v[148:151] offset:13824
	v_mfma_f32_32x32x16_bf16 v[32:47], v[156:159], v[164:167], v[32:47]
	s_waitcnt lgkmcnt(12)
	v_mfma_f32_32x32x16_bf16 v[0:15], v[152:155], v[168:171], v[0:15]
	v_mfma_f32_32x32x16_bf16 v[16:31], v[156:159], v[168:171], v[16:31]
	s_waitcnt lgkmcnt(0)
	s_barrier
	ds_read_b128 v[180:183], v126 offset:55296
	ds_read_b128 v[184:187], v126 offset:59904
	ds_read_b128 v[188:191], v124 offset:36864
	ds_read_b128 v[220:223], v124 offset:41472
	v_mfma_f32_32x32x16_bf16 v[48:63], v[80:83], v[136:139], v[48:63]
	v_mfma_f32_32x32x16_bf16 v[32:47], v[128:131], v[136:139], v[32:47]
	v_mfma_f32_32x32x16_bf16 v[0:15], v[80:83], v[144:147], v[0:15]
	v_mfma_f32_32x32x16_bf16 v[16:31], v[128:131], v[144:147], v[16:31]
	global_load_dwordx4 v[80:83], v[104:105], off offset:1920
	global_load_dwordx4 v[92:95], v[106:107], off offset:1920
	s_nop 0
	global_load_dwordx4 v[104:107], v[108:109], off offset:1920
	s_nop 0
	global_load_dwordx4 v[108:111], v[110:111], off offset:1920
	s_nop 0
	global_load_dwordx4 v[128:131], v[112:113], off offset:1920
	s_nop 0
	global_load_dwordx4 v[112:115], v[114:115], off offset:1920
	s_nop 0
	global_load_dwordx4 v[132:135], v[116:117], off offset:1920
	s_nop 0
	global_load_dwordx4 v[116:119], v[118:119], off offset:1920
	s_waitcnt lgkmcnt(1)
	v_mfma_f32_32x32x16_bf16 v[48:63], v[180:183], v[188:191], v[48:63]
	v_mfma_f32_32x32x16_bf16 v[32:47], v[184:187], v[188:191], v[32:47]
	s_waitcnt lgkmcnt(0)
	v_mfma_f32_32x32x16_bf16 v[0:15], v[180:183], v[220:223], v[0:15]
	ds_read_b128 v[136:139], v126 offset:55328
	ds_read_b128 v[144:147], v126 offset:59936
	ds_read_b128 v[152:155], v124 offset:36896
	ds_read_b128 v[156:159], v124 offset:41504
	v_mfma_f32_32x32x16_bf16 v[16:31], v[184:187], v[220:223], v[16:31]
	s_waitcnt lgkmcnt(1)
	v_mfma_f32_32x32x16_bf16 v[48:63], v[136:139], v[152:155], v[48:63]
	v_mfma_f32_32x32x16_bf16 v[32:47], v[144:147], v[152:155], v[32:47]
	s_waitcnt lgkmcnt(0)
	v_mfma_f32_32x32x16_bf16 v[0:15], v[136:139], v[156:159], v[0:15]
	ds_read_b128 v[136:139], v126 offset:55360
	ds_read_b128 v[140:143], v126 offset:59968
	ds_read_b128 v[148:151], v124 offset:36928
	ds_read_b128 v[152:155], v124 offset:41536
	s_waitcnt vmcnt(15)
	ds_write_b128 v125, v[64:67]
	s_waitcnt vmcnt(13)
	ds_write_b128 v125, v[72:75] offset:4608
	s_waitcnt vmcnt(11)
	ds_write_b128 v125, v[84:87] offset:9216
	s_waitcnt vmcnt(9)
	ds_write_b128 v125, v[96:99] offset:13824
	v_mfma_f32_32x32x16_bf16 v[16:31], v[144:147], v[156:159], v[16:31]
	s_waitcnt lgkmcnt(5)
	v_mfma_f32_32x32x16_bf16 v[48:63], v[136:139], v[148:151], v[48:63]
	ds_read_b128 v[64:67], v126 offset:55392
	ds_read_b128 v[72:75], v126 offset:60000
	ds_read_b128 v[84:87], v124 offset:36960
	ds_read_b128 v[96:99], v124 offset:41568
	ds_write_b128 v125, v[68:71] offset:18432
	ds_write_b128 v125, v[76:79] offset:23040
	ds_write_b128 v125, v[88:91] offset:27648
	s_waitcnt vmcnt(8)
	ds_write_b128 v125, v[100:103] offset:32256
	v_mfma_f32_32x32x16_bf16 v[32:47], v[140:143], v[148:151], v[32:47]
	s_waitcnt lgkmcnt(12)
	v_mfma_f32_32x32x16_bf16 v[0:15], v[136:139], v[152:155], v[0:15]
	v_mfma_f32_32x32x16_bf16 v[16:31], v[140:143], v[152:155], v[16:31]
	s_waitcnt lgkmcnt(0)
	s_barrier
; template <bool SWAP>
; DI void gemm_tile(const bf16_t* __restrict__ A, int lda, const bf16_t* __restrict__ Bt, int ldb, int K, f32x16 (&acc)[2][2], bf16_t* As, bf16_t* Bs_unused) {
;     ...
;   auto step = [&](int buf, u32x4 (&ra)[4], u32x4 (&rb)[4], bool do_write, bool do_load, int tload) __attribute__((always_inline)) {
;     const bf16_t* pa = As + buf * 2 * GT_IMG + pao; const bf16_t* pb = As + buf * 2 * GT_IMG + pbo;
;     bf16_t* Ad = As + (buf ^ 1) * 2 * GT_IMG; bf16_t* Bd = Ad + GT_IMG;
;     bf16x8 F0[4], F1[4];
;     frag_read(F0, pa, pb, 0);
;     __builtin_amdgcn_sched_barrier(0);
;     frag_read(F1, pa, pb, 16);
;     mfma4(F0);
;     __builtin_amdgcn_sched_barrier(0);
;     frag_read(F0, pa, pb, 32);
;     mfma4(F1);
;     if (do_write) {
; #pragma unroll
;       for (int i = 0; i < 4; ++i) *(u32x4*)(Ad + (lr + 32 * i) * 72 + lc) = ra[i];
;     }
;     __builtin_amdgcn_sched_barrier(0);
;     frag_read(F1, pa, pb, 48);
;     mfma4(F0);
;     if (do_write) {
; #pragma unroll
;       for (int i = 0; i < 4; ++i) *(u32x4*)(Bd + (lr + 32 * i) * 72 + lc) = rb[i];
;     }
;     __builtin_amdgcn_sched_barrier(0);
;     mfma4(F1);
;     if (do_load) load_stage(ra, rb, tload);
;     __builtin_amdgcn_sched_barrier(0);
;   };
;   const int nk = K >> 6;
;   load_stage(ra0, rb0, 0); load_stage(ra1, rb1, 1);
;   __syncthreads();
;   write_stage(ra0, rb0, 0);
;   load_stage(ra0, rb0, 2);
;   __syncthreads();
;   for (int kt = 0; kt < nk; kt += 2) {
;     step(0, ra1, rb1, true, kt + 3 < nk, kt + 3);
;     __syncthreads();
;     step(1, ra0, rb0, kt + 2 < nk, kt + 4 < nk, kt + 4);
;     __syncthreads();
	ds_read_b128 v[180:183], v126 offset:18432
	ds_read_b128 v[184:187], v126 offset:23040
	ds_read_b128 v[188:191], v124
	ds_read_b128 v[220:223], v124 offset:4608
	v_mfma_f32_32x32x16_bf16 v[48:63], v[64:67], v[84:87], v[48:63]
	v_mfma_f32_32x32x16_bf16 v[32:47], v[72:75], v[84:87], v[32:47]
	v_mfma_f32_32x32x16_bf16 v[0:15], v[64:67], v[96:99], v[0:15]
	v_mfma_f32_32x32x16_bf16 v[16:31], v[72:75], v[96:99], v[16:31]
	s_waitcnt lgkmcnt(1)
	v_mfma_f32_32x32x16_bf16 v[48:63], v[180:183], v[188:191], v[48:63]
	v_mfma_f32_32x32x16_bf16 v[32:47], v[184:187], v[188:191], v[32:47]
	s_waitcnt lgkmcnt(0)
	v_mfma_f32_32x32x16_bf16 v[0:15], v[180:183], v[220:223], v[0:15]
	ds_read_b128 v[64:67], v126 offset:18464
	ds_read_b128 v[72:75], v126 offset:23072
	ds_read_b128 v[84:87], v124 offset:32
	ds_read_b128 v[88:91], v124 offset:4640
	v_mfma_f32_32x32x16_bf16 v[16:31], v[184:187], v[220:223], v[16:31]
	s_waitcnt lgkmcnt(1)
	v_mfma_f32_32x32x16_bf16 v[48:63], v[64:67], v[84:87], v[48:63]
	v_mfma_f32_32x32x16_bf16 v[32:47], v[72:75], v[84:87], v[32:47]
	s_waitcnt lgkmcnt(0)
	v_mfma_f32_32x32x16_bf16 v[0:15], v[64:67], v[88:91], v[0:15]
	ds_read_b128 v[64:67], v126 offset:18496
	ds_read_b128 v[68:71], v126 offset:23104
	ds_read_b128 v[76:79], v124 offset:64
	ds_read_b128 v[84:87], v124 offset:4672
	s_waitcnt vmcnt(7)
	ds_write_b128 v125, v[80:83] offset:36864
	s_waitcnt vmcnt(5)
	ds_write_b128 v125, v[104:107] offset:41472
	s_waitcnt vmcnt(3)
	ds_write_b128 v125, v[128:131] offset:46080
	s_waitcnt vmcnt(1)
	ds_write_b128 v125, v[132:135] offset:50688
	v_mfma_f32_32x32x16_bf16 v[16:31], v[72:75], v[88:91], v[16:31]
	s_waitcnt lgkmcnt(5)
	v_mfma_f32_32x32x16_bf16 v[48:63], v[64:67], v[76:79], v[48:63]
	v_mfma_f32_32x32x16_bf16 v[32:47], v[68:71], v[76:79], v[32:47]
	s_waitcnt lgkmcnt(4)
	v_mfma_f32_32x32x16_bf16 v[0:15], v[64:67], v[84:87], v[0:15]
	ds_read_b128 v[64:67], v126 offset:18528
	ds_read_b128 v[72:75], v126 offset:23136
	ds_read_b128 v[76:79], v124 offset:96
	ds_read_b128 v[80:83], v124 offset:4704
	ds_write_b128 v125, v[92:95] offset:55296
	ds_write_b128 v125, v[108:111] offset:59904
	ds_write_b128 v125, v[112:115] offset:64512
	s_waitcnt vmcnt(0)
	ds_write_b128 v127, v[116:119] offset:13824
	v_mfma_f32_32x32x16_bf16 v[16:31], v[68:71], v[84:87], v[16:31]
	s_waitcnt lgkmcnt(0)
	s_barrier
	ds_read_b128 v[180:183], v126 offset:55296
	ds_read_b128 v[184:187], v126 offset:59904
	ds_read_b128 v[188:191], v124 offset:36864
	ds_read_b128 v[220:223], v124 offset:41472
	v_mfma_f32_32x32x16_bf16 v[48:63], v[64:67], v[76:79], v[48:63]
	v_mfma_f32_32x32x16_bf16 v[32:47], v[72:75], v[76:79], v[32:47]
	v_mfma_f32_32x32x16_bf16 v[0:15], v[64:67], v[80:83], v[0:15]
	v_mfma_f32_32x32x16_bf16 v[16:31], v[72:75], v[80:83], v[16:31]
	s_waitcnt lgkmcnt(1)
	v_mfma_f32_32x32x16_bf16 v[48:63], v[180:183], v[188:191], v[48:63]
	v_mfma_f32_32x32x16_bf16 v[32:47], v[184:187], v[188:191], v[32:47]
	s_waitcnt lgkmcnt(0)
	v_mfma_f32_32x32x16_bf16 v[0:15], v[180:183], v[220:223], v[0:15]
	ds_read_b128 v[64:67], v126 offset:55328
	ds_read_b128 v[72:75], v126 offset:59936
	ds_read_b128 v[80:83], v124 offset:36896
	ds_read_b128 v[84:87], v124 offset:41504
	v_mfma_f32_32x32x16_bf16 v[16:31], v[184:187], v[220:223], v[16:31]
	s_waitcnt lgkmcnt(1)
	v_mfma_f32_32x32x16_bf16 v[48:63], v[64:67], v[80:83], v[48:63]
	v_mfma_f32_32x32x16_bf16 v[32:47], v[72:75], v[80:83], v[32:47]
	s_waitcnt lgkmcnt(0)
	v_mfma_f32_32x32x16_bf16 v[0:15], v[64:67], v[84:87], v[0:15]
	ds_read_b128 v[64:67], v126 offset:59968
	ds_read_b128 v[68:71], v126 offset:55360
	ds_read_b128 v[76:79], v124 offset:41536
	ds_read_b128 v[80:83], v124 offset:36928
	v_mfma_f32_32x32x16_bf16 v[16:31], v[72:75], v[84:87], v[16:31]
	s_waitcnt lgkmcnt(0)
	v_mfma_f32_32x32x16_bf16 v[48:63], v[68:71], v[80:83], v[48:63]
	v_mfma_f32_32x32x16_bf16 v[32:47], v[64:67], v[80:83], v[32:47]
	v_mfma_f32_32x32x16_bf16 v[0:15], v[68:71], v[76:79], v[0:15]
	ds_read_b128 v[68:71], v126 offset:60000
	ds_read_b128 v[72:75], v126 offset:55392
	ds_read_b128 v[80:83], v124 offset:41568
	ds_read_b128 v[84:87], v124 offset:36960
	v_mfma_f32_32x32x16_bf16 v[16:31], v[64:67], v[76:79], v[16:31]
	s_waitcnt lgkmcnt(0)
	v_mfma_f32_32x32x16_bf16 v[48:63], v[72:75], v[84:87], v[48:63]
	v_mfma_f32_32x32x16_bf16 v[32:47], v[68:71], v[84:87], v[32:47]
	v_mfma_f32_32x32x16_bf16 v[0:15], v[72:75], v[80:83], v[0:15]
	v_mfma_f32_32x32x16_bf16 v[16:31], v[68:71], v[80:83], v[16:31]
	s_barrier
